# 8-phase GEMM K-loop merged pairwise (32 MFMA per barrier pair, 8 barriers per trip) on top of scan+conv fixes
# speedup vs baseline: 1.0136x; 1.0136x over previous
; #define PG8_STAGE(bufoff, gbase, voff) do { _Pragma("unroll") for (int _i = 0; _i < 2; ++_i) \
;         __builtin_amdgcn_global_load_lds((const unsigned*)((const char*)(gbase) + (voff)[_i]), (LAS unsigned*)(lds + (bufoff) + ldsw + _i * 8192), 16, 0, 0); } while (0)
; #define PG8_WAIT_V(n) asm volatile("s_waitcnt vmcnt(" #n ")" ::: "memory")
; #define PG8_BAR __builtin_amdgcn_s_barrier()
; template <class Epi>
; DI void gemm_phase(LAS unsigned char* lds, const Gemm g, const StaticOrder& S, const Epi& E) {
;     ...
;     const char* cA = PG8_ABASE(cur); const char* cB = PG8_BBASE(cur);
;     PG8_STAGE(PG8_SB(0, 0), cB, voffB); PG8_STAGE(PG8_SA(0, 0), cA, voffA); PG8_STAGE(PG8_SB(0, 1), cB + hstepB, voffB); PG8_STAGE(PG8_SA(0, 1), cA + hstepA, voffA);
;     if (wr == 1) PG8_BAR;
;     PG8_WAIT_V(4); PG8_BAR;
;     PG8_STAGE(PG8_SB(1, 0), cB + kstep, voffB); PG8_STAGE(PG8_SA(1, 0), cA + kstep, voffA); PG8_STAGE(PG8_SB(1, 1), cB + hstepB + kstep, voffB);
;     PG8_WAIT_V(6); PG8_BAR;
.LBB0_269:
	s_add_u32 s8, s4, 0xb400000
	s_addc_u32 s9, s5, 0
	s_lshl_b32 s4, s10, 5
	s_mov_b64 s[10:11], 0x80
	s_and_b32 s17, s4, 0x60
	s_add_i32 m0, s13, 0x18000
	v_lshl_add_u64 v[8:9], v[8:9], 0, s[10:11]
	s_lshl_b32 s16, s15, 13
	s_lshl_b32 s18, s17, 7
	s_waitcnt vmcnt(0)
	s_barrier
	global_load_lds_dwordx4 v[8:9], off
	v_lshl_add_u64 v[6:7], v[6:7], 0, s[10:11]
	s_add_i32 m0, s13, 0x1a000
	s_add_i32 s49, s13, 0x8000
	s_add_i32 s50, s13, 0xa000
	global_load_lds_dwordx4 v[6:7], off
	v_lshl_add_u64 v[4:5], v[4:5], 0, s[10:11]
	s_mov_b32 m0, s49
	s_add_u32 s4, s24, 0x80080
	global_load_lds_dwordx4 v[4:5], off
	v_lshl_add_u64 v[2:3], v[2:3], 0, s[10:11]
	s_mov_b32 m0, s50
	s_addc_u32 s5, s25, 0
	global_load_lds_dwordx4 v[2:3], off
	s_add_i32 m0, s13, 0x1c000
	v_lshl_add_u64 v[2:3], s[4:5], 0, v[132:133]
	global_load_lds_dwordx4 v[2:3], off
	v_lshl_add_u64 v[2:3], s[4:5], 0, v[136:137]
	s_add_i32 m0, s13, 0x1e000
	v_lshlrev_b32_e32 v4, 2, v254
	global_load_lds_dwordx4 v[2:3], off
	v_and_b32_e32 v2, 15, v254
	v_lshlrev_b32_e32 v3, 1, v13
	v_lshlrev_b32_e32 v5, 6, v254
	s_movk_i32 s4, 0x3c0
	v_lshl_or_b32 v1, s15, 6, v2
	v_lshl_or_b32 v2, v2, 6, v3
	v_and_b32_e32 v4, 32, v4
	v_and_or_b32 v3, v5, s4, v3
	v_bitop3_b32 v146, s18, v3, v4 bitop3:0xf6
	v_lshlrev_b32_e32 v3, 9, v254
	v_bitop3_b32 v2, v2, s16, v4 bitop3:0xde
	v_and_b32_e32 v3, 0x70000, v3
	v_lshlrev_b32_e32 v4, 12, v12
	v_or3_b32 v3, v10, v3, v4
	v_add_u32_e32 v138, v3, v11
	v_lshlrev_b32_e32 v3, 5, v14
	s_waitcnt vmcnt(6)
	v_and_b32_e32 v3, 0xf0000, v3
	v_or3_b32 v3, v10, v3, v4
	s_add_i32 s52, 0, 0x10000
	s_add_i32 s53, 0, 0x14000
	s_sext_i32_i16 s55, s14
	s_waitcnt lgkmcnt(0)
	s_ashr_i32 s51, s39, 31
	v_or_b32_e32 v147, s17, v13
	v_mov_b32_e32 v139, v133
	v_add_u32_e32 v140, v3, v11
	v_mov_b32_e32 v141, v133
	v_mov_b64_e32 v[142:143], 0x10c2
	v_mov_b64_e32 v[144:145], 0x10c1
	v_add_u32_e32 v148, s52, v146
	v_add_u32_e32 v149, 0, v2
	v_add_u32_e32 v150, s53, v146
	s_movk_i32 s54, 0x4200
	s_barrier

; #define PG8_STAGE(bufoff, gbase, voff) do { _Pragma("unroll") for (int _i = 0; _i < 2; ++_i) \
;         __builtin_amdgcn_global_load_lds((const unsigned*)((const char*)(gbase) + (voff)[_i]), (LAS unsigned*)(lds + (bufoff) + ldsw + _i * 8192), 16, 0, 0); } while (0)
; #define PG8_LDA(dst, b, h) do { _Pragma("unroll") for (int m = 0; m < 4; ++m) _Pragma("unroll") for (int k = 0; k < 2; ++k) dst[m][k] = *(const LAS bf16x8*)(lds + PG8_SA(b, h) + aoff + m * 2048 + k * 1024); } while (0)
; #define PG8_LDB(dst, b, h) do { _Pragma("unroll") for (int n = 0; n < 2; ++n) _Pragma("unroll") for (int k = 0; k < 2; ++k) dst[n][k] = *(const LAS bf16x8*)(lds + PG8_SB(b, h) + boff + n * 2048 + k * 1024); } while (0)
; #define PG8_MMA(ai, bj, At, Bt) do { __builtin_amdgcn_s_setprio(1); _Pragma("unroll") for (int m = 0; m < 4; ++m) _Pragma("unroll") for (int n = 0; n < 2; ++n) _Pragma("unroll") for (int k = 0; k < 2; ++k) \
;         acc[ai][bj][m][n] = __builtin_amdgcn_mfma_f32_16x16x32_bf16(Bt[n][k], At[m][k], acc[ai][bj][m][n], 0, 0, 0); __builtin_amdgcn_s_setprio(0); } while (0)
; #define PG8_WAIT_L(n) asm volatile("s_waitcnt lgkmcnt(" #n ")" ::: "memory")
; #define PG8_BAR __builtin_amdgcn_s_barrier()
; #define PG8_SCHED __builtin_amdgcn_sched_barrier(0)
; template <class Epi>
; DI void gemm_phase(LAS unsigned char* lds, const Gemm g, const StaticOrder& S, const Epi& E) {
;     ...
;             PG8_LDB(B0, 0, 0); PG8_SCHED; PG8_LDA(At, 0, 0); PG8_STAGE(PG8_SA(1, 1), a1 + hstepA, voffA);
;             PG8_WAIT_L(8); PG8_BAR; PG8_WAIT_L(0); PG8_MMA(0, 0, At, B0); PG8_BAR; PG8_SCHED;
;             PG8_LDB(B1, 0, 1); PG8_STAGE(PG8_SB(0, 0), b2, voffB);
;             PG8_BAR; PG8_WAIT_L(0); PG8_MMA(0, 1, At, B1); PG8_BAR;
;             PG8_LDA(At, 0, 1); PG8_STAGE(PG8_SA(0, 0), a2, voffA);
;             PG8_BAR; PG8_WAIT_L(0); PG8_MMA(1, 0, At, B0); PG8_BAR; PG8_SCHED;
;             PG8_STAGE(PG8_SB(0, 1), b2 + hstepB, voffB);
.LBB0_277:
	ds_read_b128 v[152:155], v148
	ds_read_b128 v[156:159], v148 offset:1024
	ds_read_b128 v[160:163], v148 offset:2048
	ds_read_b128 v[164:167], v148 offset:3072
	s_add_u32 s24, s22, 0xfff80080
	s_addc_u32 s25, s23, -1
	s_cmp_eq_u32 s60, 28
	s_cselect_b32 s27, s17, s25
	s_cselect_b32 s26, s56, s24
	s_cselect_b32 s25, s15, s59
	s_cselect_b32 s24, s57, s58
	v_lshl_add_u64 v[200:201], s[22:23], 0, v[138:139]
	s_add_i32 m0, s13, 0xc000
	ds_read_b128 v[168:171], v149
	ds_read_b128 v[172:175], v149 offset:1024
	ds_read_b128 v[176:179], v149 offset:2048
	ds_read_b128 v[180:183], v149 offset:3072
	ds_read_b128 v[184:187], v149 offset:4096
	ds_read_b128 v[188:191], v149 offset:5120
	ds_read_b128 v[192:195], v149 offset:6144
	ds_read_b128 v[196:199], v149 offset:7168
	global_load_lds_dwordx4 v[200:201], off
	v_lshl_add_u64 v[200:201], s[22:23], 0, v[140:141]
	s_add_i32 m0, s13, 0xe000
	s_nop 0
	global_load_lds_dwordx4 v[200:201], off
	ds_read_b128 v[200:203], v150
	ds_read_b128 v[204:207], v150 offset:1024
	ds_read_b128 v[208:211], v150 offset:2048
	ds_read_b128 v[212:215], v150 offset:3072
	s_waitcnt lgkmcnt(0)
	s_waitcnt vmcnt(8)
	s_barrier
	s_setprio 1
	v_mfma_f32_16x16x32_bf16 v[126:129], v[152:155], v[168:171], v[126:129]
	v_mfma_f32_16x16x32_bf16 v[122:125], v[160:163], v[168:171], v[122:125]
	v_mfma_f32_16x16x32_bf16 v[118:121], v[152:155], v[176:179], v[118:121]
	v_mfma_f32_16x16x32_bf16 v[114:117], v[160:163], v[176:179], v[114:117]
	v_mfma_f32_16x16x32_bf16 v[102:105], v[152:155], v[184:187], v[102:105]
	v_mfma_f32_16x16x32_bf16 v[98:101], v[160:163], v[184:187], v[98:101]
	v_mfma_f32_16x16x32_bf16 v[86:89], v[152:155], v[192:195], v[86:89]
	v_mfma_f32_16x16x32_bf16 v[82:85], v[160:163], v[192:195], v[82:85]
	v_mfma_f32_16x16x32_bf16 v[126:129], v[156:159], v[172:175], v[126:129]
	v_mfma_f32_16x16x32_bf16 v[122:125], v[164:167], v[172:175], v[122:125]
	v_mfma_f32_16x16x32_bf16 v[118:121], v[156:159], v[180:183], v[118:121]
	v_mfma_f32_16x16x32_bf16 v[114:117], v[164:167], v[180:183], v[114:117]
	v_mfma_f32_16x16x32_bf16 v[102:105], v[156:159], v[188:191], v[102:105]
	v_mfma_f32_16x16x32_bf16 v[98:101], v[164:167], v[188:191], v[98:101]
	v_mfma_f32_16x16x32_bf16 v[86:89], v[156:159], v[196:199], v[86:89]
	v_mfma_f32_16x16x32_bf16 v[82:85], v[164:167], v[196:199], v[82:85]
	v_mfma_f32_16x16x32_bf16 v[110:113], v[200:203], v[168:171], v[110:113]
	v_mfma_f32_16x16x32_bf16 v[106:109], v[208:211], v[168:171], v[106:109]
	v_mfma_f32_16x16x32_bf16 v[94:97], v[200:203], v[176:179], v[94:97]
	v_mfma_f32_16x16x32_bf16 v[90:93], v[208:211], v[176:179], v[90:93]
	v_mfma_f32_16x16x32_bf16 v[78:81], v[200:203], v[184:187], v[78:81]
	v_mfma_f32_16x16x32_bf16 v[74:77], v[208:211], v[184:187], v[74:77]
	v_mfma_f32_16x16x32_bf16 v[70:73], v[200:203], v[192:195], v[70:73]
	v_mfma_f32_16x16x32_bf16 v[66:69], v[208:211], v[192:195], v[66:69]
	v_mfma_f32_16x16x32_bf16 v[110:113], v[204:207], v[172:175], v[110:113]
	v_mfma_f32_16x16x32_bf16 v[106:109], v[212:215], v[172:175], v[106:109]
	v_mfma_f32_16x16x32_bf16 v[94:97], v[204:207], v[180:183], v[94:97]
	v_mfma_f32_16x16x32_bf16 v[90:93], v[212:215], v[180:183], v[90:93]
	v_mfma_f32_16x16x32_bf16 v[78:81], v[204:207], v[188:191], v[78:81]
	v_mfma_f32_16x16x32_bf16 v[74:77], v[212:215], v[188:191], v[74:77]
	v_mfma_f32_16x16x32_bf16 v[70:73], v[204:207], v[196:199], v[70:73]
	v_mfma_f32_16x16x32_bf16 v[66:69], v[212:215], v[196:199], v[66:69]
	s_setprio 0
	s_barrier
	s_add_i32 s61, s52, s35
	v_lshl_add_u64 v[218:219], s[24:25], 0, v[132:133]
	s_mov_b32 m0, s61
	s_nop 0
	global_load_lds_dwordx4 v[218:219], off
	v_lshl_add_u64 v[220:221], s[24:25], 0, v[136:137]
	s_add_i32 m0, s61, 0x2000
	s_nop 0
	global_load_lds_dwordx4 v[220:221], off
	s_mov_b32 m0, s13
	v_lshl_add_u64 v[222:223], s[26:27], 0, v[130:131]
	ds_read_b128 v[168:171], v149 offset:16384
	ds_read_b128 v[172:175], v149 offset:17408
	ds_read_b128 v[176:179], v149 offset:18432
	ds_read_b128 v[180:183], v149 offset:19456
	ds_read_b128 v[184:187], v149 offset:20480
	ds_read_b128 v[188:191], v149 offset:21504
	ds_read_b128 v[192:195], v149 offset:22528
	ds_read_b128 v[196:199], v149 offset:23552
	global_load_lds_dwordx4 v[222:223], off
	v_lshl_add_u64 v[224:225], s[26:27], 0, v[134:135]
	s_mov_b32 m0, s36
	s_nop 0
	global_load_lds_dwordx4 v[224:225], off
	s_add_u32 s62, s24, 0x80000
	s_addc_u32 s63, s25, 0
	s_add_i32 s61, s53, s35
	v_lshl_add_u64 v[252:253], s[62:63], 0, v[132:133]
	s_mov_b32 m0, s61
	s_nop 0
	global_load_lds_dwordx4 v[252:253], off
	v_lshl_add_u64 v[252:253], s[62:63], 0, v[136:137]
	s_add_i32 m0, s61, 0x2000
	s_nop 0
	global_load_lds_dwordx4 v[252:253], off
	s_waitcnt lgkmcnt(0)
	s_waitcnt vmcnt(8)
	s_barrier
; #define PG8_STAGE(bufoff, gbase, voff) do { _Pragma("unroll") for (int _i = 0; _i < 2; ++_i) \
;         __builtin_amdgcn_global_load_lds((const unsigned*)((const char*)(gbase) + (voff)[_i]), (LAS unsigned*)(lds + (bufoff) + ldsw + _i * 8192), 16, 0, 0); } while (0)
; #define PG8_LDA(dst, b, h) do { _Pragma("unroll") for (int m = 0; m < 4; ++m) _Pragma("unroll") for (int k = 0; k < 2; ++k) dst[m][k] = *(const LAS bf16x8*)(lds + PG8_SA(b, h) + aoff + m * 2048 + k * 1024); } while (0)
; #define PG8_LDB(dst, b, h) do { _Pragma("unroll") for (int n = 0; n < 2; ++n) _Pragma("unroll") for (int k = 0; k < 2; ++k) dst[n][k] = *(const LAS bf16x8*)(lds + PG8_SB(b, h) + boff + n * 2048 + k * 1024); } while (0)
; #define PG8_MMA(ai, bj, At, Bt) do { __builtin_amdgcn_s_setprio(1); _Pragma("unroll") for (int m = 0; m < 4; ++m) _Pragma("unroll") for (int n = 0; n < 2; ++n) _Pragma("unroll") for (int k = 0; k < 2; ++k) \
;         acc[ai][bj][m][n] = __builtin_amdgcn_mfma_f32_16x16x32_bf16(Bt[n][k], At[m][k], acc[ai][bj][m][n], 0, 0, 0); __builtin_amdgcn_s_setprio(0); } while (0)
; #define PG8_WAIT_V(n) asm volatile("s_waitcnt vmcnt(" #n ")" ::: "memory")
; #define PG8_WAIT_L(n) asm volatile("s_waitcnt lgkmcnt(" #n ")" ::: "memory")
; #define PG8_BAR __builtin_amdgcn_s_barrier()
; #define PG8_SCHED __builtin_amdgcn_sched_barrier(0)
; template <class Epi>
; DI void gemm_phase(LAS unsigned char* lds, const Gemm g, const StaticOrder& S, const Epi& E) {
;     ...
;             PG8_BAR; PG8_WAIT_L(0); PG8_MMA(1, 0, At, B0); PG8_BAR; PG8_SCHED;
;             PG8_STAGE(PG8_SB(0, 1), b2 + hstepB, voffB);
;             PG8_WAIT_V(6); PG8_BAR; PG8_MMA(1, 1, At, B1); PG8_BAR;
;             PG8_LDB(B0, 1, 0); PG8_SCHED; PG8_LDA(At, 1, 0); PG8_STAGE(PG8_SA(0, 1), a2 + hstepA, voffA);
;             PG8_WAIT_L(8); PG8_BAR; PG8_WAIT_L(0); PG8_MMA(0, 0, At, B0); PG8_BAR; PG8_SCHED;
;             PG8_LDB(B1, 1, 1); PG8_STAGE(PG8_SB(1, 0), b3, voffB);
;             PG8_BAR; PG8_WAIT_L(0); PG8_MMA(0, 1, At, B1); PG8_BAR;
	s_setprio 1
	v_mfma_f32_16x16x32_bf16 v[62:65], v[152:155], v[168:171], v[62:65]
	v_mfma_f32_16x16x32_bf16 v[58:61], v[160:163], v[168:171], v[58:61]
	v_mfma_f32_16x16x32_bf16 v[54:57], v[152:155], v[176:179], v[54:57]
	v_mfma_f32_16x16x32_bf16 v[50:53], v[160:163], v[176:179], v[50:53]
	v_mfma_f32_16x16x32_bf16 v[38:41], v[152:155], v[184:187], v[38:41]
	v_mfma_f32_16x16x32_bf16 v[34:37], v[160:163], v[184:187], v[34:37]
	v_mfma_f32_16x16x32_bf16 v[22:25], v[152:155], v[192:195], v[22:25]
	v_mfma_f32_16x16x32_bf16 v[18:21], v[160:163], v[192:195], v[18:21]
	v_mfma_f32_16x16x32_bf16 v[62:65], v[156:159], v[172:175], v[62:65]
	v_mfma_f32_16x16x32_bf16 v[58:61], v[164:167], v[172:175], v[58:61]
	v_mfma_f32_16x16x32_bf16 v[54:57], v[156:159], v[180:183], v[54:57]
	v_mfma_f32_16x16x32_bf16 v[50:53], v[164:167], v[180:183], v[50:53]
	v_mfma_f32_16x16x32_bf16 v[38:41], v[156:159], v[188:191], v[38:41]
	v_mfma_f32_16x16x32_bf16 v[34:37], v[164:167], v[188:191], v[34:37]
	v_mfma_f32_16x16x32_bf16 v[22:25], v[156:159], v[196:199], v[22:25]
	v_mfma_f32_16x16x32_bf16 v[18:21], v[164:167], v[196:199], v[18:21]
	v_mfma_f32_16x16x32_bf16 v[46:49], v[200:203], v[168:171], v[46:49]
	v_mfma_f32_16x16x32_bf16 v[42:45], v[208:211], v[168:171], v[42:45]
	v_mfma_f32_16x16x32_bf16 v[30:33], v[200:203], v[176:179], v[30:33]
	v_mfma_f32_16x16x32_bf16 v[26:29], v[208:211], v[176:179], v[26:29]
	v_mfma_f32_16x16x32_bf16 v[14:17], v[200:203], v[184:187], v[14:17]
	v_mfma_f32_16x16x32_bf16 v[10:13], v[208:211], v[184:187], v[10:13]
	v_mfma_f32_16x16x32_bf16 v[6:9], v[200:203], v[192:195], v[6:9]
	v_mfma_f32_16x16x32_bf16 v[2:5], v[208:211], v[192:195], v[2:5]
	v_mfma_f32_16x16x32_bf16 v[46:49], v[204:207], v[172:175], v[46:49]
	v_mfma_f32_16x16x32_bf16 v[42:45], v[212:215], v[172:175], v[42:45]
	v_mfma_f32_16x16x32_bf16 v[30:33], v[204:207], v[180:183], v[30:33]
	v_mfma_f32_16x16x32_bf16 v[26:29], v[212:215], v[180:183], v[26:29]
	v_mfma_f32_16x16x32_bf16 v[14:17], v[204:207], v[188:191], v[14:17]
	v_mfma_f32_16x16x32_bf16 v[10:13], v[212:215], v[188:191], v[10:13]
	v_mfma_f32_16x16x32_bf16 v[6:9], v[204:207], v[196:199], v[6:9]
	v_mfma_f32_16x16x32_bf16 v[2:5], v[212:215], v[196:199], v[2:5]
	s_setprio 0
	s_add_i32 s61, 0, 0x18000
	v_add_u32_e32 v151, s61, v146
	s_barrier
	ds_read_b128 v[152:155], v151
	ds_read_b128 v[156:159], v151 offset:1024
	ds_read_b128 v[160:163], v151 offset:2048
	ds_read_b128 v[164:167], v151 offset:3072
	s_add_u32 s26, s26, 0x80000
	s_addc_u32 s27, s27, 0
	s_mov_b32 m0, s37
	v_lshl_add_u64 v[200:201], s[26:27], 0, v[130:131]
	ds_read_b128 v[168:171], v149 offset:32768
	ds_read_b128 v[172:175], v149 offset:33792
	ds_read_b128 v[176:179], v149 offset:34816
	ds_read_b128 v[180:183], v149 offset:35840
	ds_read_b128 v[184:187], v149 offset:36864
	ds_read_b128 v[188:191], v149 offset:37888
	ds_read_b128 v[192:195], v149 offset:38912
	ds_read_b128 v[196:199], v149 offset:39936
	global_load_lds_dwordx4 v[200:201], off
	v_lshl_add_u64 v[200:201], s[26:27], 0, v[134:135]
	s_mov_b32 m0, s38
	s_nop 0
	global_load_lds_dwordx4 v[200:201], off
	s_add_i32 s26, 0, 0x1c000
	v_add_u32_e32 v151, s26, v146
	ds_read_b128 v[200:203], v151
	ds_read_b128 v[204:207], v151 offset:1024
	ds_read_b128 v[208:211], v151 offset:2048
	ds_read_b128 v[212:215], v151 offset:3072
	s_waitcnt lgkmcnt(0)
	s_waitcnt vmcnt(8)
	s_barrier
	s_setprio 1
	v_mfma_f32_16x16x32_bf16 v[126:129], v[152:155], v[168:171], v[126:129]
	v_mfma_f32_16x16x32_bf16 v[122:125], v[160:163], v[168:171], v[122:125]
	v_mfma_f32_16x16x32_bf16 v[118:121], v[152:155], v[176:179], v[118:121]
	v_mfma_f32_16x16x32_bf16 v[114:117], v[160:163], v[176:179], v[114:117]
	v_mfma_f32_16x16x32_bf16 v[102:105], v[152:155], v[184:187], v[102:105]
	v_mfma_f32_16x16x32_bf16 v[98:101], v[160:163], v[184:187], v[98:101]
	v_mfma_f32_16x16x32_bf16 v[86:89], v[152:155], v[192:195], v[86:89]
	v_mfma_f32_16x16x32_bf16 v[82:85], v[160:163], v[192:195], v[82:85]
	v_mfma_f32_16x16x32_bf16 v[126:129], v[156:159], v[172:175], v[126:129]
	v_mfma_f32_16x16x32_bf16 v[122:125], v[164:167], v[172:175], v[122:125]
	v_mfma_f32_16x16x32_bf16 v[118:121], v[156:159], v[180:183], v[118:121]
	v_mfma_f32_16x16x32_bf16 v[114:117], v[164:167], v[180:183], v[114:117]
	v_mfma_f32_16x16x32_bf16 v[102:105], v[156:159], v[188:191], v[102:105]
	v_mfma_f32_16x16x32_bf16 v[98:101], v[164:167], v[188:191], v[98:101]
	v_mfma_f32_16x16x32_bf16 v[86:89], v[156:159], v[196:199], v[86:89]
	v_mfma_f32_16x16x32_bf16 v[82:85], v[164:167], v[196:199], v[82:85]
	v_mfma_f32_16x16x32_bf16 v[110:113], v[200:203], v[168:171], v[110:113]
	v_mfma_f32_16x16x32_bf16 v[106:109], v[208:211], v[168:171], v[106:109]
	v_mfma_f32_16x16x32_bf16 v[94:97], v[200:203], v[176:179], v[94:97]
	v_mfma_f32_16x16x32_bf16 v[90:93], v[208:211], v[176:179], v[90:93]
	v_mfma_f32_16x16x32_bf16 v[78:81], v[200:203], v[184:187], v[78:81]
	v_mfma_f32_16x16x32_bf16 v[74:77], v[208:211], v[184:187], v[74:77]
	v_mfma_f32_16x16x32_bf16 v[70:73], v[200:203], v[192:195], v[70:73]
	v_mfma_f32_16x16x32_bf16 v[66:69], v[208:211], v[192:195], v[66:69]
	v_mfma_f32_16x16x32_bf16 v[110:113], v[204:207], v[172:175], v[110:113]
	v_mfma_f32_16x16x32_bf16 v[106:109], v[212:215], v[172:175], v[106:109]
	v_mfma_f32_16x16x32_bf16 v[94:97], v[204:207], v[180:183], v[94:97]
	v_mfma_f32_16x16x32_bf16 v[90:93], v[212:215], v[180:183], v[90:93]
	v_mfma_f32_16x16x32_bf16 v[78:81], v[204:207], v[188:191], v[78:81]
	v_mfma_f32_16x16x32_bf16 v[74:77], v[212:215], v[188:191], v[74:77]
	v_mfma_f32_16x16x32_bf16 v[70:73], v[204:207], v[196:199], v[70:73]
	v_mfma_f32_16x16x32_bf16 v[66:69], v[212:215], v[196:199], v[66:69]
	s_setprio 0
	s_barrier
; #define PG8_STAGE(bufoff, gbase, voff) do { _Pragma("unroll") for (int _i = 0; _i < 2; ++_i) \
;         __builtin_amdgcn_global_load_lds((const unsigned*)((const char*)(gbase) + (voff)[_i]), (LAS unsigned*)(lds + (bufoff) + ldsw + _i * 8192), 16, 0, 0); } while (0)
; #define PG8_LDA(dst, b, h) do { _Pragma("unroll") for (int m = 0; m < 4; ++m) _Pragma("unroll") for (int k = 0; k < 2; ++k) dst[m][k] = *(const LAS bf16x8*)(lds + PG8_SA(b, h) + aoff + m * 2048 + k * 1024); } while (0)
; #define PG8_LDB(dst, b, h) do { _Pragma("unroll") for (int n = 0; n < 2; ++n) _Pragma("unroll") for (int k = 0; k < 2; ++k) dst[n][k] = *(const LAS bf16x8*)(lds + PG8_SB(b, h) + boff + n * 2048 + k * 1024); } while (0)
; #define PG8_MMA(ai, bj, At, Bt) do { __builtin_amdgcn_s_setprio(1); _Pragma("unroll") for (int m = 0; m < 4; ++m) _Pragma("unroll") for (int n = 0; n < 2; ++n) _Pragma("unroll") for (int k = 0; k < 2; ++k) \
;         acc[ai][bj][m][n] = __builtin_amdgcn_mfma_f32_16x16x32_bf16(Bt[n][k], At[m][k], acc[ai][bj][m][n], 0, 0, 0); __builtin_amdgcn_s_setprio(0); } while (0)
; #define PG8_WAIT_V(n) asm volatile("s_waitcnt vmcnt(" #n ")" ::: "memory")
; #define PG8_WAIT_L(n) asm volatile("s_waitcnt lgkmcnt(" #n ")" ::: "memory")
; #define PG8_BAR __builtin_amdgcn_s_barrier()
; #define PG8_SCHED __builtin_amdgcn_sched_barrier(0)
; template <class Epi>
; DI void gemm_phase(LAS unsigned char* lds, const Gemm g, const StaticOrder& S, const Epi& E) {
;     ...
;             PG8_LDB(B1, 1, 1); PG8_STAGE(PG8_SB(1, 0), b3, voffB);
;             PG8_BAR; PG8_WAIT_L(0); PG8_MMA(0, 1, At, B1); PG8_BAR;
;             PG8_LDA(At, 1, 1); PG8_STAGE(PG8_SA(1, 0), a3, voffA);
;             PG8_BAR; PG8_WAIT_L(0); PG8_MMA(1, 0, At, B0); PG8_BAR; PG8_SCHED;
;             PG8_STAGE(PG8_SB(1, 1), b3 + hstepB, voffB);
;             PG8_WAIT_V(6); PG8_BAR; PG8_MMA(1, 1, At, B1); PG8_BAR;
;         }
	s_add_i32 s27, s61, s35
	v_lshl_add_u64 v[218:219], v[218:219], 0, s[10:11]
	s_mov_b32 m0, s27
	s_nop 0
	global_load_lds_dwordx4 v[218:219], off
	v_lshl_add_u64 v[218:219], v[220:221], 0, s[10:11]
	s_add_i32 m0, s27, 0x2000
	s_nop 0
	global_load_lds_dwordx4 v[218:219], off
	s_mov_b32 m0, s49
	v_lshl_add_u64 v[218:219], v[222:223], 0, s[10:11]
	ds_read_b128 v[168:171], v149 offset:49152
	ds_read_b128 v[172:175], v149 offset:50176
	ds_read_b128 v[176:179], v149 offset:51200
	ds_read_b128 v[180:183], v149 offset:52224
	ds_read_b128 v[184:187], v149 offset:53248
	ds_read_b128 v[188:191], v149 offset:54272
	ds_read_b128 v[192:195], v149 offset:55296
	ds_read_b128 v[196:199], v149 offset:56320
	global_load_lds_dwordx4 v[218:219], off
	v_lshl_add_u64 v[218:219], v[224:225], 0, s[10:11]
	s_mov_b32 m0, s50
	s_nop 0
	global_load_lds_dwordx4 v[218:219], off
	s_add_u32 s24, s24, 0x80080
	s_addc_u32 s25, s25, 0
	s_add_i32 s26, s26, s35
	v_lshl_add_u64 v[252:253], s[24:25], 0, v[132:133]
	s_mov_b32 m0, s26
	s_nop 0
	global_load_lds_dwordx4 v[252:253], off
	v_lshl_add_u64 v[252:253], s[24:25], 0, v[136:137]
	s_add_i32 m0, s26, 0x2000
	s_nop 0
	global_load_lds_dwordx4 v[252:253], off
	s_waitcnt lgkmcnt(0)
	s_waitcnt vmcnt(8)
	s_barrier
	s_setprio 1
	v_mfma_f32_16x16x32_bf16 v[62:65], v[152:155], v[168:171], v[62:65]
	v_mfma_f32_16x16x32_bf16 v[58:61], v[160:163], v[168:171], v[58:61]
	v_mfma_f32_16x16x32_bf16 v[54:57], v[152:155], v[176:179], v[54:57]
	v_mfma_f32_16x16x32_bf16 v[50:53], v[160:163], v[176:179], v[50:53]
	v_mfma_f32_16x16x32_bf16 v[38:41], v[152:155], v[184:187], v[38:41]
	v_mfma_f32_16x16x32_bf16 v[34:37], v[160:163], v[184:187], v[34:37]
	v_mfma_f32_16x16x32_bf16 v[22:25], v[152:155], v[192:195], v[22:25]
	v_mfma_f32_16x16x32_bf16 v[18:21], v[160:163], v[192:195], v[18:21]
	v_mfma_f32_16x16x32_bf16 v[62:65], v[156:159], v[172:175], v[62:65]
	v_mfma_f32_16x16x32_bf16 v[58:61], v[164:167], v[172:175], v[58:61]
	v_mfma_f32_16x16x32_bf16 v[54:57], v[156:159], v[180:183], v[54:57]
	v_mfma_f32_16x16x32_bf16 v[50:53], v[164:167], v[180:183], v[50:53]
	v_mfma_f32_16x16x32_bf16 v[38:41], v[156:159], v[188:191], v[38:41]
	v_mfma_f32_16x16x32_bf16 v[34:37], v[164:167], v[188:191], v[34:37]
	v_mfma_f32_16x16x32_bf16 v[22:25], v[156:159], v[196:199], v[22:25]
	v_mfma_f32_16x16x32_bf16 v[18:21], v[164:167], v[196:199], v[18:21]
	v_mfma_f32_16x16x32_bf16 v[46:49], v[200:203], v[168:171], v[46:49]
	v_mfma_f32_16x16x32_bf16 v[42:45], v[208:211], v[168:171], v[42:45]
	v_mfma_f32_16x16x32_bf16 v[30:33], v[200:203], v[176:179], v[30:33]
	v_mfma_f32_16x16x32_bf16 v[26:29], v[208:211], v[176:179], v[26:29]
	v_mfma_f32_16x16x32_bf16 v[14:17], v[200:203], v[184:187], v[14:17]
	v_mfma_f32_16x16x32_bf16 v[10:13], v[208:211], v[184:187], v[10:13]
	v_mfma_f32_16x16x32_bf16 v[6:9], v[200:203], v[192:195], v[6:9]
	v_mfma_f32_16x16x32_bf16 v[2:5], v[208:211], v[192:195], v[2:5]
	v_mfma_f32_16x16x32_bf16 v[46:49], v[204:207], v[172:175], v[46:49]
	v_mfma_f32_16x16x32_bf16 v[42:45], v[212:215], v[172:175], v[42:45]
	v_mfma_f32_16x16x32_bf16 v[30:33], v[204:207], v[180:183], v[30:33]
	v_mfma_f32_16x16x32_bf16 v[26:29], v[212:215], v[180:183], v[26:29]
	v_mfma_f32_16x16x32_bf16 v[14:17], v[204:207], v[188:191], v[14:17]
	v_mfma_f32_16x16x32_bf16 v[10:13], v[212:215], v[188:191], v[10:13]
	v_mfma_f32_16x16x32_bf16 v[6:9], v[204:207], v[196:199], v[6:9]
	v_mfma_f32_16x16x32_bf16 v[2:5], v[212:215], v[196:199], v[2:5]
	s_setprio 0
	s_add_i32 s60, s60, 2
	s_add_u32 s22, s22, 0x100
	s_addc_u32 s23, s23, 0
	s_add_u32 s58, s58, 0x100
	s_addc_u32 s59, s59, 0
	s_cmp_gt_u32 s60, 29
	s_barrier
	s_cbranch_scc0 .LBB0_277
; DI unsigned pk2(float lo, float hi) { f32x2 v = {lo, hi}; bfv2 b = __builtin_convertvector(v, bfv2); return __builtin_bit_cast(unsigned, b); }
;     DI void operator()(const f32x4 (&acc)[2][2][4][2], const pg8::Unit& u, int wr, int wc, int fr, int fq) const {
;         const int row0 = u.pm * 256 + wr * 64 + fr, col0 = u.pn * 256 + wc * 32 + 8 * fq;
; #pragma unroll
;         for (int ai = 0; ai < 2; ++ai)
; #pragma unroll
;             for (int m = 0; m < 4; ++m) { bf16_t* rowp = O + (size_t)(row0 + ai * 128 + m * 16) * ldc + col0;
; #pragma unroll
;                 for (int bj = 0; bj < 2; ++bj) { const f32x4 v0 = acc[ai][bj][m][0], v1 = acc[ai][bj][m][1];
;                     u32x4 w; w.x = pk2(v0[0], v0[1]); w.y = pk2(v0[2], v0[3]); w.z = pk2(v1[0], v1[1]); w.w = pk2(v1[2], v1[3]);
;                     *(u32x4*)(rowp + bj * 128) = w; } }
	v_lshl_add_u32 v151, s12, 8, v1
	v_lshl_or_b32 v152, s55, 8, v147
	v_ashrrev_i32_e32 v153, 31, v152
	v_mov_b64_e32 v[154:155], s[8:9]
	v_cvt_pk_bf16_f32 v70, v70, v71
	v_cvt_pk_bf16_f32 v71, v72, v73
	v_cvt_pk_bf16_f32 v72, v66, v67
	v_add_u32_e32 v66, 0x80, v151
	v_mad_i64_i32 v[156:157], s[22:23], v151, s54, v[154:155]
	v_lshlrev_b64 v[152:153], 1, v[152:153]
	v_cvt_pk_bf16_f32 v110, v110, v111
	v_cvt_pk_bf16_f32 v111, v112, v113
	v_cvt_pk_bf16_f32 v112, v106, v107
	v_or_b32_e32 v106, 16, v151
	v_mad_i64_i32 v[66:67], s[22:23], v66, s54, v[154:155]
	v_cvt_pk_bf16_f32 v46, v46, v47
	v_cvt_pk_bf16_f32 v47, v48, v49
	v_cvt_pk_bf16_f32 v48, v42, v43
	v_add_u32_e32 v42, 0x90, v151
	v_lshl_add_u64 v[156:157], v[156:157], 0, v[152:153]
	v_cvt_pk_bf16_f32 v113, v108, v109
	v_mad_i64_i32 v[106:107], s[22:23], v106, s54, v[154:155]
	v_cvt_pk_bf16_f32 v94, v94, v95
	v_cvt_pk_bf16_f32 v95, v96, v97
	v_cvt_pk_bf16_f32 v96, v90, v91
	v_or_b32_e32 v90, 32, v151
	v_lshl_add_u64 v[66:67], v[66:67], 0, v[152:153]
	v_cvt_pk_bf16_f32 v49, v44, v45
	v_mad_i64_i32 v[42:43], s[22:23], v42, s54, v[154:155]
	v_cvt_pk_bf16_f32 v30, v30, v31
	v_cvt_pk_bf16_f32 v31, v32, v33
	v_cvt_pk_bf16_f32 v32, v26, v27
	v_add_u32_e32 v26, 0xa0, v151
	global_store_dwordx4 v[156:157], v[110:113], off offset:256
	v_cvt_pk_bf16_f32 v97, v92, v93
	v_mad_i64_i32 v[90:91], s[22:23], v90, s54, v[154:155]
	v_lshl_add_u64 v[110:111], v[106:107], 0, v[152:153]
	v_cvt_pk_bf16_f32 v78, v78, v79
	v_cvt_pk_bf16_f32 v79, v80, v81
	v_cvt_pk_bf16_f32 v80, v74, v75
	v_or_b32_e32 v74, 48, v151
	global_store_dwordx4 v[66:67], v[46:49], off offset:256
	v_cvt_pk_bf16_f32 v33, v28, v29
	v_mad_i64_i32 v[26:27], s[22:23], v26, s54, v[154:155]
	v_lshl_add_u64 v[46:47], v[42:43], 0, v[152:153]
	v_cvt_pk_bf16_f32 v14, v14, v15
	v_cvt_pk_bf16_f32 v15, v16, v17
	v_cvt_pk_bf16_f32 v16, v10, v11
	v_add_u32_e32 v10, 0xb0, v151
	global_store_dwordx4 v[110:111], v[94:97], off offset:256
	v_cvt_pk_bf16_f32 v81, v76, v77
	v_mad_i64_i32 v[74:75], s[22:23], v74, s54, v[154:155]
	v_lshl_add_u64 v[94:95], v[90:91], 0, v[152:153]
	global_store_dwordx4 v[46:47], v[30:33], off offset:256
	v_cvt_pk_bf16_f32 v17, v12, v13
	v_mad_i64_i32 v[10:11], s[22:23], v10, s54, v[154:155]
	v_lshl_add_u64 v[30:31], v[26:27], 0, v[152:153]
	v_cvt_pk_bf16_f32 v126, v126, v127
	v_cvt_pk_bf16_f32 v127, v128, v129
	v_cvt_pk_bf16_f32 v128, v122, v123
	v_cvt_pk_bf16_f32 v129, v124, v125
	v_cvt_pk_bf16_f32 v106, v118, v119
	v_cvt_pk_bf16_f32 v107, v120, v121
	v_cvt_pk_bf16_f32 v108, v114, v115
	v_cvt_pk_bf16_f32 v109, v116, v117
	v_cvt_pk_bf16_f32 v90, v102, v103
	v_cvt_pk_bf16_f32 v91, v104, v105
	v_cvt_pk_bf16_f32 v92, v98, v99
	v_cvt_pk_bf16_f32 v93, v100, v101
	global_store_dwordx4 v[94:95], v[78:81], off offset:256
	v_cvt_pk_bf16_f32 v76, v82, v83
	v_cvt_pk_bf16_f32 v77, v84, v85
	v_lshl_add_u64 v[78:79], v[74:75], 0, v[152:153]
	v_cvt_pk_bf16_f32 v74, v86, v87
	v_cvt_pk_bf16_f32 v75, v88, v89
	v_cvt_pk_bf16_f32 v73, v68, v69
	v_cvt_pk_bf16_f32 v62, v62, v63
	v_cvt_pk_bf16_f32 v63, v64, v65
	v_cvt_pk_bf16_f32 v64, v58, v59
	v_cvt_pk_bf16_f32 v65, v60, v61
	v_cvt_pk_bf16_f32 v42, v54, v55
	v_cvt_pk_bf16_f32 v43, v56, v57
	v_cvt_pk_bf16_f32 v44, v50, v51
	v_cvt_pk_bf16_f32 v45, v52, v53
	v_cvt_pk_bf16_f32 v26, v38, v39
	v_cvt_pk_bf16_f32 v27, v40, v41
	v_cvt_pk_bf16_f32 v28, v34, v35
	v_cvt_pk_bf16_f32 v29, v36, v37
	global_store_dwordx4 v[30:31], v[14:17], off offset:256
	v_cvt_pk_bf16_f32 v12, v18, v19
	v_cvt_pk_bf16_f32 v13, v20, v21
	v_lshl_add_u64 v[14:15], v[10:11], 0, v[152:153]
	v_cvt_pk_bf16_f32 v10, v22, v23
	v_cvt_pk_bf16_f32 v11, v24, v25
	v_cvt_pk_bf16_f32 v6, v6, v7
	v_cvt_pk_bf16_f32 v7, v8, v9
	v_cvt_pk_bf16_f32 v8, v2, v3
	v_cvt_pk_bf16_f32 v9, v4, v5
	s_and_b64 vcc, exec, s[4:5]
	s_mov_b32 s55, s14
	s_mov_b32 s12, s16
	s_mov_b64 s[24:25], s[20:21]
	s_mov_b64 s[22:23], s[18:19]
	global_store_dwordx4 v[156:157], v[126:129], off
	global_store_dwordx4 v[110:111], v[106:109], off
	global_store_dwordx4 v[94:95], v[90:93], off
	global_store_dwordx4 v[78:79], v[74:77], off
	global_store_dwordx4 v[78:79], v[70:73], off offset:256
	global_store_dwordx4 v[66:67], v[62:65], off
	global_store_dwordx4 v[46:47], v[42:45], off
	global_store_dwordx4 v[30:31], v[26:29], off
	global_store_dwordx4 v[14:15], v[10:13], off
	global_store_dwordx4 v[14:15], v[6:9], off offset:256
	s_cbranch_vccz .LBB0_270
	s_waitcnt vmcnt(0)
	s_cmpk_gt_u32 s28, 0xff
	s_cbranch_scc1 .LBB0_281
	s_barrier

; #define PG8_STAGE(bufoff, gbase, voff) do { _Pragma("unroll") for (int _i = 0; _i < 2; ++_i) \
;         __builtin_amdgcn_global_load_lds((const unsigned*)((const char*)(gbase) + (voff)[_i]), (LAS unsigned*)(lds + (bufoff) + ldsw + _i * 8192), 16, 0, 0); } while (0)
; #define PG8_WAIT_V(n) asm volatile("s_waitcnt vmcnt(" #n ")" ::: "memory")
; #define PG8_BAR __builtin_amdgcn_s_barrier()
; template <class Epi>
; DI void gemm_phase(LAS unsigned char* lds, const Gemm g, const StaticOrder& S, const Epi& E) {
;     ...
;     const char* cA = PG8_ABASE(cur); const char* cB = PG8_BBASE(cur);
;     PG8_STAGE(PG8_SB(0, 0), cB, voffB); PG8_STAGE(PG8_SA(0, 0), cA, voffA); PG8_STAGE(PG8_SB(0, 1), cB + hstepB, voffB); PG8_STAGE(PG8_SA(0, 1), cA + hstepA, voffA);
;     if (wr == 1) PG8_BAR;
;     PG8_WAIT_V(4); PG8_BAR;
;     PG8_STAGE(PG8_SB(1, 0), cB + kstep, voffB); PG8_STAGE(PG8_SA(1, 0), cA + kstep, voffA); PG8_STAGE(PG8_SB(1, 1), cB + hstepB + kstep, voffB);
;     PG8_WAIT_V(6); PG8_BAR;
.LBB0_765:
	s_add_u32 s52, s10, 0x200000
	s_addc_u32 s53, s11, 0
	s_add_u32 s54, s10, 0x4000
	s_addc_u32 s11, s11, 0
	s_lshl_b32 s6, s6, 5
	s_and_b32 s19, s6, 0x60
	s_mov_b64 s[6:7], 0x80
	s_add_i32 m0, s48, 0x18000
	v_lshl_add_u64 v[8:9], v[8:9], 0, s[6:7]
	s_lshl_b32 s10, s18, 13
	s_lshl_b32 s22, s19, 7
	s_waitcnt vmcnt(0)
	s_barrier
	global_load_lds_dwordx4 v[8:9], off
	v_lshl_add_u64 v[6:7], v[6:7], 0, s[6:7]
	s_add_i32 m0, s48, 0x1a000
	s_add_i32 s55, s48, 0x8000
	s_add_i32 s56, s48, 0xa000
	global_load_lds_dwordx4 v[6:7], off
	v_lshl_add_u64 v[4:5], v[4:5], 0, s[6:7]
	s_mov_b32 m0, s55
	s_add_u32 s20, s28, 0x80080
	global_load_lds_dwordx4 v[4:5], off
	v_lshl_add_u64 v[2:3], v[2:3], 0, s[6:7]
	s_mov_b32 m0, s56
	s_addc_u32 s21, s29, 0
	global_load_lds_dwordx4 v[2:3], off
	s_add_i32 m0, s48, 0x1c000
	v_lshl_add_u64 v[2:3], s[20:21], 0, v[176:177]
	global_load_lds_dwordx4 v[2:3], off
	v_lshl_add_u64 v[2:3], s[20:21], 0, v[180:181]
	s_add_i32 m0, s48, 0x1e000
	v_bfe_u32 v6, v254, 4, 2
	global_load_lds_dwordx4 v[2:3], off
	s_sext_i32_i8 s62, s4
	v_and_b32_e32 v3, 15, v254
	v_lshlrev_b32_e32 v4, 4, v6
	v_lshlrev_b32_e32 v5, 2, v254
	s_movk_i32 s4, 0x3c0
	v_lshl_or_b32 v2, s18, 6, v3
	v_lshl_or_b32 v3, v3, 6, v4
	v_and_b32_e32 v5, 32, v5
	v_and_or_b32 v1, v1, s4, v4
	v_bitop3_b32 v7, v3, s10, v5 bitop3:0xde
	v_bitop3_b32 v1, s22, v1, v5 bitop3:0xf6
	v_or_b32_e32 v4, 16, v2
	v_mov_b32_e32 v5, v177
	v_lshlrev_b64 v[184:185], 13, v[4:5]
	v_or_b32_e32 v4, 32, v2
	v_lshlrev_b64 v[186:187], 13, v[4:5]
	v_or_b32_e32 v4, 48, v2
	v_lshlrev_b64 v[188:189], 13, v[4:5]
	v_add_u32_e32 v4, 0x80, v2
	s_waitcnt vmcnt(6)
	v_mov_b32_e32 v3, v177
	v_lshlrev_b64 v[190:191], 13, v[4:5]
	v_add_u32_e32 v4, 0x90, v2
	v_lshlrev_b64 v[182:183], 13, v[2:3]
	v_lshlrev_b64 v[192:193], 13, v[4:5]
	v_add_u32_e32 v4, 0xa0, v2
	v_add_u32_e32 v2, 0xb0, v2
	s_add_i32 s57, 0, 0x10000
	s_add_i32 s58, 0, 0x14000
	v_lshlrev_b64 v[194:195], 13, v[4:5]
	v_lshlrev_b64 v[196:197], 13, v[2:3]
	v_lshl_or_b32 v217, v6, 2, s19
	v_add3_u32 v198, v12, v10, v11
	v_mov_b32_e32 v199, v177
	v_add3_u32 v200, v13, v10, v11
	v_mov_b32_e32 v201, v177
	v_add_u32_e32 v224, s57, v1
	v_add_u32_e32 v225, 0, v7
	v_add_u32_e32 v226, s58, v1
	s_movk_i32 s59, 0x1800
	s_mov_b32 s10, 0x3fd744fd
	s_mov_b32 s4, s5
	s_barrier

; #define PG8_STAGE(bufoff, gbase, voff) do { _Pragma("unroll") for (int _i = 0; _i < 2; ++_i) \
;         __builtin_amdgcn_global_load_lds((const unsigned*)((const char*)(gbase) + (voff)[_i]), (LAS unsigned*)(lds + (bufoff) + ldsw + _i * 8192), 16, 0, 0); } while (0)
; #define PG8_LDA(dst, b, h) do { _Pragma("unroll") for (int m = 0; m < 4; ++m) _Pragma("unroll") for (int k = 0; k < 2; ++k) dst[m][k] = *(const LAS bf16x8*)(lds + PG8_SA(b, h) + aoff + m * 2048 + k * 1024); } while (0)
; #define PG8_LDB(dst, b, h) do { _Pragma("unroll") for (int n = 0; n < 2; ++n) _Pragma("unroll") for (int k = 0; k < 2; ++k) dst[n][k] = *(const LAS bf16x8*)(lds + PG8_SB(b, h) + boff + n * 2048 + k * 1024); } while (0)
; #define PG8_MMA(ai, bj, At, Bt) do { __builtin_amdgcn_s_setprio(1); _Pragma("unroll") for (int m = 0; m < 4; ++m) _Pragma("unroll") for (int n = 0; n < 2; ++n) _Pragma("unroll") for (int k = 0; k < 2; ++k) \
;         acc[ai][bj][m][n] = __builtin_amdgcn_mfma_f32_16x16x32_bf16(Bt[n][k], At[m][k], acc[ai][bj][m][n], 0, 0, 0); __builtin_amdgcn_s_setprio(0); } while (0)
; #define PG8_WAIT_L(n) asm volatile("s_waitcnt lgkmcnt(" #n ")" ::: "memory")
; #define PG8_BAR __builtin_amdgcn_s_barrier()
; #define PG8_SCHED __builtin_amdgcn_sched_barrier(0)
; template <class Epi>
; DI void gemm_phase(LAS unsigned char* lds, const Gemm g, const StaticOrder& S, const Epi& E) {
;     ...
;             PG8_LDB(B0, 0, 0); PG8_SCHED; PG8_LDA(At, 0, 0); PG8_STAGE(PG8_SA(1, 1), a1 + hstepA, voffA);
;             PG8_WAIT_L(8); PG8_BAR; PG8_WAIT_L(0); PG8_MMA(0, 0, At, B0); PG8_BAR; PG8_SCHED;
;             PG8_LDB(B1, 0, 1); PG8_STAGE(PG8_SB(0, 0), b2, voffB);
;             PG8_BAR; PG8_WAIT_L(0); PG8_MMA(0, 1, At, B1); PG8_BAR;
;             PG8_LDA(At, 0, 1); PG8_STAGE(PG8_SA(0, 0), a2, voffA);
;             PG8_BAR; PG8_WAIT_L(0); PG8_MMA(1, 0, At, B0); PG8_BAR; PG8_SCHED;
;             PG8_STAGE(PG8_SB(0, 1), b2 + hstepB, voffB);
.LBB0_771:
	ds_read_b128 v[130:133], v224
	ds_read_b128 v[134:137], v224 offset:1024
	ds_read_b128 v[138:141], v224 offset:2048
	ds_read_b128 v[142:145], v224 offset:3072
	s_add_u32 s28, s26, 0xffdf0080
	s_addc_u32 s29, s27, -1
	s_cmp_eq_u32 s66, 28
	s_cselect_b32 s31, s23, s29
	s_cselect_b32 s30, s22, s28
	s_cselect_b32 s29, s21, s65
	s_cselect_b32 s28, s63, s64
	v_lshl_add_u64 v[206:207], s[26:27], 0, v[198:199]
	s_add_i32 m0, s48, 0xc000
	ds_read_b128 v[146:149], v225
	ds_read_b128 v[150:153], v225 offset:1024
	ds_read_b128 v[154:157], v225 offset:2048
	ds_read_b128 v[158:161], v225 offset:3072
	ds_read_b128 v[162:165], v225 offset:4096
	ds_read_b128 v[166:169], v225 offset:5120
	ds_read_b128 v[170:173], v225 offset:6144
	ds_read_b128 v[202:205], v225 offset:7168
	global_load_lds_dwordx4 v[206:207], off
	v_lshl_add_u64 v[206:207], s[26:27], 0, v[200:201]
	s_add_i32 m0, s48, 0xe000
	s_nop 0
	global_load_lds_dwordx4 v[206:207], off
	ds_read_b128 v[206:209], v226
	ds_read_b128 v[210:213], v226 offset:1024
	ds_read_b128 v[218:221], v226 offset:2048
	ds_read_b128 v[228:231], v226 offset:3072
	s_waitcnt lgkmcnt(0)
	s_waitcnt vmcnt(8)
	s_barrier
	s_setprio 1
	v_mfma_f32_16x16x32_bf16 v[126:129], v[130:133], v[146:149], v[126:129]
	v_mfma_f32_16x16x32_bf16 v[98:101], v[138:141], v[146:149], v[98:101]
	v_mfma_f32_16x16x32_bf16 v[122:125], v[130:133], v[154:157], v[122:125]
	v_mfma_f32_16x16x32_bf16 v[94:97], v[138:141], v[154:157], v[94:97]
	v_mfma_f32_16x16x32_bf16 v[118:121], v[130:133], v[162:165], v[118:121]
	v_mfma_f32_16x16x32_bf16 v[90:93], v[138:141], v[162:165], v[90:93]
	v_mfma_f32_16x16x32_bf16 v[114:117], v[130:133], v[170:173], v[114:117]
	v_mfma_f32_16x16x32_bf16 v[86:89], v[138:141], v[170:173], v[86:89]
	v_mfma_f32_16x16x32_bf16 v[126:129], v[134:137], v[150:153], v[126:129]
	v_mfma_f32_16x16x32_bf16 v[98:101], v[142:145], v[150:153], v[98:101]
	v_mfma_f32_16x16x32_bf16 v[122:125], v[134:137], v[158:161], v[122:125]
	v_mfma_f32_16x16x32_bf16 v[94:97], v[142:145], v[158:161], v[94:97]
	v_mfma_f32_16x16x32_bf16 v[118:121], v[134:137], v[166:169], v[118:121]
	v_mfma_f32_16x16x32_bf16 v[90:93], v[142:145], v[166:169], v[90:93]
	v_mfma_f32_16x16x32_bf16 v[114:117], v[134:137], v[202:205], v[114:117]
	v_mfma_f32_16x16x32_bf16 v[86:89], v[142:145], v[202:205], v[86:89]
	v_mfma_f32_16x16x32_bf16 v[66:69], v[206:209], v[146:149], v[66:69]
	v_mfma_f32_16x16x32_bf16 v[46:49], v[218:221], v[146:149], v[46:49]
	v_mfma_f32_16x16x32_bf16 v[58:61], v[206:209], v[154:157], v[58:61]
	v_mfma_f32_16x16x32_bf16 v[38:41], v[218:221], v[154:157], v[38:41]
	v_mfma_f32_16x16x32_bf16 v[54:57], v[206:209], v[162:165], v[54:57]
	v_mfma_f32_16x16x32_bf16 v[30:33], v[218:221], v[162:165], v[30:33]
	v_mfma_f32_16x16x32_bf16 v[50:53], v[206:209], v[170:173], v[50:53]
	v_mfma_f32_16x16x32_bf16 v[22:25], v[218:221], v[170:173], v[22:25]
	v_mfma_f32_16x16x32_bf16 v[66:69], v[210:213], v[150:153], v[66:69]
	v_mfma_f32_16x16x32_bf16 v[46:49], v[228:231], v[150:153], v[46:49]
	v_mfma_f32_16x16x32_bf16 v[58:61], v[210:213], v[158:161], v[58:61]
	v_mfma_f32_16x16x32_bf16 v[38:41], v[228:231], v[158:161], v[38:41]
	v_mfma_f32_16x16x32_bf16 v[54:57], v[210:213], v[166:169], v[54:57]
	v_mfma_f32_16x16x32_bf16 v[30:33], v[228:231], v[166:169], v[30:33]
	v_mfma_f32_16x16x32_bf16 v[50:53], v[210:213], v[202:205], v[50:53]
	v_mfma_f32_16x16x32_bf16 v[22:25], v[228:231], v[202:205], v[22:25]
	s_setprio 0
	s_barrier
	s_add_i32 s67, s57, s39
	v_lshl_add_u64 v[214:215], s[28:29], 0, v[176:177]
	s_mov_b32 m0, s67
	s_nop 0
	global_load_lds_dwordx4 v[214:215], off
	v_lshl_add_u64 v[222:223], s[28:29], 0, v[180:181]
	s_add_i32 m0, s67, 0x2000
	s_nop 0
	global_load_lds_dwordx4 v[222:223], off
	s_mov_b32 m0, s48
	v_lshl_add_u64 v[232:233], s[30:31], 0, v[174:175]
	ds_read_b128 v[146:149], v225 offset:16384
	ds_read_b128 v[150:153], v225 offset:17408
	ds_read_b128 v[154:157], v225 offset:18432
	ds_read_b128 v[158:161], v225 offset:19456
	ds_read_b128 v[162:165], v225 offset:20480
	ds_read_b128 v[166:169], v225 offset:21504
	ds_read_b128 v[170:173], v225 offset:22528
	ds_read_b128 v[202:205], v225 offset:23552
	global_load_lds_dwordx4 v[232:233], off
	v_lshl_add_u64 v[234:235], s[30:31], 0, v[178:179]
	s_mov_b32 m0, s49
	s_nop 0
	global_load_lds_dwordx4 v[234:235], off
	s_add_u32 s68, s28, 0x80000
	s_addc_u32 s69, s29, 0
	s_add_i32 s67, s58, s39
	v_lshl_add_u64 v[252:253], s[68:69], 0, v[176:177]
	s_mov_b32 m0, s67
	s_nop 0
	global_load_lds_dwordx4 v[252:253], off
	v_lshl_add_u64 v[252:253], s[68:69], 0, v[180:181]
	s_add_i32 m0, s67, 0x2000
	s_nop 0
	global_load_lds_dwordx4 v[252:253], off
	s_waitcnt lgkmcnt(0)
	s_waitcnt vmcnt(8)
	s_barrier
; #define PG8_STAGE(bufoff, gbase, voff) do { _Pragma("unroll") for (int _i = 0; _i < 2; ++_i) \
;         __builtin_amdgcn_global_load_lds((const unsigned*)((const char*)(gbase) + (voff)[_i]), (LAS unsigned*)(lds + (bufoff) + ldsw + _i * 8192), 16, 0, 0); } while (0)
; #define PG8_LDA(dst, b, h) do { _Pragma("unroll") for (int m = 0; m < 4; ++m) _Pragma("unroll") for (int k = 0; k < 2; ++k) dst[m][k] = *(const LAS bf16x8*)(lds + PG8_SA(b, h) + aoff + m * 2048 + k * 1024); } while (0)
; #define PG8_LDB(dst, b, h) do { _Pragma("unroll") for (int n = 0; n < 2; ++n) _Pragma("unroll") for (int k = 0; k < 2; ++k) dst[n][k] = *(const LAS bf16x8*)(lds + PG8_SB(b, h) + boff + n * 2048 + k * 1024); } while (0)
; #define PG8_MMA(ai, bj, At, Bt) do { __builtin_amdgcn_s_setprio(1); _Pragma("unroll") for (int m = 0; m < 4; ++m) _Pragma("unroll") for (int n = 0; n < 2; ++n) _Pragma("unroll") for (int k = 0; k < 2; ++k) \
;         acc[ai][bj][m][n] = __builtin_amdgcn_mfma_f32_16x16x32_bf16(Bt[n][k], At[m][k], acc[ai][bj][m][n], 0, 0, 0); __builtin_amdgcn_s_setprio(0); } while (0)
; #define PG8_WAIT_V(n) asm volatile("s_waitcnt vmcnt(" #n ")" ::: "memory")
; #define PG8_WAIT_L(n) asm volatile("s_waitcnt lgkmcnt(" #n ")" ::: "memory")
; #define PG8_BAR __builtin_amdgcn_s_barrier()
; #define PG8_SCHED __builtin_amdgcn_sched_barrier(0)
; template <class Epi>
; DI void gemm_phase(LAS unsigned char* lds, const Gemm g, const StaticOrder& S, const Epi& E) {
;     ...
;             PG8_BAR; PG8_WAIT_L(0); PG8_MMA(1, 0, At, B0); PG8_BAR; PG8_SCHED;
;             PG8_STAGE(PG8_SB(0, 1), b2 + hstepB, voffB);
;             PG8_WAIT_V(6); PG8_BAR; PG8_MMA(1, 1, At, B1); PG8_BAR;
;             PG8_LDB(B0, 1, 0); PG8_SCHED; PG8_LDA(At, 1, 0); PG8_STAGE(PG8_SA(0, 1), a2 + hstepA, voffA);
;             PG8_WAIT_L(8); PG8_BAR; PG8_WAIT_L(0); PG8_MMA(0, 0, At, B0); PG8_BAR; PG8_SCHED;
;             PG8_LDB(B1, 1, 1); PG8_STAGE(PG8_SB(1, 0), b3, voffB);
;             PG8_BAR; PG8_WAIT_L(0); PG8_MMA(0, 1, At, B1); PG8_BAR;
	s_setprio 1
	v_mfma_f32_16x16x32_bf16 v[110:113], v[130:133], v[146:149], v[110:113]
	v_mfma_f32_16x16x32_bf16 v[78:81], v[138:141], v[146:149], v[78:81]
	v_mfma_f32_16x16x32_bf16 v[106:109], v[130:133], v[154:157], v[106:109]
	v_mfma_f32_16x16x32_bf16 v[74:77], v[138:141], v[154:157], v[74:77]
	v_mfma_f32_16x16x32_bf16 v[102:105], v[130:133], v[162:165], v[102:105]
	v_mfma_f32_16x16x32_bf16 v[70:73], v[138:141], v[162:165], v[70:73]
	v_mfma_f32_16x16x32_bf16 v[82:85], v[130:133], v[170:173], v[82:85]
	v_mfma_f32_16x16x32_bf16 v[62:65], v[138:141], v[170:173], v[62:65]
	v_mfma_f32_16x16x32_bf16 v[110:113], v[134:137], v[150:153], v[110:113]
	v_mfma_f32_16x16x32_bf16 v[78:81], v[142:145], v[150:153], v[78:81]
	v_mfma_f32_16x16x32_bf16 v[106:109], v[134:137], v[158:161], v[106:109]
	v_mfma_f32_16x16x32_bf16 v[74:77], v[142:145], v[158:161], v[74:77]
	v_mfma_f32_16x16x32_bf16 v[102:105], v[134:137], v[166:169], v[102:105]
	v_mfma_f32_16x16x32_bf16 v[70:73], v[142:145], v[166:169], v[70:73]
	v_mfma_f32_16x16x32_bf16 v[82:85], v[134:137], v[202:205], v[82:85]
	v_mfma_f32_16x16x32_bf16 v[62:65], v[142:145], v[202:205], v[62:65]
	v_mfma_f32_16x16x32_bf16 v[42:45], v[206:209], v[146:149], v[42:45]
	v_mfma_f32_16x16x32_bf16 v[14:17], v[218:221], v[146:149], v[14:17]
	v_mfma_f32_16x16x32_bf16 v[34:37], v[206:209], v[154:157], v[34:37]
	v_mfma_f32_16x16x32_bf16 v[10:13], v[218:221], v[154:157], v[10:13]
	v_mfma_f32_16x16x32_bf16 v[26:29], v[206:209], v[162:165], v[26:29]
	v_mfma_f32_16x16x32_bf16 v[6:9], v[218:221], v[162:165], v[6:9]
	v_mfma_f32_16x16x32_bf16 v[18:21], v[206:209], v[170:173], v[18:21]
	v_mfma_f32_16x16x32_bf16 v[2:5], v[218:221], v[170:173], v[2:5]
	v_mfma_f32_16x16x32_bf16 v[42:45], v[210:213], v[150:153], v[42:45]
	v_mfma_f32_16x16x32_bf16 v[14:17], v[228:231], v[150:153], v[14:17]
	v_mfma_f32_16x16x32_bf16 v[34:37], v[210:213], v[158:161], v[34:37]
	v_mfma_f32_16x16x32_bf16 v[10:13], v[228:231], v[158:161], v[10:13]
	v_mfma_f32_16x16x32_bf16 v[26:29], v[210:213], v[166:169], v[26:29]
	v_mfma_f32_16x16x32_bf16 v[6:9], v[228:231], v[166:169], v[6:9]
	v_mfma_f32_16x16x32_bf16 v[18:21], v[210:213], v[202:205], v[18:21]
	v_mfma_f32_16x16x32_bf16 v[2:5], v[228:231], v[202:205], v[2:5]
	s_setprio 0
	s_add_i32 s67, 0, 0x18000
	v_add_u32_e32 v142, s67, v1
	s_barrier
	ds_read_b128 v[130:133], v142
	ds_read_b128 v[134:137], v142 offset:1024
	ds_read_b128 v[138:141], v142 offset:2048
	ds_read_b128 v[142:145], v142 offset:3072
	s_add_u32 s30, s30, 0x210000
	s_addc_u32 s31, s31, 0
	s_mov_b32 m0, s50
	v_lshl_add_u64 v[206:207], s[30:31], 0, v[174:175]
	ds_read_b128 v[146:149], v225 offset:32768
	ds_read_b128 v[150:153], v225 offset:33792
	ds_read_b128 v[154:157], v225 offset:34816
	ds_read_b128 v[158:161], v225 offset:35840
	ds_read_b128 v[162:165], v225 offset:36864
	ds_read_b128 v[166:169], v225 offset:37888
	ds_read_b128 v[170:173], v225 offset:38912
	ds_read_b128 v[202:205], v225 offset:39936
	global_load_lds_dwordx4 v[206:207], off
	v_lshl_add_u64 v[206:207], s[30:31], 0, v[178:179]
	s_mov_b32 m0, s51
	s_nop 0
	global_load_lds_dwordx4 v[206:207], off
	s_add_i32 s30, 0, 0x1c000
	v_add_u32_e32 v216, s30, v1
	ds_read_b128 v[206:209], v216
	ds_read_b128 v[210:213], v216 offset:1024
	ds_read_b128 v[218:221], v216 offset:2048
	ds_read_b128 v[228:231], v216 offset:3072
	s_waitcnt lgkmcnt(0)
	s_waitcnt vmcnt(8)
	s_barrier
	s_setprio 1
	v_mfma_f32_16x16x32_bf16 v[126:129], v[130:133], v[146:149], v[126:129]
	v_mfma_f32_16x16x32_bf16 v[98:101], v[138:141], v[146:149], v[98:101]
	v_mfma_f32_16x16x32_bf16 v[122:125], v[130:133], v[154:157], v[122:125]
	v_mfma_f32_16x16x32_bf16 v[94:97], v[138:141], v[154:157], v[94:97]
	v_mfma_f32_16x16x32_bf16 v[118:121], v[130:133], v[162:165], v[118:121]
	v_mfma_f32_16x16x32_bf16 v[90:93], v[138:141], v[162:165], v[90:93]
	v_mfma_f32_16x16x32_bf16 v[114:117], v[130:133], v[170:173], v[114:117]
	v_mfma_f32_16x16x32_bf16 v[86:89], v[138:141], v[170:173], v[86:89]
	v_mfma_f32_16x16x32_bf16 v[126:129], v[134:137], v[150:153], v[126:129]
	v_mfma_f32_16x16x32_bf16 v[98:101], v[142:145], v[150:153], v[98:101]
	v_mfma_f32_16x16x32_bf16 v[122:125], v[134:137], v[158:161], v[122:125]
	v_mfma_f32_16x16x32_bf16 v[94:97], v[142:145], v[158:161], v[94:97]
	v_mfma_f32_16x16x32_bf16 v[118:121], v[134:137], v[166:169], v[118:121]
	v_mfma_f32_16x16x32_bf16 v[90:93], v[142:145], v[166:169], v[90:93]
	v_mfma_f32_16x16x32_bf16 v[114:117], v[134:137], v[202:205], v[114:117]
	v_mfma_f32_16x16x32_bf16 v[86:89], v[142:145], v[202:205], v[86:89]
	v_mfma_f32_16x16x32_bf16 v[66:69], v[206:209], v[146:149], v[66:69]
	v_mfma_f32_16x16x32_bf16 v[46:49], v[218:221], v[146:149], v[46:49]
	v_mfma_f32_16x16x32_bf16 v[58:61], v[206:209], v[154:157], v[58:61]
	v_mfma_f32_16x16x32_bf16 v[38:41], v[218:221], v[154:157], v[38:41]
	v_mfma_f32_16x16x32_bf16 v[54:57], v[206:209], v[162:165], v[54:57]
	v_mfma_f32_16x16x32_bf16 v[30:33], v[218:221], v[162:165], v[30:33]
	v_mfma_f32_16x16x32_bf16 v[50:53], v[206:209], v[170:173], v[50:53]
	v_mfma_f32_16x16x32_bf16 v[22:25], v[218:221], v[170:173], v[22:25]
	v_mfma_f32_16x16x32_bf16 v[66:69], v[210:213], v[150:153], v[66:69]
	v_mfma_f32_16x16x32_bf16 v[46:49], v[228:231], v[150:153], v[46:49]
	v_mfma_f32_16x16x32_bf16 v[58:61], v[210:213], v[158:161], v[58:61]
	v_mfma_f32_16x16x32_bf16 v[38:41], v[228:231], v[158:161], v[38:41]
	v_mfma_f32_16x16x32_bf16 v[54:57], v[210:213], v[166:169], v[54:57]
	v_mfma_f32_16x16x32_bf16 v[30:33], v[228:231], v[166:169], v[30:33]
	v_mfma_f32_16x16x32_bf16 v[50:53], v[210:213], v[202:205], v[50:53]
	v_mfma_f32_16x16x32_bf16 v[22:25], v[228:231], v[202:205], v[22:25]
	s_setprio 0
	s_barrier
; #define PG8_STAGE(bufoff, gbase, voff) do { _Pragma("unroll") for (int _i = 0; _i < 2; ++_i) \
;         __builtin_amdgcn_global_load_lds((const unsigned*)((const char*)(gbase) + (voff)[_i]), (LAS unsigned*)(lds + (bufoff) + ldsw + _i * 8192), 16, 0, 0); } while (0)
; #define PG8_LDA(dst, b, h) do { _Pragma("unroll") for (int m = 0; m < 4; ++m) _Pragma("unroll") for (int k = 0; k < 2; ++k) dst[m][k] = *(const LAS bf16x8*)(lds + PG8_SA(b, h) + aoff + m * 2048 + k * 1024); } while (0)
; #define PG8_WAIT_V(n) asm volatile("s_waitcnt vmcnt(" #n ")" ::: "memory")
; #define PG8_WAIT_L(n) asm volatile("s_waitcnt lgkmcnt(" #n ")" ::: "memory")
; template <class Epi>
; DI void gemm_phase(LAS unsigned char* lds, const Gemm g, const StaticOrder& S, const Epi& E) {
;     ...
;             PG8_LDB(B1, 1, 1); PG8_STAGE(PG8_SB(1, 0), b3, voffB);
;             PG8_BAR; PG8_WAIT_L(0); PG8_MMA(0, 1, At, B1); PG8_BAR;
;             PG8_LDA(At, 1, 1); PG8_STAGE(PG8_SA(1, 0), a3, voffA);
;             PG8_BAR; PG8_WAIT_L(0); PG8_MMA(1, 0, At, B0); PG8_BAR; PG8_SCHED;
;             PG8_STAGE(PG8_SB(1, 1), b3 + hstepB, voffB);
;             PG8_WAIT_V(6); PG8_BAR; PG8_MMA(1, 1, At, B1); PG8_BAR;
;         }
;     DI void operator()(const f32x4 (&acc)[2][2][4][2], const pg8::Unit& u, int wr, int wc, int fr, int fq) const {
;         const int rowt = row_base + u.pm * 256, col0 = u.pn * 256 + wc * 32 + 4 * fq, rl = wr * 64 + fr;
;         const int cd = cond_of_row(rowt);
;         const float* gtp = gt0 + (size_t)cd * 6144;
;         float* dbase = rowt < TL ? out + (size_t)rowt * D : ctxv + (size_t)(rowt - TL) * D;
;         const float* sbase = mode ? (const float*)dbase : (rowt < TL ? xin + (size_t)rowt * D : cin + (size_t)(rowt - TL) * D);
; #pragma unroll
;         for (int bj = 0; bj < 2; ++bj) {
;             f32x4 gv[2], gg[2], bb[2], xv[2][8];
; #pragma unroll
;             for (int n = 0; n < 2; ++n) {
;                 const int c = col0 + bj * 128 + n * 16;
;                 gv[n] = *(const f32x4*)(gtp + c);
;                 gg[n] = (f32x4){1.f, 1.f, 1.f, 1.f}; bb[n] = (f32x4){0.f, 0.f, 0.f, 0.f};
;                 if (mode) { gg[n] = *(const f32x4*)(lg + c); bb[n] = *(const f32x4*)(lb + c); }
; #pragma unroll
;                 for (int q = 0; q < 8; ++q) { const int rr = rl + (q >> 2) * 128 + (q & 3) * 16; xv[n][q] = *(const f32x4*)(sbase + (size_t)rr * D + c); }
	s_add_i32 s31, s67, s39
	v_lshl_add_u64 v[214:215], v[214:215], 0, s[6:7]
	s_mov_b32 m0, s31
	s_nop 0
	global_load_lds_dwordx4 v[214:215], off
	v_lshl_add_u64 v[214:215], v[222:223], 0, s[6:7]
	s_add_i32 m0, s31, 0x2000
	s_nop 0
	global_load_lds_dwordx4 v[214:215], off
	s_mov_b32 m0, s55
	v_lshl_add_u64 v[214:215], v[232:233], 0, s[6:7]
	ds_read_b128 v[146:149], v225 offset:49152
	ds_read_b128 v[150:153], v225 offset:50176
	ds_read_b128 v[154:157], v225 offset:51200
	ds_read_b128 v[158:161], v225 offset:52224
	ds_read_b128 v[162:165], v225 offset:53248
	ds_read_b128 v[166:169], v225 offset:54272
	ds_read_b128 v[170:173], v225 offset:55296
	ds_read_b128 v[202:205], v225 offset:56320
	global_load_lds_dwordx4 v[214:215], off
	v_lshl_add_u64 v[214:215], v[234:235], 0, s[6:7]
	s_mov_b32 m0, s56
	s_nop 0
	global_load_lds_dwordx4 v[214:215], off
	s_add_u32 s28, s28, 0x80080
	s_addc_u32 s29, s29, 0
	s_add_i32 s30, s30, s39
	v_lshl_add_u64 v[252:253], s[28:29], 0, v[176:177]
	s_mov_b32 m0, s30
	s_nop 0
	global_load_lds_dwordx4 v[252:253], off
	v_lshl_add_u64 v[252:253], s[28:29], 0, v[180:181]
	s_add_i32 m0, s30, 0x2000
	s_nop 0
	global_load_lds_dwordx4 v[252:253], off
	s_waitcnt lgkmcnt(0)
	s_waitcnt vmcnt(8)
	s_barrier
	s_setprio 1
	v_mfma_f32_16x16x32_bf16 v[110:113], v[130:133], v[146:149], v[110:113]
	v_mfma_f32_16x16x32_bf16 v[78:81], v[138:141], v[146:149], v[78:81]
	v_mfma_f32_16x16x32_bf16 v[106:109], v[130:133], v[154:157], v[106:109]
	v_mfma_f32_16x16x32_bf16 v[74:77], v[138:141], v[154:157], v[74:77]
	v_mfma_f32_16x16x32_bf16 v[102:105], v[130:133], v[162:165], v[102:105]
	v_mfma_f32_16x16x32_bf16 v[70:73], v[138:141], v[162:165], v[70:73]
	v_mfma_f32_16x16x32_bf16 v[82:85], v[130:133], v[170:173], v[82:85]
	v_mfma_f32_16x16x32_bf16 v[62:65], v[138:141], v[170:173], v[62:65]
	v_mfma_f32_16x16x32_bf16 v[110:113], v[134:137], v[150:153], v[110:113]
	v_mfma_f32_16x16x32_bf16 v[78:81], v[142:145], v[150:153], v[78:81]
	v_mfma_f32_16x16x32_bf16 v[106:109], v[134:137], v[158:161], v[106:109]
	v_mfma_f32_16x16x32_bf16 v[74:77], v[142:145], v[158:161], v[74:77]
	v_mfma_f32_16x16x32_bf16 v[102:105], v[134:137], v[166:169], v[102:105]
	v_mfma_f32_16x16x32_bf16 v[70:73], v[142:145], v[166:169], v[70:73]
	v_mfma_f32_16x16x32_bf16 v[82:85], v[134:137], v[202:205], v[82:85]
	v_mfma_f32_16x16x32_bf16 v[62:65], v[142:145], v[202:205], v[62:65]
	v_mfma_f32_16x16x32_bf16 v[42:45], v[206:209], v[146:149], v[42:45]
	v_mfma_f32_16x16x32_bf16 v[14:17], v[218:221], v[146:149], v[14:17]
	v_mfma_f32_16x16x32_bf16 v[34:37], v[206:209], v[154:157], v[34:37]
	v_mfma_f32_16x16x32_bf16 v[10:13], v[218:221], v[154:157], v[10:13]
	v_mfma_f32_16x16x32_bf16 v[26:29], v[206:209], v[162:165], v[26:29]
	v_mfma_f32_16x16x32_bf16 v[6:9], v[218:221], v[162:165], v[6:9]
	v_mfma_f32_16x16x32_bf16 v[18:21], v[206:209], v[170:173], v[18:21]
	v_mfma_f32_16x16x32_bf16 v[2:5], v[218:221], v[170:173], v[2:5]
	v_mfma_f32_16x16x32_bf16 v[42:45], v[210:213], v[150:153], v[42:45]
	v_mfma_f32_16x16x32_bf16 v[14:17], v[228:231], v[150:153], v[14:17]
	v_mfma_f32_16x16x32_bf16 v[34:37], v[210:213], v[158:161], v[34:37]
	v_mfma_f32_16x16x32_bf16 v[10:13], v[228:231], v[158:161], v[10:13]
	v_mfma_f32_16x16x32_bf16 v[26:29], v[210:213], v[166:169], v[26:29]
	v_mfma_f32_16x16x32_bf16 v[6:9], v[228:231], v[166:169], v[6:9]
	v_mfma_f32_16x16x32_bf16 v[18:21], v[210:213], v[202:205], v[18:21]
	v_mfma_f32_16x16x32_bf16 v[2:5], v[228:231], v[202:205], v[2:5]
	s_setprio 0
	s_add_i32 s66, s66, 2
	s_add_u32 s26, s26, 0x100
	s_addc_u32 s27, s27, 0
	s_add_u32 s64, s64, 0x100
	s_addc_u32 s65, s65, 0
	s_cmp_gt_u32 s66, 29
	s_barrier
	s_cbranch_scc0 .LBB0_771
	s_lshl_b32 s26, s61, 8
	s_add_i32 s28, s26, 0x8000
	s_cmp_gt_u32 s26, 0xffff7fff
	s_cselect_b32 s21, s59, 0x3000
	s_cmpk_gt_i32 s61, 0xffbf
	s_cselect_b32 s21, s21, 0
	s_lshl_b32 s21, s21, 2
	s_add_u32 s30, s54, s21
	s_addc_u32 s31, s11, 0
	s_ashr_i32 s29, s28, 31
	v_lshl_or_b32 v130, s62, 8, v217
	s_lshl_b64 s[62:63], s[28:29], 13
	s_mov_b32 s27, s5
	s_add_u32 s21, s14, s62
	s_addc_u32 s64, s15, s63
	s_lshl_b64 s[62:63], s[26:27], 13
	s_add_u32 s62, s16, s62
	s_addc_u32 s63, s17, s63
	s_cmp_lt_i32 s61, 0
	v_ashrrev_i32_e32 v131, 31, v130
	s_cselect_b32 s27, s29, 0
	s_cselect_b32 s26, s28, s26
	s_cselect_b32 s29, s64, s63
	s_cselect_b32 s28, s21, s62
	v_lshlrev_b64 v[222:223], 2, v[130:131]
	v_lshl_add_u64 v[130:131], s[28:29], 0, v[222:223]
	v_lshl_add_u64 v[204:205], v[130:131], 0, v[182:183]
	v_lshl_add_u64 v[202:203], s[30:31], 0, v[222:223]
	global_load_dwordx4 v[228:231], v[204:205], off
	global_load_dwordx4 v[154:157], v[202:203], off
	v_lshl_add_u64 v[206:207], v[130:131], 0, v[184:185]
	global_load_dwordx4 v[232:235], v[206:207], off
	v_lshl_add_u64 v[208:209], v[130:131], 0, v[186:187]
	global_load_dwordx4 v[236:239], v[208:209], off
	v_lshl_add_u64 v[210:211], v[130:131], 0, v[188:189]
	global_load_dwordx4 v[240:243], v[210:211], off
	v_lshl_add_u64 v[212:213], v[130:131], 0, v[190:191]
	global_load_dwordx4 v[244:247], v[212:213], off
	v_lshl_add_u64 v[214:215], v[130:131], 0, v[192:193]
	global_load_dwordx4 v[248:251], v[214:215], off
	v_lshl_add_u64 v[218:219], v[130:131], 0, v[194:195]
	global_load_dwordx4 v[252:255], v[218:219], off
	v_lshl_add_u64 v[220:221], v[130:131], 0, v[196:197]
	global_load_dwordx4 v[170:173], v[220:221], off
	global_load_dwordx4 v[130:133], v[202:203], off offset:64
	global_load_dwordx4 v[166:169], v[204:205], off offset:64
	global_load_dwordx4 v[162:165], v[206:207], off offset:64
	global_load_dwordx4 v[158:161], v[208:209], off offset:64
	global_load_dwordx4 v[150:153], v[210:211], off offset:64
	global_load_dwordx4 v[142:145], v[212:213], off offset:64
	global_load_dwordx4 v[146:149], v[214:215], off offset:64
	global_load_dwordx4 v[138:141], v[218:219], off offset:64
	global_load_dwordx4 v[134:137], v[220:221], off offset:64
	s_cselect_b32 s61, s9, s53
	s_cselect_b32 s65, s8, s52
	s_lshl_b64 s[26:27], s[26:27], 13
	s_add_u32 s26, s65, s26
	s_addc_u32 s27, s61, s27
	v_lshl_add_u64 v[222:223], s[26:27], 0, v[222:223]
	s_and_b64 vcc, exec, s[18:19]
	s_mov_b32 s62, s20
	s_mov_b32 s61, s60
	s_mov_b64 s[28:29], s[24:25]
	s_mov_b64 s[26:27], s[22:23]
	s_waitcnt vmcnt(0)
;     DI void operator()(const f32x4 (&acc)[2][2][4][2], const pg8::Unit& u, int wr, int wc, int fr, int fq) const {
;     ...
;                 for (int q = 0; q < 8; ++q) { const int rr = rl + (q >> 2) * 128 + (q & 3) * 16; xv[n][q] = *(const f32x4*)(sbase + (size_t)rr * D + c); }
;             }
; #pragma unroll
;             for (int n = 0; n < 2; ++n) {
;                 const int c = col0 + bj * 128 + n * 16;
; #pragma unroll
;                 for (int q = 0; q < 8; ++q) {
;                     const int rr = rl + (q >> 2) * 128 + (q & 3) * 16;
;                     f32x4 x = xv[n][q];
;                     if (mode) { const float mu = stats[2 * (rowt + rr)], rs = stats[2 * (rowt + rr) + 1]; x = (x - mu) * rs * gg[n] + bb[n]; }
;                     *(f32x4*)(dbase + (size_t)rr * D + c) = ALPHA * x + gv[n] * acc[q >> 2][bj][q & 3][n];
;                 }
;             }
	v_pk_mul_f32 v[230:231], v[230:231], s[10:11] op_sel_hi:[1,0]
	v_pk_mul_f32 v[228:229], v[228:229], s[10:11] op_sel_hi:[1,0]
	v_pk_fma_f32 v[230:231], v[128:129], v[156:157], v[230:231]
	v_pk_fma_f32 v[228:229], v[126:127], v[154:155], v[228:229]
	v_lshl_add_u64 v[126:127], v[222:223], 0, v[182:183]
	global_store_dwordx4 v[126:127], v[228:231], off
	v_pk_mul_f32 v[128:129], v[234:235], s[10:11] op_sel_hi:[1,0]
	s_nop 0
	v_pk_mul_f32 v[228:229], v[232:233], s[10:11] op_sel_hi:[1,0]
	v_pk_fma_f32 v[230:231], v[124:125], v[156:157], v[128:129]
	v_pk_fma_f32 v[228:229], v[122:123], v[154:155], v[228:229]
	v_lshl_add_u64 v[122:123], v[222:223], 0, v[184:185]
	v_pk_mul_f32 v[124:125], v[238:239], s[10:11] op_sel_hi:[1,0]
	v_pk_mul_f32 v[128:129], v[236:237], s[10:11] op_sel_hi:[1,0]
	global_store_dwordx4 v[122:123], v[228:231], off
	s_nop 1
	v_pk_fma_f32 v[230:231], v[120:121], v[156:157], v[124:125]
	v_pk_fma_f32 v[228:229], v[118:119], v[154:155], v[128:129]
	v_lshl_add_u64 v[118:119], v[222:223], 0, v[186:187]
	v_pk_mul_f32 v[120:121], v[242:243], s[10:11] op_sel_hi:[1,0]
	v_pk_mul_f32 v[124:125], v[240:241], s[10:11] op_sel_hi:[1,0]
	global_store_dwordx4 v[118:119], v[228:231], off
	s_nop 1
	v_pk_fma_f32 v[230:231], v[116:117], v[156:157], v[120:121]
	v_pk_fma_f32 v[228:229], v[114:115], v[154:155], v[124:125]
	v_lshl_add_u64 v[114:115], v[222:223], 0, v[188:189]
	v_pk_mul_f32 v[116:117], v[246:247], s[10:11] op_sel_hi:[1,0]
	v_pk_mul_f32 v[120:121], v[244:245], s[10:11] op_sel_hi:[1,0]
	global_store_dwordx4 v[114:115], v[228:231], off
	s_nop 1
	v_pk_fma_f32 v[230:231], v[112:113], v[156:157], v[116:117]
	v_pk_fma_f32 v[228:229], v[110:111], v[154:155], v[120:121]
	v_lshl_add_u64 v[110:111], v[222:223], 0, v[190:191]
	v_pk_mul_f32 v[112:113], v[250:251], s[10:11] op_sel_hi:[1,0]
	v_pk_mul_f32 v[116:117], v[248:249], s[10:11] op_sel_hi:[1,0]
	global_store_dwordx4 v[110:111], v[228:231], off
	s_nop 1
	v_pk_fma_f32 v[230:231], v[108:109], v[156:157], v[112:113]
	v_pk_fma_f32 v[228:229], v[106:107], v[154:155], v[116:117]
	v_lshl_add_u64 v[106:107], v[222:223], 0, v[192:193]
	v_pk_mul_f32 v[108:109], v[254:255], s[10:11] op_sel_hi:[1,0]
	global_store_dwordx4 v[106:107], v[228:231], off
	v_pk_mul_f32 v[112:113], v[252:253], s[10:11] op_sel_hi:[1,0]
	v_and_b32_e32 v254, 0x3ff, v0
	v_pk_fma_f32 v[230:231], v[104:105], v[156:157], v[108:109]
	v_pk_mul_f32 v[104:105], v[172:173], s[10:11] op_sel_hi:[1,0]
	v_pk_fma_f32 v[228:229], v[102:103], v[154:155], v[112:113]
	v_pk_fma_f32 v[156:157], v[84:85], v[156:157], v[104:105]
	v_pk_mul_f32 v[84:85], v[168:169], s[10:11] op_sel_hi:[1,0]
	v_pk_mul_f32 v[104:105], v[166:167], s[10:11] op_sel_hi:[1,0]
	v_pk_fma_f32 v[100:101], v[100:101], v[132:133], v[84:85]
	v_pk_fma_f32 v[98:99], v[98:99], v[130:131], v[104:105]
	global_store_dwordx4 v[126:127], v[98:101], off offset:64
	v_pk_mul_f32 v[84:85], v[164:165], s[10:11] op_sel_hi:[1,0]
	v_lshl_add_u64 v[102:103], v[222:223], 0, v[194:195]
	v_pk_mul_f32 v[98:99], v[162:163], s[10:11] op_sel_hi:[1,0]
	v_pk_fma_f32 v[96:97], v[96:97], v[132:133], v[84:85]
	v_pk_fma_f32 v[94:95], v[94:95], v[130:131], v[98:99]
	global_store_dwordx4 v[122:123], v[94:97], off offset:64
	v_pk_mul_f32 v[84:85], v[160:161], s[10:11] op_sel_hi:[1,0]
	v_pk_mul_f32 v[108:109], v[170:171], s[10:11] op_sel_hi:[1,0]
	v_pk_mul_f32 v[94:95], v[158:159], s[10:11] op_sel_hi:[1,0]
	v_pk_fma_f32 v[92:93], v[92:93], v[132:133], v[84:85]
	v_pk_fma_f32 v[90:91], v[90:91], v[130:131], v[94:95]
	global_store_dwordx4 v[118:119], v[90:93], off offset:64
	v_pk_mul_f32 v[84:85], v[152:153], s[10:11] op_sel_hi:[1,0]
	v_pk_fma_f32 v[154:155], v[82:83], v[154:155], v[108:109]
	v_pk_mul_f32 v[90:91], v[150:151], s[10:11] op_sel_hi:[1,0]
	v_pk_fma_f32 v[88:89], v[88:89], v[132:133], v[84:85]
	v_pk_fma_f32 v[86:87], v[86:87], v[130:131], v[90:91]
	global_store_dwordx4 v[114:115], v[86:89], off offset:64
	v_pk_mul_f32 v[84:85], v[144:145], s[10:11] op_sel_hi:[1,0]
	v_lshl_add_u64 v[82:83], v[222:223], 0, v[196:197]
	v_pk_mul_f32 v[86:87], v[142:143], s[10:11] op_sel_hi:[1,0]
	v_pk_fma_f32 v[80:81], v[80:81], v[132:133], v[84:85]
	v_pk_fma_f32 v[78:79], v[78:79], v[130:131], v[86:87]
	global_store_dwordx4 v[110:111], v[78:81], off offset:64
	global_store_dwordx4 v[102:103], v[228:231], off
	global_store_dwordx4 v[82:83], v[154:157], off
	v_pk_mul_f32 v[78:79], v[148:149], s[10:11] op_sel_hi:[1,0]
	v_pk_mul_f32 v[80:81], v[146:147], s[10:11] op_sel_hi:[1,0]
	v_pk_fma_f32 v[76:77], v[76:77], v[132:133], v[78:79]
	v_pk_fma_f32 v[74:75], v[74:75], v[130:131], v[80:81]
	global_store_dwordx4 v[106:107], v[74:77], off offset:64
	s_nop 1
	v_pk_mul_f32 v[74:75], v[140:141], s[10:11] op_sel_hi:[1,0]
	v_pk_mul_f32 v[76:77], v[138:139], s[10:11] op_sel_hi:[1,0]
	v_pk_fma_f32 v[72:73], v[72:73], v[132:133], v[74:75]
	v_pk_fma_f32 v[70:71], v[70:71], v[130:131], v[76:77]
	global_store_dwordx4 v[102:103], v[70:73], off offset:64
	s_nop 1
	v_pk_mul_f32 v[70:71], v[136:137], s[10:11] op_sel_hi:[1,0]
	v_pk_mul_f32 v[72:73], v[134:135], s[10:11] op_sel_hi:[1,0]
	v_pk_fma_f32 v[64:65], v[64:65], v[132:133], v[70:71]
	v_pk_fma_f32 v[62:63], v[62:63], v[130:131], v[72:73]
	global_store_dwordx4 v[82:83], v[62:65], off offset:64
	global_load_dwordx4 v[74:77], v[202:203], off offset:512
	global_load_dwordx4 v[78:81], v[204:205], off offset:512
	global_load_dwordx4 v[84:87], v[206:207], off offset:512
	global_load_dwordx4 v[88:91], v[208:209], off offset:512
	global_load_dwordx4 v[92:95], v[210:211], off offset:512
	global_load_dwordx4 v[96:99], v[212:213], off offset:512
	global_load_dwordx4 v[128:131], v[214:215], off offset:512
	global_load_dwordx4 v[132:135], v[218:219], off offset:512
	global_load_dwordx4 v[136:139], v[220:221], off offset:512
	global_load_dwordx4 v[62:65], v[202:203], off offset:576
	global_load_dwordx4 v[140:143], v[204:205], off offset:576
	global_load_dwordx4 v[144:147], v[206:207], off offset:576
	global_load_dwordx4 v[148:151], v[208:209], off offset:576
	global_load_dwordx4 v[152:155], v[210:211], off offset:576
	global_load_dwordx4 v[156:159], v[212:213], off offset:576
	global_load_dwordx4 v[160:163], v[214:215], off offset:576
	global_load_dwordx4 v[164:167], v[218:219], off offset:576
	global_load_dwordx4 v[70:73], v[220:221], off offset:576
	s_waitcnt vmcnt(0)
;     DI void operator()(const f32x4 (&acc)[2][2][4][2], const pg8::Unit& u, int wr, int wc, int fr, int fq) const {
;     ...
; #pragma unroll
;             for (int n = 0; n < 2; ++n) {
;                 const int c = col0 + bj * 128 + n * 16;
; #pragma unroll
;                 for (int q = 0; q < 8; ++q) {
;                     const int rr = rl + (q >> 2) * 128 + (q & 3) * 16;
;                     f32x4 x = xv[n][q];
;                     if (mode) { const float mu = stats[2 * (rowt + rr)], rs = stats[2 * (rowt + rr) + 1]; x = (x - mu) * rs * gg[n] + bb[n]; }
;                     *(f32x4*)(dbase + (size_t)rr * D + c) = ALPHA * x + gv[n] * acc[q >> 2][bj][q & 3][n];
;                 }
;             }
	v_pk_mul_f32 v[80:81], v[80:81], s[10:11] op_sel_hi:[1,0]
	v_pk_mul_f32 v[78:79], v[78:79], s[10:11] op_sel_hi:[1,0]
	v_pk_fma_f32 v[68:69], v[68:69], v[76:77], v[80:81]
	v_pk_fma_f32 v[66:67], v[66:67], v[74:75], v[78:79]
	global_store_dwordx4 v[126:127], v[66:69], off offset:512
	s_nop 1
	v_pk_mul_f32 v[66:67], v[86:87], s[10:11] op_sel_hi:[1,0]
	v_pk_mul_f32 v[68:69], v[84:85], s[10:11] op_sel_hi:[1,0]
	v_pk_fma_f32 v[60:61], v[60:61], v[76:77], v[66:67]
	v_pk_fma_f32 v[58:59], v[58:59], v[74:75], v[68:69]
	global_store_dwordx4 v[122:123], v[58:61], off offset:512
	s_nop 1
	v_pk_mul_f32 v[58:59], v[90:91], s[10:11] op_sel_hi:[1,0]
	v_pk_mul_f32 v[60:61], v[88:89], s[10:11] op_sel_hi:[1,0]
	v_pk_fma_f32 v[56:57], v[56:57], v[76:77], v[58:59]
	v_pk_fma_f32 v[54:55], v[54:55], v[74:75], v[60:61]
	global_store_dwordx4 v[118:119], v[54:57], off offset:512
	s_nop 1
	v_pk_mul_f32 v[54:55], v[94:95], s[10:11] op_sel_hi:[1,0]
	v_pk_mul_f32 v[56:57], v[92:93], s[10:11] op_sel_hi:[1,0]
	v_pk_fma_f32 v[52:53], v[52:53], v[76:77], v[54:55]
	v_pk_fma_f32 v[50:51], v[50:51], v[74:75], v[56:57]
	global_store_dwordx4 v[114:115], v[50:53], off offset:512
	s_nop 1
	v_pk_mul_f32 v[50:51], v[98:99], s[10:11] op_sel_hi:[1,0]
	v_pk_mul_f32 v[52:53], v[96:97], s[10:11] op_sel_hi:[1,0]
	v_pk_fma_f32 v[44:45], v[44:45], v[76:77], v[50:51]
	v_pk_fma_f32 v[42:43], v[42:43], v[74:75], v[52:53]
	global_store_dwordx4 v[110:111], v[42:45], off offset:512
	s_nop 1
	v_pk_mul_f32 v[42:43], v[130:131], s[10:11] op_sel_hi:[1,0]
	v_pk_mul_f32 v[44:45], v[128:129], s[10:11] op_sel_hi:[1,0]
	v_pk_fma_f32 v[36:37], v[36:37], v[76:77], v[42:43]
	v_pk_fma_f32 v[34:35], v[34:35], v[74:75], v[44:45]
	global_store_dwordx4 v[106:107], v[34:37], off offset:512
	s_nop 1
	v_pk_mul_f32 v[34:35], v[134:135], s[10:11] op_sel_hi:[1,0]
	v_pk_mul_f32 v[36:37], v[132:133], s[10:11] op_sel_hi:[1,0]
	v_pk_fma_f32 v[28:29], v[28:29], v[76:77], v[34:35]
	v_pk_fma_f32 v[26:27], v[26:27], v[74:75], v[36:37]
	global_store_dwordx4 v[102:103], v[26:29], off offset:512
	s_nop 1
	v_pk_mul_f32 v[26:27], v[138:139], s[10:11] op_sel_hi:[1,0]
	v_pk_mul_f32 v[28:29], v[136:137], s[10:11] op_sel_hi:[1,0]
	v_pk_fma_f32 v[20:21], v[20:21], v[76:77], v[26:27]
	v_pk_fma_f32 v[18:19], v[18:19], v[74:75], v[28:29]
	global_store_dwordx4 v[82:83], v[18:21], off offset:512
	v_pk_mul_f32 v[26:27], v[140:141], s[10:11] op_sel_hi:[1,0]
	s_nop 0
	v_pk_mul_f32 v[18:19], v[142:143], s[10:11] op_sel_hi:[1,0]
	s_nop 0
	v_pk_fma_f32 v[20:21], v[48:49], v[64:65], v[18:19]
	v_pk_fma_f32 v[18:19], v[46:47], v[62:63], v[26:27]
	global_store_dwordx4 v[126:127], v[18:21], off offset:576
	v_pk_mul_f32 v[26:27], v[144:145], s[10:11] op_sel_hi:[1,0]
	s_nop 0
	v_pk_mul_f32 v[18:19], v[146:147], s[10:11] op_sel_hi:[1,0]
	s_nop 0
	v_pk_fma_f32 v[20:21], v[40:41], v[64:65], v[18:19]
	v_pk_fma_f32 v[18:19], v[38:39], v[62:63], v[26:27]
	global_store_dwordx4 v[122:123], v[18:21], off offset:576
	v_pk_mul_f32 v[26:27], v[148:149], s[10:11] op_sel_hi:[1,0]
	s_nop 0
	v_pk_mul_f32 v[18:19], v[150:151], s[10:11] op_sel_hi:[1,0]
	s_nop 0
	v_pk_fma_f32 v[20:21], v[32:33], v[64:65], v[18:19]
	v_pk_fma_f32 v[18:19], v[30:31], v[62:63], v[26:27]
	global_store_dwordx4 v[118:119], v[18:21], off offset:576
	v_pk_mul_f32 v[26:27], v[152:153], s[10:11] op_sel_hi:[1,0]
	s_nop 0
	v_pk_mul_f32 v[18:19], v[154:155], s[10:11] op_sel_hi:[1,0]
	s_nop 0
	v_pk_fma_f32 v[20:21], v[24:25], v[64:65], v[18:19]
	v_pk_fma_f32 v[18:19], v[22:23], v[62:63], v[26:27]
	global_store_dwordx4 v[114:115], v[18:21], off offset:576
	s_nop 1
	v_pk_mul_f32 v[18:19], v[158:159], s[10:11] op_sel_hi:[1,0]
	v_pk_mul_f32 v[20:21], v[156:157], s[10:11] op_sel_hi:[1,0]
	v_pk_fma_f32 v[16:17], v[16:17], v[64:65], v[18:19]
	v_pk_fma_f32 v[14:15], v[14:15], v[62:63], v[20:21]
	global_store_dwordx4 v[110:111], v[14:17], off offset:576
	s_nop 1
	v_pk_mul_f32 v[14:15], v[162:163], s[10:11] op_sel_hi:[1,0]
	v_pk_mul_f32 v[16:17], v[160:161], s[10:11] op_sel_hi:[1,0]
	v_pk_fma_f32 v[12:13], v[12:13], v[64:65], v[14:15]
	v_pk_fma_f32 v[10:11], v[10:11], v[62:63], v[16:17]
	global_store_dwordx4 v[106:107], v[10:13], off offset:576
	s_nop 1
	v_pk_mul_f32 v[10:11], v[166:167], s[10:11] op_sel_hi:[1,0]
	v_pk_mul_f32 v[12:13], v[164:165], s[10:11] op_sel_hi:[1,0]
	v_pk_fma_f32 v[8:9], v[8:9], v[64:65], v[10:11]
	v_pk_fma_f32 v[6:7], v[6:7], v[62:63], v[12:13]
	global_store_dwordx4 v[102:103], v[6:9], off offset:576
	s_nop 1
	v_pk_mul_f32 v[6:7], v[72:73], s[10:11] op_sel_hi:[1,0]
	v_pk_mul_f32 v[8:9], v[70:71], s[10:11] op_sel_hi:[1,0]
	v_pk_fma_f32 v[4:5], v[4:5], v[64:65], v[6:7]
	v_pk_fma_f32 v[2:3], v[2:3], v[62:63], v[8:9]
	global_store_dwordx4 v[82:83], v[2:5], off offset:576
	s_cbranch_vccz .LBB0_766
	s_waitcnt vmcnt(0)
	s_cmpk_gt_u32 s34, 0xff
	s_cbranch_scc1 .LBB0_775
	s_barrier

; #define PG8_STAGE(bufoff, gbase, voff) do { _Pragma("unroll") for (int _i = 0; _i < 2; ++_i) \
;         __builtin_amdgcn_global_load_lds((const unsigned*)((const char*)(gbase) + (voff)[_i]), (LAS unsigned*)(lds + (bufoff) + ldsw + _i * 8192), 16, 0, 0); } while (0)
; #define PG8_WAIT_V(n) asm volatile("s_waitcnt vmcnt(" #n ")" ::: "memory")
; #define PG8_BAR __builtin_amdgcn_s_barrier()
; template <class Epi>
; DI void gemm_phase(LAS unsigned char* lds, const Gemm g, const StaticOrder& S, const Epi& E) {
;     ...
;     const char* cA = PG8_ABASE(cur); const char* cB = PG8_BBASE(cur);
;     PG8_STAGE(PG8_SB(0, 0), cB, voffB); PG8_STAGE(PG8_SA(0, 0), cA, voffA); PG8_STAGE(PG8_SB(0, 1), cB + hstepB, voffB); PG8_STAGE(PG8_SA(0, 1), cA + hstepA, voffA);
;     if (wr == 1) PG8_BAR;
;     PG8_WAIT_V(4); PG8_BAR;
;     PG8_STAGE(PG8_SB(1, 0), cB + kstep, voffB); PG8_STAGE(PG8_SA(1, 0), cA + kstep, voffA); PG8_STAGE(PG8_SB(1, 1), cB + hstepB + kstep, voffB);
;     PG8_WAIT_V(6); PG8_BAR;
.LBB0_852:
	s_add_u32 s52, s10, 0x200000
	s_addc_u32 s53, s11, 0
	s_add_u32 s54, s10, 0x4000
	s_addc_u32 s55, s11, 0
	s_lshl_b32 s4, s18, 5
	s_mov_b64 s[10:11], 0x80
	s_and_b32 s22, s4, 0x60
	s_add_i32 m0, s39, 0x18000
	v_lshl_add_u64 v[8:9], v[8:9], 0, s[10:11]
	s_lshl_b32 s20, s7, 13
	s_lshl_b32 s23, s22, 7
	s_waitcnt vmcnt(0)
	s_barrier
	global_load_lds_dwordx4 v[8:9], off
	v_lshl_add_u64 v[6:7], v[6:7], 0, s[10:11]
	s_add_i32 m0, s39, 0x1a000
	s_add_i32 s56, s39, 0x8000
	s_add_i32 s57, s39, 0xa000
	global_load_lds_dwordx4 v[6:7], off
	v_lshl_add_u64 v[4:5], v[4:5], 0, s[10:11]
	s_mov_b32 m0, s56
	s_add_u32 s4, s28, 0x80080
	global_load_lds_dwordx4 v[4:5], off
	v_lshl_add_u64 v[2:3], v[2:3], 0, s[10:11]
	s_mov_b32 m0, s57
	s_addc_u32 s5, s29, 0
	global_load_lds_dwordx4 v[2:3], off
	s_add_i32 m0, s39, 0x1c000
	v_lshl_add_u64 v[2:3], s[4:5], 0, v[180:181]
	global_load_lds_dwordx4 v[2:3], off
	v_lshl_add_u64 v[2:3], s[4:5], 0, v[184:185]
	s_add_i32 m0, s39, 0x1e000
	v_bfe_u32 v6, v254, 4, 2
	global_load_lds_dwordx4 v[2:3], off
	v_and_b32_e32 v1, 15, v254
	v_lshlrev_b32_e32 v3, 4, v6
	v_lshlrev_b32_e32 v4, 2, v254
	v_lshl_or_b32 v2, s7, 6, v1
	v_lshl_or_b32 v1, v1, 6, v3
	v_and_b32_e32 v4, 32, v4
	v_bitop3_b32 v7, v1, s20, v4 bitop3:0xde
	v_lshlrev_b32_e32 v1, 6, v254
	s_movk_i32 s4, 0x3c0
	v_and_or_b32 v1, v1, s4, v3
	v_bitop3_b32 v1, s23, v1, v4 bitop3:0xf6
	v_or_b32_e32 v4, 16, v2
	v_mov_b32_e32 v5, v181
	v_lshlrev_b64 v[188:189], 13, v[4:5]
	v_or_b32_e32 v4, 32, v2
	v_lshlrev_b64 v[190:191], 13, v[4:5]
	v_or_b32_e32 v4, 48, v2
	v_lshlrev_b64 v[192:193], 13, v[4:5]
	v_add_u32_e32 v4, 0x80, v2
	s_waitcnt vmcnt(6)
	v_mov_b32_e32 v3, v181
	v_lshlrev_b64 v[194:195], 13, v[4:5]
	v_add_u32_e32 v4, 0x90, v2
	v_lshlrev_b64 v[186:187], 13, v[2:3]
	v_lshlrev_b64 v[196:197], 13, v[4:5]
	v_add_u32_e32 v4, 0xa0, v2
	v_add_u32_e32 v2, 0xb0, v2
	s_add_i32 s59, 0, 0x10000
	s_add_i32 s60, 0, 0x14000
	s_sext_i32_i8 s18, s6
	v_lshlrev_b64 v[198:199], 13, v[4:5]
	v_lshlrev_b64 v[200:201], 13, v[2:3]
	s_waitcnt lgkmcnt(0)
	s_ashr_i32 s58, s51, 31
	v_lshl_or_b32 v217, v6, 2, s22
	v_add3_u32 v202, v12, v10, v11
	v_mov_b32_e32 v203, v181
	v_add3_u32 v204, v13, v10, v11
	v_mov_b32_e32 v205, v181
	v_add_u32_e32 v228, s59, v1
	v_add_u32_e32 v229, 0, v7
	v_add_u32_e32 v230, s60, v1
	s_movk_i32 s61, 0x1800
	s_mov_b32 s20, 0x3fd744fd
	s_mov_b32 s62, 0
	s_barrier

; #define PG8_STAGE(bufoff, gbase, voff) do { _Pragma("unroll") for (int _i = 0; _i < 2; ++_i) \
;         __builtin_amdgcn_global_load_lds((const unsigned*)((const char*)(gbase) + (voff)[_i]), (LAS unsigned*)(lds + (bufoff) + ldsw + _i * 8192), 16, 0, 0); } while (0)
; #define PG8_LDA(dst, b, h) do { _Pragma("unroll") for (int m = 0; m < 4; ++m) _Pragma("unroll") for (int k = 0; k < 2; ++k) dst[m][k] = *(const LAS bf16x8*)(lds + PG8_SA(b, h) + aoff + m * 2048 + k * 1024); } while (0)
; #define PG8_LDB(dst, b, h) do { _Pragma("unroll") for (int n = 0; n < 2; ++n) _Pragma("unroll") for (int k = 0; k < 2; ++k) dst[n][k] = *(const LAS bf16x8*)(lds + PG8_SB(b, h) + boff + n * 2048 + k * 1024); } while (0)
; #define PG8_MMA(ai, bj, At, Bt) do { __builtin_amdgcn_s_setprio(1); _Pragma("unroll") for (int m = 0; m < 4; ++m) _Pragma("unroll") for (int n = 0; n < 2; ++n) _Pragma("unroll") for (int k = 0; k < 2; ++k) \
;         acc[ai][bj][m][n] = __builtin_amdgcn_mfma_f32_16x16x32_bf16(Bt[n][k], At[m][k], acc[ai][bj][m][n], 0, 0, 0); __builtin_amdgcn_s_setprio(0); } while (0)
; #define PG8_WAIT_L(n) asm volatile("s_waitcnt lgkmcnt(" #n ")" ::: "memory")
; #define PG8_BAR __builtin_amdgcn_s_barrier()
; #define PG8_SCHED __builtin_amdgcn_sched_barrier(0)
; template <class Epi>
; DI void gemm_phase(LAS unsigned char* lds, const Gemm g, const StaticOrder& S, const Epi& E) {
;     ...
;             PG8_LDB(B0, 0, 0); PG8_SCHED; PG8_LDA(At, 0, 0); PG8_STAGE(PG8_SA(1, 1), a1 + hstepA, voffA);
;             PG8_WAIT_L(8); PG8_BAR; PG8_WAIT_L(0); PG8_MMA(0, 0, At, B0); PG8_BAR; PG8_SCHED;
;             PG8_LDB(B1, 0, 1); PG8_STAGE(PG8_SB(0, 0), b2, voffB);
;             PG8_BAR; PG8_WAIT_L(0); PG8_MMA(0, 1, At, B1); PG8_BAR;
;             PG8_LDA(At, 0, 1); PG8_STAGE(PG8_SA(0, 0), a2, voffA);
;             PG8_BAR; PG8_WAIT_L(0); PG8_MMA(1, 0, At, B0); PG8_BAR; PG8_SCHED;
;             PG8_STAGE(PG8_SB(0, 1), b2 + hstepB, voffB);
.LBB0_858:
	ds_read_b128 v[130:133], v228
	ds_read_b128 v[134:137], v228 offset:1024
	ds_read_b128 v[138:141], v228 offset:2048
	ds_read_b128 v[142:145], v228 offset:3072
	s_add_u32 s28, s6, 0xffdf0080
	s_addc_u32 s29, s7, -1
	s_cmp_eq_u32 s68, 28
	s_cselect_b32 s31, s25, s29
	s_cselect_b32 s30, s24, s28
	s_cselect_b32 s29, s23, s67
	s_cselect_b32 s28, s65, s66
	v_lshl_add_u64 v[206:207], s[6:7], 0, v[202:203]
	s_add_i32 m0, s39, 0xc000
	ds_read_b128 v[146:149], v229
	ds_read_b128 v[150:153], v229 offset:1024
	ds_read_b128 v[154:157], v229 offset:2048
	ds_read_b128 v[158:161], v229 offset:3072
	ds_read_b128 v[162:165], v229 offset:4096
	ds_read_b128 v[166:169], v229 offset:5120
	ds_read_b128 v[170:173], v229 offset:6144
	ds_read_b128 v[174:177], v229 offset:7168
	global_load_lds_dwordx4 v[206:207], off
	v_lshl_add_u64 v[206:207], s[6:7], 0, v[204:205]
	s_add_i32 m0, s39, 0xe000
	s_nop 0
	global_load_lds_dwordx4 v[206:207], off
	ds_read_b128 v[206:209], v230
	ds_read_b128 v[210:213], v230 offset:1024
	ds_read_b128 v[218:221], v230 offset:2048
	ds_read_b128 v[222:225], v230 offset:3072
	s_waitcnt lgkmcnt(0)
	s_waitcnt vmcnt(8)
	s_barrier
	s_setprio 1
	v_mfma_f32_16x16x32_bf16 v[126:129], v[130:133], v[146:149], v[126:129]
	v_mfma_f32_16x16x32_bf16 v[102:105], v[138:141], v[146:149], v[102:105]
	v_mfma_f32_16x16x32_bf16 v[122:125], v[130:133], v[154:157], v[122:125]
	v_mfma_f32_16x16x32_bf16 v[98:101], v[138:141], v[154:157], v[98:101]
	v_mfma_f32_16x16x32_bf16 v[118:121], v[130:133], v[162:165], v[118:121]
	v_mfma_f32_16x16x32_bf16 v[90:93], v[138:141], v[162:165], v[90:93]
	v_mfma_f32_16x16x32_bf16 v[114:117], v[130:133], v[170:173], v[114:117]
	v_mfma_f32_16x16x32_bf16 v[86:89], v[138:141], v[170:173], v[86:89]
	v_mfma_f32_16x16x32_bf16 v[126:129], v[134:137], v[150:153], v[126:129]
	v_mfma_f32_16x16x32_bf16 v[102:105], v[142:145], v[150:153], v[102:105]
	v_mfma_f32_16x16x32_bf16 v[122:125], v[134:137], v[158:161], v[122:125]
	v_mfma_f32_16x16x32_bf16 v[98:101], v[142:145], v[158:161], v[98:101]
	v_mfma_f32_16x16x32_bf16 v[118:121], v[134:137], v[166:169], v[118:121]
	v_mfma_f32_16x16x32_bf16 v[90:93], v[142:145], v[166:169], v[90:93]
	v_mfma_f32_16x16x32_bf16 v[114:117], v[134:137], v[174:177], v[114:117]
	v_mfma_f32_16x16x32_bf16 v[86:89], v[142:145], v[174:177], v[86:89]
	v_mfma_f32_16x16x32_bf16 v[66:69], v[206:209], v[146:149], v[66:69]
	v_mfma_f32_16x16x32_bf16 v[46:49], v[218:221], v[146:149], v[46:49]
	v_mfma_f32_16x16x32_bf16 v[58:61], v[206:209], v[154:157], v[58:61]
	v_mfma_f32_16x16x32_bf16 v[38:41], v[218:221], v[154:157], v[38:41]
	v_mfma_f32_16x16x32_bf16 v[54:57], v[206:209], v[162:165], v[54:57]
	v_mfma_f32_16x16x32_bf16 v[30:33], v[218:221], v[162:165], v[30:33]
	v_mfma_f32_16x16x32_bf16 v[50:53], v[206:209], v[170:173], v[50:53]
	v_mfma_f32_16x16x32_bf16 v[22:25], v[218:221], v[170:173], v[22:25]
	v_mfma_f32_16x16x32_bf16 v[66:69], v[210:213], v[150:153], v[66:69]
	v_mfma_f32_16x16x32_bf16 v[46:49], v[222:225], v[150:153], v[46:49]
	v_mfma_f32_16x16x32_bf16 v[58:61], v[210:213], v[158:161], v[58:61]
	v_mfma_f32_16x16x32_bf16 v[38:41], v[222:225], v[158:161], v[38:41]
	v_mfma_f32_16x16x32_bf16 v[54:57], v[210:213], v[166:169], v[54:57]
	v_mfma_f32_16x16x32_bf16 v[30:33], v[222:225], v[166:169], v[30:33]
	v_mfma_f32_16x16x32_bf16 v[50:53], v[210:213], v[174:177], v[50:53]
	v_mfma_f32_16x16x32_bf16 v[22:25], v[222:225], v[174:177], v[22:25]
	s_setprio 0
	s_barrier
	s_add_i32 s69, s59, s38
	v_lshl_add_u64 v[214:215], s[28:29], 0, v[180:181]
	s_mov_b32 m0, s69
	s_nop 0
	global_load_lds_dwordx4 v[214:215], off
	v_lshl_add_u64 v[226:227], s[28:29], 0, v[184:185]
	s_add_i32 m0, s69, 0x2000
	s_nop 0
	global_load_lds_dwordx4 v[226:227], off
	s_mov_b32 m0, s39
	v_lshl_add_u64 v[232:233], s[30:31], 0, v[178:179]
	ds_read_b128 v[146:149], v229 offset:16384
	ds_read_b128 v[150:153], v229 offset:17408
	ds_read_b128 v[154:157], v229 offset:18432
	ds_read_b128 v[158:161], v229 offset:19456
	ds_read_b128 v[162:165], v229 offset:20480
	ds_read_b128 v[166:169], v229 offset:21504
	ds_read_b128 v[170:173], v229 offset:22528
	ds_read_b128 v[174:177], v229 offset:23552
	global_load_lds_dwordx4 v[232:233], off
	v_lshl_add_u64 v[234:235], s[30:31], 0, v[182:183]
	s_mov_b32 m0, s48
	s_nop 0
	global_load_lds_dwordx4 v[234:235], off
	s_add_u32 s70, s28, 0x80000
	s_addc_u32 s71, s29, 0
	s_add_i32 s69, s60, s38
	v_lshl_add_u64 v[252:253], s[70:71], 0, v[180:181]
	s_mov_b32 m0, s69
	s_nop 0
	global_load_lds_dwordx4 v[252:253], off
	v_lshl_add_u64 v[252:253], s[70:71], 0, v[184:185]
	s_add_i32 m0, s69, 0x2000
	s_nop 0
	global_load_lds_dwordx4 v[252:253], off
	s_waitcnt lgkmcnt(0)
	s_waitcnt vmcnt(8)
	s_barrier
; #define PG8_STAGE(bufoff, gbase, voff) do { _Pragma("unroll") for (int _i = 0; _i < 2; ++_i) \
;         __builtin_amdgcn_global_load_lds((const unsigned*)((const char*)(gbase) + (voff)[_i]), (LAS unsigned*)(lds + (bufoff) + ldsw + _i * 8192), 16, 0, 0); } while (0)
; #define PG8_LDA(dst, b, h) do { _Pragma("unroll") for (int m = 0; m < 4; ++m) _Pragma("unroll") for (int k = 0; k < 2; ++k) dst[m][k] = *(const LAS bf16x8*)(lds + PG8_SA(b, h) + aoff + m * 2048 + k * 1024); } while (0)
; #define PG8_LDB(dst, b, h) do { _Pragma("unroll") for (int n = 0; n < 2; ++n) _Pragma("unroll") for (int k = 0; k < 2; ++k) dst[n][k] = *(const LAS bf16x8*)(lds + PG8_SB(b, h) + boff + n * 2048 + k * 1024); } while (0)
; #define PG8_MMA(ai, bj, At, Bt) do { __builtin_amdgcn_s_setprio(1); _Pragma("unroll") for (int m = 0; m < 4; ++m) _Pragma("unroll") for (int n = 0; n < 2; ++n) _Pragma("unroll") for (int k = 0; k < 2; ++k) \
;         acc[ai][bj][m][n] = __builtin_amdgcn_mfma_f32_16x16x32_bf16(Bt[n][k], At[m][k], acc[ai][bj][m][n], 0, 0, 0); __builtin_amdgcn_s_setprio(0); } while (0)
; #define PG8_WAIT_V(n) asm volatile("s_waitcnt vmcnt(" #n ")" ::: "memory")
; #define PG8_WAIT_L(n) asm volatile("s_waitcnt lgkmcnt(" #n ")" ::: "memory")
; #define PG8_BAR __builtin_amdgcn_s_barrier()
; #define PG8_SCHED __builtin_amdgcn_sched_barrier(0)
; template <class Epi>
; DI void gemm_phase(LAS unsigned char* lds, const Gemm g, const StaticOrder& S, const Epi& E) {
;     ...
;             PG8_BAR; PG8_WAIT_L(0); PG8_MMA(1, 0, At, B0); PG8_BAR; PG8_SCHED;
;             PG8_STAGE(PG8_SB(0, 1), b2 + hstepB, voffB);
;             PG8_WAIT_V(6); PG8_BAR; PG8_MMA(1, 1, At, B1); PG8_BAR;
;             PG8_LDB(B0, 1, 0); PG8_SCHED; PG8_LDA(At, 1, 0); PG8_STAGE(PG8_SA(0, 1), a2 + hstepA, voffA);
;             PG8_WAIT_L(8); PG8_BAR; PG8_WAIT_L(0); PG8_MMA(0, 0, At, B0); PG8_BAR; PG8_SCHED;
;             PG8_LDB(B1, 1, 1); PG8_STAGE(PG8_SB(1, 0), b3, voffB);
;             PG8_BAR; PG8_WAIT_L(0); PG8_MMA(0, 1, At, B1); PG8_BAR;
	s_setprio 1
	v_mfma_f32_16x16x32_bf16 v[110:113], v[130:133], v[146:149], v[110:113]
	v_mfma_f32_16x16x32_bf16 v[78:81], v[138:141], v[146:149], v[78:81]
	v_mfma_f32_16x16x32_bf16 v[106:109], v[130:133], v[154:157], v[106:109]
	v_mfma_f32_16x16x32_bf16 v[74:77], v[138:141], v[154:157], v[74:77]
	v_mfma_f32_16x16x32_bf16 v[94:97], v[130:133], v[162:165], v[94:97]
	v_mfma_f32_16x16x32_bf16 v[70:73], v[138:141], v[162:165], v[70:73]
	v_mfma_f32_16x16x32_bf16 v[82:85], v[130:133], v[170:173], v[82:85]
	v_mfma_f32_16x16x32_bf16 v[62:65], v[138:141], v[170:173], v[62:65]
	v_mfma_f32_16x16x32_bf16 v[110:113], v[134:137], v[150:153], v[110:113]
	v_mfma_f32_16x16x32_bf16 v[78:81], v[142:145], v[150:153], v[78:81]
	v_mfma_f32_16x16x32_bf16 v[106:109], v[134:137], v[158:161], v[106:109]
	v_mfma_f32_16x16x32_bf16 v[74:77], v[142:145], v[158:161], v[74:77]
	v_mfma_f32_16x16x32_bf16 v[94:97], v[134:137], v[166:169], v[94:97]
	v_mfma_f32_16x16x32_bf16 v[70:73], v[142:145], v[166:169], v[70:73]
	v_mfma_f32_16x16x32_bf16 v[82:85], v[134:137], v[174:177], v[82:85]
	v_mfma_f32_16x16x32_bf16 v[62:65], v[142:145], v[174:177], v[62:65]
	v_mfma_f32_16x16x32_bf16 v[42:45], v[206:209], v[146:149], v[42:45]
	v_mfma_f32_16x16x32_bf16 v[14:17], v[218:221], v[146:149], v[14:17]
	v_mfma_f32_16x16x32_bf16 v[34:37], v[206:209], v[154:157], v[34:37]
	v_mfma_f32_16x16x32_bf16 v[10:13], v[218:221], v[154:157], v[10:13]
	v_mfma_f32_16x16x32_bf16 v[26:29], v[206:209], v[162:165], v[26:29]
	v_mfma_f32_16x16x32_bf16 v[6:9], v[218:221], v[162:165], v[6:9]
	v_mfma_f32_16x16x32_bf16 v[18:21], v[206:209], v[170:173], v[18:21]
	v_mfma_f32_16x16x32_bf16 v[2:5], v[218:221], v[170:173], v[2:5]
	v_mfma_f32_16x16x32_bf16 v[42:45], v[210:213], v[150:153], v[42:45]
	v_mfma_f32_16x16x32_bf16 v[14:17], v[222:225], v[150:153], v[14:17]
	v_mfma_f32_16x16x32_bf16 v[34:37], v[210:213], v[158:161], v[34:37]
	v_mfma_f32_16x16x32_bf16 v[10:13], v[222:225], v[158:161], v[10:13]
	v_mfma_f32_16x16x32_bf16 v[26:29], v[210:213], v[166:169], v[26:29]
	v_mfma_f32_16x16x32_bf16 v[6:9], v[222:225], v[166:169], v[6:9]
	v_mfma_f32_16x16x32_bf16 v[18:21], v[210:213], v[174:177], v[18:21]
	v_mfma_f32_16x16x32_bf16 v[2:5], v[222:225], v[174:177], v[2:5]
	s_setprio 0
	s_add_i32 s69, 0, 0x18000
	v_add_u32_e32 v142, s69, v1
	s_barrier
	ds_read_b128 v[130:133], v142
	ds_read_b128 v[134:137], v142 offset:1024
	ds_read_b128 v[138:141], v142 offset:2048
	ds_read_b128 v[142:145], v142 offset:3072
	s_add_u32 s30, s30, 0x210000
	s_addc_u32 s31, s31, 0
	s_mov_b32 m0, s49
	v_lshl_add_u64 v[206:207], s[30:31], 0, v[178:179]
	ds_read_b128 v[146:149], v229 offset:32768
	ds_read_b128 v[150:153], v229 offset:33792
	ds_read_b128 v[154:157], v229 offset:34816
	ds_read_b128 v[158:161], v229 offset:35840
	ds_read_b128 v[162:165], v229 offset:36864
	ds_read_b128 v[166:169], v229 offset:37888
	ds_read_b128 v[170:173], v229 offset:38912
	ds_read_b128 v[174:177], v229 offset:39936
	global_load_lds_dwordx4 v[206:207], off
	v_lshl_add_u64 v[206:207], s[30:31], 0, v[182:183]
	s_mov_b32 m0, s50
	s_nop 0
	global_load_lds_dwordx4 v[206:207], off
	s_add_i32 s30, 0, 0x1c000
	v_add_u32_e32 v216, s30, v1
	ds_read_b128 v[206:209], v216
	ds_read_b128 v[210:213], v216 offset:1024
	ds_read_b128 v[218:221], v216 offset:2048
	ds_read_b128 v[222:225], v216 offset:3072
	s_waitcnt lgkmcnt(0)
	s_waitcnt vmcnt(8)
	s_barrier
	s_setprio 1
	v_mfma_f32_16x16x32_bf16 v[126:129], v[130:133], v[146:149], v[126:129]
	v_mfma_f32_16x16x32_bf16 v[102:105], v[138:141], v[146:149], v[102:105]
	v_mfma_f32_16x16x32_bf16 v[122:125], v[130:133], v[154:157], v[122:125]
	v_mfma_f32_16x16x32_bf16 v[98:101], v[138:141], v[154:157], v[98:101]
	v_mfma_f32_16x16x32_bf16 v[118:121], v[130:133], v[162:165], v[118:121]
	v_mfma_f32_16x16x32_bf16 v[90:93], v[138:141], v[162:165], v[90:93]
	v_mfma_f32_16x16x32_bf16 v[114:117], v[130:133], v[170:173], v[114:117]
	v_mfma_f32_16x16x32_bf16 v[86:89], v[138:141], v[170:173], v[86:89]
	v_mfma_f32_16x16x32_bf16 v[126:129], v[134:137], v[150:153], v[126:129]
	v_mfma_f32_16x16x32_bf16 v[102:105], v[142:145], v[150:153], v[102:105]
	v_mfma_f32_16x16x32_bf16 v[122:125], v[134:137], v[158:161], v[122:125]
	v_mfma_f32_16x16x32_bf16 v[98:101], v[142:145], v[158:161], v[98:101]
	v_mfma_f32_16x16x32_bf16 v[118:121], v[134:137], v[166:169], v[118:121]
	v_mfma_f32_16x16x32_bf16 v[90:93], v[142:145], v[166:169], v[90:93]
	v_mfma_f32_16x16x32_bf16 v[114:117], v[134:137], v[174:177], v[114:117]
	v_mfma_f32_16x16x32_bf16 v[86:89], v[142:145], v[174:177], v[86:89]
	v_mfma_f32_16x16x32_bf16 v[66:69], v[206:209], v[146:149], v[66:69]
	v_mfma_f32_16x16x32_bf16 v[46:49], v[218:221], v[146:149], v[46:49]
	v_mfma_f32_16x16x32_bf16 v[58:61], v[206:209], v[154:157], v[58:61]
	v_mfma_f32_16x16x32_bf16 v[38:41], v[218:221], v[154:157], v[38:41]
	v_mfma_f32_16x16x32_bf16 v[54:57], v[206:209], v[162:165], v[54:57]
	v_mfma_f32_16x16x32_bf16 v[30:33], v[218:221], v[162:165], v[30:33]
	v_mfma_f32_16x16x32_bf16 v[50:53], v[206:209], v[170:173], v[50:53]
	v_mfma_f32_16x16x32_bf16 v[22:25], v[218:221], v[170:173], v[22:25]
	v_mfma_f32_16x16x32_bf16 v[66:69], v[210:213], v[150:153], v[66:69]
	v_mfma_f32_16x16x32_bf16 v[46:49], v[222:225], v[150:153], v[46:49]
	v_mfma_f32_16x16x32_bf16 v[58:61], v[210:213], v[158:161], v[58:61]
	v_mfma_f32_16x16x32_bf16 v[38:41], v[222:225], v[158:161], v[38:41]
	v_mfma_f32_16x16x32_bf16 v[54:57], v[210:213], v[166:169], v[54:57]
	v_mfma_f32_16x16x32_bf16 v[30:33], v[222:225], v[166:169], v[30:33]
	v_mfma_f32_16x16x32_bf16 v[50:53], v[210:213], v[174:177], v[50:53]
	v_mfma_f32_16x16x32_bf16 v[22:25], v[222:225], v[174:177], v[22:25]
	s_setprio 0
	s_barrier
; #define PG8_STAGE(bufoff, gbase, voff) do { _Pragma("unroll") for (int _i = 0; _i < 2; ++_i) \
;         __builtin_amdgcn_global_load_lds((const unsigned*)((const char*)(gbase) + (voff)[_i]), (LAS unsigned*)(lds + (bufoff) + ldsw + _i * 8192), 16, 0, 0); } while (0)
; #define PG8_LDA(dst, b, h) do { _Pragma("unroll") for (int m = 0; m < 4; ++m) _Pragma("unroll") for (int k = 0; k < 2; ++k) dst[m][k] = *(const LAS bf16x8*)(lds + PG8_SA(b, h) + aoff + m * 2048 + k * 1024); } while (0)
; #define PG8_WAIT_V(n) asm volatile("s_waitcnt vmcnt(" #n ")" ::: "memory")
; #define PG8_WAIT_L(n) asm volatile("s_waitcnt lgkmcnt(" #n ")" ::: "memory")
; template <class Epi>
; DI void gemm_phase(LAS unsigned char* lds, const Gemm g, const StaticOrder& S, const Epi& E) {
;     ...
;             PG8_LDB(B1, 1, 1); PG8_STAGE(PG8_SB(1, 0), b3, voffB);
;             PG8_BAR; PG8_WAIT_L(0); PG8_MMA(0, 1, At, B1); PG8_BAR;
;             PG8_LDA(At, 1, 1); PG8_STAGE(PG8_SA(1, 0), a3, voffA);
;             PG8_BAR; PG8_WAIT_L(0); PG8_MMA(1, 0, At, B0); PG8_BAR; PG8_SCHED;
;             PG8_STAGE(PG8_SB(1, 1), b3 + hstepB, voffB);
;             PG8_WAIT_V(6); PG8_BAR; PG8_MMA(1, 1, At, B1); PG8_BAR;
;         }
;     DI void operator()(const f32x4 (&acc)[2][2][4][2], const pg8::Unit& u, int wr, int wc, int fr, int fq) const {
;         const int rowt = row_base + u.pm * 256, col0 = u.pn * 256 + wc * 32 + 4 * fq, rl = wr * 64 + fr;
;         const int cd = cond_of_row(rowt);
;         const float* gtp = gt0 + (size_t)cd * 6144;
;         float* dbase = rowt < TL ? out + (size_t)rowt * D : ctxv + (size_t)(rowt - TL) * D;
;         const float* sbase = mode ? (const float*)dbase : (rowt < TL ? xin + (size_t)rowt * D : cin + (size_t)(rowt - TL) * D);
; #pragma unroll
;         for (int bj = 0; bj < 2; ++bj) {
;             f32x4 gv[2], gg[2], bb[2], xv[2][8];
; #pragma unroll
;             for (int n = 0; n < 2; ++n) {
;                 const int c = col0 + bj * 128 + n * 16;
;                 gv[n] = *(const f32x4*)(gtp + c);
;                 gg[n] = (f32x4){1.f, 1.f, 1.f, 1.f}; bb[n] = (f32x4){0.f, 0.f, 0.f, 0.f};
;                 if (mode) { gg[n] = *(const f32x4*)(lg + c); bb[n] = *(const f32x4*)(lb + c); }
; #pragma unroll
;                 for (int q = 0; q < 8; ++q) { const int rr = rl + (q >> 2) * 128 + (q & 3) * 16; xv[n][q] = *(const f32x4*)(sbase + (size_t)rr * D + c); }
	s_add_i32 s31, s69, s38
	v_lshl_add_u64 v[214:215], v[214:215], 0, s[10:11]
	s_mov_b32 m0, s31
	s_nop 0
	global_load_lds_dwordx4 v[214:215], off
	v_lshl_add_u64 v[214:215], v[226:227], 0, s[10:11]
	s_add_i32 m0, s31, 0x2000
	s_nop 0
	global_load_lds_dwordx4 v[214:215], off
	s_mov_b32 m0, s56
	v_lshl_add_u64 v[214:215], v[232:233], 0, s[10:11]
	ds_read_b128 v[146:149], v229 offset:49152
	ds_read_b128 v[150:153], v229 offset:50176
	ds_read_b128 v[154:157], v229 offset:51200
	ds_read_b128 v[158:161], v229 offset:52224
	ds_read_b128 v[162:165], v229 offset:53248
	ds_read_b128 v[166:169], v229 offset:54272
	ds_read_b128 v[170:173], v229 offset:55296
	ds_read_b128 v[174:177], v229 offset:56320
	global_load_lds_dwordx4 v[214:215], off
	v_lshl_add_u64 v[214:215], v[234:235], 0, s[10:11]
	s_mov_b32 m0, s57
	s_nop 0
	global_load_lds_dwordx4 v[214:215], off
	s_add_u32 s28, s28, 0x80080
	s_addc_u32 s29, s29, 0
	s_add_i32 s30, s30, s38
	v_lshl_add_u64 v[252:253], s[28:29], 0, v[180:181]
	s_mov_b32 m0, s30
	s_nop 0
	global_load_lds_dwordx4 v[252:253], off
	v_lshl_add_u64 v[252:253], s[28:29], 0, v[184:185]
	s_add_i32 m0, s30, 0x2000
	s_nop 0
	global_load_lds_dwordx4 v[252:253], off
	s_waitcnt lgkmcnt(0)
	s_waitcnt vmcnt(8)
	s_barrier
	s_setprio 1
	v_mfma_f32_16x16x32_bf16 v[110:113], v[130:133], v[146:149], v[110:113]
	v_mfma_f32_16x16x32_bf16 v[78:81], v[138:141], v[146:149], v[78:81]
	v_mfma_f32_16x16x32_bf16 v[106:109], v[130:133], v[154:157], v[106:109]
	v_mfma_f32_16x16x32_bf16 v[74:77], v[138:141], v[154:157], v[74:77]
	v_mfma_f32_16x16x32_bf16 v[94:97], v[130:133], v[162:165], v[94:97]
	v_mfma_f32_16x16x32_bf16 v[70:73], v[138:141], v[162:165], v[70:73]
	v_mfma_f32_16x16x32_bf16 v[82:85], v[130:133], v[170:173], v[82:85]
	v_mfma_f32_16x16x32_bf16 v[62:65], v[138:141], v[170:173], v[62:65]
	v_mfma_f32_16x16x32_bf16 v[110:113], v[134:137], v[150:153], v[110:113]
	v_mfma_f32_16x16x32_bf16 v[78:81], v[142:145], v[150:153], v[78:81]
	v_mfma_f32_16x16x32_bf16 v[106:109], v[134:137], v[158:161], v[106:109]
	v_mfma_f32_16x16x32_bf16 v[74:77], v[142:145], v[158:161], v[74:77]
	v_mfma_f32_16x16x32_bf16 v[94:97], v[134:137], v[166:169], v[94:97]
	v_mfma_f32_16x16x32_bf16 v[70:73], v[142:145], v[166:169], v[70:73]
	v_mfma_f32_16x16x32_bf16 v[82:85], v[134:137], v[174:177], v[82:85]
	v_mfma_f32_16x16x32_bf16 v[62:65], v[142:145], v[174:177], v[62:65]
	v_mfma_f32_16x16x32_bf16 v[42:45], v[206:209], v[146:149], v[42:45]
	v_mfma_f32_16x16x32_bf16 v[14:17], v[218:221], v[146:149], v[14:17]
	v_mfma_f32_16x16x32_bf16 v[34:37], v[206:209], v[154:157], v[34:37]
	v_mfma_f32_16x16x32_bf16 v[10:13], v[218:221], v[154:157], v[10:13]
	v_mfma_f32_16x16x32_bf16 v[26:29], v[206:209], v[162:165], v[26:29]
	v_mfma_f32_16x16x32_bf16 v[6:9], v[218:221], v[162:165], v[6:9]
	v_mfma_f32_16x16x32_bf16 v[18:21], v[206:209], v[170:173], v[18:21]
	v_mfma_f32_16x16x32_bf16 v[2:5], v[218:221], v[170:173], v[2:5]
	v_mfma_f32_16x16x32_bf16 v[42:45], v[210:213], v[150:153], v[42:45]
	v_mfma_f32_16x16x32_bf16 v[14:17], v[222:225], v[150:153], v[14:17]
	v_mfma_f32_16x16x32_bf16 v[34:37], v[210:213], v[158:161], v[34:37]
	v_mfma_f32_16x16x32_bf16 v[10:13], v[222:225], v[158:161], v[10:13]
	v_mfma_f32_16x16x32_bf16 v[26:29], v[210:213], v[166:169], v[26:29]
	v_mfma_f32_16x16x32_bf16 v[6:9], v[222:225], v[166:169], v[6:9]
	v_mfma_f32_16x16x32_bf16 v[18:21], v[210:213], v[174:177], v[18:21]
	v_mfma_f32_16x16x32_bf16 v[2:5], v[222:225], v[174:177], v[2:5]
	s_setprio 0
	s_add_i32 s68, s68, 2
	s_add_u32 s6, s6, 0x100
	s_addc_u32 s7, s7, 0
	s_add_u32 s66, s66, 0x100
	s_addc_u32 s67, s67, 0
	s_cmp_gt_u32 s68, 29
	s_barrier
	s_cbranch_scc0 .LBB0_858
	s_lshl_b32 s6, s64, 8
	v_mov_b32_e32 v131, 0x8000
	v_sub_co_u32_e32 v131, vcc, s6, v131
	s_and_b64 s[28:29], vcc, exec
	s_cselect_b32 s7, s61, 0x3000
	s_cmp_gt_i32 s64, 63
	s_cselect_b32 s7, s7, 0
	s_lshl_b32 s7, s7, 2
	s_add_u32 s28, s54, s7
	s_addc_u32 s29, s55, 0
	s_ashr_i32 s7, s6, 31
	s_lshl_b64 s[30:31], s[6:7], 13
	v_lshl_or_b32 v130, s18, 8, v217
	v_readfirstlane_b32 s18, v131
	s_add_u32 s23, s12, s30
	s_addc_u32 s65, s13, s31
	s_lshl_b64 s[30:31], s[18:19], 13
	s_add_u32 s30, s16, s30
	s_addc_u32 s31, s17, s31
	s_cmpk_lt_i32 s64, 0x80
	v_ashrrev_i32_e32 v131, 31, v130
	s_cselect_b32 s31, s65, s31
	s_cselect_b32 s30, s23, s30
	v_lshlrev_b64 v[226:227], 2, v[130:131]
	v_lshl_add_u64 v[130:131], s[30:31], 0, v[226:227]
	v_lshl_add_u64 v[210:211], v[130:131], 0, v[186:187]
	v_lshl_add_u64 v[206:207], s[28:29], 0, v[226:227]
	global_load_dwordx4 v[232:235], v[210:211], off
	global_load_dwordx4 v[154:157], v[206:207], off
	v_lshl_add_u64 v[208:209], v[130:131], 0, v[188:189]
	global_load_dwordx4 v[236:239], v[208:209], off
	v_lshl_add_u64 v[212:213], v[130:131], 0, v[190:191]
	global_load_dwordx4 v[240:243], v[212:213], off
	v_lshl_add_u64 v[214:215], v[130:131], 0, v[192:193]
	global_load_dwordx4 v[244:247], v[214:215], off
	v_lshl_add_u64 v[218:219], v[130:131], 0, v[194:195]
	global_load_dwordx4 v[248:251], v[218:219], off
	v_lshl_add_u64 v[220:221], v[130:131], 0, v[196:197]
	global_load_dwordx4 v[252:255], v[220:221], off
	v_lshl_add_u64 v[222:223], v[130:131], 0, v[198:199]
	global_load_dwordx4 v[174:177], v[222:223], off
	v_lshl_add_u64 v[224:225], v[130:131], 0, v[200:201]
	global_load_dwordx4 v[170:173], v[224:225], off
	global_load_dwordx4 v[130:133], v[206:207], off offset:64
	global_load_dwordx4 v[166:169], v[210:211], off offset:64
	global_load_dwordx4 v[162:165], v[208:209], off offset:64
	global_load_dwordx4 v[158:161], v[212:213], off offset:64
	global_load_dwordx4 v[150:153], v[214:215], off offset:64
	global_load_dwordx4 v[138:141], v[218:219], off offset:64
	global_load_dwordx4 v[142:145], v[220:221], off offset:64
	global_load_dwordx4 v[146:149], v[222:223], off offset:64
	global_load_dwordx4 v[134:137], v[224:225], off offset:64
	s_cselect_b32 s7, s7, 0
	s_cselect_b32 s6, s6, s18
	s_cselect_b32 s18, s9, s53
	s_cselect_b32 s64, s8, s52
	s_lshl_b64 s[6:7], s[6:7], 13
	s_add_u32 s6, s64, s6
	s_addc_u32 s7, s18, s7
	v_lshl_add_u64 v[226:227], s[6:7], 0, v[226:227]
	s_and_b64 vcc, exec, s[4:5]
	s_mov_b32 s18, s22
	s_mov_b32 s64, s63
	s_mov_b64 s[28:29], s[26:27]
	s_mov_b64 s[30:31], s[24:25]
	s_waitcnt vmcnt(0)
;     DI void operator()(const f32x4 (&acc)[2][2][4][2], const pg8::Unit& u, int wr, int wc, int fr, int fq) const {
;     ...
;                 for (int q = 0; q < 8; ++q) { const int rr = rl + (q >> 2) * 128 + (q & 3) * 16; xv[n][q] = *(const f32x4*)(sbase + (size_t)rr * D + c); }
;             }
; #pragma unroll
;             for (int n = 0; n < 2; ++n) {
;                 const int c = col0 + bj * 128 + n * 16;
; #pragma unroll
;                 for (int q = 0; q < 8; ++q) {
;                     const int rr = rl + (q >> 2) * 128 + (q & 3) * 16;
;                     f32x4 x = xv[n][q];
;                     if (mode) { const float mu = stats[2 * (rowt + rr)], rs = stats[2 * (rowt + rr) + 1]; x = (x - mu) * rs * gg[n] + bb[n]; }
;                     *(f32x4*)(dbase + (size_t)rr * D + c) = ALPHA * x + gv[n] * acc[q >> 2][bj][q & 3][n];
;                 }
;             }
	v_pk_mul_f32 v[234:235], v[234:235], s[20:21] op_sel_hi:[1,0]
	v_pk_mul_f32 v[232:233], v[232:233], s[20:21] op_sel_hi:[1,0]
	v_pk_fma_f32 v[234:235], v[128:129], v[156:157], v[234:235]
	v_pk_fma_f32 v[232:233], v[126:127], v[154:155], v[232:233]
	v_lshl_add_u64 v[126:127], v[226:227], 0, v[186:187]
	global_store_dwordx4 v[126:127], v[232:235], off
	v_pk_mul_f32 v[128:129], v[238:239], s[20:21] op_sel_hi:[1,0]
	s_nop 0
	v_pk_mul_f32 v[232:233], v[236:237], s[20:21] op_sel_hi:[1,0]
	v_pk_fma_f32 v[234:235], v[124:125], v[156:157], v[128:129]
	v_pk_fma_f32 v[232:233], v[122:123], v[154:155], v[232:233]
	v_lshl_add_u64 v[122:123], v[226:227], 0, v[188:189]
	v_pk_mul_f32 v[124:125], v[242:243], s[20:21] op_sel_hi:[1,0]
	v_pk_mul_f32 v[128:129], v[240:241], s[20:21] op_sel_hi:[1,0]
	global_store_dwordx4 v[122:123], v[232:235], off
	s_nop 1
	v_pk_fma_f32 v[234:235], v[120:121], v[156:157], v[124:125]
	v_pk_fma_f32 v[232:233], v[118:119], v[154:155], v[128:129]
	v_lshl_add_u64 v[118:119], v[226:227], 0, v[190:191]
	v_pk_mul_f32 v[120:121], v[246:247], s[20:21] op_sel_hi:[1,0]
	v_pk_mul_f32 v[124:125], v[244:245], s[20:21] op_sel_hi:[1,0]
	global_store_dwordx4 v[118:119], v[232:235], off
	s_nop 1
	v_pk_fma_f32 v[234:235], v[116:117], v[156:157], v[120:121]
	v_pk_fma_f32 v[232:233], v[114:115], v[154:155], v[124:125]
	v_lshl_add_u64 v[114:115], v[226:227], 0, v[192:193]
	v_pk_mul_f32 v[116:117], v[250:251], s[20:21] op_sel_hi:[1,0]
	v_pk_mul_f32 v[120:121], v[248:249], s[20:21] op_sel_hi:[1,0]
	global_store_dwordx4 v[114:115], v[232:235], off
	s_nop 1
	v_pk_fma_f32 v[234:235], v[112:113], v[156:157], v[116:117]
	v_pk_fma_f32 v[232:233], v[110:111], v[154:155], v[120:121]
	v_lshl_add_u64 v[110:111], v[226:227], 0, v[194:195]
	v_pk_mul_f32 v[112:113], v[254:255], s[20:21] op_sel_hi:[1,0]
	global_store_dwordx4 v[110:111], v[232:235], off
	v_pk_mul_f32 v[116:117], v[252:253], s[20:21] op_sel_hi:[1,0]
	v_and_b32_e32 v254, 0x3ff, v0
	v_pk_fma_f32 v[234:235], v[108:109], v[156:157], v[112:113]
	v_pk_mul_f32 v[108:109], v[176:177], s[20:21] op_sel_hi:[1,0]
	v_pk_fma_f32 v[232:233], v[106:107], v[154:155], v[116:117]
	v_pk_fma_f32 v[176:177], v[96:97], v[156:157], v[108:109]
	v_pk_mul_f32 v[96:97], v[172:173], s[20:21] op_sel_hi:[1,0]
	v_lshl_add_u64 v[106:107], v[226:227], 0, v[196:197]
	v_pk_fma_f32 v[156:157], v[84:85], v[156:157], v[96:97]
	v_pk_mul_f32 v[84:85], v[168:169], s[20:21] op_sel_hi:[1,0]
	v_pk_mul_f32 v[96:97], v[166:167], s[20:21] op_sel_hi:[1,0]
	v_pk_fma_f32 v[104:105], v[104:105], v[132:133], v[84:85]
	v_pk_fma_f32 v[102:103], v[102:103], v[130:131], v[96:97]
	v_pk_mul_f32 v[84:85], v[164:165], s[20:21] op_sel_hi:[1,0]
	v_pk_mul_f32 v[96:97], v[162:163], s[20:21] op_sel_hi:[1,0]
	v_pk_fma_f32 v[100:101], v[100:101], v[132:133], v[84:85]
	v_pk_fma_f32 v[98:99], v[98:99], v[130:131], v[96:97]
	v_pk_mul_f32 v[84:85], v[160:161], s[20:21] op_sel_hi:[1,0]
	v_pk_mul_f32 v[96:97], v[158:159], s[20:21] op_sel_hi:[1,0]
	v_pk_fma_f32 v[92:93], v[92:93], v[132:133], v[84:85]
	v_pk_fma_f32 v[90:91], v[90:91], v[130:131], v[96:97]
	global_store_dwordx4 v[118:119], v[90:93], off offset:64
	v_pk_mul_f32 v[84:85], v[152:153], s[20:21] op_sel_hi:[1,0]
	v_pk_mul_f32 v[112:113], v[174:175], s[20:21] op_sel_hi:[1,0]
	v_pk_mul_f32 v[90:91], v[150:151], s[20:21] op_sel_hi:[1,0]
	v_pk_fma_f32 v[88:89], v[88:89], v[132:133], v[84:85]
	v_pk_fma_f32 v[86:87], v[86:87], v[130:131], v[90:91]
	global_store_dwordx4 v[114:115], v[86:89], off offset:64
	v_pk_mul_f32 v[84:85], v[140:141], s[20:21] op_sel_hi:[1,0]
	v_pk_fma_f32 v[174:175], v[94:95], v[154:155], v[112:113]
	v_pk_mul_f32 v[86:87], v[138:139], s[20:21] op_sel_hi:[1,0]
	v_pk_fma_f32 v[80:81], v[80:81], v[132:133], v[84:85]
	v_pk_fma_f32 v[78:79], v[78:79], v[130:131], v[86:87]
	global_store_dwordx4 v[110:111], v[78:81], off offset:64
	v_lshl_add_u64 v[94:95], v[226:227], 0, v[198:199]
	v_pk_mul_f32 v[108:109], v[170:171], s[20:21] op_sel_hi:[1,0]
	v_pk_mul_f32 v[78:79], v[144:145], s[20:21] op_sel_hi:[1,0]
	v_pk_mul_f32 v[80:81], v[142:143], s[20:21] op_sel_hi:[1,0]
	v_pk_fma_f32 v[76:77], v[76:77], v[132:133], v[78:79]
	v_pk_fma_f32 v[74:75], v[74:75], v[130:131], v[80:81]
	global_store_dwordx4 v[106:107], v[74:77], off offset:64
	v_pk_fma_f32 v[154:155], v[82:83], v[154:155], v[108:109]
	v_lshl_add_u64 v[82:83], v[226:227], 0, v[200:201]
	v_pk_mul_f32 v[74:75], v[148:149], s[20:21] op_sel_hi:[1,0]
	v_pk_mul_f32 v[76:77], v[146:147], s[20:21] op_sel_hi:[1,0]
	v_pk_fma_f32 v[72:73], v[72:73], v[132:133], v[74:75]
	v_pk_fma_f32 v[70:71], v[70:71], v[130:131], v[76:77]
	global_store_dwordx4 v[94:95], v[70:73], off offset:64
	global_store_dwordx4 v[106:107], v[232:235], off
	global_store_dwordx4 v[94:95], v[174:177], off
	v_pk_mul_f32 v[70:71], v[136:137], s[20:21] op_sel_hi:[1,0]
	v_pk_mul_f32 v[72:73], v[134:135], s[20:21] op_sel_hi:[1,0]
	v_pk_fma_f32 v[64:65], v[64:65], v[132:133], v[70:71]
	v_pk_fma_f32 v[62:63], v[62:63], v[130:131], v[72:73]
	global_store_dwordx4 v[82:83], v[154:157], off
	global_store_dwordx4 v[126:127], v[102:105], off offset:64
	global_store_dwordx4 v[122:123], v[98:101], off offset:64
	global_store_dwordx4 v[82:83], v[62:65], off offset:64
	global_load_dwordx4 v[78:81], v[206:207], off offset:512
	global_load_dwordx4 v[84:87], v[210:211], off offset:512
	global_load_dwordx4 v[88:91], v[208:209], off offset:512
	s_nop 0
	global_load_dwordx4 v[96:99], v[212:213], off offset:512
	global_load_dwordx4 v[100:103], v[214:215], off offset:512
	global_load_dwordx4 v[128:131], v[218:219], off offset:512
	global_load_dwordx4 v[132:135], v[220:221], off offset:512
	global_load_dwordx4 v[136:139], v[222:223], off offset:512
	global_load_dwordx4 v[140:143], v[224:225], off offset:512
	global_load_dwordx4 v[62:65], v[206:207], off offset:576
	global_load_dwordx4 v[144:147], v[210:211], off offset:576
	global_load_dwordx4 v[148:151], v[208:209], off offset:576
	global_load_dwordx4 v[152:155], v[212:213], off offset:576
	global_load_dwordx4 v[156:159], v[214:215], off offset:576
	global_load_dwordx4 v[160:163], v[218:219], off offset:576
	global_load_dwordx4 v[164:167], v[220:221], off offset:576
	global_load_dwordx4 v[74:77], v[222:223], off offset:576
	global_load_dwordx4 v[70:73], v[224:225], off offset:576
	s_waitcnt vmcnt(0)
;     DI void operator()(const f32x4 (&acc)[2][2][4][2], const pg8::Unit& u, int wr, int wc, int fr, int fq) const {
;     ...
; #pragma unroll
;             for (int n = 0; n < 2; ++n) {
;                 const int c = col0 + bj * 128 + n * 16;
; #pragma unroll
;                 for (int q = 0; q < 8; ++q) {
;                     const int rr = rl + (q >> 2) * 128 + (q & 3) * 16;
;                     f32x4 x = xv[n][q];
;                     if (mode) { const float mu = stats[2 * (rowt + rr)], rs = stats[2 * (rowt + rr) + 1]; x = (x - mu) * rs * gg[n] + bb[n]; }
;                     *(f32x4*)(dbase + (size_t)rr * D + c) = ALPHA * x + gv[n] * acc[q >> 2][bj][q & 3][n];
;                 }
;             }
	v_pk_mul_f32 v[86:87], v[86:87], s[20:21] op_sel_hi:[1,0]
	v_pk_mul_f32 v[84:85], v[84:85], s[20:21] op_sel_hi:[1,0]
	v_pk_fma_f32 v[68:69], v[68:69], v[80:81], v[86:87]
	v_pk_fma_f32 v[66:67], v[66:67], v[78:79], v[84:85]
	global_store_dwordx4 v[126:127], v[66:69], off offset:512
	s_nop 1
	v_pk_mul_f32 v[66:67], v[90:91], s[20:21] op_sel_hi:[1,0]
	v_pk_mul_f32 v[68:69], v[88:89], s[20:21] op_sel_hi:[1,0]
	v_pk_fma_f32 v[60:61], v[60:61], v[80:81], v[66:67]
	v_pk_fma_f32 v[58:59], v[58:59], v[78:79], v[68:69]
	global_store_dwordx4 v[122:123], v[58:61], off offset:512
	s_nop 1
	v_pk_mul_f32 v[58:59], v[98:99], s[20:21] op_sel_hi:[1,0]
	v_pk_mul_f32 v[60:61], v[96:97], s[20:21] op_sel_hi:[1,0]
	v_pk_fma_f32 v[56:57], v[56:57], v[80:81], v[58:59]
	v_pk_fma_f32 v[54:55], v[54:55], v[78:79], v[60:61]
	global_store_dwordx4 v[118:119], v[54:57], off offset:512
	s_nop 1
	v_pk_mul_f32 v[54:55], v[102:103], s[20:21] op_sel_hi:[1,0]
	v_pk_mul_f32 v[56:57], v[100:101], s[20:21] op_sel_hi:[1,0]
	v_pk_fma_f32 v[52:53], v[52:53], v[80:81], v[54:55]
	v_pk_fma_f32 v[50:51], v[50:51], v[78:79], v[56:57]
	global_store_dwordx4 v[114:115], v[50:53], off offset:512
	s_nop 1
	v_pk_mul_f32 v[50:51], v[130:131], s[20:21] op_sel_hi:[1,0]
	v_pk_mul_f32 v[52:53], v[128:129], s[20:21] op_sel_hi:[1,0]
	v_pk_fma_f32 v[44:45], v[44:45], v[80:81], v[50:51]
	v_pk_fma_f32 v[42:43], v[42:43], v[78:79], v[52:53]
	global_store_dwordx4 v[110:111], v[42:45], off offset:512
	s_nop 1
	v_pk_mul_f32 v[42:43], v[134:135], s[20:21] op_sel_hi:[1,0]
	v_pk_mul_f32 v[44:45], v[132:133], s[20:21] op_sel_hi:[1,0]
	v_pk_fma_f32 v[36:37], v[36:37], v[80:81], v[42:43]
	v_pk_fma_f32 v[34:35], v[34:35], v[78:79], v[44:45]
	global_store_dwordx4 v[106:107], v[34:37], off offset:512
	s_nop 1
	v_pk_mul_f32 v[34:35], v[138:139], s[20:21] op_sel_hi:[1,0]
	v_pk_mul_f32 v[36:37], v[136:137], s[20:21] op_sel_hi:[1,0]
	v_pk_fma_f32 v[28:29], v[28:29], v[80:81], v[34:35]
	v_pk_fma_f32 v[26:27], v[26:27], v[78:79], v[36:37]
	global_store_dwordx4 v[94:95], v[26:29], off offset:512
	s_nop 1
	v_pk_mul_f32 v[26:27], v[142:143], s[20:21] op_sel_hi:[1,0]
	v_pk_mul_f32 v[28:29], v[140:141], s[20:21] op_sel_hi:[1,0]
	v_pk_fma_f32 v[20:21], v[20:21], v[80:81], v[26:27]
	v_pk_fma_f32 v[18:19], v[18:19], v[78:79], v[28:29]
	global_store_dwordx4 v[82:83], v[18:21], off offset:512
	v_pk_mul_f32 v[26:27], v[144:145], s[20:21] op_sel_hi:[1,0]
	s_nop 0
	v_pk_mul_f32 v[18:19], v[146:147], s[20:21] op_sel_hi:[1,0]
	s_nop 0
	v_pk_fma_f32 v[20:21], v[48:49], v[64:65], v[18:19]
	v_pk_fma_f32 v[18:19], v[46:47], v[62:63], v[26:27]
	global_store_dwordx4 v[126:127], v[18:21], off offset:576
	v_pk_mul_f32 v[26:27], v[148:149], s[20:21] op_sel_hi:[1,0]
	s_nop 0
	v_pk_mul_f32 v[18:19], v[150:151], s[20:21] op_sel_hi:[1,0]
	s_nop 0
	v_pk_fma_f32 v[20:21], v[40:41], v[64:65], v[18:19]
	v_pk_fma_f32 v[18:19], v[38:39], v[62:63], v[26:27]
	global_store_dwordx4 v[122:123], v[18:21], off offset:576
	v_pk_mul_f32 v[26:27], v[152:153], s[20:21] op_sel_hi:[1,0]
	s_nop 0
	v_pk_mul_f32 v[18:19], v[154:155], s[20:21] op_sel_hi:[1,0]
	s_nop 0
	v_pk_fma_f32 v[20:21], v[32:33], v[64:65], v[18:19]
	v_pk_fma_f32 v[18:19], v[30:31], v[62:63], v[26:27]
	global_store_dwordx4 v[118:119], v[18:21], off offset:576
	v_pk_mul_f32 v[26:27], v[156:157], s[20:21] op_sel_hi:[1,0]
	s_nop 0
	v_pk_mul_f32 v[18:19], v[158:159], s[20:21] op_sel_hi:[1,0]
	s_nop 0
	v_pk_fma_f32 v[20:21], v[24:25], v[64:65], v[18:19]
	v_pk_fma_f32 v[18:19], v[22:23], v[62:63], v[26:27]
	global_store_dwordx4 v[114:115], v[18:21], off offset:576
	s_nop 1
	v_pk_mul_f32 v[18:19], v[162:163], s[20:21] op_sel_hi:[1,0]
	v_pk_mul_f32 v[20:21], v[160:161], s[20:21] op_sel_hi:[1,0]
	v_pk_fma_f32 v[16:17], v[16:17], v[64:65], v[18:19]
	v_pk_fma_f32 v[14:15], v[14:15], v[62:63], v[20:21]
	global_store_dwordx4 v[110:111], v[14:17], off offset:576
	s_nop 1
	v_pk_mul_f32 v[14:15], v[166:167], s[20:21] op_sel_hi:[1,0]
	v_pk_mul_f32 v[16:17], v[164:165], s[20:21] op_sel_hi:[1,0]
	v_pk_fma_f32 v[12:13], v[12:13], v[64:65], v[14:15]
	v_pk_fma_f32 v[10:11], v[10:11], v[62:63], v[16:17]
	global_store_dwordx4 v[106:107], v[10:13], off offset:576
	s_nop 1
	v_pk_mul_f32 v[10:11], v[76:77], s[20:21] op_sel_hi:[1,0]
	v_pk_mul_f32 v[12:13], v[74:75], s[20:21] op_sel_hi:[1,0]
	v_pk_fma_f32 v[8:9], v[8:9], v[64:65], v[10:11]
	v_pk_fma_f32 v[6:7], v[6:7], v[62:63], v[12:13]
	global_store_dwordx4 v[94:95], v[6:9], off offset:576
	s_nop 1
	v_pk_mul_f32 v[6:7], v[72:73], s[20:21] op_sel_hi:[1,0]
	v_pk_mul_f32 v[8:9], v[70:71], s[20:21] op_sel_hi:[1,0]
	v_pk_fma_f32 v[4:5], v[4:5], v[64:65], v[6:7]
	v_pk_fma_f32 v[2:3], v[2:3], v[62:63], v[8:9]
	global_store_dwordx4 v[82:83], v[2:5], off offset:576
	s_cbranch_vccz .LBB0_853
	s_waitcnt vmcnt(0)
	s_cmpk_gt_u32 s21, 0xff
	s_cbranch_scc1 .LBB0_862
	s_barrier

; #define PG8_STAGE(bufoff, gbase, voff) do { _Pragma("unroll") for (int _i = 0; _i < 2; ++_i) \
;         __builtin_amdgcn_global_load_lds((const unsigned*)((const char*)(gbase) + (voff)[_i]), (LAS unsigned*)(lds + (bufoff) + ldsw + _i * 8192), 16, 0, 0); } while (0)
; #define PG8_WAIT_V(n) asm volatile("s_waitcnt vmcnt(" #n ")" ::: "memory")
; #define PG8_BAR __builtin_amdgcn_s_barrier()
; template <class Epi>
; DI void gemm_phase(LAS unsigned char* lds, const Gemm g, const StaticOrder& S, const Epi& E) {
;     ...
;     const char* cA = PG8_ABASE(cur); const char* cB = PG8_BBASE(cur);
;     PG8_STAGE(PG8_SB(0, 0), cB, voffB); PG8_STAGE(PG8_SA(0, 0), cA, voffA); PG8_STAGE(PG8_SB(0, 1), cB + hstepB, voffB); PG8_STAGE(PG8_SA(0, 1), cA + hstepA, voffA);
;     if (wr == 1) PG8_BAR;
;     PG8_WAIT_V(4); PG8_BAR;
;     PG8_STAGE(PG8_SB(1, 0), cB + kstep, voffB); PG8_STAGE(PG8_SA(1, 0), cA + kstep, voffA); PG8_STAGE(PG8_SB(1, 1), cB + hstepB + kstep, voffB);
;     PG8_WAIT_V(6); PG8_BAR;
.LBB0_962:
	s_add_u32 s6, s10, 0x1b800000
	s_addc_u32 s7, s11, 0
	s_lshl_b32 s4, s4, 5
	s_mov_b64 s[8:9], 0x80
	s_and_b32 s4, s4, 0x60
	s_add_i32 m0, s13, 0x18000
	v_lshl_add_u64 v[8:9], v[8:9], 0, s[8:9]
	s_lshl_b32 s19, s18, 13
	s_lshl_b32 s20, s4, 7
	s_waitcnt vmcnt(0)
	s_barrier
	global_load_lds_dwordx4 v[8:9], off
	v_lshl_add_u64 v[6:7], v[6:7], 0, s[8:9]
	s_add_i32 m0, s13, 0x1a000
	s_add_i32 s50, s13, 0x8000
	s_add_i32 s51, s13, 0xa000
	global_load_lds_dwordx4 v[6:7], off
	v_lshl_add_u64 v[4:5], v[4:5], 0, s[8:9]
	s_mov_b32 m0, s50
	s_add_u32 s10, s28, 0x80080
	global_load_lds_dwordx4 v[4:5], off
	v_lshl_add_u64 v[2:3], v[2:3], 0, s[8:9]
	s_mov_b32 m0, s51
	s_addc_u32 s11, s29, 0
	global_load_lds_dwordx4 v[2:3], off
	s_add_i32 m0, s13, 0x1c000
	v_lshl_add_u64 v[2:3], s[10:11], 0, v[132:133]
	global_load_lds_dwordx4 v[2:3], off
	v_lshl_add_u64 v[2:3], s[10:11], 0, v[136:137]
	s_add_i32 m0, s13, 0x1e000
	v_lshlrev_b32_e32 v4, 2, v254
	global_load_lds_dwordx4 v[2:3], off
	v_and_b32_e32 v2, 15, v254
	v_lshlrev_b32_e32 v3, 1, v13
	v_lshlrev_b32_e32 v5, 6, v254
	s_movk_i32 s10, 0x3c0
	v_lshl_or_b32 v1, s18, 6, v2
	v_lshl_or_b32 v2, v2, 6, v3
	v_and_b32_e32 v4, 32, v4
	v_and_or_b32 v3, v5, s10, v3
	v_bitop3_b32 v142, s20, v3, v4 bitop3:0xf6
	v_lshlrev_b32_e32 v3, 9, v254
	v_bitop3_b32 v2, v2, s19, v4 bitop3:0xde
	v_and_b32_e32 v3, 0x70000, v3
	v_lshlrev_b32_e32 v4, 12, v12
	v_or3_b32 v3, v10, v3, v4
	v_add_u32_e32 v138, v3, v11
	v_lshlrev_b32_e32 v3, 5, v14
	s_waitcnt vmcnt(6)
	v_and_b32_e32 v3, 0xf0000, v3
	v_or3_b32 v3, v10, v3, v4
	s_add_i32 s52, 0, 0x10000
	s_add_i32 s53, 0, 0x14000
	v_or_b32_e32 v143, s4, v13
	v_mov_b32_e32 v139, v133
	v_add_u32_e32 v140, v3, v11
	v_mov_b32_e32 v141, v133
	v_add_u32_e32 v144, s52, v142
	v_add_u32_e32 v145, 0, v2
	v_add_u32_e32 v146, s53, v142
	s_movk_i32 s54, 0x2080
	s_mov_b32 s4, s5
	s_barrier

; #define PG8_STAGE(bufoff, gbase, voff) do { _Pragma("unroll") for (int _i = 0; _i < 2; ++_i) \
;         __builtin_amdgcn_global_load_lds((const unsigned*)((const char*)(gbase) + (voff)[_i]), (LAS unsigned*)(lds + (bufoff) + ldsw + _i * 8192), 16, 0, 0); } while (0)
; #define PG8_LDA(dst, b, h) do { _Pragma("unroll") for (int m = 0; m < 4; ++m) _Pragma("unroll") for (int k = 0; k < 2; ++k) dst[m][k] = *(const LAS bf16x8*)(lds + PG8_SA(b, h) + aoff + m * 2048 + k * 1024); } while (0)
; #define PG8_LDB(dst, b, h) do { _Pragma("unroll") for (int n = 0; n < 2; ++n) _Pragma("unroll") for (int k = 0; k < 2; ++k) dst[n][k] = *(const LAS bf16x8*)(lds + PG8_SB(b, h) + boff + n * 2048 + k * 1024); } while (0)
; #define PG8_MMA(ai, bj, At, Bt) do { __builtin_amdgcn_s_setprio(1); _Pragma("unroll") for (int m = 0; m < 4; ++m) _Pragma("unroll") for (int n = 0; n < 2; ++n) _Pragma("unroll") for (int k = 0; k < 2; ++k) \
;         acc[ai][bj][m][n] = __builtin_amdgcn_mfma_f32_16x16x32_bf16(Bt[n][k], At[m][k], acc[ai][bj][m][n], 0, 0, 0); __builtin_amdgcn_s_setprio(0); } while (0)
; #define PG8_WAIT_L(n) asm volatile("s_waitcnt lgkmcnt(" #n ")" ::: "memory")
; #define PG8_BAR __builtin_amdgcn_s_barrier()
; #define PG8_SCHED __builtin_amdgcn_sched_barrier(0)
; template <class Epi>
; DI void gemm_phase(LAS unsigned char* lds, const Gemm g, const StaticOrder& S, const Epi& E) {
;     ...
;             PG8_LDB(B0, 0, 0); PG8_SCHED; PG8_LDA(At, 0, 0); PG8_STAGE(PG8_SA(1, 1), a1 + hstepA, voffA);
;             PG8_WAIT_L(8); PG8_BAR; PG8_WAIT_L(0); PG8_MMA(0, 0, At, B0); PG8_BAR; PG8_SCHED;
;             PG8_LDB(B1, 0, 1); PG8_STAGE(PG8_SB(0, 0), b2, voffB);
;             PG8_BAR; PG8_WAIT_L(0); PG8_MMA(0, 1, At, B1); PG8_BAR;
;             PG8_LDA(At, 0, 1); PG8_STAGE(PG8_SA(0, 0), a2, voffA);
;             PG8_BAR; PG8_WAIT_L(0); PG8_MMA(1, 0, At, B0); PG8_BAR; PG8_SCHED;
;             PG8_STAGE(PG8_SB(0, 1), b2 + hstepB, voffB);
.LBB0_970:
	ds_read_b128 v[148:151], v144
	ds_read_b128 v[152:155], v144 offset:1024
	ds_read_b128 v[156:159], v144 offset:2048
	ds_read_b128 v[160:163], v144 offset:3072
	s_add_u32 s28, s26, 0xfff80080
	s_addc_u32 s29, s27, -1
	s_cmp_eq_u32 s59, 28
	s_cselect_b32 s31, s21, s29
	s_cselect_b32 s30, s55, s28
	s_cselect_b32 s29, s19, s58
	s_cselect_b32 s28, s56, s57
	v_lshl_add_u64 v[196:197], s[26:27], 0, v[138:139]
	s_add_i32 m0, s13, 0xc000
	ds_read_b128 v[164:167], v145
	ds_read_b128 v[168:171], v145 offset:1024
	ds_read_b128 v[172:175], v145 offset:2048
	ds_read_b128 v[176:179], v145 offset:3072
	ds_read_b128 v[180:183], v145 offset:4096
	ds_read_b128 v[184:187], v145 offset:5120
	ds_read_b128 v[188:191], v145 offset:6144
	ds_read_b128 v[192:195], v145 offset:7168
	global_load_lds_dwordx4 v[196:197], off
	v_lshl_add_u64 v[196:197], s[26:27], 0, v[140:141]
	s_add_i32 m0, s13, 0xe000
	s_nop 0
	global_load_lds_dwordx4 v[196:197], off
	ds_read_b128 v[196:199], v146
	ds_read_b128 v[200:203], v146 offset:1024
	ds_read_b128 v[204:207], v146 offset:2048
	ds_read_b128 v[208:211], v146 offset:3072
	s_waitcnt lgkmcnt(0)
	s_waitcnt vmcnt(8)
	s_barrier
	s_setprio 1
	v_mfma_f32_16x16x32_bf16 v[126:129], v[148:151], v[164:167], v[126:129]
	v_mfma_f32_16x16x32_bf16 v[122:125], v[156:159], v[164:167], v[122:125]
	v_mfma_f32_16x16x32_bf16 v[118:121], v[148:151], v[172:175], v[118:121]
	v_mfma_f32_16x16x32_bf16 v[114:117], v[156:159], v[172:175], v[114:117]
	v_mfma_f32_16x16x32_bf16 v[102:105], v[148:151], v[180:183], v[102:105]
	v_mfma_f32_16x16x32_bf16 v[98:101], v[156:159], v[180:183], v[98:101]
	v_mfma_f32_16x16x32_bf16 v[86:89], v[148:151], v[188:191], v[86:89]
	v_mfma_f32_16x16x32_bf16 v[82:85], v[156:159], v[188:191], v[82:85]
	v_mfma_f32_16x16x32_bf16 v[126:129], v[152:155], v[168:171], v[126:129]
	v_mfma_f32_16x16x32_bf16 v[122:125], v[160:163], v[168:171], v[122:125]
	v_mfma_f32_16x16x32_bf16 v[118:121], v[152:155], v[176:179], v[118:121]
	v_mfma_f32_16x16x32_bf16 v[114:117], v[160:163], v[176:179], v[114:117]
	v_mfma_f32_16x16x32_bf16 v[102:105], v[152:155], v[184:187], v[102:105]
	v_mfma_f32_16x16x32_bf16 v[98:101], v[160:163], v[184:187], v[98:101]
	v_mfma_f32_16x16x32_bf16 v[86:89], v[152:155], v[192:195], v[86:89]
	v_mfma_f32_16x16x32_bf16 v[82:85], v[160:163], v[192:195], v[82:85]
	v_mfma_f32_16x16x32_bf16 v[110:113], v[196:199], v[164:167], v[110:113]
	v_mfma_f32_16x16x32_bf16 v[106:109], v[204:207], v[164:167], v[106:109]
	v_mfma_f32_16x16x32_bf16 v[94:97], v[196:199], v[172:175], v[94:97]
	v_mfma_f32_16x16x32_bf16 v[90:93], v[204:207], v[172:175], v[90:93]
	v_mfma_f32_16x16x32_bf16 v[78:81], v[196:199], v[180:183], v[78:81]
	v_mfma_f32_16x16x32_bf16 v[74:77], v[204:207], v[180:183], v[74:77]
	v_mfma_f32_16x16x32_bf16 v[70:73], v[196:199], v[188:191], v[70:73]
	v_mfma_f32_16x16x32_bf16 v[66:69], v[204:207], v[188:191], v[66:69]
	v_mfma_f32_16x16x32_bf16 v[110:113], v[200:203], v[168:171], v[110:113]
	v_mfma_f32_16x16x32_bf16 v[106:109], v[208:211], v[168:171], v[106:109]
	v_mfma_f32_16x16x32_bf16 v[94:97], v[200:203], v[176:179], v[94:97]
	v_mfma_f32_16x16x32_bf16 v[90:93], v[208:211], v[176:179], v[90:93]
	v_mfma_f32_16x16x32_bf16 v[78:81], v[200:203], v[184:187], v[78:81]
	v_mfma_f32_16x16x32_bf16 v[74:77], v[208:211], v[184:187], v[74:77]
	v_mfma_f32_16x16x32_bf16 v[70:73], v[200:203], v[192:195], v[70:73]
	v_mfma_f32_16x16x32_bf16 v[66:69], v[208:211], v[192:195], v[66:69]
	s_setprio 0
	s_barrier
	s_add_i32 s60, s52, s39
	v_lshl_add_u64 v[212:213], s[28:29], 0, v[132:133]
	s_mov_b32 m0, s60
	s_nop 0
	global_load_lds_dwordx4 v[212:213], off
	v_lshl_add_u64 v[214:215], s[28:29], 0, v[136:137]
	s_add_i32 m0, s60, 0x2000
	s_nop 0
	global_load_lds_dwordx4 v[214:215], off
	s_mov_b32 m0, s13
	v_lshl_add_u64 v[218:219], s[30:31], 0, v[130:131]
	ds_read_b128 v[164:167], v145 offset:16384
	ds_read_b128 v[168:171], v145 offset:17408
	ds_read_b128 v[172:175], v145 offset:18432
	ds_read_b128 v[176:179], v145 offset:19456
	ds_read_b128 v[180:183], v145 offset:20480
	ds_read_b128 v[184:187], v145 offset:21504
	ds_read_b128 v[188:191], v145 offset:22528
	ds_read_b128 v[192:195], v145 offset:23552
	global_load_lds_dwordx4 v[218:219], off
	v_lshl_add_u64 v[220:221], s[30:31], 0, v[134:135]
	s_mov_b32 m0, s15
	s_nop 0
	global_load_lds_dwordx4 v[220:221], off
	s_add_u32 s60, s28, 0x80000
	s_addc_u32 s61, s29, 0
	s_add_i32 s62, s53, s39
	v_lshl_add_u64 v[252:253], s[60:61], 0, v[132:133]
	s_mov_b32 m0, s62
	s_nop 0
	global_load_lds_dwordx4 v[252:253], off
	v_lshl_add_u64 v[252:253], s[60:61], 0, v[136:137]
	s_add_i32 m0, s62, 0x2000
	s_nop 0
	global_load_lds_dwordx4 v[252:253], off
	s_waitcnt lgkmcnt(0)
	s_waitcnt vmcnt(8)
	s_barrier
; #define PG8_STAGE(bufoff, gbase, voff) do { _Pragma("unroll") for (int _i = 0; _i < 2; ++_i) \
;         __builtin_amdgcn_global_load_lds((const unsigned*)((const char*)(gbase) + (voff)[_i]), (LAS unsigned*)(lds + (bufoff) + ldsw + _i * 8192), 16, 0, 0); } while (0)
; #define PG8_LDA(dst, b, h) do { _Pragma("unroll") for (int m = 0; m < 4; ++m) _Pragma("unroll") for (int k = 0; k < 2; ++k) dst[m][k] = *(const LAS bf16x8*)(lds + PG8_SA(b, h) + aoff + m * 2048 + k * 1024); } while (0)
; #define PG8_LDB(dst, b, h) do { _Pragma("unroll") for (int n = 0; n < 2; ++n) _Pragma("unroll") for (int k = 0; k < 2; ++k) dst[n][k] = *(const LAS bf16x8*)(lds + PG8_SB(b, h) + boff + n * 2048 + k * 1024); } while (0)
; #define PG8_MMA(ai, bj, At, Bt) do { __builtin_amdgcn_s_setprio(1); _Pragma("unroll") for (int m = 0; m < 4; ++m) _Pragma("unroll") for (int n = 0; n < 2; ++n) _Pragma("unroll") for (int k = 0; k < 2; ++k) \
;         acc[ai][bj][m][n] = __builtin_amdgcn_mfma_f32_16x16x32_bf16(Bt[n][k], At[m][k], acc[ai][bj][m][n], 0, 0, 0); __builtin_amdgcn_s_setprio(0); } while (0)
; #define PG8_WAIT_V(n) asm volatile("s_waitcnt vmcnt(" #n ")" ::: "memory")
; #define PG8_WAIT_L(n) asm volatile("s_waitcnt lgkmcnt(" #n ")" ::: "memory")
; #define PG8_BAR __builtin_amdgcn_s_barrier()
; #define PG8_SCHED __builtin_amdgcn_sched_barrier(0)
; template <class Epi>
; DI void gemm_phase(LAS unsigned char* lds, const Gemm g, const StaticOrder& S, const Epi& E) {
;     ...
;             PG8_BAR; PG8_WAIT_L(0); PG8_MMA(1, 0, At, B0); PG8_BAR; PG8_SCHED;
;             PG8_STAGE(PG8_SB(0, 1), b2 + hstepB, voffB);
;             PG8_WAIT_V(6); PG8_BAR; PG8_MMA(1, 1, At, B1); PG8_BAR;
;             PG8_LDB(B0, 1, 0); PG8_SCHED; PG8_LDA(At, 1, 0); PG8_STAGE(PG8_SA(0, 1), a2 + hstepA, voffA);
;             PG8_WAIT_L(8); PG8_BAR; PG8_WAIT_L(0); PG8_MMA(0, 0, At, B0); PG8_BAR; PG8_SCHED;
;             PG8_LDB(B1, 1, 1); PG8_STAGE(PG8_SB(1, 0), b3, voffB);
;             PG8_BAR; PG8_WAIT_L(0); PG8_MMA(0, 1, At, B1); PG8_BAR;
	s_setprio 1
	v_mfma_f32_16x16x32_bf16 v[62:65], v[148:151], v[164:167], v[62:65]
	v_mfma_f32_16x16x32_bf16 v[58:61], v[156:159], v[164:167], v[58:61]
	v_mfma_f32_16x16x32_bf16 v[54:57], v[148:151], v[172:175], v[54:57]
	v_mfma_f32_16x16x32_bf16 v[50:53], v[156:159], v[172:175], v[50:53]
	v_mfma_f32_16x16x32_bf16 v[38:41], v[148:151], v[180:183], v[38:41]
	v_mfma_f32_16x16x32_bf16 v[34:37], v[156:159], v[180:183], v[34:37]
	v_mfma_f32_16x16x32_bf16 v[22:25], v[148:151], v[188:191], v[22:25]
	v_mfma_f32_16x16x32_bf16 v[18:21], v[156:159], v[188:191], v[18:21]
	v_mfma_f32_16x16x32_bf16 v[62:65], v[152:155], v[168:171], v[62:65]
	v_mfma_f32_16x16x32_bf16 v[58:61], v[160:163], v[168:171], v[58:61]
	v_mfma_f32_16x16x32_bf16 v[54:57], v[152:155], v[176:179], v[54:57]
	v_mfma_f32_16x16x32_bf16 v[50:53], v[160:163], v[176:179], v[50:53]
	v_mfma_f32_16x16x32_bf16 v[38:41], v[152:155], v[184:187], v[38:41]
	v_mfma_f32_16x16x32_bf16 v[34:37], v[160:163], v[184:187], v[34:37]
	v_mfma_f32_16x16x32_bf16 v[22:25], v[152:155], v[192:195], v[22:25]
	v_mfma_f32_16x16x32_bf16 v[18:21], v[160:163], v[192:195], v[18:21]
	v_mfma_f32_16x16x32_bf16 v[46:49], v[196:199], v[164:167], v[46:49]
	v_mfma_f32_16x16x32_bf16 v[42:45], v[204:207], v[164:167], v[42:45]
	v_mfma_f32_16x16x32_bf16 v[30:33], v[196:199], v[172:175], v[30:33]
	v_mfma_f32_16x16x32_bf16 v[26:29], v[204:207], v[172:175], v[26:29]
	v_mfma_f32_16x16x32_bf16 v[14:17], v[196:199], v[180:183], v[14:17]
	v_mfma_f32_16x16x32_bf16 v[10:13], v[204:207], v[180:183], v[10:13]
	v_mfma_f32_16x16x32_bf16 v[6:9], v[196:199], v[188:191], v[6:9]
	v_mfma_f32_16x16x32_bf16 v[2:5], v[204:207], v[188:191], v[2:5]
	v_mfma_f32_16x16x32_bf16 v[46:49], v[200:203], v[168:171], v[46:49]
	v_mfma_f32_16x16x32_bf16 v[42:45], v[208:211], v[168:171], v[42:45]
	v_mfma_f32_16x16x32_bf16 v[30:33], v[200:203], v[176:179], v[30:33]
	v_mfma_f32_16x16x32_bf16 v[26:29], v[208:211], v[176:179], v[26:29]
	v_mfma_f32_16x16x32_bf16 v[14:17], v[200:203], v[184:187], v[14:17]
	v_mfma_f32_16x16x32_bf16 v[10:13], v[208:211], v[184:187], v[10:13]
	v_mfma_f32_16x16x32_bf16 v[6:9], v[200:203], v[192:195], v[6:9]
	v_mfma_f32_16x16x32_bf16 v[2:5], v[208:211], v[192:195], v[2:5]
	s_setprio 0
	s_add_i32 s60, 0, 0x18000
	v_add_u32_e32 v147, s60, v142
	s_barrier
	ds_read_b128 v[148:151], v147
	ds_read_b128 v[152:155], v147 offset:1024
	ds_read_b128 v[156:159], v147 offset:2048
	ds_read_b128 v[160:163], v147 offset:3072
	s_add_u32 s30, s30, 0x80000
	s_addc_u32 s31, s31, 0
	s_mov_b32 m0, s48
	v_lshl_add_u64 v[196:197], s[30:31], 0, v[130:131]
	ds_read_b128 v[164:167], v145 offset:32768
	ds_read_b128 v[168:171], v145 offset:33792
	ds_read_b128 v[172:175], v145 offset:34816
	ds_read_b128 v[176:179], v145 offset:35840
	ds_read_b128 v[180:183], v145 offset:36864
	ds_read_b128 v[184:187], v145 offset:37888
	ds_read_b128 v[188:191], v145 offset:38912
	ds_read_b128 v[192:195], v145 offset:39936
	global_load_lds_dwordx4 v[196:197], off
	v_lshl_add_u64 v[196:197], s[30:31], 0, v[134:135]
	s_mov_b32 m0, s49
	s_nop 0
	global_load_lds_dwordx4 v[196:197], off
	s_add_i32 s30, 0, 0x1c000
	v_add_u32_e32 v147, s30, v142
	ds_read_b128 v[196:199], v147
	ds_read_b128 v[200:203], v147 offset:1024
	ds_read_b128 v[204:207], v147 offset:2048
	ds_read_b128 v[208:211], v147 offset:3072
	s_waitcnt lgkmcnt(0)
	s_waitcnt vmcnt(8)
	s_barrier
	s_setprio 1
	v_mfma_f32_16x16x32_bf16 v[126:129], v[148:151], v[164:167], v[126:129]
	v_mfma_f32_16x16x32_bf16 v[122:125], v[156:159], v[164:167], v[122:125]
	v_mfma_f32_16x16x32_bf16 v[118:121], v[148:151], v[172:175], v[118:121]
	v_mfma_f32_16x16x32_bf16 v[114:117], v[156:159], v[172:175], v[114:117]
	v_mfma_f32_16x16x32_bf16 v[102:105], v[148:151], v[180:183], v[102:105]
	v_mfma_f32_16x16x32_bf16 v[98:101], v[156:159], v[180:183], v[98:101]
	v_mfma_f32_16x16x32_bf16 v[86:89], v[148:151], v[188:191], v[86:89]
	v_mfma_f32_16x16x32_bf16 v[82:85], v[156:159], v[188:191], v[82:85]
	v_mfma_f32_16x16x32_bf16 v[126:129], v[152:155], v[168:171], v[126:129]
	v_mfma_f32_16x16x32_bf16 v[122:125], v[160:163], v[168:171], v[122:125]
	v_mfma_f32_16x16x32_bf16 v[118:121], v[152:155], v[176:179], v[118:121]
	v_mfma_f32_16x16x32_bf16 v[114:117], v[160:163], v[176:179], v[114:117]
	v_mfma_f32_16x16x32_bf16 v[102:105], v[152:155], v[184:187], v[102:105]
	v_mfma_f32_16x16x32_bf16 v[98:101], v[160:163], v[184:187], v[98:101]
	v_mfma_f32_16x16x32_bf16 v[86:89], v[152:155], v[192:195], v[86:89]
	v_mfma_f32_16x16x32_bf16 v[82:85], v[160:163], v[192:195], v[82:85]
	v_mfma_f32_16x16x32_bf16 v[110:113], v[196:199], v[164:167], v[110:113]
	v_mfma_f32_16x16x32_bf16 v[106:109], v[204:207], v[164:167], v[106:109]
	v_mfma_f32_16x16x32_bf16 v[94:97], v[196:199], v[172:175], v[94:97]
	v_mfma_f32_16x16x32_bf16 v[90:93], v[204:207], v[172:175], v[90:93]
	v_mfma_f32_16x16x32_bf16 v[78:81], v[196:199], v[180:183], v[78:81]
	v_mfma_f32_16x16x32_bf16 v[74:77], v[204:207], v[180:183], v[74:77]
	v_mfma_f32_16x16x32_bf16 v[70:73], v[196:199], v[188:191], v[70:73]
	v_mfma_f32_16x16x32_bf16 v[66:69], v[204:207], v[188:191], v[66:69]
	v_mfma_f32_16x16x32_bf16 v[110:113], v[200:203], v[168:171], v[110:113]
	v_mfma_f32_16x16x32_bf16 v[106:109], v[208:211], v[168:171], v[106:109]
	v_mfma_f32_16x16x32_bf16 v[94:97], v[200:203], v[176:179], v[94:97]
	v_mfma_f32_16x16x32_bf16 v[90:93], v[208:211], v[176:179], v[90:93]
	v_mfma_f32_16x16x32_bf16 v[78:81], v[200:203], v[184:187], v[78:81]
	v_mfma_f32_16x16x32_bf16 v[74:77], v[208:211], v[184:187], v[74:77]
	v_mfma_f32_16x16x32_bf16 v[70:73], v[200:203], v[192:195], v[70:73]
	v_mfma_f32_16x16x32_bf16 v[66:69], v[208:211], v[192:195], v[66:69]
	s_setprio 0
	s_barrier
; #define PG8_STAGE(bufoff, gbase, voff) do { _Pragma("unroll") for (int _i = 0; _i < 2; ++_i) \
;         __builtin_amdgcn_global_load_lds((const unsigned*)((const char*)(gbase) + (voff)[_i]), (LAS unsigned*)(lds + (bufoff) + ldsw + _i * 8192), 16, 0, 0); } while (0)
; #define PG8_LDA(dst, b, h) do { _Pragma("unroll") for (int m = 0; m < 4; ++m) _Pragma("unroll") for (int k = 0; k < 2; ++k) dst[m][k] = *(const LAS bf16x8*)(lds + PG8_SA(b, h) + aoff + m * 2048 + k * 1024); } while (0)
; #define PG8_LDB(dst, b, h) do { _Pragma("unroll") for (int n = 0; n < 2; ++n) _Pragma("unroll") for (int k = 0; k < 2; ++k) dst[n][k] = *(const LAS bf16x8*)(lds + PG8_SB(b, h) + boff + n * 2048 + k * 1024); } while (0)
; #define PG8_MMA(ai, bj, At, Bt) do { __builtin_amdgcn_s_setprio(1); _Pragma("unroll") for (int m = 0; m < 4; ++m) _Pragma("unroll") for (int n = 0; n < 2; ++n) _Pragma("unroll") for (int k = 0; k < 2; ++k) \
;         acc[ai][bj][m][n] = __builtin_amdgcn_mfma_f32_16x16x32_bf16(Bt[n][k], At[m][k], acc[ai][bj][m][n], 0, 0, 0); __builtin_amdgcn_s_setprio(0); } while (0)
; #define PG8_WAIT_V(n) asm volatile("s_waitcnt vmcnt(" #n ")" ::: "memory")
; #define PG8_WAIT_L(n) asm volatile("s_waitcnt lgkmcnt(" #n ")" ::: "memory")
; #define PG8_BAR __builtin_amdgcn_s_barrier()
; #define PG8_SCHED __builtin_amdgcn_sched_barrier(0)
; template <class Epi>
; DI void gemm_phase(LAS unsigned char* lds, const Gemm g, const StaticOrder& S, const Epi& E) {
;     ...
;             PG8_LDB(B1, 1, 1); PG8_STAGE(PG8_SB(1, 0), b3, voffB);
;             PG8_BAR; PG8_WAIT_L(0); PG8_MMA(0, 1, At, B1); PG8_BAR;
;             PG8_LDA(At, 1, 1); PG8_STAGE(PG8_SA(1, 0), a3, voffA);
;             PG8_BAR; PG8_WAIT_L(0); PG8_MMA(1, 0, At, B0); PG8_BAR; PG8_SCHED;
;             PG8_STAGE(PG8_SB(1, 1), b3 + hstepB, voffB);
;             PG8_WAIT_V(6); PG8_BAR; PG8_MMA(1, 1, At, B1); PG8_BAR;
;         }
	s_add_i32 s31, s60, s39
	v_lshl_add_u64 v[212:213], v[212:213], 0, s[8:9]
	s_mov_b32 m0, s31
	s_nop 0
	global_load_lds_dwordx4 v[212:213], off
	v_lshl_add_u64 v[212:213], v[214:215], 0, s[8:9]
	s_add_i32 m0, s31, 0x2000
	s_nop 0
	global_load_lds_dwordx4 v[212:213], off
	s_mov_b32 m0, s50
	v_lshl_add_u64 v[212:213], v[218:219], 0, s[8:9]
	ds_read_b128 v[164:167], v145 offset:49152
	ds_read_b128 v[168:171], v145 offset:50176
	ds_read_b128 v[172:175], v145 offset:51200
	ds_read_b128 v[176:179], v145 offset:52224
	ds_read_b128 v[180:183], v145 offset:53248
	ds_read_b128 v[184:187], v145 offset:54272
	ds_read_b128 v[188:191], v145 offset:55296
	ds_read_b128 v[192:195], v145 offset:56320
	global_load_lds_dwordx4 v[212:213], off
	v_lshl_add_u64 v[212:213], v[220:221], 0, s[8:9]
	s_mov_b32 m0, s51
	s_nop 0
	global_load_lds_dwordx4 v[212:213], off
	s_add_u32 s28, s28, 0x80080
	s_addc_u32 s29, s29, 0
	s_add_i32 s30, s30, s39
	v_lshl_add_u64 v[252:253], s[28:29], 0, v[132:133]
	s_mov_b32 m0, s30
	s_nop 0
	global_load_lds_dwordx4 v[252:253], off
	v_lshl_add_u64 v[252:253], s[28:29], 0, v[136:137]
	s_add_i32 m0, s30, 0x2000
	s_nop 0
	global_load_lds_dwordx4 v[252:253], off
	s_waitcnt lgkmcnt(0)
	s_waitcnt vmcnt(8)
	s_barrier
	s_setprio 1
	v_mfma_f32_16x16x32_bf16 v[62:65], v[148:151], v[164:167], v[62:65]
	v_mfma_f32_16x16x32_bf16 v[58:61], v[156:159], v[164:167], v[58:61]
	v_mfma_f32_16x16x32_bf16 v[54:57], v[148:151], v[172:175], v[54:57]
	v_mfma_f32_16x16x32_bf16 v[50:53], v[156:159], v[172:175], v[50:53]
	v_mfma_f32_16x16x32_bf16 v[38:41], v[148:151], v[180:183], v[38:41]
	v_mfma_f32_16x16x32_bf16 v[34:37], v[156:159], v[180:183], v[34:37]
	v_mfma_f32_16x16x32_bf16 v[22:25], v[148:151], v[188:191], v[22:25]
	v_mfma_f32_16x16x32_bf16 v[18:21], v[156:159], v[188:191], v[18:21]
	v_mfma_f32_16x16x32_bf16 v[62:65], v[152:155], v[168:171], v[62:65]
	v_mfma_f32_16x16x32_bf16 v[58:61], v[160:163], v[168:171], v[58:61]
	v_mfma_f32_16x16x32_bf16 v[54:57], v[152:155], v[176:179], v[54:57]
	v_mfma_f32_16x16x32_bf16 v[50:53], v[160:163], v[176:179], v[50:53]
	v_mfma_f32_16x16x32_bf16 v[38:41], v[152:155], v[184:187], v[38:41]
	v_mfma_f32_16x16x32_bf16 v[34:37], v[160:163], v[184:187], v[34:37]
	v_mfma_f32_16x16x32_bf16 v[22:25], v[152:155], v[192:195], v[22:25]
	v_mfma_f32_16x16x32_bf16 v[18:21], v[160:163], v[192:195], v[18:21]
	v_mfma_f32_16x16x32_bf16 v[46:49], v[196:199], v[164:167], v[46:49]
	v_mfma_f32_16x16x32_bf16 v[42:45], v[204:207], v[164:167], v[42:45]
	v_mfma_f32_16x16x32_bf16 v[30:33], v[196:199], v[172:175], v[30:33]
	v_mfma_f32_16x16x32_bf16 v[26:29], v[204:207], v[172:175], v[26:29]
	v_mfma_f32_16x16x32_bf16 v[14:17], v[196:199], v[180:183], v[14:17]
	v_mfma_f32_16x16x32_bf16 v[10:13], v[204:207], v[180:183], v[10:13]
	v_mfma_f32_16x16x32_bf16 v[6:9], v[196:199], v[188:191], v[6:9]
	v_mfma_f32_16x16x32_bf16 v[2:5], v[204:207], v[188:191], v[2:5]
	v_mfma_f32_16x16x32_bf16 v[46:49], v[200:203], v[168:171], v[46:49]
	v_mfma_f32_16x16x32_bf16 v[42:45], v[208:211], v[168:171], v[42:45]
	v_mfma_f32_16x16x32_bf16 v[30:33], v[200:203], v[176:179], v[30:33]
	v_mfma_f32_16x16x32_bf16 v[26:29], v[208:211], v[176:179], v[26:29]
	v_mfma_f32_16x16x32_bf16 v[14:17], v[200:203], v[184:187], v[14:17]
	v_mfma_f32_16x16x32_bf16 v[10:13], v[208:211], v[184:187], v[10:13]
	v_mfma_f32_16x16x32_bf16 v[6:9], v[200:203], v[192:195], v[6:9]
	v_mfma_f32_16x16x32_bf16 v[2:5], v[208:211], v[192:195], v[2:5]
	s_setprio 0
	s_add_i32 s59, s59, 2
	s_add_u32 s26, s26, 0x100
	s_addc_u32 s27, s27, 0
	s_add_u32 s57, s57, 0x100
	s_addc_u32 s58, s58, 0
	s_cmp_gt_u32 s59, 29
	s_barrier
	s_cbranch_scc0 .LBB0_970
; DI unsigned pk2(float lo, float hi) { f32x2 v = {lo, hi}; bfv2 b = __builtin_convertvector(v, bfv2); return __builtin_bit_cast(unsigned, b); }
;     DI void operator()(const f32x4 (&acc)[2][2][4][2], const pg8::Unit& u, int wr, int wc, int fr, int fq) const {
;         const int row0 = u.pm * 256 + wr * 64 + fr, col0 = u.pn * 256 + wc * 32 + 8 * fq;
; #pragma unroll
;         for (int ai = 0; ai < 2; ++ai)
; #pragma unroll
;             for (int m = 0; m < 4; ++m) { bf16_t* rowp = O + (size_t)(row0 + ai * 128 + m * 16) * ldc + col0;
; #pragma unroll
;                 for (int bj = 0; bj < 2; ++bj) { const f32x4 v0 = acc[ai][bj][m][0], v1 = acc[ai][bj][m][1];
;                     u32x4 w; w.x = pk2(v0[0], v0[1]); w.y = pk2(v0[2], v0[3]); w.z = pk2(v1[0], v1[1]); w.w = pk2(v1[2], v1[3]);
;                     *(u32x4*)(rowp + bj * 128) = w; } }
	v_lshl_add_u32 v147, s14, 8, v1
	v_lshl_or_b32 v148, s12, 8, v143
	v_ashrrev_i32_e32 v149, 31, v148
	v_mov_b64_e32 v[150:151], s[6:7]
	v_cvt_pk_bf16_f32 v70, v70, v71
	v_cvt_pk_bf16_f32 v71, v72, v73
	v_cvt_pk_bf16_f32 v72, v66, v67
	v_add_u32_e32 v66, 0x80, v147
	v_mad_i64_i32 v[152:153], s[26:27], v147, s54, v[150:151]
	v_lshlrev_b64 v[148:149], 1, v[148:149]
	v_cvt_pk_bf16_f32 v110, v110, v111
	v_cvt_pk_bf16_f32 v111, v112, v113
	v_cvt_pk_bf16_f32 v112, v106, v107
	v_or_b32_e32 v106, 16, v147
	v_mad_i64_i32 v[66:67], s[26:27], v66, s54, v[150:151]
	v_cvt_pk_bf16_f32 v46, v46, v47
	v_cvt_pk_bf16_f32 v47, v48, v49
	v_cvt_pk_bf16_f32 v48, v42, v43
	v_add_u32_e32 v42, 0x90, v147
	v_lshl_add_u64 v[152:153], v[152:153], 0, v[148:149]
	v_cvt_pk_bf16_f32 v113, v108, v109
	v_mad_i64_i32 v[106:107], s[26:27], v106, s54, v[150:151]
	v_cvt_pk_bf16_f32 v94, v94, v95
	v_cvt_pk_bf16_f32 v95, v96, v97
	v_cvt_pk_bf16_f32 v96, v90, v91
	v_or_b32_e32 v90, 32, v147
	v_lshl_add_u64 v[66:67], v[66:67], 0, v[148:149]
	v_cvt_pk_bf16_f32 v49, v44, v45
	v_mad_i64_i32 v[42:43], s[26:27], v42, s54, v[150:151]
	v_cvt_pk_bf16_f32 v30, v30, v31
	v_cvt_pk_bf16_f32 v31, v32, v33
	v_cvt_pk_bf16_f32 v32, v26, v27
	v_add_u32_e32 v26, 0xa0, v147
	global_store_dwordx4 v[152:153], v[110:113], off offset:256
	v_cvt_pk_bf16_f32 v97, v92, v93
	v_mad_i64_i32 v[90:91], s[26:27], v90, s54, v[150:151]
	v_lshl_add_u64 v[110:111], v[106:107], 0, v[148:149]
	v_cvt_pk_bf16_f32 v78, v78, v79
	v_cvt_pk_bf16_f32 v79, v80, v81
	v_cvt_pk_bf16_f32 v80, v74, v75
	v_or_b32_e32 v74, 48, v147
	global_store_dwordx4 v[66:67], v[46:49], off offset:256
	v_cvt_pk_bf16_f32 v33, v28, v29
	v_mad_i64_i32 v[26:27], s[26:27], v26, s54, v[150:151]
	v_lshl_add_u64 v[46:47], v[42:43], 0, v[148:149]
	v_cvt_pk_bf16_f32 v14, v14, v15
	v_cvt_pk_bf16_f32 v15, v16, v17
	v_cvt_pk_bf16_f32 v16, v10, v11
	v_add_u32_e32 v10, 0xb0, v147
	global_store_dwordx4 v[110:111], v[94:97], off offset:256
	v_cvt_pk_bf16_f32 v81, v76, v77
	v_mad_i64_i32 v[74:75], s[26:27], v74, s54, v[150:151]
	v_lshl_add_u64 v[94:95], v[90:91], 0, v[148:149]
	global_store_dwordx4 v[46:47], v[30:33], off offset:256
	v_cvt_pk_bf16_f32 v17, v12, v13
	v_mad_i64_i32 v[10:11], s[26:27], v10, s54, v[150:151]
	v_lshl_add_u64 v[30:31], v[26:27], 0, v[148:149]
	v_cvt_pk_bf16_f32 v126, v126, v127
	v_cvt_pk_bf16_f32 v127, v128, v129
	v_cvt_pk_bf16_f32 v128, v122, v123
	v_cvt_pk_bf16_f32 v129, v124, v125
	v_cvt_pk_bf16_f32 v106, v118, v119
	v_cvt_pk_bf16_f32 v107, v120, v121
	v_cvt_pk_bf16_f32 v108, v114, v115
	v_cvt_pk_bf16_f32 v109, v116, v117
	v_cvt_pk_bf16_f32 v90, v102, v103
	v_cvt_pk_bf16_f32 v91, v104, v105
	v_cvt_pk_bf16_f32 v92, v98, v99
	v_cvt_pk_bf16_f32 v93, v100, v101
	global_store_dwordx4 v[94:95], v[78:81], off offset:256
	v_cvt_pk_bf16_f32 v76, v82, v83
	v_cvt_pk_bf16_f32 v77, v84, v85
	v_lshl_add_u64 v[78:79], v[74:75], 0, v[148:149]
	v_cvt_pk_bf16_f32 v74, v86, v87
	v_cvt_pk_bf16_f32 v75, v88, v89
	v_cvt_pk_bf16_f32 v73, v68, v69
	v_cvt_pk_bf16_f32 v62, v62, v63
	v_cvt_pk_bf16_f32 v63, v64, v65
	v_cvt_pk_bf16_f32 v64, v58, v59
	v_cvt_pk_bf16_f32 v65, v60, v61
	v_cvt_pk_bf16_f32 v42, v54, v55
	v_cvt_pk_bf16_f32 v43, v56, v57
	v_cvt_pk_bf16_f32 v44, v50, v51
	v_cvt_pk_bf16_f32 v45, v52, v53
	v_cvt_pk_bf16_f32 v26, v38, v39
	v_cvt_pk_bf16_f32 v27, v40, v41
	v_cvt_pk_bf16_f32 v28, v34, v35
	v_cvt_pk_bf16_f32 v29, v36, v37
	global_store_dwordx4 v[30:31], v[14:17], off offset:256
	v_cvt_pk_bf16_f32 v12, v18, v19
	v_cvt_pk_bf16_f32 v13, v20, v21
	v_lshl_add_u64 v[14:15], v[10:11], 0, v[148:149]
	v_cvt_pk_bf16_f32 v10, v22, v23
	v_cvt_pk_bf16_f32 v11, v24, v25
	v_cvt_pk_bf16_f32 v6, v6, v7
	v_cvt_pk_bf16_f32 v7, v8, v9
	v_cvt_pk_bf16_f32 v8, v2, v3
	v_cvt_pk_bf16_f32 v9, v4, v5
	s_and_b64 vcc, exec, s[10:11]
	s_mov_b32 s12, s18
	s_mov_b32 s14, s20
	s_mov_b64 s[28:29], s[24:25]
	s_mov_b64 s[26:27], s[22:23]
	global_store_dwordx4 v[152:153], v[126:129], off
	global_store_dwordx4 v[110:111], v[106:109], off
	global_store_dwordx4 v[94:95], v[90:93], off
	global_store_dwordx4 v[78:79], v[74:77], off
	global_store_dwordx4 v[78:79], v[70:73], off offset:256
	global_store_dwordx4 v[66:67], v[62:65], off
	global_store_dwordx4 v[46:47], v[42:45], off
	global_store_dwordx4 v[30:31], v[26:29], off
	global_store_dwordx4 v[14:15], v[10:13], off
	global_store_dwordx4 v[14:15], v[6:9], off offset:256
	s_cbranch_vccz .LBB0_963
	s_waitcnt vmcnt(0)
	s_cmpk_gt_u32 s34, 0xff
	s_cbranch_scc1 .LBB0_974
	s_barrier

; #define PG8_STAGE(bufoff, gbase, voff) do { _Pragma("unroll") for (int _i = 0; _i < 2; ++_i) \
;         __builtin_amdgcn_global_load_lds((const unsigned*)((const char*)(gbase) + (voff)[_i]), (LAS unsigned*)(lds + (bufoff) + ldsw + _i * 8192), 16, 0, 0); } while (0)
; #define PG8_WAIT_V(n) asm volatile("s_waitcnt vmcnt(" #n ")" ::: "memory")
; #define PG8_BAR __builtin_amdgcn_s_barrier()
; template <class Epi>
; DI void gemm_phase(LAS unsigned char* lds, const Gemm g, const StaticOrder& S, const Epi& E) {
;     ...
;     const char* cA = PG8_ABASE(cur); const char* cB = PG8_BBASE(cur);
;     PG8_STAGE(PG8_SB(0, 0), cB, voffB); PG8_STAGE(PG8_SA(0, 0), cA, voffA); PG8_STAGE(PG8_SB(0, 1), cB + hstepB, voffB); PG8_STAGE(PG8_SA(0, 1), cA + hstepA, voffA);
;     if (wr == 1) PG8_BAR;
;     PG8_WAIT_V(4); PG8_BAR;
;     PG8_STAGE(PG8_SB(1, 0), cB + kstep, voffB); PG8_STAGE(PG8_SA(1, 0), cA + kstep, voffA); PG8_STAGE(PG8_SB(1, 1), cB + hstepB + kstep, voffB);
;     PG8_WAIT_V(6); PG8_BAR;
.LBB0_1051:
	s_add_u32 s8, s4, 0xb400000
	s_addc_u32 s9, s5, 0
	s_lshl_b32 s4, s10, 5
	s_mov_b64 s[10:11], 0x80
	s_and_b32 s17, s4, 0x60
	s_add_i32 m0, s13, 0x18000
	v_lshl_add_u64 v[8:9], v[8:9], 0, s[10:11]
	s_lshl_b32 s16, s15, 13
	s_lshl_b32 s18, s17, 7
	s_waitcnt vmcnt(0)
	s_barrier
	global_load_lds_dwordx4 v[8:9], off
	v_lshl_add_u64 v[6:7], v[6:7], 0, s[10:11]
	s_add_i32 m0, s13, 0x1a000
	s_add_i32 s49, s13, 0x8000
	s_add_i32 s50, s13, 0xa000
	global_load_lds_dwordx4 v[6:7], off
	v_lshl_add_u64 v[4:5], v[4:5], 0, s[10:11]
	s_mov_b32 m0, s49
	s_add_u32 s4, s24, 0x80080
	global_load_lds_dwordx4 v[4:5], off
	v_lshl_add_u64 v[2:3], v[2:3], 0, s[10:11]
	s_mov_b32 m0, s50
	s_addc_u32 s5, s25, 0
	global_load_lds_dwordx4 v[2:3], off
	s_add_i32 m0, s13, 0x1c000
	v_lshl_add_u64 v[2:3], s[4:5], 0, v[132:133]
	global_load_lds_dwordx4 v[2:3], off
	v_lshl_add_u64 v[2:3], s[4:5], 0, v[136:137]
	s_add_i32 m0, s13, 0x1e000
	v_lshlrev_b32_e32 v4, 2, v254
	global_load_lds_dwordx4 v[2:3], off
	v_and_b32_e32 v2, 15, v254
	v_lshlrev_b32_e32 v3, 1, v13
	v_lshlrev_b32_e32 v5, 6, v254
	s_movk_i32 s4, 0x3c0
	v_lshl_or_b32 v1, s15, 6, v2
	v_lshl_or_b32 v2, v2, 6, v3
	v_and_b32_e32 v4, 32, v4
	v_and_or_b32 v3, v5, s4, v3
	v_bitop3_b32 v146, s18, v3, v4 bitop3:0xf6
	v_lshlrev_b32_e32 v3, 9, v254
	v_bitop3_b32 v2, v2, s16, v4 bitop3:0xde
	v_and_b32_e32 v3, 0x70000, v3
	v_lshlrev_b32_e32 v4, 12, v12
	v_or3_b32 v3, v10, v3, v4
	v_add_u32_e32 v138, v3, v11
	v_lshlrev_b32_e32 v3, 5, v14
	s_waitcnt vmcnt(6)
	v_and_b32_e32 v3, 0xf0000, v3
	v_or3_b32 v3, v10, v3, v4
	s_add_i32 s52, 0, 0x10000
	s_add_i32 s53, 0, 0x14000
	s_sext_i32_i8 s55, s14
	s_waitcnt lgkmcnt(0)
	s_ashr_i32 s51, s39, 31
	v_or_b32_e32 v147, s17, v13
	v_mov_b32_e32 v139, v133
	v_add_u32_e32 v140, v3, v11
	v_mov_b32_e32 v141, v133
	v_mov_b64_e32 v[142:143], 0x800
	v_mov_b64_e32 v[144:145], 0x7ff
	v_add_u32_e32 v148, s52, v146
	v_add_u32_e32 v149, 0, v2
	v_add_u32_e32 v150, s53, v146
	s_movk_i32 s54, 0x2080
	s_barrier

; #define PG8_STAGE(bufoff, gbase, voff) do { _Pragma("unroll") for (int _i = 0; _i < 2; ++_i) \
;         __builtin_amdgcn_global_load_lds((const unsigned*)((const char*)(gbase) + (voff)[_i]), (LAS unsigned*)(lds + (bufoff) + ldsw + _i * 8192), 16, 0, 0); } while (0)
; #define PG8_WAIT_V(n) asm volatile("s_waitcnt vmcnt(" #n ")" ::: "memory")
; #define PG8_BAR __builtin_amdgcn_s_barrier()
; template <class Epi>
; DI void gemm_phase(LAS unsigned char* lds, const Gemm g, const StaticOrder& S, const Epi& E) {
;     ...
;     const char* cA = PG8_ABASE(cur); const char* cB = PG8_BBASE(cur);
;     PG8_STAGE(PG8_SB(0, 0), cB, voffB); PG8_STAGE(PG8_SA(0, 0), cA, voffA); PG8_STAGE(PG8_SB(0, 1), cB + hstepB, voffB); PG8_STAGE(PG8_SA(0, 1), cA + hstepA, voffA);
;     if (wr == 1) PG8_BAR;
;     PG8_WAIT_V(4); PG8_BAR;
;     PG8_STAGE(PG8_SB(1, 0), cB + kstep, voffB); PG8_STAGE(PG8_SA(1, 0), cA + kstep, voffA); PG8_STAGE(PG8_SB(1, 1), cB + hstepB + kstep, voffB);
;     PG8_WAIT_V(6); PG8_BAR;
.LBB0_1199:
	s_add_u32 s51, s14, 0x200000
	s_addc_u32 s52, s15, 0
	s_add_u32 s53, s14, 0x16000
	s_addc_u32 s54, s15, 0
	s_add_u32 s6, s14, 0x100000
	s_addc_u32 s7, s15, 0
	s_lshl_b32 s8, s8, 5
	s_and_b32 s21, s8, 0x60
	s_mov_b64 s[8:9], 0x80
	s_add_i32 m0, s39, 0x18000
	v_lshl_add_u64 v[8:9], v[8:9], 0, s[8:9]
	s_lshl_b32 s20, s10, 13
	s_lshl_b32 s22, s21, 7
	s_waitcnt vmcnt(0)
	s_barrier
	global_load_lds_dwordx4 v[8:9], off
	v_lshl_add_u64 v[6:7], v[6:7], 0, s[8:9]
	s_add_i32 m0, s39, 0x1a000
	s_add_i32 s55, s39, 0x8000
	s_add_i32 s56, s39, 0xa000
	global_load_lds_dwordx4 v[6:7], off
	v_lshl_add_u64 v[4:5], v[4:5], 0, s[8:9]
	s_mov_b32 m0, s55
	s_add_u32 s14, s28, 0x80080
	global_load_lds_dwordx4 v[4:5], off
	v_lshl_add_u64 v[2:3], v[2:3], 0, s[8:9]
	s_mov_b32 m0, s56
	s_addc_u32 s15, s29, 0
	global_load_lds_dwordx4 v[2:3], off
	s_add_i32 m0, s39, 0x1c000
	v_lshl_add_u64 v[2:3], s[14:15], 0, v[160:161]
	global_load_lds_dwordx4 v[2:3], off
	v_lshl_add_u64 v[2:3], s[14:15], 0, v[164:165]
	s_add_i32 m0, s39, 0x1e000
	v_and_b32_e32 v1, 15, v254
	global_load_lds_dwordx4 v[2:3], off
	v_bfe_u32 v2, v254, 4, 2
	v_lshlrev_b32_e32 v3, 4, v2
	v_lshlrev_b32_e32 v4, 2, v254
	v_lshl_or_b32 v166, s10, 6, v1
	v_lshl_or_b32 v1, v1, 6, v3
	v_and_b32_e32 v4, 32, v4
	s_sext_i32_i8 s62, s4
	v_bitop3_b32 v5, v1, s20, v4 bitop3:0xde
	v_lshlrev_b32_e32 v1, 6, v254
	s_movk_i32 s4, 0x3c0
	v_and_or_b32 v1, v1, s4, v3
	s_waitcnt vmcnt(6)
	v_bitop3_b32 v1, s22, v1, v4 bitop3:0xf6
	v_mov_b32_e32 v167, v161
	v_or_b32_e32 v170, 16, v166
	v_mov_b32_e32 v171, v161
	v_or_b32_e32 v174, 32, v166
	v_mov_b32_e32 v175, v161
	v_or_b32_e32 v178, 48, v166
	v_mov_b32_e32 v179, v161
	v_add_u32_e32 v182, 0x80, v166
	v_mov_b32_e32 v183, v161
	v_add_u32_e32 v186, 0x90, v166
	v_mov_b32_e32 v187, v161
	v_add_u32_e32 v190, 0xa0, v166
	v_mov_b32_e32 v191, v161
	v_add_u32_e32 v194, 0xb0, v166
	v_mov_b32_e32 v195, v161
	s_add_i32 s57, 0, 0x10000
	s_add_i32 s58, 0, 0x14000
	v_lshlrev_b64 v[168:169], 13, v[166:167]
	v_lshlrev_b64 v[172:173], 13, v[170:171]
	v_lshlrev_b64 v[176:177], 13, v[174:175]
	v_lshlrev_b64 v[180:181], 13, v[178:179]
	v_lshlrev_b64 v[184:185], 13, v[182:183]
	v_lshlrev_b64 v[188:189], 13, v[186:187]
	v_lshlrev_b64 v[192:193], 13, v[190:191]
	v_lshlrev_b64 v[196:197], 13, v[194:195]
	v_lshl_or_b32 v167, v2, 2, s21
	v_add3_u32 v198, v12, v10, v11
	v_mov_b32_e32 v199, v161
	v_add3_u32 v200, v13, v10, v11
	v_mov_b32_e32 v201, v161
	v_add_u32_e32 v171, s57, v1
	v_add_u32_e32 v175, 0, v5
	v_add_u32_e32 v179, s58, v1
	s_movk_i32 s59, 0x1800
	s_mov_b32 s10, 0x3fd744fd
	s_mov_b32 s4, s5
	s_barrier

; #define PG8_STAGE(bufoff, gbase, voff) do { _Pragma("unroll") for (int _i = 0; _i < 2; ++_i) \
;         __builtin_amdgcn_global_load_lds((const unsigned*)((const char*)(gbase) + (voff)[_i]), (LAS unsigned*)(lds + (bufoff) + ldsw + _i * 8192), 16, 0, 0); } while (0)
; #define PG8_LDA(dst, b, h) do { _Pragma("unroll") for (int m = 0; m < 4; ++m) _Pragma("unroll") for (int k = 0; k < 2; ++k) dst[m][k] = *(const LAS bf16x8*)(lds + PG8_SA(b, h) + aoff + m * 2048 + k * 1024); } while (0)
; #define PG8_LDB(dst, b, h) do { _Pragma("unroll") for (int n = 0; n < 2; ++n) _Pragma("unroll") for (int k = 0; k < 2; ++k) dst[n][k] = *(const LAS bf16x8*)(lds + PG8_SB(b, h) + boff + n * 2048 + k * 1024); } while (0)
; #define PG8_MMA(ai, bj, At, Bt) do { __builtin_amdgcn_s_setprio(1); _Pragma("unroll") for (int m = 0; m < 4; ++m) _Pragma("unroll") for (int n = 0; n < 2; ++n) _Pragma("unroll") for (int k = 0; k < 2; ++k) \
;         acc[ai][bj][m][n] = __builtin_amdgcn_mfma_f32_16x16x32_bf16(Bt[n][k], At[m][k], acc[ai][bj][m][n], 0, 0, 0); __builtin_amdgcn_s_setprio(0); } while (0)
; #define PG8_WAIT_L(n) asm volatile("s_waitcnt lgkmcnt(" #n ")" ::: "memory")
; #define PG8_BAR __builtin_amdgcn_s_barrier()
; #define PG8_SCHED __builtin_amdgcn_sched_barrier(0)
; template <class Epi>
; DI void gemm_phase(LAS unsigned char* lds, const Gemm g, const StaticOrder& S, const Epi& E) {
;     ...
;             PG8_LDB(B0, 0, 0); PG8_SCHED; PG8_LDA(At, 0, 0); PG8_STAGE(PG8_SA(1, 1), a1 + hstepA, voffA);
;             PG8_WAIT_L(8); PG8_BAR; PG8_WAIT_L(0); PG8_MMA(0, 0, At, B0); PG8_BAR; PG8_SCHED;
;             PG8_LDB(B1, 0, 1); PG8_STAGE(PG8_SB(0, 0), b2, voffB);
;             PG8_BAR; PG8_WAIT_L(0); PG8_MMA(0, 1, At, B1); PG8_BAR;
;             PG8_LDA(At, 0, 1); PG8_STAGE(PG8_SA(0, 0), a2, voffA);
;             PG8_BAR; PG8_WAIT_L(0); PG8_MMA(1, 0, At, B0); PG8_BAR; PG8_SCHED;
;             PG8_STAGE(PG8_SB(0, 1), b2 + hstepB, voffB);
.LBB0_1205:
	ds_read_b128 v[130:133], v171
	ds_read_b128 v[134:137], v171 offset:1024
	ds_read_b128 v[138:141], v171 offset:2048
	ds_read_b128 v[142:145], v171 offset:3072
	s_add_u32 s28, s26, 0xffefc080
	s_addc_u32 s29, s27, -1
	s_cmp_eq_u32 s66, 28
	s_cselect_b32 s31, s23, s29
	s_cselect_b32 s30, s22, s28
	s_cselect_b32 s29, s21, s65
	s_cselect_b32 s28, s63, s64
	v_lshl_add_u64 v[214:215], s[26:27], 0, v[198:199]
	s_add_i32 m0, s39, 0xc000
	ds_read_b128 v[146:149], v175
	ds_read_b128 v[150:153], v175 offset:1024
	ds_read_b128 v[154:157], v175 offset:2048
	ds_read_b128 v[202:205], v175 offset:3072
	ds_read_b128 v[206:209], v175 offset:4096
	ds_read_b128 v[210:213], v175 offset:5120
	ds_read_b128 v[218:221], v175 offset:6144
	ds_read_b128 v[222:225], v175 offset:7168
	global_load_lds_dwordx4 v[214:215], off
	v_lshl_add_u64 v[214:215], s[26:27], 0, v[200:201]
	s_add_i32 m0, s39, 0xe000
	s_nop 0
	global_load_lds_dwordx4 v[214:215], off
	ds_read_b128 v[226:229], v179
	ds_read_b128 v[230:233], v179 offset:1024
	ds_read_b128 v[234:237], v179 offset:2048
	ds_read_b128 v[238:241], v179 offset:3072
	s_waitcnt lgkmcnt(0)
	s_waitcnt vmcnt(8)
	s_barrier
	s_setprio 1
	v_mfma_f32_16x16x32_bf16 v[126:129], v[130:133], v[146:149], v[126:129]
	v_mfma_f32_16x16x32_bf16 v[102:105], v[138:141], v[146:149], v[102:105]
	v_mfma_f32_16x16x32_bf16 v[122:125], v[130:133], v[154:157], v[122:125]
	v_mfma_f32_16x16x32_bf16 v[94:97], v[138:141], v[154:157], v[94:97]
	v_mfma_f32_16x16x32_bf16 v[118:121], v[130:133], v[206:209], v[118:121]
	v_mfma_f32_16x16x32_bf16 v[86:89], v[138:141], v[206:209], v[86:89]
	v_mfma_f32_16x16x32_bf16 v[114:117], v[130:133], v[218:221], v[114:117]
	v_mfma_f32_16x16x32_bf16 v[82:85], v[138:141], v[218:221], v[82:85]
	v_mfma_f32_16x16x32_bf16 v[126:129], v[134:137], v[150:153], v[126:129]
	v_mfma_f32_16x16x32_bf16 v[102:105], v[142:145], v[150:153], v[102:105]
	v_mfma_f32_16x16x32_bf16 v[122:125], v[134:137], v[202:205], v[122:125]
	v_mfma_f32_16x16x32_bf16 v[94:97], v[142:145], v[202:205], v[94:97]
	v_mfma_f32_16x16x32_bf16 v[118:121], v[134:137], v[210:213], v[118:121]
	v_mfma_f32_16x16x32_bf16 v[86:89], v[142:145], v[210:213], v[86:89]
	v_mfma_f32_16x16x32_bf16 v[114:117], v[134:137], v[222:225], v[114:117]
	v_mfma_f32_16x16x32_bf16 v[82:85], v[142:145], v[222:225], v[82:85]
	v_mfma_f32_16x16x32_bf16 v[66:69], v[226:229], v[146:149], v[66:69]
	v_mfma_f32_16x16x32_bf16 v[38:41], v[234:237], v[146:149], v[38:41]
	v_mfma_f32_16x16x32_bf16 v[58:61], v[226:229], v[154:157], v[58:61]
	v_mfma_f32_16x16x32_bf16 v[30:33], v[234:237], v[154:157], v[30:33]
	v_mfma_f32_16x16x32_bf16 v[54:57], v[226:229], v[206:209], v[54:57]
	v_mfma_f32_16x16x32_bf16 v[22:25], v[234:237], v[206:209], v[22:25]
	v_mfma_f32_16x16x32_bf16 v[50:53], v[226:229], v[218:221], v[50:53]
	v_mfma_f32_16x16x32_bf16 v[18:21], v[234:237], v[218:221], v[18:21]
	v_mfma_f32_16x16x32_bf16 v[66:69], v[230:233], v[150:153], v[66:69]
	v_mfma_f32_16x16x32_bf16 v[38:41], v[238:241], v[150:153], v[38:41]
	v_mfma_f32_16x16x32_bf16 v[58:61], v[230:233], v[202:205], v[58:61]
	v_mfma_f32_16x16x32_bf16 v[30:33], v[238:241], v[202:205], v[30:33]
	v_mfma_f32_16x16x32_bf16 v[54:57], v[230:233], v[210:213], v[54:57]
	v_mfma_f32_16x16x32_bf16 v[22:25], v[238:241], v[210:213], v[22:25]
	v_mfma_f32_16x16x32_bf16 v[50:53], v[230:233], v[222:225], v[50:53]
	v_mfma_f32_16x16x32_bf16 v[18:21], v[238:241], v[222:225], v[18:21]
	s_setprio 0
	s_barrier
	s_add_i32 s67, s57, s38
	v_lshl_add_u64 v[214:215], s[28:29], 0, v[160:161]
	s_mov_b32 m0, s67
	s_nop 0
	global_load_lds_dwordx4 v[214:215], off
	v_lshl_add_u64 v[242:243], s[28:29], 0, v[164:165]
	s_add_i32 m0, s67, 0x2000
	s_nop 0
	global_load_lds_dwordx4 v[242:243], off
	s_mov_b32 m0, s39
	v_lshl_add_u64 v[244:245], s[30:31], 0, v[158:159]
	ds_read_b128 v[146:149], v175 offset:16384
	ds_read_b128 v[150:153], v175 offset:17408
	ds_read_b128 v[154:157], v175 offset:18432
	ds_read_b128 v[202:205], v175 offset:19456
	ds_read_b128 v[206:209], v175 offset:20480
	ds_read_b128 v[210:213], v175 offset:21504
	ds_read_b128 v[218:221], v175 offset:22528
	ds_read_b128 v[222:225], v175 offset:23552
	global_load_lds_dwordx4 v[244:245], off
	v_lshl_add_u64 v[246:247], s[30:31], 0, v[162:163]
	s_mov_b32 m0, s48
	s_nop 0
	global_load_lds_dwordx4 v[246:247], off
	s_add_u32 s68, s28, 0x80000
	s_addc_u32 s69, s29, 0
	s_add_i32 s67, s58, s38
	v_lshl_add_u64 v[250:251], s[68:69], 0, v[160:161]
	s_mov_b32 m0, s67
	s_nop 0
	global_load_lds_dwordx4 v[250:251], off
	v_lshl_add_u64 v[250:251], s[68:69], 0, v[164:165]
	s_add_i32 m0, s67, 0x2000
	s_nop 0
	global_load_lds_dwordx4 v[250:251], off
	s_waitcnt lgkmcnt(0)
	s_waitcnt vmcnt(8)
	s_barrier
; #define PG8_STAGE(bufoff, gbase, voff) do { _Pragma("unroll") for (int _i = 0; _i < 2; ++_i) \
;         __builtin_amdgcn_global_load_lds((const unsigned*)((const char*)(gbase) + (voff)[_i]), (LAS unsigned*)(lds + (bufoff) + ldsw + _i * 8192), 16, 0, 0); } while (0)
; #define PG8_LDA(dst, b, h) do { _Pragma("unroll") for (int m = 0; m < 4; ++m) _Pragma("unroll") for (int k = 0; k < 2; ++k) dst[m][k] = *(const LAS bf16x8*)(lds + PG8_SA(b, h) + aoff + m * 2048 + k * 1024); } while (0)
; #define PG8_LDB(dst, b, h) do { _Pragma("unroll") for (int n = 0; n < 2; ++n) _Pragma("unroll") for (int k = 0; k < 2; ++k) dst[n][k] = *(const LAS bf16x8*)(lds + PG8_SB(b, h) + boff + n * 2048 + k * 1024); } while (0)
; #define PG8_MMA(ai, bj, At, Bt) do { __builtin_amdgcn_s_setprio(1); _Pragma("unroll") for (int m = 0; m < 4; ++m) _Pragma("unroll") for (int n = 0; n < 2; ++n) _Pragma("unroll") for (int k = 0; k < 2; ++k) \
;         acc[ai][bj][m][n] = __builtin_amdgcn_mfma_f32_16x16x32_bf16(Bt[n][k], At[m][k], acc[ai][bj][m][n], 0, 0, 0); __builtin_amdgcn_s_setprio(0); } while (0)
; #define PG8_WAIT_V(n) asm volatile("s_waitcnt vmcnt(" #n ")" ::: "memory")
; #define PG8_WAIT_L(n) asm volatile("s_waitcnt lgkmcnt(" #n ")" ::: "memory")
; #define PG8_BAR __builtin_amdgcn_s_barrier()
; #define PG8_SCHED __builtin_amdgcn_sched_barrier(0)
; template <class Epi>
; DI void gemm_phase(LAS unsigned char* lds, const Gemm g, const StaticOrder& S, const Epi& E) {
;     ...
;             PG8_BAR; PG8_WAIT_L(0); PG8_MMA(1, 0, At, B0); PG8_BAR; PG8_SCHED;
;             PG8_STAGE(PG8_SB(0, 1), b2 + hstepB, voffB);
;             PG8_WAIT_V(6); PG8_BAR; PG8_MMA(1, 1, At, B1); PG8_BAR;
;             PG8_LDB(B0, 1, 0); PG8_SCHED; PG8_LDA(At, 1, 0); PG8_STAGE(PG8_SA(0, 1), a2 + hstepA, voffA);
;             PG8_WAIT_L(8); PG8_BAR; PG8_WAIT_L(0); PG8_MMA(0, 0, At, B0); PG8_BAR; PG8_SCHED;
;             PG8_LDB(B1, 1, 1); PG8_STAGE(PG8_SB(1, 0), b3, voffB);
;             PG8_BAR; PG8_WAIT_L(0); PG8_MMA(0, 1, At, B1); PG8_BAR;
	s_setprio 1
	v_mfma_f32_16x16x32_bf16 v[110:113], v[130:133], v[146:149], v[110:113]
	v_mfma_f32_16x16x32_bf16 v[78:81], v[138:141], v[146:149], v[78:81]
	v_mfma_f32_16x16x32_bf16 v[106:109], v[130:133], v[154:157], v[106:109]
	v_mfma_f32_16x16x32_bf16 v[74:77], v[138:141], v[154:157], v[74:77]
	v_mfma_f32_16x16x32_bf16 v[98:101], v[130:133], v[206:209], v[98:101]
	v_mfma_f32_16x16x32_bf16 v[70:73], v[138:141], v[206:209], v[70:73]
	v_mfma_f32_16x16x32_bf16 v[90:93], v[130:133], v[218:221], v[90:93]
	v_mfma_f32_16x16x32_bf16 v[62:65], v[138:141], v[218:221], v[62:65]
	v_mfma_f32_16x16x32_bf16 v[110:113], v[134:137], v[150:153], v[110:113]
	v_mfma_f32_16x16x32_bf16 v[78:81], v[142:145], v[150:153], v[78:81]
	v_mfma_f32_16x16x32_bf16 v[106:109], v[134:137], v[202:205], v[106:109]
	v_mfma_f32_16x16x32_bf16 v[74:77], v[142:145], v[202:205], v[74:77]
	v_mfma_f32_16x16x32_bf16 v[98:101], v[134:137], v[210:213], v[98:101]
	v_mfma_f32_16x16x32_bf16 v[70:73], v[142:145], v[210:213], v[70:73]
	v_mfma_f32_16x16x32_bf16 v[90:93], v[134:137], v[222:225], v[90:93]
	v_mfma_f32_16x16x32_bf16 v[62:65], v[142:145], v[222:225], v[62:65]
	v_mfma_f32_16x16x32_bf16 v[46:49], v[226:229], v[146:149], v[46:49]
	v_mfma_f32_16x16x32_bf16 v[14:17], v[234:237], v[146:149], v[14:17]
	v_mfma_f32_16x16x32_bf16 v[42:45], v[226:229], v[154:157], v[42:45]
	v_mfma_f32_16x16x32_bf16 v[10:13], v[234:237], v[154:157], v[10:13]
	v_mfma_f32_16x16x32_bf16 v[34:37], v[226:229], v[206:209], v[34:37]
	v_mfma_f32_16x16x32_bf16 v[6:9], v[234:237], v[206:209], v[6:9]
	v_mfma_f32_16x16x32_bf16 v[26:29], v[226:229], v[218:221], v[26:29]
	v_mfma_f32_16x16x32_bf16 v[2:5], v[234:237], v[218:221], v[2:5]
	v_mfma_f32_16x16x32_bf16 v[46:49], v[230:233], v[150:153], v[46:49]
	v_mfma_f32_16x16x32_bf16 v[14:17], v[238:241], v[150:153], v[14:17]
	v_mfma_f32_16x16x32_bf16 v[42:45], v[230:233], v[202:205], v[42:45]
	v_mfma_f32_16x16x32_bf16 v[10:13], v[238:241], v[202:205], v[10:13]
	v_mfma_f32_16x16x32_bf16 v[34:37], v[230:233], v[210:213], v[34:37]
	v_mfma_f32_16x16x32_bf16 v[6:9], v[238:241], v[210:213], v[6:9]
	v_mfma_f32_16x16x32_bf16 v[26:29], v[230:233], v[222:225], v[26:29]
	v_mfma_f32_16x16x32_bf16 v[2:5], v[238:241], v[222:225], v[2:5]
	s_setprio 0
	s_add_i32 s67, 0, 0x18000
	v_add_u32_e32 v142, s67, v1
	s_barrier
	ds_read_b128 v[130:133], v142
	ds_read_b128 v[134:137], v142 offset:1024
	ds_read_b128 v[138:141], v142 offset:2048
	ds_read_b128 v[142:145], v142 offset:3072
	s_add_u32 s30, s30, 0x104000
	s_addc_u32 s31, s31, 0
	s_mov_b32 m0, s49
	v_lshl_add_u64 v[226:227], s[30:31], 0, v[158:159]
	ds_read_b128 v[146:149], v175 offset:32768
	ds_read_b128 v[150:153], v175 offset:33792
	ds_read_b128 v[154:157], v175 offset:34816
	ds_read_b128 v[202:205], v175 offset:35840
	ds_read_b128 v[206:209], v175 offset:36864
	ds_read_b128 v[210:213], v175 offset:37888
	ds_read_b128 v[218:221], v175 offset:38912
	ds_read_b128 v[222:225], v175 offset:39936
	global_load_lds_dwordx4 v[226:227], off
	v_lshl_add_u64 v[226:227], s[30:31], 0, v[162:163]
	s_mov_b32 m0, s50
	s_nop 0
	global_load_lds_dwordx4 v[226:227], off
	s_add_i32 s30, 0, 0x1c000
	v_add_u32_e32 v183, s30, v1
	ds_read_b128 v[226:229], v183
	ds_read_b128 v[230:233], v183 offset:1024
	ds_read_b128 v[234:237], v183 offset:2048
	ds_read_b128 v[238:241], v183 offset:3072
	s_waitcnt lgkmcnt(0)
	s_waitcnt vmcnt(8)
	s_barrier
	s_setprio 1
	v_mfma_f32_16x16x32_bf16 v[126:129], v[130:133], v[146:149], v[126:129]
	v_mfma_f32_16x16x32_bf16 v[102:105], v[138:141], v[146:149], v[102:105]
	v_mfma_f32_16x16x32_bf16 v[122:125], v[130:133], v[154:157], v[122:125]
	v_mfma_f32_16x16x32_bf16 v[94:97], v[138:141], v[154:157], v[94:97]
	v_mfma_f32_16x16x32_bf16 v[118:121], v[130:133], v[206:209], v[118:121]
	v_mfma_f32_16x16x32_bf16 v[86:89], v[138:141], v[206:209], v[86:89]
	v_mfma_f32_16x16x32_bf16 v[114:117], v[130:133], v[218:221], v[114:117]
	v_mfma_f32_16x16x32_bf16 v[82:85], v[138:141], v[218:221], v[82:85]
	v_mfma_f32_16x16x32_bf16 v[126:129], v[134:137], v[150:153], v[126:129]
	v_mfma_f32_16x16x32_bf16 v[102:105], v[142:145], v[150:153], v[102:105]
	v_mfma_f32_16x16x32_bf16 v[122:125], v[134:137], v[202:205], v[122:125]
	v_mfma_f32_16x16x32_bf16 v[94:97], v[142:145], v[202:205], v[94:97]
	v_mfma_f32_16x16x32_bf16 v[118:121], v[134:137], v[210:213], v[118:121]
	v_mfma_f32_16x16x32_bf16 v[86:89], v[142:145], v[210:213], v[86:89]
	v_mfma_f32_16x16x32_bf16 v[114:117], v[134:137], v[222:225], v[114:117]
	v_mfma_f32_16x16x32_bf16 v[82:85], v[142:145], v[222:225], v[82:85]
	v_mfma_f32_16x16x32_bf16 v[66:69], v[226:229], v[146:149], v[66:69]
	v_mfma_f32_16x16x32_bf16 v[38:41], v[234:237], v[146:149], v[38:41]
	v_mfma_f32_16x16x32_bf16 v[58:61], v[226:229], v[154:157], v[58:61]
	v_mfma_f32_16x16x32_bf16 v[30:33], v[234:237], v[154:157], v[30:33]
	v_mfma_f32_16x16x32_bf16 v[54:57], v[226:229], v[206:209], v[54:57]
	v_mfma_f32_16x16x32_bf16 v[22:25], v[234:237], v[206:209], v[22:25]
	v_mfma_f32_16x16x32_bf16 v[50:53], v[226:229], v[218:221], v[50:53]
	v_mfma_f32_16x16x32_bf16 v[18:21], v[234:237], v[218:221], v[18:21]
	v_mfma_f32_16x16x32_bf16 v[66:69], v[230:233], v[150:153], v[66:69]
	v_mfma_f32_16x16x32_bf16 v[38:41], v[238:241], v[150:153], v[38:41]
	v_mfma_f32_16x16x32_bf16 v[58:61], v[230:233], v[202:205], v[58:61]
	v_mfma_f32_16x16x32_bf16 v[30:33], v[238:241], v[202:205], v[30:33]
	v_mfma_f32_16x16x32_bf16 v[54:57], v[230:233], v[210:213], v[54:57]
	v_mfma_f32_16x16x32_bf16 v[22:25], v[238:241], v[210:213], v[22:25]
	v_mfma_f32_16x16x32_bf16 v[50:53], v[230:233], v[222:225], v[50:53]
	v_mfma_f32_16x16x32_bf16 v[18:21], v[238:241], v[222:225], v[18:21]
	s_setprio 0
	s_barrier
; #define PG8_STAGE(bufoff, gbase, voff) do { _Pragma("unroll") for (int _i = 0; _i < 2; ++_i) \
;         __builtin_amdgcn_global_load_lds((const unsigned*)((const char*)(gbase) + (voff)[_i]), (LAS unsigned*)(lds + (bufoff) + ldsw + _i * 8192), 16, 0, 0); } while (0)
; #define PG8_LDA(dst, b, h) do { _Pragma("unroll") for (int m = 0; m < 4; ++m) _Pragma("unroll") for (int k = 0; k < 2; ++k) dst[m][k] = *(const LAS bf16x8*)(lds + PG8_SA(b, h) + aoff + m * 2048 + k * 1024); } while (0)
; #define PG8_WAIT_V(n) asm volatile("s_waitcnt vmcnt(" #n ")" ::: "memory")
; template <class Epi>
; DI void gemm_phase(LAS unsigned char* lds, const Gemm g, const StaticOrder& S, const Epi& E) {
;     ...
;             PG8_LDB(B1, 1, 1); PG8_STAGE(PG8_SB(1, 0), b3, voffB);
;             PG8_BAR; PG8_WAIT_L(0); PG8_MMA(0, 1, At, B1); PG8_BAR;
;             PG8_LDA(At, 1, 1); PG8_STAGE(PG8_SA(1, 0), a3, voffA);
;             PG8_BAR; PG8_WAIT_L(0); PG8_MMA(1, 0, At, B0); PG8_BAR; PG8_SCHED;
;             PG8_STAGE(PG8_SB(1, 1), b3 + hstepB, voffB);
;             PG8_WAIT_V(6); PG8_BAR; PG8_MMA(1, 1, At, B1); PG8_BAR;
;         }
;         E(acc, cur, wr, wc, fr, fq);
;         if (!has_next) break;
;     DI void operator()(const f32x4 (&acc)[2][2][4][2], const pg8::Unit& u, int wr, int wc, int fr, int fq) const {
;         const int rowt = row_base + u.pm * 256, col0 = u.pn * 256 + wc * 32 + 4 * fq, rl = wr * 64 + fr;
;         const int cd = cond_of_row(rowt);
;         const float* gtp = gt0 + (size_t)cd * 6144;
;         float* dbase = rowt < TL ? out + (size_t)rowt * D : ctxv + (size_t)(rowt - TL) * D;
;         const float* sbase = mode ? (const float*)dbase : (rowt < TL ? xin + (size_t)rowt * D : cin + (size_t)(rowt - TL) * D);
; #pragma unroll
;         for (int bj = 0; bj < 2; ++bj) {
;             f32x4 gv[2], gg[2], bb[2], xv[2][8];
; #pragma unroll
;             for (int n = 0; n < 2; ++n) {
;                 const int c = col0 + bj * 128 + n * 16;
;                 gv[n] = *(const f32x4*)(gtp + c);
;                 gg[n] = (f32x4){1.f, 1.f, 1.f, 1.f}; bb[n] = (f32x4){0.f, 0.f, 0.f, 0.f};
;                 if (mode) { gg[n] = *(const f32x4*)(lg + c); bb[n] = *(const f32x4*)(lb + c); }
; #pragma unroll
;                 for (int q = 0; q < 8; ++q) { const int rr = rl + (q >> 2) * 128 + (q & 3) * 16; xv[n][q] = *(const f32x4*)(sbase + (size_t)rr * D + c); }
	s_add_i32 s31, s67, s38
	v_lshl_add_u64 v[214:215], v[214:215], 0, s[8:9]
	s_mov_b32 m0, s31
	s_nop 0
	global_load_lds_dwordx4 v[214:215], off
	v_lshl_add_u64 v[214:215], v[242:243], 0, s[8:9]
	s_add_i32 m0, s31, 0x2000
	s_nop 0
	global_load_lds_dwordx4 v[214:215], off
	s_mov_b32 m0, s55
	v_lshl_add_u64 v[214:215], v[244:245], 0, s[8:9]
	ds_read_b128 v[146:149], v175 offset:49152
	ds_read_b128 v[150:153], v175 offset:50176
	ds_read_b128 v[154:157], v175 offset:51200
	ds_read_b128 v[202:205], v175 offset:52224
	ds_read_b128 v[206:209], v175 offset:53248
	ds_read_b128 v[210:213], v175 offset:54272
	ds_read_b128 v[218:221], v175 offset:55296
	ds_read_b128 v[222:225], v175 offset:56320
	global_load_lds_dwordx4 v[214:215], off
	v_lshl_add_u64 v[214:215], v[246:247], 0, s[8:9]
	s_mov_b32 m0, s56
	s_nop 0
	global_load_lds_dwordx4 v[214:215], off
	s_add_u32 s28, s28, 0x80080
	s_addc_u32 s29, s29, 0
	s_add_i32 s30, s30, s38
	v_lshl_add_u64 v[250:251], s[28:29], 0, v[160:161]
	s_mov_b32 m0, s30
	s_nop 0
	global_load_lds_dwordx4 v[250:251], off
	v_lshl_add_u64 v[250:251], s[28:29], 0, v[164:165]
	s_add_i32 m0, s30, 0x2000
	s_nop 0
	global_load_lds_dwordx4 v[250:251], off
	s_waitcnt lgkmcnt(0)
	s_waitcnt vmcnt(8)
	s_barrier
	s_setprio 1
	v_mfma_f32_16x16x32_bf16 v[110:113], v[130:133], v[146:149], v[110:113]
	v_mfma_f32_16x16x32_bf16 v[78:81], v[138:141], v[146:149], v[78:81]
	v_mfma_f32_16x16x32_bf16 v[106:109], v[130:133], v[154:157], v[106:109]
	v_mfma_f32_16x16x32_bf16 v[74:77], v[138:141], v[154:157], v[74:77]
	v_mfma_f32_16x16x32_bf16 v[98:101], v[130:133], v[206:209], v[98:101]
	v_mfma_f32_16x16x32_bf16 v[70:73], v[138:141], v[206:209], v[70:73]
	v_mfma_f32_16x16x32_bf16 v[90:93], v[130:133], v[218:221], v[90:93]
	v_mfma_f32_16x16x32_bf16 v[62:65], v[138:141], v[218:221], v[62:65]
	v_mfma_f32_16x16x32_bf16 v[110:113], v[134:137], v[150:153], v[110:113]
	v_mfma_f32_16x16x32_bf16 v[78:81], v[142:145], v[150:153], v[78:81]
	v_mfma_f32_16x16x32_bf16 v[106:109], v[134:137], v[202:205], v[106:109]
	v_mfma_f32_16x16x32_bf16 v[74:77], v[142:145], v[202:205], v[74:77]
	v_mfma_f32_16x16x32_bf16 v[98:101], v[134:137], v[210:213], v[98:101]
	v_mfma_f32_16x16x32_bf16 v[70:73], v[142:145], v[210:213], v[70:73]
	v_mfma_f32_16x16x32_bf16 v[90:93], v[134:137], v[222:225], v[90:93]
	v_mfma_f32_16x16x32_bf16 v[62:65], v[142:145], v[222:225], v[62:65]
	v_mfma_f32_16x16x32_bf16 v[46:49], v[226:229], v[146:149], v[46:49]
	v_mfma_f32_16x16x32_bf16 v[14:17], v[234:237], v[146:149], v[14:17]
	v_mfma_f32_16x16x32_bf16 v[42:45], v[226:229], v[154:157], v[42:45]
	v_mfma_f32_16x16x32_bf16 v[10:13], v[234:237], v[154:157], v[10:13]
	v_mfma_f32_16x16x32_bf16 v[34:37], v[226:229], v[206:209], v[34:37]
	v_mfma_f32_16x16x32_bf16 v[6:9], v[234:237], v[206:209], v[6:9]
	v_mfma_f32_16x16x32_bf16 v[26:29], v[226:229], v[218:221], v[26:29]
	v_mfma_f32_16x16x32_bf16 v[2:5], v[234:237], v[218:221], v[2:5]
	v_mfma_f32_16x16x32_bf16 v[46:49], v[230:233], v[150:153], v[46:49]
	v_mfma_f32_16x16x32_bf16 v[14:17], v[238:241], v[150:153], v[14:17]
	v_mfma_f32_16x16x32_bf16 v[42:45], v[230:233], v[202:205], v[42:45]
	v_mfma_f32_16x16x32_bf16 v[10:13], v[238:241], v[202:205], v[10:13]
	v_mfma_f32_16x16x32_bf16 v[34:37], v[230:233], v[210:213], v[34:37]
	v_mfma_f32_16x16x32_bf16 v[6:9], v[238:241], v[210:213], v[6:9]
	v_mfma_f32_16x16x32_bf16 v[26:29], v[230:233], v[222:225], v[26:29]
	v_mfma_f32_16x16x32_bf16 v[2:5], v[238:241], v[222:225], v[2:5]
	s_setprio 0
	s_add_i32 s66, s66, 2
	s_add_u32 s26, s26, 0x100
	s_addc_u32 s27, s27, 0
	s_add_u32 s64, s64, 0x100
	s_addc_u32 s65, s65, 0
	s_cmp_gt_u32 s66, 29
	s_barrier
	s_cbranch_scc0 .LBB0_1205
	s_lshl_b32 s28, s61, 8
	s_add_i32 s21, s28, 0x8000
	s_cmp_gt_u32 s28, 0xffff7fff
	s_cselect_b32 s26, s59, 0x3000
	s_cmpk_gt_i32 s61, 0xffbf
	s_cselect_b32 s26, s26, 0
	s_lshl_b32 s26, s26, 2
	s_add_u32 s26, s53, s26
	s_addc_u32 s27, s54, 0
	s_ashr_i32 s29, s21, 31
	s_cmp_lt_i32 s61, 0
	s_cselect_b32 s29, s29, 0
	s_cselect_b32 s28, s21, s28
	v_lshl_or_b32 v130, s62, 8, v167
	s_cselect_b32 s30, s13, s52
	s_cselect_b32 s31, s12, s51
	s_lshl_b64 s[28:29], s[28:29], 13
	s_add_u32 s28, s31, s28
	v_ashrrev_i32_e32 v131, 31, v130
	s_addc_u32 s29, s30, s29
	v_lshlrev_b64 v[130:131], 2, v[130:131]
	v_add_lshl_u32 v132, s21, v166, 1
	v_lshl_add_u64 v[230:231], s[28:29], 0, v[130:131]
	v_ashrrev_i32_e32 v133, 31, v132
	v_lshl_add_u64 v[202:203], v[230:231], 0, v[168:169]
	v_lshl_add_u64 v[206:207], v[132:133], 2, s[6:7]
	global_load_dwordx4 v[212:215], v[202:203], off
	global_load_dwordx2 v[208:209], v[206:207], off
	v_lshl_add_u64 v[224:225], s[16:17], 0, v[130:131]
	v_lshl_add_u64 v[226:227], s[18:19], 0, v[130:131]
	global_load_dwordx4 v[146:149], v[224:225], off
	global_load_dwordx4 v[150:153], v[226:227], off
	v_lshl_add_u64 v[228:229], s[26:27], 0, v[130:131]
	global_load_dwordx4 v[142:145], v[228:229], off
	v_add_lshl_u32 v134, s21, v170, 1
	v_ashrrev_i32_e32 v135, 31, v134
	v_lshl_add_u64 v[204:205], v[230:231], 0, v[172:173]
	global_load_dwordx4 v[130:133], v[224:225], off offset:64
	global_load_dwordx4 v[138:141], v[226:227], off offset:64
	v_lshl_add_u64 v[210:211], v[134:135], 2, s[6:7]
	global_load_dwordx4 v[134:137], v[228:229], off offset:64
	global_load_dwordx4 v[218:221], v[204:205], off
	global_load_dwordx4 v[154:157], v[202:203], off offset:64
	s_mov_b32 s62, s20
	s_mov_b64 s[28:29], s[24:25]
	s_mov_b64 s[26:27], s[22:23]
	s_mov_b32 s61, s60
	s_and_b64 vcc, exec, s[14:15]
	s_waitcnt vmcnt(0)
;     DI void operator()(const f32x4 (&acc)[2][2][4][2], const pg8::Unit& u, int wr, int wc, int fr, int fq) const {
;     ...
;             for (int n = 0; n < 2; ++n) {
;                 const int c = col0 + bj * 128 + n * 16;
; #pragma unroll
;                 for (int q = 0; q < 8; ++q) {
;                     const int rr = rl + (q >> 2) * 128 + (q & 3) * 16;
;                     f32x4 x = xv[n][q];
;                     if (mode) { const float mu = stats[2 * (rowt + rr)], rs = stats[2 * (rowt + rr) + 1]; x = (x - mu) * rs * gg[n] + bb[n]; }
;                     *(f32x4*)(dbase + (size_t)rr * D + c) = ALPHA * x + gv[n] * acc[q >> 2][bj][q & 3][n];
;                 }
;             }
	v_sub_f32_e32 v215, v215, v208
	v_sub_f32_e32 v214, v214, v208
	v_sub_f32_e32 v213, v213, v208
	v_sub_f32_e32 v212, v212, v208
	v_pk_mul_f32 v[212:213], v[212:213], v[208:209] op_sel:[0,1]
	v_pk_mul_f32 v[208:209], v[214:215], v[208:209] op_sel:[0,1]
	v_pk_fma_f32 v[212:213], v[146:147], v[212:213], v[150:151]
	v_pk_fma_f32 v[208:209], v[148:149], v[208:209], v[152:153]
	v_pk_mul_f32 v[212:213], v[212:213], s[10:11] op_sel_hi:[1,0]
	v_pk_mul_f32 v[208:209], v[208:209], s[10:11] op_sel_hi:[1,0]
	v_pk_fma_f32 v[126:127], v[126:127], v[142:143], v[212:213]
	v_pk_fma_f32 v[128:129], v[128:129], v[144:145], v[208:209]
	global_store_dwordx4 v[202:203], v[126:129], off
	global_load_dword v183, v[210:211], off
	global_load_dword v212, v[210:211], off offset:4
	v_add_lshl_u32 v126, s21, v174, 1
	v_ashrrev_i32_e32 v127, 31, v126
	v_lshl_add_u64 v[208:209], v[230:231], 0, v[176:177]
	v_lshl_add_u64 v[214:215], v[126:127], 2, s[6:7]
	global_load_dwordx4 v[232:235], v[208:209], off
	global_load_dwordx4 v[126:129], v[204:205], off offset:64
	s_waitcnt vmcnt(0)
	v_sub_f32_e32 v221, v221, v183
	v_sub_f32_e32 v220, v220, v183
	v_sub_f32_e32 v219, v219, v183
	v_sub_f32_e32 v218, v218, v183
	v_pk_mul_f32 v[218:219], v[218:219], v[212:213] op_sel_hi:[1,0]
	v_pk_mul_f32 v[212:213], v[220:221], v[212:213] op_sel_hi:[1,0]
	v_pk_fma_f32 v[218:219], v[146:147], v[218:219], v[150:151]
	v_pk_fma_f32 v[212:213], v[148:149], v[212:213], v[152:153]
	v_pk_mul_f32 v[218:219], v[218:219], s[10:11] op_sel_hi:[1,0]
	v_pk_mul_f32 v[212:213], v[212:213], s[10:11] op_sel_hi:[1,0]
	v_pk_fma_f32 v[122:123], v[122:123], v[142:143], v[218:219]
	v_pk_fma_f32 v[124:125], v[124:125], v[144:145], v[212:213]
	global_store_dwordx4 v[204:205], v[122:125], off
	global_load_dword v183, v[214:215], off
	global_load_dword v218, v[214:215], off offset:4
	v_add_lshl_u32 v122, s21, v178, 1
	v_ashrrev_i32_e32 v123, 31, v122
	v_lshl_add_u64 v[212:213], v[230:231], 0, v[180:181]
	v_lshl_add_u64 v[220:221], v[122:123], 2, s[6:7]
	global_load_dwordx4 v[236:239], v[212:213], off
	global_load_dwordx4 v[122:125], v[208:209], off offset:64
	s_waitcnt vmcnt(0)
	v_sub_f32_e32 v223, v235, v183
	v_sub_f32_e32 v222, v234, v183
	v_sub_f32_e32 v233, v233, v183
	v_sub_f32_e32 v232, v232, v183
	v_pk_mul_f32 v[232:233], v[232:233], v[218:219] op_sel_hi:[1,0]
	v_pk_mul_f32 v[218:219], v[222:223], v[218:219] op_sel_hi:[1,0]
	v_pk_fma_f32 v[222:223], v[146:147], v[232:233], v[150:151]
	v_pk_fma_f32 v[218:219], v[148:149], v[218:219], v[152:153]
	v_pk_mul_f32 v[222:223], v[222:223], s[10:11] op_sel_hi:[1,0]
	v_pk_mul_f32 v[218:219], v[218:219], s[10:11] op_sel_hi:[1,0]
	v_pk_fma_f32 v[118:119], v[118:119], v[142:143], v[222:223]
	v_pk_fma_f32 v[120:121], v[120:121], v[144:145], v[218:219]
	global_store_dwordx4 v[208:209], v[118:121], off
	global_load_dword v183, v[220:221], off
	global_load_dword v240, v[220:221], off offset:4
	v_add_lshl_u32 v118, s21, v182, 1
	v_ashrrev_i32_e32 v119, 31, v118
	v_lshl_add_u64 v[218:219], v[230:231], 0, v[184:185]
	v_lshl_add_u64 v[222:223], v[118:119], 2, s[6:7]
	global_load_dwordx4 v[232:235], v[218:219], off
	global_load_dwordx4 v[118:121], v[212:213], off offset:64
	s_waitcnt vmcnt(0)
	v_sub_f32_e32 v239, v239, v183
	v_sub_f32_e32 v238, v238, v183
	v_sub_f32_e32 v237, v237, v183
	v_sub_f32_e32 v236, v236, v183
	v_pk_mul_f32 v[236:237], v[236:237], v[240:241] op_sel_hi:[1,0]
	v_pk_mul_f32 v[238:239], v[238:239], v[240:241] op_sel_hi:[1,0]
	v_pk_fma_f32 v[236:237], v[146:147], v[236:237], v[150:151]
	v_pk_fma_f32 v[238:239], v[148:149], v[238:239], v[152:153]
	v_pk_mul_f32 v[236:237], v[236:237], s[10:11] op_sel_hi:[1,0]
	v_pk_mul_f32 v[238:239], v[238:239], s[10:11] op_sel_hi:[1,0]
	v_pk_fma_f32 v[114:115], v[114:115], v[142:143], v[236:237]
	v_pk_fma_f32 v[116:117], v[116:117], v[144:145], v[238:239]
	global_store_dwordx4 v[212:213], v[114:117], off
	global_load_dwordx2 v[244:245], v[222:223], off
	s_waitcnt vmcnt(0)
	v_sub_f32_e32 v235, v235, v244
	v_sub_f32_e32 v234, v234, v244
	v_sub_f32_e32 v233, v233, v244
	v_sub_f32_e32 v232, v232, v244
	v_pk_mul_f32 v[232:233], v[232:233], v[244:245] op_sel:[0,1]
	v_pk_mul_f32 v[234:235], v[234:235], v[244:245] op_sel:[0,1]
	v_add_lshl_u32 v114, s21, v186, 1
	v_pk_fma_f32 v[234:235], v[148:149], v[234:235], v[152:153]
	v_pk_fma_f32 v[232:233], v[146:147], v[232:233], v[150:151]
	v_ashrrev_i32_e32 v115, 31, v114
	v_pk_mul_f32 v[232:233], v[232:233], s[10:11] op_sel_hi:[1,0]
	v_pk_mul_f32 v[234:235], v[234:235], s[10:11] op_sel_hi:[1,0]
	v_lshl_add_u64 v[116:117], v[114:115], 2, s[6:7]
	v_lshl_add_u64 v[114:115], v[230:231], 0, v[188:189]
	v_pk_fma_f32 v[112:113], v[112:113], v[144:145], v[234:235]
	v_pk_fma_f32 v[110:111], v[110:111], v[142:143], v[232:233]
	global_load_dwordx4 v[236:239], v[114:115], off
	global_load_dwordx4 v[240:243], v[218:219], off offset:64
	s_nop 0
	global_store_dwordx4 v[218:219], v[110:113], off
	global_load_dword v183, v[116:117], off
	global_load_dword v248, v[116:117], off offset:4
	v_add_lshl_u32 v110, s21, v190, 1
	v_ashrrev_i32_e32 v111, 31, v110
	v_lshl_add_u64 v[112:113], v[110:111], 2, s[6:7]
	v_lshl_add_u64 v[110:111], v[230:231], 0, v[192:193]
	global_load_dwordx4 v[232:235], v[110:111], off
	global_load_dwordx4 v[244:247], v[114:115], off offset:64
	s_waitcnt vmcnt(0)
;     DI void operator()(const f32x4 (&acc)[2][2][4][2], const pg8::Unit& u, int wr, int wc, int fr, int fq) const {
;     ...
;             for (int n = 0; n < 2; ++n) {
;                 const int c = col0 + bj * 128 + n * 16;
; #pragma unroll
;                 for (int q = 0; q < 8; ++q) {
;                     const int rr = rl + (q >> 2) * 128 + (q & 3) * 16;
;                     f32x4 x = xv[n][q];
;                     if (mode) { const float mu = stats[2 * (rowt + rr)], rs = stats[2 * (rowt + rr) + 1]; x = (x - mu) * rs * gg[n] + bb[n]; }
;                     *(f32x4*)(dbase + (size_t)rr * D + c) = ALPHA * x + gv[n] * acc[q >> 2][bj][q & 3][n];
;                 }
;             }
	v_sub_f32_e32 v239, v239, v183
	v_sub_f32_e32 v238, v238, v183
	v_sub_f32_e32 v237, v237, v183
	v_sub_f32_e32 v236, v236, v183
	v_pk_mul_f32 v[236:237], v[236:237], v[248:249] op_sel_hi:[1,0]
	v_pk_mul_f32 v[238:239], v[238:239], v[248:249] op_sel_hi:[1,0]
	v_pk_fma_f32 v[236:237], v[146:147], v[236:237], v[150:151]
	v_pk_fma_f32 v[238:239], v[148:149], v[238:239], v[152:153]
	v_pk_mul_f32 v[236:237], v[236:237], s[10:11] op_sel_hi:[1,0]
	v_pk_mul_f32 v[238:239], v[238:239], s[10:11] op_sel_hi:[1,0]
	v_pk_fma_f32 v[106:107], v[106:107], v[142:143], v[236:237]
	v_pk_fma_f32 v[108:109], v[108:109], v[144:145], v[238:239]
	global_store_dwordx4 v[114:115], v[106:109], off
	global_load_dword v183, v[112:113], off
	global_load_dword v252, v[112:113], off offset:4
	v_add_lshl_u32 v106, s21, v194, 1
	v_ashrrev_i32_e32 v107, 31, v106
	v_lshl_add_u64 v[108:109], v[106:107], 2, s[6:7]
	v_lshl_add_u64 v[106:107], v[230:231], 0, v[196:197]
	global_load_dwordx4 v[236:239], v[106:107], off
	global_load_dwordx4 v[248:251], v[110:111], off offset:64
	s_waitcnt vmcnt(0)
	v_sub_f32_e32 v231, v235, v183
	v_sub_f32_e32 v230, v234, v183
	v_sub_f32_e32 v233, v233, v183
	v_sub_f32_e32 v232, v232, v183
	v_pk_mul_f32 v[232:233], v[232:233], v[252:253] op_sel_hi:[1,0]
	v_pk_mul_f32 v[230:231], v[230:231], v[252:253] op_sel_hi:[1,0]
	v_pk_fma_f32 v[232:233], v[146:147], v[232:233], v[150:151]
	v_pk_fma_f32 v[230:231], v[148:149], v[230:231], v[152:153]
	v_pk_mul_f32 v[232:233], v[232:233], s[10:11] op_sel_hi:[1,0]
	v_pk_mul_f32 v[230:231], v[230:231], s[10:11] op_sel_hi:[1,0]
	v_pk_fma_f32 v[98:99], v[98:99], v[142:143], v[232:233]
	v_pk_fma_f32 v[100:101], v[100:101], v[144:145], v[230:231]
	global_store_dwordx4 v[110:111], v[98:101], off
	global_load_dword v183, v[108:109], off
	global_load_dword v230, v[108:109], off offset:4
	s_nop 0
	global_load_dwordx4 v[98:101], v[106:107], off offset:64
	s_waitcnt vmcnt(0)
	v_sub_f32_e32 v233, v239, v183
	v_sub_f32_e32 v232, v238, v183
	v_sub_f32_e32 v235, v237, v183
	v_sub_f32_e32 v234, v236, v183
	v_pk_mul_f32 v[234:235], v[234:235], v[230:231] op_sel_hi:[1,0]
	v_pk_mul_f32 v[230:231], v[232:233], v[230:231] op_sel_hi:[1,0]
	v_pk_fma_f32 v[146:147], v[146:147], v[234:235], v[150:151]
	v_pk_fma_f32 v[148:149], v[148:149], v[230:231], v[152:153]
	v_pk_mul_f32 v[146:147], v[146:147], s[10:11] op_sel_hi:[1,0]
	v_pk_mul_f32 v[148:149], v[148:149], s[10:11] op_sel_hi:[1,0]
	v_pk_fma_f32 v[90:91], v[90:91], v[142:143], v[146:147]
	v_pk_fma_f32 v[92:93], v[92:93], v[144:145], v[148:149]
	global_store_dwordx4 v[106:107], v[90:93], off
	global_load_dwordx2 v[90:91], v[206:207], off
	s_waitcnt vmcnt(0)
	v_sub_f32_e32 v143, v155, v90
	v_sub_f32_e32 v93, v157, v90
	v_sub_f32_e32 v92, v156, v90
	v_sub_f32_e32 v142, v154, v90
	v_pk_mul_f32 v[142:143], v[142:143], v[90:91] op_sel:[0,1]
	v_pk_mul_f32 v[90:91], v[92:93], v[90:91] op_sel:[0,1]
	v_pk_fma_f32 v[92:93], v[130:131], v[142:143], v[138:139]
	v_pk_fma_f32 v[90:91], v[132:133], v[90:91], v[140:141]
	v_pk_mul_f32 v[142:143], v[92:93], s[10:11] op_sel_hi:[1,0]
	v_pk_mul_f32 v[90:91], v[90:91], s[10:11] op_sel_hi:[1,0]
	s_nop 0
	v_pk_fma_f32 v[92:93], v[104:105], v[136:137], v[90:91]
	v_pk_fma_f32 v[90:91], v[102:103], v[134:135], v[142:143]
	global_store_dwordx4 v[202:203], v[90:93], off offset:64
	global_load_dword v91, v[210:211], off
	s_nop 0
	global_load_dword v90, v[210:211], off offset:4
	s_waitcnt vmcnt(0)
	v_sub_f32_e32 v93, v129, v91
	v_sub_f32_e32 v92, v128, v91
	v_sub_f32_e32 v103, v127, v91
	v_sub_f32_e32 v102, v126, v91
	v_pk_mul_f32 v[102:103], v[102:103], v[90:91] op_sel_hi:[1,0]
	v_pk_mul_f32 v[90:91], v[92:93], v[90:91] op_sel_hi:[1,0]
	v_pk_fma_f32 v[92:93], v[130:131], v[102:103], v[138:139]
	v_pk_fma_f32 v[90:91], v[132:133], v[90:91], v[140:141]
	v_pk_mul_f32 v[102:103], v[92:93], s[10:11] op_sel_hi:[1,0]
	v_pk_mul_f32 v[90:91], v[90:91], s[10:11] op_sel_hi:[1,0]
	s_nop 0
	v_pk_fma_f32 v[92:93], v[96:97], v[136:137], v[90:91]
	v_pk_fma_f32 v[90:91], v[94:95], v[134:135], v[102:103]
	global_store_dwordx4 v[204:205], v[90:93], off offset:64
	global_load_dword v91, v[214:215], off
	s_nop 0
	global_load_dword v90, v[214:215], off offset:4
	s_waitcnt vmcnt(0)
	v_sub_f32_e32 v93, v125, v91
	v_sub_f32_e32 v92, v124, v91
	v_sub_f32_e32 v95, v123, v91
	v_sub_f32_e32 v94, v122, v91
	v_pk_mul_f32 v[94:95], v[94:95], v[90:91] op_sel_hi:[1,0]
	v_pk_mul_f32 v[90:91], v[92:93], v[90:91] op_sel_hi:[1,0]
	v_pk_fma_f32 v[92:93], v[130:131], v[94:95], v[138:139]
	v_pk_fma_f32 v[90:91], v[132:133], v[90:91], v[140:141]
	v_pk_mul_f32 v[92:93], v[92:93], s[10:11] op_sel_hi:[1,0]
	v_pk_mul_f32 v[90:91], v[90:91], s[10:11] op_sel_hi:[1,0]
	v_pk_fma_f32 v[86:87], v[86:87], v[134:135], v[92:93]
	v_pk_fma_f32 v[88:89], v[88:89], v[136:137], v[90:91]
	global_store_dwordx4 v[208:209], v[86:89], off offset:64
	global_load_dword v87, v[220:221], off
	s_nop 0
	global_load_dword v86, v[220:221], off offset:4
	s_waitcnt vmcnt(0)
	v_sub_f32_e32 v89, v121, v87
	v_sub_f32_e32 v88, v120, v87
	v_sub_f32_e32 v91, v119, v87
	v_sub_f32_e32 v90, v118, v87
	v_pk_mul_f32 v[90:91], v[90:91], v[86:87] op_sel_hi:[1,0]
	v_pk_mul_f32 v[86:87], v[88:89], v[86:87] op_sel_hi:[1,0]
	v_pk_fma_f32 v[88:89], v[130:131], v[90:91], v[138:139]
	v_pk_fma_f32 v[86:87], v[132:133], v[86:87], v[140:141]
	v_pk_mul_f32 v[88:89], v[88:89], s[10:11] op_sel_hi:[1,0]
	v_pk_mul_f32 v[86:87], v[86:87], s[10:11] op_sel_hi:[1,0]
	v_pk_fma_f32 v[82:83], v[82:83], v[134:135], v[88:89]
	v_pk_fma_f32 v[84:85], v[84:85], v[136:137], v[86:87]
	global_store_dwordx4 v[212:213], v[82:85], off offset:64
	global_load_dwordx2 v[82:83], v[222:223], off
	s_waitcnt vmcnt(0)
;     DI void operator()(const f32x4 (&acc)[2][2][4][2], const pg8::Unit& u, int wr, int wc, int fr, int fq) const {
;     ...
;                 for (int q = 0; q < 8; ++q) { const int rr = rl + (q >> 2) * 128 + (q & 3) * 16; xv[n][q] = *(const f32x4*)(sbase + (size_t)rr * D + c); }
;             }
; #pragma unroll
;             for (int n = 0; n < 2; ++n) {
;                 const int c = col0 + bj * 128 + n * 16;
; #pragma unroll
;                 for (int q = 0; q < 8; ++q) {
;                     const int rr = rl + (q >> 2) * 128 + (q & 3) * 16;
;                     f32x4 x = xv[n][q];
;                     if (mode) { const float mu = stats[2 * (rowt + rr)], rs = stats[2 * (rowt + rr) + 1]; x = (x - mu) * rs * gg[n] + bb[n]; }
;                     *(f32x4*)(dbase + (size_t)rr * D + c) = ALPHA * x + gv[n] * acc[q >> 2][bj][q & 3][n];
;                 }
;             }
	v_sub_f32_e32 v87, v241, v82
	v_sub_f32_e32 v85, v243, v82
	v_sub_f32_e32 v84, v242, v82
	v_sub_f32_e32 v86, v240, v82
	v_pk_mul_f32 v[86:87], v[86:87], v[82:83] op_sel:[0,1]
	v_pk_mul_f32 v[82:83], v[84:85], v[82:83] op_sel:[0,1]
	v_pk_fma_f32 v[84:85], v[130:131], v[86:87], v[138:139]
	v_pk_fma_f32 v[82:83], v[132:133], v[82:83], v[140:141]
	v_pk_mul_f32 v[84:85], v[84:85], s[10:11] op_sel_hi:[1,0]
	v_pk_mul_f32 v[82:83], v[82:83], s[10:11] op_sel_hi:[1,0]
	v_pk_fma_f32 v[78:79], v[78:79], v[134:135], v[84:85]
	v_pk_fma_f32 v[80:81], v[80:81], v[136:137], v[82:83]
	global_store_dwordx4 v[218:219], v[78:81], off offset:64
	global_load_dword v79, v[116:117], off
	s_nop 0
	global_load_dword v78, v[116:117], off offset:4
	s_waitcnt vmcnt(0)
	v_sub_f32_e32 v81, v247, v79
	v_sub_f32_e32 v80, v246, v79
	v_sub_f32_e32 v83, v245, v79
	v_sub_f32_e32 v82, v244, v79
	v_pk_mul_f32 v[82:83], v[82:83], v[78:79] op_sel_hi:[1,0]
	v_pk_mul_f32 v[78:79], v[80:81], v[78:79] op_sel_hi:[1,0]
	v_pk_fma_f32 v[80:81], v[130:131], v[82:83], v[138:139]
	v_pk_fma_f32 v[78:79], v[132:133], v[78:79], v[140:141]
	v_pk_mul_f32 v[80:81], v[80:81], s[10:11] op_sel_hi:[1,0]
	v_pk_mul_f32 v[78:79], v[78:79], s[10:11] op_sel_hi:[1,0]
	v_pk_fma_f32 v[74:75], v[74:75], v[134:135], v[80:81]
	v_pk_fma_f32 v[76:77], v[76:77], v[136:137], v[78:79]
	global_store_dwordx4 v[114:115], v[74:77], off offset:64
	global_load_dword v75, v[112:113], off
	s_nop 0
	global_load_dword v74, v[112:113], off offset:4
	s_waitcnt vmcnt(0)
	v_sub_f32_e32 v77, v251, v75
	v_sub_f32_e32 v76, v250, v75
	v_sub_f32_e32 v79, v249, v75
	v_sub_f32_e32 v78, v248, v75
	v_pk_mul_f32 v[78:79], v[78:79], v[74:75] op_sel_hi:[1,0]
	v_pk_mul_f32 v[74:75], v[76:77], v[74:75] op_sel_hi:[1,0]
	v_pk_fma_f32 v[76:77], v[130:131], v[78:79], v[138:139]
	v_pk_fma_f32 v[74:75], v[132:133], v[74:75], v[140:141]
	v_pk_mul_f32 v[76:77], v[76:77], s[10:11] op_sel_hi:[1,0]
	v_pk_mul_f32 v[74:75], v[74:75], s[10:11] op_sel_hi:[1,0]
	v_pk_fma_f32 v[70:71], v[70:71], v[134:135], v[76:77]
	v_pk_fma_f32 v[72:73], v[72:73], v[136:137], v[74:75]
	global_store_dwordx4 v[110:111], v[70:73], off offset:64
	global_load_dword v71, v[108:109], off
	s_nop 0
	global_load_dword v70, v[108:109], off offset:4
	global_load_dwordx4 v[78:81], v[202:203], off offset:512
	s_waitcnt vmcnt(0)
	v_sub_f32_e32 v73, v101, v71
	v_sub_f32_e32 v72, v100, v71
	v_sub_f32_e32 v75, v99, v71
	v_sub_f32_e32 v74, v98, v71
	v_pk_mul_f32 v[74:75], v[74:75], v[70:71] op_sel_hi:[1,0]
	v_pk_mul_f32 v[70:71], v[72:73], v[70:71] op_sel_hi:[1,0]
	v_pk_fma_f32 v[72:73], v[130:131], v[74:75], v[138:139]
	v_pk_fma_f32 v[70:71], v[132:133], v[70:71], v[140:141]
	v_pk_mul_f32 v[72:73], v[72:73], s[10:11] op_sel_hi:[1,0]
	v_pk_mul_f32 v[70:71], v[70:71], s[10:11] op_sel_hi:[1,0]
	v_pk_fma_f32 v[62:63], v[62:63], v[134:135], v[72:73]
	v_pk_fma_f32 v[64:65], v[64:65], v[136:137], v[70:71]
	global_store_dwordx4 v[106:107], v[62:65], off offset:64
	global_load_dwordx2 v[102:103], v[206:207], off
	global_load_dwordx4 v[82:85], v[224:225], off offset:512
	global_load_dwordx4 v[86:89], v[226:227], off offset:512
	global_load_dwordx4 v[90:93], v[228:229], off offset:512
	global_load_dwordx4 v[94:97], v[204:205], off offset:512
	global_load_dwordx4 v[98:101], v[202:203], off offset:576
	global_load_dwordx4 v[62:65], v[228:229], off offset:576
	global_load_dwordx4 v[70:73], v[224:225], off offset:576
	global_load_dwordx4 v[74:77], v[226:227], off offset:576
	s_waitcnt vmcnt(0)
	v_sub_f32_e32 v81, v81, v102
	v_sub_f32_e32 v80, v80, v102
	v_sub_f32_e32 v79, v79, v102
	v_sub_f32_e32 v78, v78, v102
	v_pk_mul_f32 v[78:79], v[78:79], v[102:103] op_sel:[0,1]
	v_pk_mul_f32 v[80:81], v[80:81], v[102:103] op_sel:[0,1]
	v_pk_fma_f32 v[78:79], v[82:83], v[78:79], v[86:87]
	v_pk_fma_f32 v[80:81], v[84:85], v[80:81], v[88:89]
	v_pk_mul_f32 v[78:79], v[78:79], s[10:11] op_sel_hi:[1,0]
	v_pk_mul_f32 v[80:81], v[80:81], s[10:11] op_sel_hi:[1,0]
	v_pk_fma_f32 v[66:67], v[66:67], v[90:91], v[78:79]
	v_pk_fma_f32 v[68:69], v[68:69], v[92:93], v[80:81]
	global_store_dwordx4 v[202:203], v[66:69], off offset:512
	global_load_dword v103, v[210:211], off
	global_load_dword v102, v[210:211], off offset:4
	s_nop 0
	global_load_dwordx4 v[66:69], v[208:209], off offset:512
	global_load_dwordx4 v[78:81], v[204:205], off offset:576
	s_waitcnt vmcnt(0)
	v_sub_f32_e32 v97, v97, v103
	v_sub_f32_e32 v96, v96, v103
	v_sub_f32_e32 v95, v95, v103
	v_sub_f32_e32 v94, v94, v103
	v_pk_mul_f32 v[94:95], v[94:95], v[102:103] op_sel_hi:[1,0]
	v_pk_mul_f32 v[96:97], v[96:97], v[102:103] op_sel_hi:[1,0]
	v_pk_fma_f32 v[94:95], v[82:83], v[94:95], v[86:87]
	v_pk_fma_f32 v[96:97], v[84:85], v[96:97], v[88:89]
	v_pk_mul_f32 v[94:95], v[94:95], s[10:11] op_sel_hi:[1,0]
	v_pk_mul_f32 v[96:97], v[96:97], s[10:11] op_sel_hi:[1,0]
	v_pk_fma_f32 v[58:59], v[58:59], v[90:91], v[94:95]
	v_pk_fma_f32 v[60:61], v[60:61], v[92:93], v[96:97]
	global_store_dwordx4 v[204:205], v[58:61], off offset:512
	global_load_dword v103, v[214:215], off
	global_load_dword v102, v[214:215], off offset:4
	s_nop 0
	global_load_dwordx4 v[58:61], v[212:213], off offset:512
	global_load_dwordx4 v[94:97], v[208:209], off offset:576
	s_waitcnt vmcnt(0)
;     DI void operator()(const f32x4 (&acc)[2][2][4][2], const pg8::Unit& u, int wr, int wc, int fr, int fq) const {
;     ...
;             for (int n = 0; n < 2; ++n) {
;                 const int c = col0 + bj * 128 + n * 16;
; #pragma unroll
;                 for (int q = 0; q < 8; ++q) {
;                     const int rr = rl + (q >> 2) * 128 + (q & 3) * 16;
;                     f32x4 x = xv[n][q];
;                     if (mode) { const float mu = stats[2 * (rowt + rr)], rs = stats[2 * (rowt + rr) + 1]; x = (x - mu) * rs * gg[n] + bb[n]; }
;                     *(f32x4*)(dbase + (size_t)rr * D + c) = ALPHA * x + gv[n] * acc[q >> 2][bj][q & 3][n];
;                 }
;             }
	v_sub_f32_e32 v69, v69, v103
	v_sub_f32_e32 v68, v68, v103
	v_sub_f32_e32 v67, v67, v103
	v_sub_f32_e32 v66, v66, v103
	v_pk_mul_f32 v[66:67], v[66:67], v[102:103] op_sel_hi:[1,0]
	v_pk_mul_f32 v[68:69], v[68:69], v[102:103] op_sel_hi:[1,0]
	v_pk_fma_f32 v[66:67], v[82:83], v[66:67], v[86:87]
	v_pk_fma_f32 v[68:69], v[84:85], v[68:69], v[88:89]
	v_pk_mul_f32 v[66:67], v[66:67], s[10:11] op_sel_hi:[1,0]
	v_pk_mul_f32 v[68:69], v[68:69], s[10:11] op_sel_hi:[1,0]
	v_pk_fma_f32 v[54:55], v[54:55], v[90:91], v[66:67]
	v_pk_fma_f32 v[56:57], v[56:57], v[92:93], v[68:69]
	global_store_dwordx4 v[208:209], v[54:57], off offset:512
	global_load_dword v103, v[220:221], off
	global_load_dword v102, v[220:221], off offset:4
	s_nop 0
	global_load_dwordx4 v[54:57], v[218:219], off offset:512
	global_load_dwordx4 v[66:69], v[212:213], off offset:576
	s_waitcnt vmcnt(0)
	v_sub_f32_e32 v61, v61, v103
	v_sub_f32_e32 v60, v60, v103
	v_sub_f32_e32 v59, v59, v103
	v_sub_f32_e32 v58, v58, v103
	v_pk_mul_f32 v[58:59], v[58:59], v[102:103] op_sel_hi:[1,0]
	v_pk_mul_f32 v[60:61], v[60:61], v[102:103] op_sel_hi:[1,0]
	v_pk_fma_f32 v[58:59], v[82:83], v[58:59], v[86:87]
	v_pk_fma_f32 v[60:61], v[84:85], v[60:61], v[88:89]
	v_pk_mul_f32 v[58:59], v[58:59], s[10:11] op_sel_hi:[1,0]
	v_pk_mul_f32 v[60:61], v[60:61], s[10:11] op_sel_hi:[1,0]
	v_pk_fma_f32 v[50:51], v[50:51], v[90:91], v[58:59]
	v_pk_fma_f32 v[52:53], v[52:53], v[92:93], v[60:61]
	global_store_dwordx4 v[212:213], v[50:53], off offset:512
	global_load_dwordx2 v[102:103], v[222:223], off
	s_nop 0
	global_load_dwordx4 v[50:53], v[114:115], off offset:512
	global_load_dwordx4 v[58:61], v[218:219], off offset:576
	s_waitcnt vmcnt(0)
	v_sub_f32_e32 v57, v57, v102
	v_sub_f32_e32 v56, v56, v102
	v_sub_f32_e32 v55, v55, v102
	v_sub_f32_e32 v54, v54, v102
	v_pk_mul_f32 v[54:55], v[54:55], v[102:103] op_sel:[0,1]
	v_pk_mul_f32 v[56:57], v[56:57], v[102:103] op_sel:[0,1]
	v_pk_fma_f32 v[54:55], v[82:83], v[54:55], v[86:87]
	v_pk_fma_f32 v[56:57], v[84:85], v[56:57], v[88:89]
	v_pk_mul_f32 v[54:55], v[54:55], s[10:11] op_sel_hi:[1,0]
	v_pk_mul_f32 v[56:57], v[56:57], s[10:11] op_sel_hi:[1,0]
	v_pk_fma_f32 v[46:47], v[46:47], v[90:91], v[54:55]
	v_pk_fma_f32 v[48:49], v[48:49], v[92:93], v[56:57]
	global_store_dwordx4 v[218:219], v[46:49], off offset:512
	global_load_dword v103, v[116:117], off
	global_load_dword v102, v[116:117], off offset:4
	s_nop 0
	global_load_dwordx4 v[46:49], v[110:111], off offset:512
	global_load_dwordx4 v[54:57], v[114:115], off offset:576
	s_waitcnt vmcnt(0)
	v_sub_f32_e32 v53, v53, v103
	v_sub_f32_e32 v52, v52, v103
	v_sub_f32_e32 v51, v51, v103
	v_sub_f32_e32 v50, v50, v103
	v_pk_mul_f32 v[50:51], v[50:51], v[102:103] op_sel_hi:[1,0]
	v_pk_mul_f32 v[52:53], v[52:53], v[102:103] op_sel_hi:[1,0]
	v_pk_fma_f32 v[50:51], v[82:83], v[50:51], v[86:87]
	v_pk_fma_f32 v[52:53], v[84:85], v[52:53], v[88:89]
	v_pk_mul_f32 v[50:51], v[50:51], s[10:11] op_sel_hi:[1,0]
	v_pk_mul_f32 v[52:53], v[52:53], s[10:11] op_sel_hi:[1,0]
	v_pk_fma_f32 v[42:43], v[42:43], v[90:91], v[50:51]
	v_pk_fma_f32 v[44:45], v[44:45], v[92:93], v[52:53]
	global_store_dwordx4 v[114:115], v[42:45], off offset:512
	global_load_dword v103, v[112:113], off
	global_load_dword v102, v[112:113], off offset:4
	s_nop 0
	global_load_dwordx4 v[42:45], v[106:107], off offset:512
	global_load_dwordx4 v[50:53], v[110:111], off offset:576
	s_waitcnt vmcnt(0)
	v_sub_f32_e32 v49, v49, v103
	v_sub_f32_e32 v48, v48, v103
	v_sub_f32_e32 v47, v47, v103
	v_sub_f32_e32 v46, v46, v103
	v_pk_mul_f32 v[46:47], v[46:47], v[102:103] op_sel_hi:[1,0]
	v_pk_mul_f32 v[48:49], v[48:49], v[102:103] op_sel_hi:[1,0]
	v_pk_fma_f32 v[46:47], v[82:83], v[46:47], v[86:87]
	v_pk_fma_f32 v[48:49], v[84:85], v[48:49], v[88:89]
	v_pk_mul_f32 v[46:47], v[46:47], s[10:11] op_sel_hi:[1,0]
	v_pk_mul_f32 v[48:49], v[48:49], s[10:11] op_sel_hi:[1,0]
	v_pk_fma_f32 v[34:35], v[34:35], v[90:91], v[46:47]
	v_pk_fma_f32 v[36:37], v[36:37], v[92:93], v[48:49]
	global_store_dwordx4 v[110:111], v[34:37], off offset:512
	global_load_dword v47, v[108:109], off
	global_load_dword v46, v[108:109], off offset:4
	s_nop 0
	global_load_dwordx4 v[34:37], v[106:107], off offset:576
	s_waitcnt vmcnt(0)
	v_sub_f32_e32 v45, v45, v47
	v_sub_f32_e32 v44, v44, v47
	v_sub_f32_e32 v43, v43, v47
	v_sub_f32_e32 v42, v42, v47
	v_pk_mul_f32 v[42:43], v[42:43], v[46:47] op_sel_hi:[1,0]
	v_pk_mul_f32 v[44:45], v[44:45], v[46:47] op_sel_hi:[1,0]
	v_pk_fma_f32 v[42:43], v[82:83], v[42:43], v[86:87]
	v_pk_fma_f32 v[44:45], v[84:85], v[44:45], v[88:89]
	v_pk_mul_f32 v[42:43], v[42:43], s[10:11] op_sel_hi:[1,0]
	v_pk_mul_f32 v[44:45], v[44:45], s[10:11] op_sel_hi:[1,0]
	v_pk_fma_f32 v[26:27], v[26:27], v[90:91], v[42:43]
	v_pk_fma_f32 v[28:29], v[28:29], v[92:93], v[44:45]
	global_store_dwordx4 v[106:107], v[26:29], off offset:512
	global_load_dwordx2 v[26:27], v[206:207], off
	s_waitcnt vmcnt(0)
	v_sub_f32_e32 v43, v99, v26
	v_sub_f32_e32 v29, v101, v26
	v_sub_f32_e32 v28, v100, v26
	v_sub_f32_e32 v42, v98, v26
	v_pk_mul_f32 v[42:43], v[42:43], v[26:27] op_sel:[0,1]
	v_pk_mul_f32 v[26:27], v[28:29], v[26:27] op_sel:[0,1]
	v_pk_fma_f32 v[28:29], v[70:71], v[42:43], v[74:75]
	v_pk_fma_f32 v[26:27], v[72:73], v[26:27], v[76:77]
	v_pk_mul_f32 v[42:43], v[28:29], s[10:11] op_sel_hi:[1,0]
	v_pk_mul_f32 v[26:27], v[26:27], s[10:11] op_sel_hi:[1,0]
	s_nop 0
	v_pk_fma_f32 v[28:29], v[40:41], v[64:65], v[26:27]
	v_pk_fma_f32 v[26:27], v[38:39], v[62:63], v[42:43]
	global_store_dwordx4 v[202:203], v[26:29], off offset:576
	global_load_dword v27, v[210:211], off
	s_nop 0
	global_load_dword v26, v[210:211], off offset:4
	s_waitcnt vmcnt(0)
; #define PG8_WAIT_V(n) asm volatile("s_waitcnt vmcnt(" #n ")" ::: "memory")
; #define PG8_BAR __builtin_amdgcn_s_barrier()
; template <class Epi>
; DI void gemm_phase(LAS unsigned char* lds, const Gemm g, const StaticOrder& S, const Epi& E) {
;     ...
;         if (!has_next) break;
; #pragma unroll
;         for (int a = 0; a < 2; ++a)
; #pragma unroll
;             for (int b = 0; b < 2; ++b)
; #pragma unroll
;                 for (int m = 0; m < 4; ++m)
; #pragma unroll
;                     for (int n = 0; n < 2; ++n) acc[a][b][m][n] = (f32x4){0.f, 0.f, 0.f, 0.f};
;         cur = nxt; cA = nA; cB = nB; ++ui;
;     }
;     PG8_WAIT_V(0);
;     if (wr == 0) PG8_BAR;
;     PG8_BAR;
;     DI void operator()(const f32x4 (&acc)[2][2][4][2], const pg8::Unit& u, int wr, int wc, int fr, int fq) const {
;     ...
;             for (int n = 0; n < 2; ++n) {
;                 const int c = col0 + bj * 128 + n * 16;
; #pragma unroll
;                 for (int q = 0; q < 8; ++q) {
;                     const int rr = rl + (q >> 2) * 128 + (q & 3) * 16;
;                     f32x4 x = xv[n][q];
;                     if (mode) { const float mu = stats[2 * (rowt + rr)], rs = stats[2 * (rowt + rr) + 1]; x = (x - mu) * rs * gg[n] + bb[n]; }
;                     *(f32x4*)(dbase + (size_t)rr * D + c) = ALPHA * x + gv[n] * acc[q >> 2][bj][q & 3][n];
;                 }
;             }
	v_sub_f32_e32 v29, v81, v27
	v_sub_f32_e32 v28, v80, v27
	v_sub_f32_e32 v39, v79, v27
	v_sub_f32_e32 v38, v78, v27
	v_pk_mul_f32 v[38:39], v[38:39], v[26:27] op_sel_hi:[1,0]
	v_pk_mul_f32 v[26:27], v[28:29], v[26:27] op_sel_hi:[1,0]
	v_pk_fma_f32 v[28:29], v[70:71], v[38:39], v[74:75]
	v_pk_fma_f32 v[26:27], v[72:73], v[26:27], v[76:77]
	v_pk_mul_f32 v[38:39], v[28:29], s[10:11] op_sel_hi:[1,0]
	v_pk_mul_f32 v[26:27], v[26:27], s[10:11] op_sel_hi:[1,0]
	s_nop 0
	v_pk_fma_f32 v[28:29], v[32:33], v[64:65], v[26:27]
	v_pk_fma_f32 v[26:27], v[30:31], v[62:63], v[38:39]
	global_store_dwordx4 v[204:205], v[26:29], off offset:576
	global_load_dword v27, v[214:215], off
	s_nop 0
	global_load_dword v26, v[214:215], off offset:4
	s_waitcnt vmcnt(0)
	v_sub_f32_e32 v29, v97, v27
	v_sub_f32_e32 v28, v96, v27
	v_sub_f32_e32 v31, v95, v27
	v_sub_f32_e32 v30, v94, v27
	v_pk_mul_f32 v[30:31], v[30:31], v[26:27] op_sel_hi:[1,0]
	v_pk_mul_f32 v[26:27], v[28:29], v[26:27] op_sel_hi:[1,0]
	v_pk_fma_f32 v[28:29], v[70:71], v[30:31], v[74:75]
	v_pk_fma_f32 v[26:27], v[72:73], v[26:27], v[76:77]
	v_pk_mul_f32 v[28:29], v[28:29], s[10:11] op_sel_hi:[1,0]
	v_pk_mul_f32 v[26:27], v[26:27], s[10:11] op_sel_hi:[1,0]
	v_pk_fma_f32 v[22:23], v[22:23], v[62:63], v[28:29]
	v_pk_fma_f32 v[24:25], v[24:25], v[64:65], v[26:27]
	global_store_dwordx4 v[208:209], v[22:25], off offset:576
	global_load_dword v23, v[220:221], off
	s_nop 0
	global_load_dword v22, v[220:221], off offset:4
	s_waitcnt vmcnt(0)
	v_sub_f32_e32 v25, v69, v23
	v_sub_f32_e32 v24, v68, v23
	v_sub_f32_e32 v27, v67, v23
	v_sub_f32_e32 v26, v66, v23
	v_pk_mul_f32 v[26:27], v[26:27], v[22:23] op_sel_hi:[1,0]
	v_pk_mul_f32 v[22:23], v[24:25], v[22:23] op_sel_hi:[1,0]
	v_pk_fma_f32 v[24:25], v[70:71], v[26:27], v[74:75]
	v_pk_fma_f32 v[22:23], v[72:73], v[22:23], v[76:77]
	v_pk_mul_f32 v[24:25], v[24:25], s[10:11] op_sel_hi:[1,0]
	v_pk_mul_f32 v[22:23], v[22:23], s[10:11] op_sel_hi:[1,0]
	v_pk_fma_f32 v[18:19], v[18:19], v[62:63], v[24:25]
	v_pk_fma_f32 v[20:21], v[20:21], v[64:65], v[22:23]
	global_store_dwordx4 v[212:213], v[18:21], off offset:576
	global_load_dwordx2 v[18:19], v[222:223], off
	s_waitcnt vmcnt(0)
	v_sub_f32_e32 v23, v59, v18
	v_sub_f32_e32 v21, v61, v18
	v_sub_f32_e32 v20, v60, v18
	v_sub_f32_e32 v22, v58, v18
	v_pk_mul_f32 v[22:23], v[22:23], v[18:19] op_sel:[0,1]
	v_pk_mul_f32 v[18:19], v[20:21], v[18:19] op_sel:[0,1]
	v_pk_fma_f32 v[20:21], v[70:71], v[22:23], v[74:75]
	v_pk_fma_f32 v[18:19], v[72:73], v[18:19], v[76:77]
	v_pk_mul_f32 v[20:21], v[20:21], s[10:11] op_sel_hi:[1,0]
	v_pk_mul_f32 v[18:19], v[18:19], s[10:11] op_sel_hi:[1,0]
	v_pk_fma_f32 v[14:15], v[14:15], v[62:63], v[20:21]
	v_pk_fma_f32 v[16:17], v[16:17], v[64:65], v[18:19]
	global_store_dwordx4 v[218:219], v[14:17], off offset:576
	global_load_dword v15, v[116:117], off
	s_nop 0
	global_load_dword v14, v[116:117], off offset:4
	s_waitcnt vmcnt(0)
	v_sub_f32_e32 v17, v57, v15
	v_sub_f32_e32 v16, v56, v15
	v_sub_f32_e32 v19, v55, v15
	v_sub_f32_e32 v18, v54, v15
	v_pk_mul_f32 v[18:19], v[18:19], v[14:15] op_sel_hi:[1,0]
	v_pk_mul_f32 v[14:15], v[16:17], v[14:15] op_sel_hi:[1,0]
	v_pk_fma_f32 v[16:17], v[70:71], v[18:19], v[74:75]
	v_pk_fma_f32 v[14:15], v[72:73], v[14:15], v[76:77]
	v_pk_mul_f32 v[16:17], v[16:17], s[10:11] op_sel_hi:[1,0]
	v_pk_mul_f32 v[14:15], v[14:15], s[10:11] op_sel_hi:[1,0]
	v_pk_fma_f32 v[10:11], v[10:11], v[62:63], v[16:17]
	v_pk_fma_f32 v[12:13], v[12:13], v[64:65], v[14:15]
	global_store_dwordx4 v[114:115], v[10:13], off offset:576
	global_load_dword v11, v[112:113], off
	s_nop 0
	global_load_dword v10, v[112:113], off offset:4
	s_waitcnt vmcnt(0)
	v_sub_f32_e32 v13, v53, v11
	v_sub_f32_e32 v12, v52, v11
	v_sub_f32_e32 v15, v51, v11
	v_sub_f32_e32 v14, v50, v11
	v_pk_mul_f32 v[14:15], v[14:15], v[10:11] op_sel_hi:[1,0]
	v_pk_mul_f32 v[10:11], v[12:13], v[10:11] op_sel_hi:[1,0]
	v_pk_fma_f32 v[12:13], v[70:71], v[14:15], v[74:75]
	v_pk_fma_f32 v[10:11], v[72:73], v[10:11], v[76:77]
	v_pk_mul_f32 v[12:13], v[12:13], s[10:11] op_sel_hi:[1,0]
	v_pk_mul_f32 v[10:11], v[10:11], s[10:11] op_sel_hi:[1,0]
	v_pk_fma_f32 v[6:7], v[6:7], v[62:63], v[12:13]
	v_pk_fma_f32 v[8:9], v[8:9], v[64:65], v[10:11]
	global_store_dwordx4 v[110:111], v[6:9], off offset:576
	global_load_dword v7, v[108:109], off
	s_nop 0
	global_load_dword v6, v[108:109], off offset:4
	s_waitcnt vmcnt(0)
	v_sub_f32_e32 v9, v37, v7
	v_sub_f32_e32 v8, v36, v7
	v_sub_f32_e32 v11, v35, v7
	v_sub_f32_e32 v10, v34, v7
	v_pk_mul_f32 v[10:11], v[10:11], v[6:7] op_sel_hi:[1,0]
	v_pk_mul_f32 v[6:7], v[8:9], v[6:7] op_sel_hi:[1,0]
	v_pk_fma_f32 v[8:9], v[70:71], v[10:11], v[74:75]
	v_pk_fma_f32 v[6:7], v[72:73], v[6:7], v[76:77]
	v_pk_mul_f32 v[8:9], v[8:9], s[10:11] op_sel_hi:[1,0]
	v_pk_mul_f32 v[6:7], v[6:7], s[10:11] op_sel_hi:[1,0]
	v_pk_fma_f32 v[2:3], v[2:3], v[62:63], v[8:9]
	v_pk_fma_f32 v[4:5], v[4:5], v[64:65], v[6:7]
	global_store_dwordx4 v[106:107], v[2:5], off offset:576
	s_cbranch_vccz .LBB0_1200
	s_waitcnt vmcnt(0)
	s_cmpk_gt_u32 s33, 0xff
	s_cbranch_scc1 .LBB0_1209
	s_barrier

; #define PG8_STAGE(bufoff, gbase, voff) do { _Pragma("unroll") for (int _i = 0; _i < 2; ++_i) \
;         __builtin_amdgcn_global_load_lds((const unsigned*)((const char*)(gbase) + (voff)[_i]), (LAS unsigned*)(lds + (bufoff) + ldsw + _i * 8192), 16, 0, 0); } while (0)
; #define PG8_WAIT_V(n) asm volatile("s_waitcnt vmcnt(" #n ")" ::: "memory")
; #define PG8_BAR __builtin_amdgcn_s_barrier()
; template <class Epi>
; DI void gemm_phase(LAS unsigned char* lds, const Gemm g, const StaticOrder& S, const Epi& E) {
;     ...
;     const char* cA = PG8_ABASE(cur); const char* cB = PG8_BBASE(cur);
;     PG8_STAGE(PG8_SB(0, 0), cB, voffB); PG8_STAGE(PG8_SA(0, 0), cA, voffA); PG8_STAGE(PG8_SB(0, 1), cB + hstepB, voffB); PG8_STAGE(PG8_SA(0, 1), cA + hstepA, voffA);
;     if (wr == 1) PG8_BAR;
;     PG8_WAIT_V(4); PG8_BAR;
;     PG8_STAGE(PG8_SB(1, 0), cB + kstep, voffB); PG8_STAGE(PG8_SA(1, 0), cA + kstep, voffA); PG8_STAGE(PG8_SB(1, 1), cB + hstepB + kstep, voffB);
;     PG8_WAIT_V(6); PG8_BAR;
.LBB0_1286:
	s_add_u32 s53, s10, 0x200000
	s_addc_u32 s54, s11, 0
	s_add_u32 s55, s10, 0x16000
	s_addc_u32 s56, s11, 0
	s_add_u32 s10, s10, 0x100000
	s_addc_u32 s11, s11, 0
	s_lshl_b32 s4, s18, 5
	s_mov_b64 s[18:19], 0x80
	s_and_b32 s22, s4, 0x60
	s_add_i32 m0, s39, 0x18000
	v_lshl_add_u64 v[8:9], v[8:9], 0, s[18:19]
	s_lshl_b32 s20, s7, 13
	s_lshl_b32 s23, s22, 7
	s_waitcnt vmcnt(0)
	s_barrier
	global_load_lds_dwordx4 v[8:9], off
	v_lshl_add_u64 v[6:7], v[6:7], 0, s[18:19]
	s_add_i32 m0, s39, 0x1a000
	s_add_i32 s57, s39, 0x8000
	s_add_i32 s58, s39, 0xa000
	global_load_lds_dwordx4 v[6:7], off
	v_lshl_add_u64 v[4:5], v[4:5], 0, s[18:19]
	s_mov_b32 m0, s57
	s_add_u32 s4, s28, 0x80080
	global_load_lds_dwordx4 v[4:5], off
	v_lshl_add_u64 v[2:3], v[2:3], 0, s[18:19]
	s_mov_b32 m0, s58
	s_addc_u32 s5, s29, 0
	global_load_lds_dwordx4 v[2:3], off
	s_add_i32 m0, s39, 0x1c000
	v_lshl_add_u64 v[2:3], s[4:5], 0, v[160:161]
	global_load_lds_dwordx4 v[2:3], off
	v_lshl_add_u64 v[2:3], s[4:5], 0, v[164:165]
	s_add_i32 m0, s39, 0x1e000
	v_and_b32_e32 v1, 15, v254
	global_load_lds_dwordx4 v[2:3], off
	v_bfe_u32 v2, v254, 4, 2
	v_lshlrev_b32_e32 v3, 4, v2
	v_lshlrev_b32_e32 v4, 2, v254
	v_lshl_or_b32 v166, s7, 6, v1
	v_lshl_or_b32 v1, v1, 6, v3
	v_and_b32_e32 v4, 32, v4
	v_bitop3_b32 v5, v1, s20, v4 bitop3:0xde
	v_lshlrev_b32_e32 v1, 6, v254
	s_movk_i32 s4, 0x3c0
	v_and_or_b32 v1, v1, s4, v3
	s_waitcnt vmcnt(6)
	v_bitop3_b32 v1, s23, v1, v4 bitop3:0xf6
	v_mov_b32_e32 v167, v161
	v_or_b32_e32 v170, 16, v166
	v_mov_b32_e32 v171, v161
	v_or_b32_e32 v174, 32, v166
	v_mov_b32_e32 v175, v161
	v_or_b32_e32 v178, 48, v166
	v_mov_b32_e32 v179, v161
	v_add_u32_e32 v182, 0x80, v166
	v_mov_b32_e32 v183, v161
	v_add_u32_e32 v186, 0x90, v166
	v_mov_b32_e32 v187, v161
	v_add_u32_e32 v190, 0xa0, v166
	v_mov_b32_e32 v191, v161
	v_add_u32_e32 v194, 0xb0, v166
	v_mov_b32_e32 v195, v161
	s_add_i32 s60, 0, 0x10000
	s_add_i32 s61, 0, 0x14000
	s_sext_i32_i8 s65, s6
	v_lshlrev_b64 v[168:169], 13, v[166:167]
	v_lshlrev_b64 v[172:173], 13, v[170:171]
	v_lshlrev_b64 v[176:177], 13, v[174:175]
	v_lshlrev_b64 v[180:181], 13, v[178:179]
	v_lshlrev_b64 v[184:185], 13, v[182:183]
	v_lshlrev_b64 v[188:189], 13, v[186:187]
	v_lshlrev_b64 v[192:193], 13, v[190:191]
	v_lshlrev_b64 v[196:197], 13, v[194:195]
	s_waitcnt lgkmcnt(0)
	s_ashr_i32 s59, s51, 31
	v_lshl_or_b32 v167, v2, 2, s22
	v_add3_u32 v198, v12, v10, v11
	v_mov_b32_e32 v199, v161
	v_add3_u32 v200, v13, v10, v11
	v_mov_b32_e32 v201, v161
	v_mov_b64_e32 v[202:203], 0x400
	v_mov_b64_e32 v[204:205], 0x3ff
	v_add_u32_e32 v171, s60, v1
	v_add_u32_e32 v175, 0, v5
	v_add_u32_e32 v179, s61, v1
	s_movk_i32 s62, 0x1800
	s_mov_b32 s20, 0x3fd744fd
	v_mov_b32_e32 v183, 0x8000
	s_barrier

; #define PG8_STAGE(bufoff, gbase, voff) do { _Pragma("unroll") for (int _i = 0; _i < 2; ++_i) \
;         __builtin_amdgcn_global_load_lds((const unsigned*)((const char*)(gbase) + (voff)[_i]), (LAS unsigned*)(lds + (bufoff) + ldsw + _i * 8192), 16, 0, 0); } while (0)
; #define PG8_LDA(dst, b, h) do { _Pragma("unroll") for (int m = 0; m < 4; ++m) _Pragma("unroll") for (int k = 0; k < 2; ++k) dst[m][k] = *(const LAS bf16x8*)(lds + PG8_SA(b, h) + aoff + m * 2048 + k * 1024); } while (0)
; #define PG8_LDB(dst, b, h) do { _Pragma("unroll") for (int n = 0; n < 2; ++n) _Pragma("unroll") for (int k = 0; k < 2; ++k) dst[n][k] = *(const LAS bf16x8*)(lds + PG8_SB(b, h) + boff + n * 2048 + k * 1024); } while (0)
; #define PG8_MMA(ai, bj, At, Bt) do { __builtin_amdgcn_s_setprio(1); _Pragma("unroll") for (int m = 0; m < 4; ++m) _Pragma("unroll") for (int n = 0; n < 2; ++n) _Pragma("unroll") for (int k = 0; k < 2; ++k) \
;         acc[ai][bj][m][n] = __builtin_amdgcn_mfma_f32_16x16x32_bf16(Bt[n][k], At[m][k], acc[ai][bj][m][n], 0, 0, 0); __builtin_amdgcn_s_setprio(0); } while (0)
; #define PG8_WAIT_V(n) asm volatile("s_waitcnt vmcnt(" #n ")" ::: "memory")
; #define PG8_WAIT_L(n) asm volatile("s_waitcnt lgkmcnt(" #n ")" ::: "memory")
; #define PG8_BAR __builtin_amdgcn_s_barrier()
; #define PG8_SCHED __builtin_amdgcn_sched_barrier(0)
; template <class Epi>
; DI void gemm_phase(LAS unsigned char* lds, const Gemm g, const StaticOrder& S, const Epi& E) {
;     ...
;             PG8_LDB(B0, 0, 0); PG8_SCHED; PG8_LDA(At, 0, 0); PG8_STAGE(PG8_SA(1, 1), a1 + hstepA, voffA);
;             PG8_WAIT_L(8); PG8_BAR; PG8_WAIT_L(0); PG8_MMA(0, 0, At, B0); PG8_BAR; PG8_SCHED;
;             PG8_LDB(B1, 0, 1); PG8_STAGE(PG8_SB(0, 0), b2, voffB);
;             PG8_BAR; PG8_WAIT_L(0); PG8_MMA(0, 1, At, B1); PG8_BAR;
;             PG8_LDA(At, 0, 1); PG8_STAGE(PG8_SA(0, 0), a2, voffA);
;             PG8_BAR; PG8_WAIT_L(0); PG8_MMA(1, 0, At, B0); PG8_BAR; PG8_SCHED;
;             PG8_STAGE(PG8_SB(0, 1), b2 + hstepB, voffB);
;             PG8_WAIT_V(6); PG8_BAR; PG8_MMA(1, 1, At, B1); PG8_BAR;
.LBB0_1292:
	ds_read_b128 v[130:133], v171
	ds_read_b128 v[134:137], v171 offset:1024
	ds_read_b128 v[138:141], v171 offset:2048
	ds_read_b128 v[142:145], v171 offset:3072
	s_add_u32 s28, s6, 0xffefc080
	s_addc_u32 s29, s7, -1
	s_cmp_eq_u32 s69, 28
	s_cselect_b32 s31, s25, s29
	s_cselect_b32 s30, s24, s28
	s_cselect_b32 s29, s23, s68
	s_cselect_b32 s28, s66, s67
	v_lshl_add_u64 v[214:215], s[6:7], 0, v[198:199]
	s_add_i32 m0, s39, 0xc000
	ds_read_b128 v[146:149], v175
	ds_read_b128 v[150:153], v175 offset:1024
	ds_read_b128 v[154:157], v175 offset:2048
	ds_read_b128 v[206:209], v175 offset:3072
	ds_read_b128 v[210:213], v175 offset:4096
	ds_read_b128 v[218:221], v175 offset:5120
	ds_read_b128 v[222:225], v175 offset:6144
	ds_read_b128 v[226:229], v175 offset:7168
	global_load_lds_dwordx4 v[214:215], off
	v_lshl_add_u64 v[214:215], s[6:7], 0, v[200:201]
	s_add_i32 m0, s39, 0xe000
	s_nop 0
	global_load_lds_dwordx4 v[214:215], off
	ds_read_b128 v[230:233], v179
	ds_read_b128 v[234:237], v179 offset:1024
	ds_read_b128 v[238:241], v179 offset:2048
	ds_read_b128 v[242:245], v179 offset:3072
	s_waitcnt lgkmcnt(0)
	s_waitcnt vmcnt(8)
	s_barrier
	s_setprio 1
	v_mfma_f32_16x16x32_bf16 v[126:129], v[130:133], v[146:149], v[126:129]
	v_mfma_f32_16x16x32_bf16 v[102:105], v[138:141], v[146:149], v[102:105]
	v_mfma_f32_16x16x32_bf16 v[122:125], v[130:133], v[154:157], v[122:125]
	v_mfma_f32_16x16x32_bf16 v[94:97], v[138:141], v[154:157], v[94:97]
	v_mfma_f32_16x16x32_bf16 v[118:121], v[130:133], v[210:213], v[118:121]
	v_mfma_f32_16x16x32_bf16 v[86:89], v[138:141], v[210:213], v[86:89]
	v_mfma_f32_16x16x32_bf16 v[114:117], v[130:133], v[222:225], v[114:117]
	v_mfma_f32_16x16x32_bf16 v[82:85], v[138:141], v[222:225], v[82:85]
	v_mfma_f32_16x16x32_bf16 v[126:129], v[134:137], v[150:153], v[126:129]
	v_mfma_f32_16x16x32_bf16 v[102:105], v[142:145], v[150:153], v[102:105]
	v_mfma_f32_16x16x32_bf16 v[122:125], v[134:137], v[206:209], v[122:125]
	v_mfma_f32_16x16x32_bf16 v[94:97], v[142:145], v[206:209], v[94:97]
	v_mfma_f32_16x16x32_bf16 v[118:121], v[134:137], v[218:221], v[118:121]
	v_mfma_f32_16x16x32_bf16 v[86:89], v[142:145], v[218:221], v[86:89]
	v_mfma_f32_16x16x32_bf16 v[114:117], v[134:137], v[226:229], v[114:117]
	v_mfma_f32_16x16x32_bf16 v[82:85], v[142:145], v[226:229], v[82:85]
	v_mfma_f32_16x16x32_bf16 v[66:69], v[230:233], v[146:149], v[66:69]
	v_mfma_f32_16x16x32_bf16 v[38:41], v[238:241], v[146:149], v[38:41]
	v_mfma_f32_16x16x32_bf16 v[58:61], v[230:233], v[154:157], v[58:61]
	v_mfma_f32_16x16x32_bf16 v[30:33], v[238:241], v[154:157], v[30:33]
	v_mfma_f32_16x16x32_bf16 v[54:57], v[230:233], v[210:213], v[54:57]
	v_mfma_f32_16x16x32_bf16 v[22:25], v[238:241], v[210:213], v[22:25]
	v_mfma_f32_16x16x32_bf16 v[50:53], v[230:233], v[222:225], v[50:53]
	v_mfma_f32_16x16x32_bf16 v[18:21], v[238:241], v[222:225], v[18:21]
	v_mfma_f32_16x16x32_bf16 v[66:69], v[234:237], v[150:153], v[66:69]
	v_mfma_f32_16x16x32_bf16 v[38:41], v[242:245], v[150:153], v[38:41]
	v_mfma_f32_16x16x32_bf16 v[58:61], v[234:237], v[206:209], v[58:61]
	v_mfma_f32_16x16x32_bf16 v[30:33], v[242:245], v[206:209], v[30:33]
	v_mfma_f32_16x16x32_bf16 v[54:57], v[234:237], v[218:221], v[54:57]
	v_mfma_f32_16x16x32_bf16 v[22:25], v[242:245], v[218:221], v[22:25]
	v_mfma_f32_16x16x32_bf16 v[50:53], v[234:237], v[226:229], v[50:53]
	v_mfma_f32_16x16x32_bf16 v[18:21], v[242:245], v[226:229], v[18:21]
	s_setprio 0
	s_barrier
	s_add_i32 s70, s60, s38
	v_lshl_add_u64 v[214:215], s[28:29], 0, v[160:161]
	s_mov_b32 m0, s70
	s_nop 0
	global_load_lds_dwordx4 v[214:215], off
	v_lshl_add_u64 v[216:217], s[28:29], 0, v[164:165]
	s_add_i32 m0, s70, 0x2000
	s_nop 0
	global_load_lds_dwordx4 v[216:217], off
	s_mov_b32 m0, s39
	v_lshl_add_u64 v[246:247], s[30:31], 0, v[158:159]
	ds_read_b128 v[146:149], v175 offset:16384
	ds_read_b128 v[150:153], v175 offset:17408
	ds_read_b128 v[154:157], v175 offset:18432
	ds_read_b128 v[206:209], v175 offset:19456
	ds_read_b128 v[210:213], v175 offset:20480
	ds_read_b128 v[218:221], v175 offset:21504
	ds_read_b128 v[222:225], v175 offset:22528
	ds_read_b128 v[226:229], v175 offset:23552
	global_load_lds_dwordx4 v[246:247], off
	v_lshl_add_u64 v[248:249], s[30:31], 0, v[162:163]
	s_mov_b32 m0, s48
	s_nop 0
	global_load_lds_dwordx4 v[248:249], off
	s_add_u32 s70, s28, 0x80000
	s_addc_u32 s71, s29, 0
	s_add_i32 s72, s61, s38
	v_lshl_add_u64 v[250:251], s[70:71], 0, v[160:161]
	s_mov_b32 m0, s72
	s_nop 0
	global_load_lds_dwordx4 v[250:251], off
	v_lshl_add_u64 v[250:251], s[70:71], 0, v[164:165]
	s_add_i32 m0, s72, 0x2000
	s_nop 0
	global_load_lds_dwordx4 v[250:251], off
	s_waitcnt lgkmcnt(0)
	s_waitcnt vmcnt(8)
	s_barrier
; #define PG8_STAGE(bufoff, gbase, voff) do { _Pragma("unroll") for (int _i = 0; _i < 2; ++_i) \
;         __builtin_amdgcn_global_load_lds((const unsigned*)((const char*)(gbase) + (voff)[_i]), (LAS unsigned*)(lds + (bufoff) + ldsw + _i * 8192), 16, 0, 0); } while (0)
; #define PG8_LDA(dst, b, h) do { _Pragma("unroll") for (int m = 0; m < 4; ++m) _Pragma("unroll") for (int k = 0; k < 2; ++k) dst[m][k] = *(const LAS bf16x8*)(lds + PG8_SA(b, h) + aoff + m * 2048 + k * 1024); } while (0)
; #define PG8_LDB(dst, b, h) do { _Pragma("unroll") for (int n = 0; n < 2; ++n) _Pragma("unroll") for (int k = 0; k < 2; ++k) dst[n][k] = *(const LAS bf16x8*)(lds + PG8_SB(b, h) + boff + n * 2048 + k * 1024); } while (0)
; #define PG8_MMA(ai, bj, At, Bt) do { __builtin_amdgcn_s_setprio(1); _Pragma("unroll") for (int m = 0; m < 4; ++m) _Pragma("unroll") for (int n = 0; n < 2; ++n) _Pragma("unroll") for (int k = 0; k < 2; ++k) \
;         acc[ai][bj][m][n] = __builtin_amdgcn_mfma_f32_16x16x32_bf16(Bt[n][k], At[m][k], acc[ai][bj][m][n], 0, 0, 0); __builtin_amdgcn_s_setprio(0); } while (0)
; #define PG8_WAIT_V(n) asm volatile("s_waitcnt vmcnt(" #n ")" ::: "memory")
; #define PG8_WAIT_L(n) asm volatile("s_waitcnt lgkmcnt(" #n ")" ::: "memory")
; #define PG8_BAR __builtin_amdgcn_s_barrier()
; #define PG8_SCHED __builtin_amdgcn_sched_barrier(0)
; template <class Epi>
; DI void gemm_phase(LAS unsigned char* lds, const Gemm g, const StaticOrder& S, const Epi& E) {
;     ...
;             PG8_BAR; PG8_WAIT_L(0); PG8_MMA(1, 0, At, B0); PG8_BAR; PG8_SCHED;
;             PG8_STAGE(PG8_SB(0, 1), b2 + hstepB, voffB);
;             PG8_WAIT_V(6); PG8_BAR; PG8_MMA(1, 1, At, B1); PG8_BAR;
;             PG8_LDB(B0, 1, 0); PG8_SCHED; PG8_LDA(At, 1, 0); PG8_STAGE(PG8_SA(0, 1), a2 + hstepA, voffA);
;             PG8_WAIT_L(8); PG8_BAR; PG8_WAIT_L(0); PG8_MMA(0, 0, At, B0); PG8_BAR; PG8_SCHED;
;             PG8_LDB(B1, 1, 1); PG8_STAGE(PG8_SB(1, 0), b3, voffB);
;             PG8_BAR; PG8_WAIT_L(0); PG8_MMA(0, 1, At, B1); PG8_BAR;
;             PG8_LDA(At, 1, 1); PG8_STAGE(PG8_SA(1, 0), a3, voffA);
;             PG8_BAR; PG8_WAIT_L(0); PG8_MMA(1, 0, At, B0); PG8_BAR; PG8_SCHED;
	s_setprio 1
	v_mfma_f32_16x16x32_bf16 v[110:113], v[130:133], v[146:149], v[110:113]
	v_mfma_f32_16x16x32_bf16 v[78:81], v[138:141], v[146:149], v[78:81]
	v_mfma_f32_16x16x32_bf16 v[106:109], v[130:133], v[154:157], v[106:109]
	v_mfma_f32_16x16x32_bf16 v[74:77], v[138:141], v[154:157], v[74:77]
	v_mfma_f32_16x16x32_bf16 v[98:101], v[130:133], v[210:213], v[98:101]
	v_mfma_f32_16x16x32_bf16 v[70:73], v[138:141], v[210:213], v[70:73]
	v_mfma_f32_16x16x32_bf16 v[90:93], v[130:133], v[222:225], v[90:93]
	v_mfma_f32_16x16x32_bf16 v[62:65], v[138:141], v[222:225], v[62:65]
	v_mfma_f32_16x16x32_bf16 v[110:113], v[134:137], v[150:153], v[110:113]
	v_mfma_f32_16x16x32_bf16 v[78:81], v[142:145], v[150:153], v[78:81]
	v_mfma_f32_16x16x32_bf16 v[106:109], v[134:137], v[206:209], v[106:109]
	v_mfma_f32_16x16x32_bf16 v[74:77], v[142:145], v[206:209], v[74:77]
	v_mfma_f32_16x16x32_bf16 v[98:101], v[134:137], v[218:221], v[98:101]
	v_mfma_f32_16x16x32_bf16 v[70:73], v[142:145], v[218:221], v[70:73]
	v_mfma_f32_16x16x32_bf16 v[90:93], v[134:137], v[226:229], v[90:93]
	v_mfma_f32_16x16x32_bf16 v[62:65], v[142:145], v[226:229], v[62:65]
	v_mfma_f32_16x16x32_bf16 v[46:49], v[230:233], v[146:149], v[46:49]
	v_mfma_f32_16x16x32_bf16 v[14:17], v[238:241], v[146:149], v[14:17]
	v_mfma_f32_16x16x32_bf16 v[42:45], v[230:233], v[154:157], v[42:45]
	v_mfma_f32_16x16x32_bf16 v[10:13], v[238:241], v[154:157], v[10:13]
	v_mfma_f32_16x16x32_bf16 v[34:37], v[230:233], v[210:213], v[34:37]
	v_mfma_f32_16x16x32_bf16 v[6:9], v[238:241], v[210:213], v[6:9]
	v_mfma_f32_16x16x32_bf16 v[26:29], v[230:233], v[222:225], v[26:29]
	v_mfma_f32_16x16x32_bf16 v[2:5], v[238:241], v[222:225], v[2:5]
	v_mfma_f32_16x16x32_bf16 v[46:49], v[234:237], v[150:153], v[46:49]
	v_mfma_f32_16x16x32_bf16 v[14:17], v[242:245], v[150:153], v[14:17]
	v_mfma_f32_16x16x32_bf16 v[42:45], v[234:237], v[206:209], v[42:45]
	v_mfma_f32_16x16x32_bf16 v[10:13], v[242:245], v[206:209], v[10:13]
	v_mfma_f32_16x16x32_bf16 v[34:37], v[234:237], v[218:221], v[34:37]
	v_mfma_f32_16x16x32_bf16 v[6:9], v[242:245], v[218:221], v[6:9]
	v_mfma_f32_16x16x32_bf16 v[26:29], v[234:237], v[226:229], v[26:29]
	v_mfma_f32_16x16x32_bf16 v[2:5], v[242:245], v[226:229], v[2:5]
	s_setprio 0
	s_add_i32 s70, 0, 0x18000
	v_add_u32_e32 v142, s70, v1
	s_barrier
	ds_read_b128 v[130:133], v142
	ds_read_b128 v[134:137], v142 offset:1024
	ds_read_b128 v[138:141], v142 offset:2048
	ds_read_b128 v[142:145], v142 offset:3072
	s_add_u32 s30, s30, 0x104000
	s_addc_u32 s31, s31, 0
	s_mov_b32 m0, s49
	v_lshl_add_u64 v[230:231], s[30:31], 0, v[158:159]
	ds_read_b128 v[146:149], v175 offset:32768
	ds_read_b128 v[150:153], v175 offset:33792
	ds_read_b128 v[154:157], v175 offset:34816
	ds_read_b128 v[206:209], v175 offset:35840
	ds_read_b128 v[210:213], v175 offset:36864
	ds_read_b128 v[218:221], v175 offset:37888
	ds_read_b128 v[222:225], v175 offset:38912
	ds_read_b128 v[226:229], v175 offset:39936
	global_load_lds_dwordx4 v[230:231], off
	v_lshl_add_u64 v[230:231], s[30:31], 0, v[162:163]
	s_mov_b32 m0, s50
	s_nop 0
	global_load_lds_dwordx4 v[230:231], off
	s_add_i32 s30, 0, 0x1c000
	v_add_u32_e32 v187, s30, v1
	ds_read_b128 v[230:233], v187
	ds_read_b128 v[234:237], v187 offset:1024
	ds_read_b128 v[238:241], v187 offset:2048
	ds_read_b128 v[242:245], v187 offset:3072
	s_waitcnt lgkmcnt(0)
	s_waitcnt vmcnt(8)
	s_barrier
	s_setprio 1
	v_mfma_f32_16x16x32_bf16 v[126:129], v[130:133], v[146:149], v[126:129]
	v_mfma_f32_16x16x32_bf16 v[102:105], v[138:141], v[146:149], v[102:105]
	v_mfma_f32_16x16x32_bf16 v[122:125], v[130:133], v[154:157], v[122:125]
	v_mfma_f32_16x16x32_bf16 v[94:97], v[138:141], v[154:157], v[94:97]
	v_mfma_f32_16x16x32_bf16 v[118:121], v[130:133], v[210:213], v[118:121]
	v_mfma_f32_16x16x32_bf16 v[86:89], v[138:141], v[210:213], v[86:89]
	v_mfma_f32_16x16x32_bf16 v[114:117], v[130:133], v[222:225], v[114:117]
	v_mfma_f32_16x16x32_bf16 v[82:85], v[138:141], v[222:225], v[82:85]
	v_mfma_f32_16x16x32_bf16 v[126:129], v[134:137], v[150:153], v[126:129]
	v_mfma_f32_16x16x32_bf16 v[102:105], v[142:145], v[150:153], v[102:105]
	v_mfma_f32_16x16x32_bf16 v[122:125], v[134:137], v[206:209], v[122:125]
	v_mfma_f32_16x16x32_bf16 v[94:97], v[142:145], v[206:209], v[94:97]
	v_mfma_f32_16x16x32_bf16 v[118:121], v[134:137], v[218:221], v[118:121]
	v_mfma_f32_16x16x32_bf16 v[86:89], v[142:145], v[218:221], v[86:89]
	v_mfma_f32_16x16x32_bf16 v[114:117], v[134:137], v[226:229], v[114:117]
	v_mfma_f32_16x16x32_bf16 v[82:85], v[142:145], v[226:229], v[82:85]
	v_mfma_f32_16x16x32_bf16 v[66:69], v[230:233], v[146:149], v[66:69]
	v_mfma_f32_16x16x32_bf16 v[38:41], v[238:241], v[146:149], v[38:41]
	v_mfma_f32_16x16x32_bf16 v[58:61], v[230:233], v[154:157], v[58:61]
	v_mfma_f32_16x16x32_bf16 v[30:33], v[238:241], v[154:157], v[30:33]
	v_mfma_f32_16x16x32_bf16 v[54:57], v[230:233], v[210:213], v[54:57]
	v_mfma_f32_16x16x32_bf16 v[22:25], v[238:241], v[210:213], v[22:25]
	v_mfma_f32_16x16x32_bf16 v[50:53], v[230:233], v[222:225], v[50:53]
	v_mfma_f32_16x16x32_bf16 v[18:21], v[238:241], v[222:225], v[18:21]
	v_mfma_f32_16x16x32_bf16 v[66:69], v[234:237], v[150:153], v[66:69]
	v_mfma_f32_16x16x32_bf16 v[38:41], v[242:245], v[150:153], v[38:41]
	v_mfma_f32_16x16x32_bf16 v[58:61], v[234:237], v[206:209], v[58:61]
	v_mfma_f32_16x16x32_bf16 v[30:33], v[242:245], v[206:209], v[30:33]
	v_mfma_f32_16x16x32_bf16 v[54:57], v[234:237], v[218:221], v[54:57]
	v_mfma_f32_16x16x32_bf16 v[22:25], v[242:245], v[218:221], v[22:25]
	v_mfma_f32_16x16x32_bf16 v[50:53], v[234:237], v[226:229], v[50:53]
	v_mfma_f32_16x16x32_bf16 v[18:21], v[242:245], v[226:229], v[18:21]
	s_setprio 0
	s_barrier
; #define PG8_STAGE(bufoff, gbase, voff) do { _Pragma("unroll") for (int _i = 0; _i < 2; ++_i) \
;         __builtin_amdgcn_global_load_lds((const unsigned*)((const char*)(gbase) + (voff)[_i]), (LAS unsigned*)(lds + (bufoff) + ldsw + _i * 8192), 16, 0, 0); } while (0)
; #define PG8_LDA(dst, b, h) do { _Pragma("unroll") for (int m = 0; m < 4; ++m) _Pragma("unroll") for (int k = 0; k < 2; ++k) dst[m][k] = *(const LAS bf16x8*)(lds + PG8_SA(b, h) + aoff + m * 2048 + k * 1024); } while (0)
; #define PG8_WAIT_V(n) asm volatile("s_waitcnt vmcnt(" #n ")" ::: "memory")
; template <class Epi>
; DI void gemm_phase(LAS unsigned char* lds, const Gemm g, const StaticOrder& S, const Epi& E) {
;     ...
;             PG8_LDB(B1, 1, 1); PG8_STAGE(PG8_SB(1, 0), b3, voffB);
;             PG8_BAR; PG8_WAIT_L(0); PG8_MMA(0, 1, At, B1); PG8_BAR;
;             PG8_LDA(At, 1, 1); PG8_STAGE(PG8_SA(1, 0), a3, voffA);
;             PG8_BAR; PG8_WAIT_L(0); PG8_MMA(1, 0, At, B0); PG8_BAR; PG8_SCHED;
;             PG8_STAGE(PG8_SB(1, 1), b3 + hstepB, voffB);
;             PG8_WAIT_V(6); PG8_BAR; PG8_MMA(1, 1, At, B1); PG8_BAR;
;         }
;         E(acc, cur, wr, wc, fr, fq);
;         if (!has_next) break;
;     DI void operator()(const f32x4 (&acc)[2][2][4][2], const pg8::Unit& u, int wr, int wc, int fr, int fq) const {
;         const int rowt = row_base + u.pm * 256, col0 = u.pn * 256 + wc * 32 + 4 * fq, rl = wr * 64 + fr;
;         const int cd = cond_of_row(rowt);
;         const float* gtp = gt0 + (size_t)cd * 6144;
;         float* dbase = rowt < TL ? out + (size_t)rowt * D : ctxv + (size_t)(rowt - TL) * D;
;         const float* sbase = mode ? (const float*)dbase : (rowt < TL ? xin + (size_t)rowt * D : cin + (size_t)(rowt - TL) * D);
; #pragma unroll
;         for (int bj = 0; bj < 2; ++bj) {
;             f32x4 gv[2], gg[2], bb[2], xv[2][8];
; #pragma unroll
;             for (int n = 0; n < 2; ++n) {
;                 const int c = col0 + bj * 128 + n * 16;
;                 gv[n] = *(const f32x4*)(gtp + c);
;                 gg[n] = (f32x4){1.f, 1.f, 1.f, 1.f}; bb[n] = (f32x4){0.f, 0.f, 0.f, 0.f};
;                 if (mode) { gg[n] = *(const f32x4*)(lg + c); bb[n] = *(const f32x4*)(lb + c); }
; #pragma unroll
;                 for (int q = 0; q < 8; ++q) { const int rr = rl + (q >> 2) * 128 + (q & 3) * 16; xv[n][q] = *(const f32x4*)(sbase + (size_t)rr * D + c); }
	s_add_i32 s31, s70, s38
	v_lshl_add_u64 v[214:215], v[214:215], 0, s[18:19]
	s_mov_b32 m0, s31
	s_nop 0
	global_load_lds_dwordx4 v[214:215], off
	v_lshl_add_u64 v[214:215], v[216:217], 0, s[18:19]
	s_add_i32 m0, s31, 0x2000
	s_nop 0
	global_load_lds_dwordx4 v[214:215], off
	s_mov_b32 m0, s57
	v_lshl_add_u64 v[214:215], v[246:247], 0, s[18:19]
	ds_read_b128 v[146:149], v175 offset:49152
	ds_read_b128 v[150:153], v175 offset:50176
	ds_read_b128 v[154:157], v175 offset:51200
	ds_read_b128 v[206:209], v175 offset:52224
	ds_read_b128 v[210:213], v175 offset:53248
	ds_read_b128 v[218:221], v175 offset:54272
	ds_read_b128 v[222:225], v175 offset:55296
	ds_read_b128 v[226:229], v175 offset:56320
	global_load_lds_dwordx4 v[214:215], off
	v_lshl_add_u64 v[214:215], v[248:249], 0, s[18:19]
	s_mov_b32 m0, s58
	s_nop 0
	global_load_lds_dwordx4 v[214:215], off
	s_add_u32 s28, s28, 0x80080
	s_addc_u32 s29, s29, 0
	s_add_i32 s30, s30, s38
	v_lshl_add_u64 v[250:251], s[28:29], 0, v[160:161]
	s_mov_b32 m0, s30
	s_nop 0
	global_load_lds_dwordx4 v[250:251], off
	v_lshl_add_u64 v[250:251], s[28:29], 0, v[164:165]
	s_add_i32 m0, s30, 0x2000
	s_nop 0
	global_load_lds_dwordx4 v[250:251], off
	s_waitcnt lgkmcnt(0)
	s_waitcnt vmcnt(8)
	s_barrier
	s_setprio 1
	v_mfma_f32_16x16x32_bf16 v[110:113], v[130:133], v[146:149], v[110:113]
	v_mfma_f32_16x16x32_bf16 v[78:81], v[138:141], v[146:149], v[78:81]
	v_mfma_f32_16x16x32_bf16 v[106:109], v[130:133], v[154:157], v[106:109]
	v_mfma_f32_16x16x32_bf16 v[74:77], v[138:141], v[154:157], v[74:77]
	v_mfma_f32_16x16x32_bf16 v[98:101], v[130:133], v[210:213], v[98:101]
	v_mfma_f32_16x16x32_bf16 v[70:73], v[138:141], v[210:213], v[70:73]
	v_mfma_f32_16x16x32_bf16 v[90:93], v[130:133], v[222:225], v[90:93]
	v_mfma_f32_16x16x32_bf16 v[62:65], v[138:141], v[222:225], v[62:65]
	v_mfma_f32_16x16x32_bf16 v[110:113], v[134:137], v[150:153], v[110:113]
	v_mfma_f32_16x16x32_bf16 v[78:81], v[142:145], v[150:153], v[78:81]
	v_mfma_f32_16x16x32_bf16 v[106:109], v[134:137], v[206:209], v[106:109]
	v_mfma_f32_16x16x32_bf16 v[74:77], v[142:145], v[206:209], v[74:77]
	v_mfma_f32_16x16x32_bf16 v[98:101], v[134:137], v[218:221], v[98:101]
	v_mfma_f32_16x16x32_bf16 v[70:73], v[142:145], v[218:221], v[70:73]
	v_mfma_f32_16x16x32_bf16 v[90:93], v[134:137], v[226:229], v[90:93]
	v_mfma_f32_16x16x32_bf16 v[62:65], v[142:145], v[226:229], v[62:65]
	v_mfma_f32_16x16x32_bf16 v[46:49], v[230:233], v[146:149], v[46:49]
	v_mfma_f32_16x16x32_bf16 v[14:17], v[238:241], v[146:149], v[14:17]
	v_mfma_f32_16x16x32_bf16 v[42:45], v[230:233], v[154:157], v[42:45]
	v_mfma_f32_16x16x32_bf16 v[10:13], v[238:241], v[154:157], v[10:13]
	v_mfma_f32_16x16x32_bf16 v[34:37], v[230:233], v[210:213], v[34:37]
	v_mfma_f32_16x16x32_bf16 v[6:9], v[238:241], v[210:213], v[6:9]
	v_mfma_f32_16x16x32_bf16 v[26:29], v[230:233], v[222:225], v[26:29]
	v_mfma_f32_16x16x32_bf16 v[2:5], v[238:241], v[222:225], v[2:5]
	v_mfma_f32_16x16x32_bf16 v[46:49], v[234:237], v[150:153], v[46:49]
	v_mfma_f32_16x16x32_bf16 v[14:17], v[242:245], v[150:153], v[14:17]
	v_mfma_f32_16x16x32_bf16 v[42:45], v[234:237], v[206:209], v[42:45]
	v_mfma_f32_16x16x32_bf16 v[10:13], v[242:245], v[206:209], v[10:13]
	v_mfma_f32_16x16x32_bf16 v[34:37], v[234:237], v[218:221], v[34:37]
	v_mfma_f32_16x16x32_bf16 v[6:9], v[242:245], v[218:221], v[6:9]
	v_mfma_f32_16x16x32_bf16 v[26:29], v[234:237], v[226:229], v[26:29]
	v_mfma_f32_16x16x32_bf16 v[2:5], v[242:245], v[226:229], v[2:5]
	s_setprio 0
	s_add_i32 s69, s69, 2
	s_add_u32 s6, s6, 0x100
	s_addc_u32 s7, s7, 0
	s_add_u32 s67, s67, 0x100
	s_addc_u32 s68, s68, 0
	s_cmp_gt_u32 s69, 29
	s_barrier
	s_cbranch_scc0 .LBB0_1292
	s_lshl_b32 s6, s64, 8
	v_sub_co_u32_e32 v131, vcc, s6, v183
	s_and_b64 s[28:29], vcc, exec
	s_cselect_b32 s7, s62, 0x3000
	s_cmp_gt_i32 s64, 63
	s_cselect_b32 s7, s7, 0
	s_lshl_b32 s7, s7, 2
	s_add_u32 s28, s55, s7
	s_addc_u32 s29, s56, 0
	s_ashr_i32 s7, s6, 31
	s_cmpk_lt_i32 s64, 0x80
	v_mov_b32_e32 v132, s7
	s_cselect_b64 vcc, -1, 0
	v_cndmask_b32_e32 v133, 0, v132, vcc
	v_mov_b32_e32 v132, s6
	v_lshl_or_b32 v130, s65, 8, v167
	v_cndmask_b32_e32 v132, v131, v132, vcc
	s_cselect_b32 s31, s9, s54
	s_cselect_b32 s30, s8, s53
	v_lshlrev_b64 v[132:133], 13, v[132:133]
	v_ashrrev_i32_e32 v131, 31, v130
	v_lshl_add_u64 v[132:133], s[30:31], 0, v[132:133]
	v_lshlrev_b64 v[130:131], 2, v[130:131]
	v_lshl_add_u64 v[234:235], v[132:133], 0, v[130:131]
	v_add_lshl_u32 v132, s6, v166, 1
	v_ashrrev_i32_e32 v133, 31, v132
	v_lshl_add_u64 v[206:207], v[234:235], 0, v[168:169]
	v_lshl_add_u64 v[210:211], v[132:133], 2, s[10:11]
	global_load_dwordx4 v[218:221], v[206:207], off
	global_load_dwordx2 v[214:215], v[210:211], off
	v_lshl_add_u64 v[228:229], s[12:13], 0, v[130:131]
	v_lshl_add_u64 v[230:231], s[14:15], 0, v[130:131]
	global_load_dwordx4 v[146:149], v[228:229], off
	global_load_dwordx4 v[150:153], v[230:231], off
	v_lshl_add_u64 v[232:233], s[28:29], 0, v[130:131]
	global_load_dwordx4 v[142:145], v[232:233], off
	v_add_lshl_u32 v130, s6, v170, 1
	v_ashrrev_i32_e32 v131, 31, v130
	v_lshl_add_u64 v[208:209], v[234:235], 0, v[172:173]
	v_lshl_add_u64 v[212:213], v[130:131], 2, s[10:11]
	global_load_dwordx4 v[134:137], v[228:229], off offset:64
	global_load_dwordx4 v[138:141], v[230:231], off offset:64
	global_load_dwordx4 v[130:133], v[232:233], off offset:64
	global_load_dwordx4 v[222:225], v[208:209], off
	global_load_dwordx4 v[154:157], v[206:207], off offset:64
	s_mov_b32 s65, s22
	s_mov_b64 s[28:29], s[26:27]
	s_mov_b64 s[30:31], s[24:25]
	s_mov_b32 s64, s63
	s_and_b64 vcc, exec, s[4:5]
	s_waitcnt vmcnt(0)
;     DI void operator()(const f32x4 (&acc)[2][2][4][2], const pg8::Unit& u, int wr, int wc, int fr, int fq) const {
;     ...
;             for (int n = 0; n < 2; ++n) {
;                 const int c = col0 + bj * 128 + n * 16;
; #pragma unroll
;                 for (int q = 0; q < 8; ++q) {
;                     const int rr = rl + (q >> 2) * 128 + (q & 3) * 16;
;                     f32x4 x = xv[n][q];
;                     if (mode) { const float mu = stats[2 * (rowt + rr)], rs = stats[2 * (rowt + rr) + 1]; x = (x - mu) * rs * gg[n] + bb[n]; }
;                     *(f32x4*)(dbase + (size_t)rr * D + c) = ALPHA * x + gv[n] * acc[q >> 2][bj][q & 3][n];
;                 }
;             }
	v_sub_f32_e32 v221, v221, v214
	v_sub_f32_e32 v220, v220, v214
	v_sub_f32_e32 v219, v219, v214
	v_sub_f32_e32 v218, v218, v214
	v_pk_mul_f32 v[218:219], v[218:219], v[214:215] op_sel:[0,1]
	v_pk_mul_f32 v[214:215], v[220:221], v[214:215] op_sel:[0,1]
	v_pk_fma_f32 v[218:219], v[146:147], v[218:219], v[150:151]
	v_pk_fma_f32 v[214:215], v[148:149], v[214:215], v[152:153]
	v_pk_mul_f32 v[218:219], v[218:219], s[20:21] op_sel_hi:[1,0]
	v_pk_mul_f32 v[214:215], v[214:215], s[20:21] op_sel_hi:[1,0]
	v_pk_fma_f32 v[126:127], v[126:127], v[142:143], v[218:219]
	v_pk_fma_f32 v[128:129], v[128:129], v[144:145], v[214:215]
	global_store_dwordx4 v[206:207], v[126:129], off
	global_load_dword v187, v[212:213], off
	global_load_dword v218, v[212:213], off offset:4
	v_add_lshl_u32 v126, s6, v174, 1
	v_ashrrev_i32_e32 v127, 31, v126
	v_lshl_add_u64 v[214:215], v[234:235], 0, v[176:177]
	v_lshl_add_u64 v[220:221], v[126:127], 2, s[10:11]
	global_load_dwordx4 v[236:239], v[214:215], off
	global_load_dwordx4 v[126:129], v[208:209], off offset:64
	s_waitcnt vmcnt(0)
	v_sub_f32_e32 v225, v225, v187
	v_sub_f32_e32 v224, v224, v187
	v_sub_f32_e32 v223, v223, v187
	v_sub_f32_e32 v222, v222, v187
	v_pk_mul_f32 v[222:223], v[222:223], v[218:219] op_sel_hi:[1,0]
	v_pk_mul_f32 v[218:219], v[224:225], v[218:219] op_sel_hi:[1,0]
	v_pk_fma_f32 v[222:223], v[146:147], v[222:223], v[150:151]
	v_pk_fma_f32 v[218:219], v[148:149], v[218:219], v[152:153]
	v_pk_mul_f32 v[222:223], v[222:223], s[20:21] op_sel_hi:[1,0]
	v_pk_mul_f32 v[218:219], v[218:219], s[20:21] op_sel_hi:[1,0]
	v_pk_fma_f32 v[122:123], v[122:123], v[142:143], v[222:223]
	v_pk_fma_f32 v[124:125], v[124:125], v[144:145], v[218:219]
	global_store_dwordx4 v[208:209], v[122:125], off
	global_load_dword v187, v[220:221], off
	global_load_dword v222, v[220:221], off offset:4
	v_add_lshl_u32 v122, s6, v178, 1
	v_ashrrev_i32_e32 v123, 31, v122
	v_lshl_add_u64 v[218:219], v[234:235], 0, v[180:181]
	v_lshl_add_u64 v[224:225], v[122:123], 2, s[10:11]
	global_load_dwordx4 v[240:243], v[218:219], off
	global_load_dwordx4 v[122:125], v[214:215], off offset:64
	s_waitcnt vmcnt(0)
	v_sub_f32_e32 v227, v239, v187
	v_sub_f32_e32 v226, v238, v187
	v_sub_f32_e32 v237, v237, v187
	v_sub_f32_e32 v236, v236, v187
	v_pk_mul_f32 v[236:237], v[236:237], v[222:223] op_sel_hi:[1,0]
	v_pk_mul_f32 v[222:223], v[226:227], v[222:223] op_sel_hi:[1,0]
	v_pk_fma_f32 v[226:227], v[146:147], v[236:237], v[150:151]
	v_pk_fma_f32 v[222:223], v[148:149], v[222:223], v[152:153]
	v_pk_mul_f32 v[226:227], v[226:227], s[20:21] op_sel_hi:[1,0]
	v_pk_mul_f32 v[222:223], v[222:223], s[20:21] op_sel_hi:[1,0]
	v_pk_fma_f32 v[118:119], v[118:119], v[142:143], v[226:227]
	v_pk_fma_f32 v[120:121], v[120:121], v[144:145], v[222:223]
	global_store_dwordx4 v[214:215], v[118:121], off
	global_load_dword v187, v[224:225], off
	global_load_dword v244, v[224:225], off offset:4
	v_add_lshl_u32 v118, s6, v182, 1
	v_ashrrev_i32_e32 v119, 31, v118
	v_lshl_add_u64 v[222:223], v[234:235], 0, v[184:185]
	v_lshl_add_u64 v[226:227], v[118:119], 2, s[10:11]
	global_load_dwordx4 v[236:239], v[222:223], off
	global_load_dwordx4 v[118:121], v[218:219], off offset:64
	s_waitcnt vmcnt(0)
	v_sub_f32_e32 v243, v243, v187
	v_sub_f32_e32 v242, v242, v187
	v_sub_f32_e32 v241, v241, v187
	v_sub_f32_e32 v240, v240, v187
	v_pk_mul_f32 v[240:241], v[240:241], v[244:245] op_sel_hi:[1,0]
	v_pk_mul_f32 v[242:243], v[242:243], v[244:245] op_sel_hi:[1,0]
	v_pk_fma_f32 v[240:241], v[146:147], v[240:241], v[150:151]
	v_pk_fma_f32 v[242:243], v[148:149], v[242:243], v[152:153]
	v_pk_mul_f32 v[240:241], v[240:241], s[20:21] op_sel_hi:[1,0]
	v_pk_mul_f32 v[242:243], v[242:243], s[20:21] op_sel_hi:[1,0]
	v_pk_fma_f32 v[114:115], v[114:115], v[142:143], v[240:241]
	v_pk_fma_f32 v[116:117], v[116:117], v[144:145], v[242:243]
	global_store_dwordx4 v[218:219], v[114:117], off
	global_load_dwordx2 v[248:249], v[226:227], off
	s_waitcnt vmcnt(0)
	v_sub_f32_e32 v239, v239, v248
	v_sub_f32_e32 v238, v238, v248
	v_sub_f32_e32 v237, v237, v248
	v_sub_f32_e32 v236, v236, v248
	v_pk_mul_f32 v[236:237], v[236:237], v[248:249] op_sel:[0,1]
	v_pk_mul_f32 v[238:239], v[238:239], v[248:249] op_sel:[0,1]
	v_add_lshl_u32 v114, s6, v186, 1
	v_pk_fma_f32 v[238:239], v[148:149], v[238:239], v[152:153]
	v_pk_fma_f32 v[236:237], v[146:147], v[236:237], v[150:151]
	v_ashrrev_i32_e32 v115, 31, v114
	v_pk_mul_f32 v[236:237], v[236:237], s[20:21] op_sel_hi:[1,0]
	v_pk_mul_f32 v[238:239], v[238:239], s[20:21] op_sel_hi:[1,0]
	v_lshl_add_u64 v[116:117], v[114:115], 2, s[10:11]
	v_lshl_add_u64 v[114:115], v[234:235], 0, v[188:189]
	v_pk_fma_f32 v[112:113], v[112:113], v[144:145], v[238:239]
	v_pk_fma_f32 v[110:111], v[110:111], v[142:143], v[236:237]
	global_load_dwordx4 v[240:243], v[114:115], off
	global_load_dwordx4 v[244:247], v[222:223], off offset:64
	s_nop 0
	global_store_dwordx4 v[222:223], v[110:113], off
	global_load_dword v187, v[116:117], off
	global_load_dword v252, v[116:117], off offset:4
	v_add_lshl_u32 v110, s6, v190, 1
	v_ashrrev_i32_e32 v111, 31, v110
	v_lshl_add_u64 v[112:113], v[110:111], 2, s[10:11]
	v_lshl_add_u64 v[110:111], v[234:235], 0, v[192:193]
	global_load_dwordx4 v[236:239], v[110:111], off
	global_load_dwordx4 v[248:251], v[114:115], off offset:64
	s_waitcnt vmcnt(0)
;     DI void operator()(const f32x4 (&acc)[2][2][4][2], const pg8::Unit& u, int wr, int wc, int fr, int fq) const {
;     ...
;             for (int n = 0; n < 2; ++n) {
;                 const int c = col0 + bj * 128 + n * 16;
; #pragma unroll
;                 for (int q = 0; q < 8; ++q) {
;                     const int rr = rl + (q >> 2) * 128 + (q & 3) * 16;
;                     f32x4 x = xv[n][q];
;                     if (mode) { const float mu = stats[2 * (rowt + rr)], rs = stats[2 * (rowt + rr) + 1]; x = (x - mu) * rs * gg[n] + bb[n]; }
;                     *(f32x4*)(dbase + (size_t)rr * D + c) = ALPHA * x + gv[n] * acc[q >> 2][bj][q & 3][n];
;                 }
;             }
	v_sub_f32_e32 v243, v243, v187
	v_sub_f32_e32 v242, v242, v187
	v_sub_f32_e32 v241, v241, v187
	v_sub_f32_e32 v240, v240, v187
	v_pk_mul_f32 v[240:241], v[240:241], v[252:253] op_sel_hi:[1,0]
	v_pk_mul_f32 v[242:243], v[242:243], v[252:253] op_sel_hi:[1,0]
	v_pk_fma_f32 v[240:241], v[146:147], v[240:241], v[150:151]
	v_pk_fma_f32 v[242:243], v[148:149], v[242:243], v[152:153]
	v_pk_mul_f32 v[240:241], v[240:241], s[20:21] op_sel_hi:[1,0]
	v_pk_mul_f32 v[242:243], v[242:243], s[20:21] op_sel_hi:[1,0]
	v_pk_fma_f32 v[106:107], v[106:107], v[142:143], v[240:241]
	v_pk_fma_f32 v[108:109], v[108:109], v[144:145], v[242:243]
	global_store_dwordx4 v[114:115], v[106:109], off
	global_load_dword v187, v[112:113], off
	global_load_dword v216, v[112:113], off offset:4
	v_add_lshl_u32 v106, s6, v194, 1
	v_ashrrev_i32_e32 v107, 31, v106
	v_lshl_add_u64 v[108:109], v[106:107], 2, s[10:11]
	v_lshl_add_u64 v[106:107], v[234:235], 0, v[196:197]
	global_load_dwordx4 v[240:243], v[106:107], off
	global_load_dwordx4 v[252:255], v[110:111], off offset:64
	s_waitcnt vmcnt(0)
	v_sub_f32_e32 v235, v239, v187
	v_sub_f32_e32 v234, v238, v187
	v_sub_f32_e32 v237, v237, v187
	v_sub_f32_e32 v236, v236, v187
	v_pk_mul_f32 v[236:237], v[236:237], v[216:217] op_sel_hi:[1,0]
	v_pk_mul_f32 v[216:217], v[234:235], v[216:217] op_sel_hi:[1,0]
	v_pk_fma_f32 v[234:235], v[146:147], v[236:237], v[150:151]
	v_pk_fma_f32 v[216:217], v[148:149], v[216:217], v[152:153]
	v_pk_mul_f32 v[234:235], v[234:235], s[20:21] op_sel_hi:[1,0]
	v_pk_mul_f32 v[216:217], v[216:217], s[20:21] op_sel_hi:[1,0]
	v_pk_fma_f32 v[98:99], v[98:99], v[142:143], v[234:235]
	v_pk_fma_f32 v[100:101], v[100:101], v[144:145], v[216:217]
	global_store_dwordx4 v[110:111], v[98:101], off
	global_load_dword v187, v[108:109], off
	global_load_dword v216, v[108:109], off offset:4
	s_nop 0
	global_load_dwordx4 v[98:101], v[106:107], off offset:64
	s_waitcnt vmcnt(0)
	v_sub_f32_e32 v235, v243, v187
	v_sub_f32_e32 v234, v242, v187
	v_sub_f32_e32 v237, v241, v187
	v_sub_f32_e32 v236, v240, v187
	v_pk_mul_f32 v[236:237], v[236:237], v[216:217] op_sel_hi:[1,0]
	v_pk_mul_f32 v[216:217], v[234:235], v[216:217] op_sel_hi:[1,0]
	v_pk_fma_f32 v[146:147], v[146:147], v[236:237], v[150:151]
	v_pk_fma_f32 v[148:149], v[148:149], v[216:217], v[152:153]
	v_pk_mul_f32 v[146:147], v[146:147], s[20:21] op_sel_hi:[1,0]
	v_pk_mul_f32 v[148:149], v[148:149], s[20:21] op_sel_hi:[1,0]
	v_pk_fma_f32 v[90:91], v[90:91], v[142:143], v[146:147]
	v_pk_fma_f32 v[92:93], v[92:93], v[144:145], v[148:149]
	global_store_dwordx4 v[106:107], v[90:93], off
	global_load_dwordx2 v[90:91], v[210:211], off
	s_waitcnt vmcnt(0)
	v_sub_f32_e32 v143, v155, v90
	v_sub_f32_e32 v93, v157, v90
	v_sub_f32_e32 v92, v156, v90
	v_sub_f32_e32 v142, v154, v90
	v_pk_mul_f32 v[142:143], v[142:143], v[90:91] op_sel:[0,1]
	v_pk_mul_f32 v[90:91], v[92:93], v[90:91] op_sel:[0,1]
	v_pk_fma_f32 v[92:93], v[134:135], v[142:143], v[138:139]
	v_pk_fma_f32 v[90:91], v[136:137], v[90:91], v[140:141]
	v_pk_mul_f32 v[142:143], v[92:93], s[20:21] op_sel_hi:[1,0]
	v_pk_mul_f32 v[90:91], v[90:91], s[20:21] op_sel_hi:[1,0]
	s_nop 0
	v_pk_fma_f32 v[92:93], v[104:105], v[132:133], v[90:91]
	v_pk_fma_f32 v[90:91], v[102:103], v[130:131], v[142:143]
	global_store_dwordx4 v[206:207], v[90:93], off offset:64
	global_load_dword v91, v[212:213], off
	s_nop 0
	global_load_dword v90, v[212:213], off offset:4
	s_waitcnt vmcnt(0)
	v_sub_f32_e32 v93, v129, v91
	v_sub_f32_e32 v92, v128, v91
	v_sub_f32_e32 v103, v127, v91
	v_sub_f32_e32 v102, v126, v91
	v_pk_mul_f32 v[102:103], v[102:103], v[90:91] op_sel_hi:[1,0]
	v_pk_mul_f32 v[90:91], v[92:93], v[90:91] op_sel_hi:[1,0]
	v_pk_fma_f32 v[92:93], v[134:135], v[102:103], v[138:139]
	v_pk_fma_f32 v[90:91], v[136:137], v[90:91], v[140:141]
	v_pk_mul_f32 v[102:103], v[92:93], s[20:21] op_sel_hi:[1,0]
	v_pk_mul_f32 v[90:91], v[90:91], s[20:21] op_sel_hi:[1,0]
	s_nop 0
	v_pk_fma_f32 v[92:93], v[96:97], v[132:133], v[90:91]
	v_pk_fma_f32 v[90:91], v[94:95], v[130:131], v[102:103]
	global_store_dwordx4 v[208:209], v[90:93], off offset:64
	global_load_dword v91, v[220:221], off
	s_nop 0
	global_load_dword v90, v[220:221], off offset:4
	s_waitcnt vmcnt(0)
	v_sub_f32_e32 v93, v125, v91
	v_sub_f32_e32 v92, v124, v91
	v_sub_f32_e32 v95, v123, v91
	v_sub_f32_e32 v94, v122, v91
	v_pk_mul_f32 v[94:95], v[94:95], v[90:91] op_sel_hi:[1,0]
	v_pk_mul_f32 v[90:91], v[92:93], v[90:91] op_sel_hi:[1,0]
	v_pk_fma_f32 v[92:93], v[134:135], v[94:95], v[138:139]
	v_pk_fma_f32 v[90:91], v[136:137], v[90:91], v[140:141]
	v_pk_mul_f32 v[92:93], v[92:93], s[20:21] op_sel_hi:[1,0]
	v_pk_mul_f32 v[90:91], v[90:91], s[20:21] op_sel_hi:[1,0]
	v_pk_fma_f32 v[86:87], v[86:87], v[130:131], v[92:93]
	v_pk_fma_f32 v[88:89], v[88:89], v[132:133], v[90:91]
	global_store_dwordx4 v[214:215], v[86:89], off offset:64
	global_load_dword v87, v[224:225], off
	s_nop 0
	global_load_dword v86, v[224:225], off offset:4
	s_waitcnt vmcnt(0)
	v_sub_f32_e32 v89, v121, v87
	v_sub_f32_e32 v88, v120, v87
	v_sub_f32_e32 v91, v119, v87
	v_sub_f32_e32 v90, v118, v87
	v_pk_mul_f32 v[90:91], v[90:91], v[86:87] op_sel_hi:[1,0]
	v_pk_mul_f32 v[86:87], v[88:89], v[86:87] op_sel_hi:[1,0]
	v_pk_fma_f32 v[88:89], v[134:135], v[90:91], v[138:139]
	v_pk_fma_f32 v[86:87], v[136:137], v[86:87], v[140:141]
	v_pk_mul_f32 v[88:89], v[88:89], s[20:21] op_sel_hi:[1,0]
	v_pk_mul_f32 v[86:87], v[86:87], s[20:21] op_sel_hi:[1,0]
	v_pk_fma_f32 v[82:83], v[82:83], v[130:131], v[88:89]
	v_pk_fma_f32 v[84:85], v[84:85], v[132:133], v[86:87]
	global_store_dwordx4 v[218:219], v[82:85], off offset:64
	global_load_dwordx2 v[82:83], v[226:227], off
	s_waitcnt vmcnt(0)
;     DI void operator()(const f32x4 (&acc)[2][2][4][2], const pg8::Unit& u, int wr, int wc, int fr, int fq) const {
;     ...
;                 for (int q = 0; q < 8; ++q) { const int rr = rl + (q >> 2) * 128 + (q & 3) * 16; xv[n][q] = *(const f32x4*)(sbase + (size_t)rr * D + c); }
;             }
; #pragma unroll
;             for (int n = 0; n < 2; ++n) {
;                 const int c = col0 + bj * 128 + n * 16;
; #pragma unroll
;                 for (int q = 0; q < 8; ++q) {
;                     const int rr = rl + (q >> 2) * 128 + (q & 3) * 16;
;                     f32x4 x = xv[n][q];
;                     if (mode) { const float mu = stats[2 * (rowt + rr)], rs = stats[2 * (rowt + rr) + 1]; x = (x - mu) * rs * gg[n] + bb[n]; }
;                     *(f32x4*)(dbase + (size_t)rr * D + c) = ALPHA * x + gv[n] * acc[q >> 2][bj][q & 3][n];
;                 }
;             }
	v_sub_f32_e32 v87, v245, v82
	v_sub_f32_e32 v85, v247, v82
	v_sub_f32_e32 v84, v246, v82
	v_sub_f32_e32 v86, v244, v82
	v_pk_mul_f32 v[86:87], v[86:87], v[82:83] op_sel:[0,1]
	v_pk_mul_f32 v[82:83], v[84:85], v[82:83] op_sel:[0,1]
	v_pk_fma_f32 v[84:85], v[134:135], v[86:87], v[138:139]
	v_pk_fma_f32 v[82:83], v[136:137], v[82:83], v[140:141]
	v_pk_mul_f32 v[84:85], v[84:85], s[20:21] op_sel_hi:[1,0]
	v_pk_mul_f32 v[82:83], v[82:83], s[20:21] op_sel_hi:[1,0]
	v_pk_fma_f32 v[78:79], v[78:79], v[130:131], v[84:85]
	v_pk_fma_f32 v[80:81], v[80:81], v[132:133], v[82:83]
	global_store_dwordx4 v[222:223], v[78:81], off offset:64
	global_load_dword v79, v[116:117], off
	s_nop 0
	global_load_dword v78, v[116:117], off offset:4
	s_waitcnt vmcnt(0)
	v_sub_f32_e32 v81, v251, v79
	v_sub_f32_e32 v80, v250, v79
	v_sub_f32_e32 v83, v249, v79
	v_sub_f32_e32 v82, v248, v79
	v_pk_mul_f32 v[82:83], v[82:83], v[78:79] op_sel_hi:[1,0]
	v_pk_mul_f32 v[78:79], v[80:81], v[78:79] op_sel_hi:[1,0]
	v_pk_fma_f32 v[80:81], v[134:135], v[82:83], v[138:139]
	v_pk_fma_f32 v[78:79], v[136:137], v[78:79], v[140:141]
	v_pk_mul_f32 v[80:81], v[80:81], s[20:21] op_sel_hi:[1,0]
	v_pk_mul_f32 v[78:79], v[78:79], s[20:21] op_sel_hi:[1,0]
	v_pk_fma_f32 v[74:75], v[74:75], v[130:131], v[80:81]
	v_pk_fma_f32 v[76:77], v[76:77], v[132:133], v[78:79]
	global_store_dwordx4 v[114:115], v[74:77], off offset:64
	global_load_dword v75, v[112:113], off
	s_nop 0
	global_load_dword v74, v[112:113], off offset:4
	s_waitcnt vmcnt(0)
	v_sub_f32_e32 v77, v255, v75
	v_sub_f32_e32 v76, v254, v75
	v_sub_f32_e32 v79, v253, v75
	v_sub_f32_e32 v78, v252, v75
	v_pk_mul_f32 v[78:79], v[78:79], v[74:75] op_sel_hi:[1,0]
	v_pk_mul_f32 v[74:75], v[76:77], v[74:75] op_sel_hi:[1,0]
	v_pk_fma_f32 v[76:77], v[134:135], v[78:79], v[138:139]
	v_pk_fma_f32 v[74:75], v[136:137], v[74:75], v[140:141]
	v_pk_mul_f32 v[76:77], v[76:77], s[20:21] op_sel_hi:[1,0]
	v_pk_mul_f32 v[74:75], v[74:75], s[20:21] op_sel_hi:[1,0]
	v_pk_fma_f32 v[70:71], v[70:71], v[130:131], v[76:77]
	v_pk_fma_f32 v[72:73], v[72:73], v[132:133], v[74:75]
	global_store_dwordx4 v[110:111], v[70:73], off offset:64
	global_load_dword v71, v[108:109], off
	s_nop 0
	global_load_dword v70, v[108:109], off offset:4
	global_load_dwordx4 v[78:81], v[206:207], off offset:512
	v_and_b32_e32 v254, 0x3ff, v0
	s_waitcnt vmcnt(0)
	v_sub_f32_e32 v73, v101, v71
	v_sub_f32_e32 v72, v100, v71
	v_sub_f32_e32 v75, v99, v71
	v_sub_f32_e32 v74, v98, v71
	v_pk_mul_f32 v[74:75], v[74:75], v[70:71] op_sel_hi:[1,0]
	v_pk_mul_f32 v[70:71], v[72:73], v[70:71] op_sel_hi:[1,0]
	v_pk_fma_f32 v[72:73], v[134:135], v[74:75], v[138:139]
	v_pk_fma_f32 v[70:71], v[136:137], v[70:71], v[140:141]
	v_pk_mul_f32 v[72:73], v[72:73], s[20:21] op_sel_hi:[1,0]
	v_pk_mul_f32 v[70:71], v[70:71], s[20:21] op_sel_hi:[1,0]
	v_pk_fma_f32 v[62:63], v[62:63], v[130:131], v[72:73]
	v_pk_fma_f32 v[64:65], v[64:65], v[132:133], v[70:71]
	global_store_dwordx4 v[106:107], v[62:65], off offset:64
	global_load_dwordx2 v[102:103], v[210:211], off
	global_load_dwordx4 v[82:85], v[228:229], off offset:512
	global_load_dwordx4 v[86:89], v[230:231], off offset:512
	global_load_dwordx4 v[90:93], v[232:233], off offset:512
	global_load_dwordx4 v[94:97], v[208:209], off offset:512
	global_load_dwordx4 v[98:101], v[206:207], off offset:576
	global_load_dwordx4 v[62:65], v[232:233], off offset:576
	global_load_dwordx4 v[70:73], v[228:229], off offset:576
	global_load_dwordx4 v[74:77], v[230:231], off offset:576
	s_waitcnt vmcnt(0)
	v_sub_f32_e32 v81, v81, v102
	v_sub_f32_e32 v80, v80, v102
	v_sub_f32_e32 v79, v79, v102
	v_sub_f32_e32 v78, v78, v102
	v_pk_mul_f32 v[78:79], v[78:79], v[102:103] op_sel:[0,1]
	v_pk_mul_f32 v[80:81], v[80:81], v[102:103] op_sel:[0,1]
	v_pk_fma_f32 v[78:79], v[82:83], v[78:79], v[86:87]
	v_pk_fma_f32 v[80:81], v[84:85], v[80:81], v[88:89]
	v_pk_mul_f32 v[78:79], v[78:79], s[20:21] op_sel_hi:[1,0]
	v_pk_mul_f32 v[80:81], v[80:81], s[20:21] op_sel_hi:[1,0]
	v_pk_fma_f32 v[66:67], v[66:67], v[90:91], v[78:79]
	v_pk_fma_f32 v[68:69], v[68:69], v[92:93], v[80:81]
	global_store_dwordx4 v[206:207], v[66:69], off offset:512
	global_load_dword v103, v[212:213], off
	global_load_dword v102, v[212:213], off offset:4
	s_nop 0
	global_load_dwordx4 v[66:69], v[214:215], off offset:512
	global_load_dwordx4 v[78:81], v[208:209], off offset:576
	s_waitcnt vmcnt(0)
	v_sub_f32_e32 v97, v97, v103
	v_sub_f32_e32 v96, v96, v103
	v_sub_f32_e32 v95, v95, v103
	v_sub_f32_e32 v94, v94, v103
	v_pk_mul_f32 v[94:95], v[94:95], v[102:103] op_sel_hi:[1,0]
	v_pk_mul_f32 v[96:97], v[96:97], v[102:103] op_sel_hi:[1,0]
	v_pk_fma_f32 v[94:95], v[82:83], v[94:95], v[86:87]
	v_pk_fma_f32 v[96:97], v[84:85], v[96:97], v[88:89]
	v_pk_mul_f32 v[94:95], v[94:95], s[20:21] op_sel_hi:[1,0]
	v_pk_mul_f32 v[96:97], v[96:97], s[20:21] op_sel_hi:[1,0]
	v_pk_fma_f32 v[58:59], v[58:59], v[90:91], v[94:95]
	v_pk_fma_f32 v[60:61], v[60:61], v[92:93], v[96:97]
	global_store_dwordx4 v[208:209], v[58:61], off offset:512
	global_load_dword v103, v[220:221], off
	global_load_dword v102, v[220:221], off offset:4
	s_nop 0
	global_load_dwordx4 v[58:61], v[218:219], off offset:512
	global_load_dwordx4 v[94:97], v[214:215], off offset:576
	s_waitcnt vmcnt(0)
;     DI void operator()(const f32x4 (&acc)[2][2][4][2], const pg8::Unit& u, int wr, int wc, int fr, int fq) const {
;     ...
;             for (int n = 0; n < 2; ++n) {
;                 const int c = col0 + bj * 128 + n * 16;
; #pragma unroll
;                 for (int q = 0; q < 8; ++q) {
;                     const int rr = rl + (q >> 2) * 128 + (q & 3) * 16;
;                     f32x4 x = xv[n][q];
;                     if (mode) { const float mu = stats[2 * (rowt + rr)], rs = stats[2 * (rowt + rr) + 1]; x = (x - mu) * rs * gg[n] + bb[n]; }
;                     *(f32x4*)(dbase + (size_t)rr * D + c) = ALPHA * x + gv[n] * acc[q >> 2][bj][q & 3][n];
;                 }
;             }
	v_sub_f32_e32 v69, v69, v103
	v_sub_f32_e32 v68, v68, v103
	v_sub_f32_e32 v67, v67, v103
	v_sub_f32_e32 v66, v66, v103
	v_pk_mul_f32 v[66:67], v[66:67], v[102:103] op_sel_hi:[1,0]
	v_pk_mul_f32 v[68:69], v[68:69], v[102:103] op_sel_hi:[1,0]
	v_pk_fma_f32 v[66:67], v[82:83], v[66:67], v[86:87]
	v_pk_fma_f32 v[68:69], v[84:85], v[68:69], v[88:89]
	v_pk_mul_f32 v[66:67], v[66:67], s[20:21] op_sel_hi:[1,0]
	v_pk_mul_f32 v[68:69], v[68:69], s[20:21] op_sel_hi:[1,0]
	v_pk_fma_f32 v[54:55], v[54:55], v[90:91], v[66:67]
	v_pk_fma_f32 v[56:57], v[56:57], v[92:93], v[68:69]
	global_store_dwordx4 v[214:215], v[54:57], off offset:512
	global_load_dword v103, v[224:225], off
	global_load_dword v102, v[224:225], off offset:4
	s_nop 0
	global_load_dwordx4 v[54:57], v[222:223], off offset:512
	global_load_dwordx4 v[66:69], v[218:219], off offset:576
	s_waitcnt vmcnt(0)
	v_sub_f32_e32 v61, v61, v103
	v_sub_f32_e32 v60, v60, v103
	v_sub_f32_e32 v59, v59, v103
	v_sub_f32_e32 v58, v58, v103
	v_pk_mul_f32 v[58:59], v[58:59], v[102:103] op_sel_hi:[1,0]
	v_pk_mul_f32 v[60:61], v[60:61], v[102:103] op_sel_hi:[1,0]
	v_pk_fma_f32 v[58:59], v[82:83], v[58:59], v[86:87]
	v_pk_fma_f32 v[60:61], v[84:85], v[60:61], v[88:89]
	v_pk_mul_f32 v[58:59], v[58:59], s[20:21] op_sel_hi:[1,0]
	v_pk_mul_f32 v[60:61], v[60:61], s[20:21] op_sel_hi:[1,0]
	v_pk_fma_f32 v[50:51], v[50:51], v[90:91], v[58:59]
	v_pk_fma_f32 v[52:53], v[52:53], v[92:93], v[60:61]
	global_store_dwordx4 v[218:219], v[50:53], off offset:512
	global_load_dwordx2 v[102:103], v[226:227], off
	s_nop 0
	global_load_dwordx4 v[50:53], v[114:115], off offset:512
	global_load_dwordx4 v[58:61], v[222:223], off offset:576
	s_waitcnt vmcnt(0)
	v_sub_f32_e32 v57, v57, v102
	v_sub_f32_e32 v56, v56, v102
	v_sub_f32_e32 v55, v55, v102
	v_sub_f32_e32 v54, v54, v102
	v_pk_mul_f32 v[54:55], v[54:55], v[102:103] op_sel:[0,1]
	v_pk_mul_f32 v[56:57], v[56:57], v[102:103] op_sel:[0,1]
	v_pk_fma_f32 v[54:55], v[82:83], v[54:55], v[86:87]
	v_pk_fma_f32 v[56:57], v[84:85], v[56:57], v[88:89]
	v_pk_mul_f32 v[54:55], v[54:55], s[20:21] op_sel_hi:[1,0]
	v_pk_mul_f32 v[56:57], v[56:57], s[20:21] op_sel_hi:[1,0]
	v_pk_fma_f32 v[46:47], v[46:47], v[90:91], v[54:55]
	v_pk_fma_f32 v[48:49], v[48:49], v[92:93], v[56:57]
	global_store_dwordx4 v[222:223], v[46:49], off offset:512
	global_load_dword v103, v[116:117], off
	global_load_dword v102, v[116:117], off offset:4
	s_nop 0
	global_load_dwordx4 v[46:49], v[110:111], off offset:512
	global_load_dwordx4 v[54:57], v[114:115], off offset:576
	s_waitcnt vmcnt(0)
	v_sub_f32_e32 v53, v53, v103
	v_sub_f32_e32 v52, v52, v103
	v_sub_f32_e32 v51, v51, v103
	v_sub_f32_e32 v50, v50, v103
	v_pk_mul_f32 v[50:51], v[50:51], v[102:103] op_sel_hi:[1,0]
	v_pk_mul_f32 v[52:53], v[52:53], v[102:103] op_sel_hi:[1,0]
	v_pk_fma_f32 v[50:51], v[82:83], v[50:51], v[86:87]
	v_pk_fma_f32 v[52:53], v[84:85], v[52:53], v[88:89]
	v_pk_mul_f32 v[50:51], v[50:51], s[20:21] op_sel_hi:[1,0]
	v_pk_mul_f32 v[52:53], v[52:53], s[20:21] op_sel_hi:[1,0]
	v_pk_fma_f32 v[42:43], v[42:43], v[90:91], v[50:51]
	v_pk_fma_f32 v[44:45], v[44:45], v[92:93], v[52:53]
	global_store_dwordx4 v[114:115], v[42:45], off offset:512
	global_load_dword v103, v[112:113], off
	global_load_dword v102, v[112:113], off offset:4
	s_nop 0
	global_load_dwordx4 v[42:45], v[106:107], off offset:512
	global_load_dwordx4 v[50:53], v[110:111], off offset:576
	s_waitcnt vmcnt(0)
	v_sub_f32_e32 v49, v49, v103
	v_sub_f32_e32 v48, v48, v103
	v_sub_f32_e32 v47, v47, v103
	v_sub_f32_e32 v46, v46, v103
	v_pk_mul_f32 v[46:47], v[46:47], v[102:103] op_sel_hi:[1,0]
	v_pk_mul_f32 v[48:49], v[48:49], v[102:103] op_sel_hi:[1,0]
	v_pk_fma_f32 v[46:47], v[82:83], v[46:47], v[86:87]
	v_pk_fma_f32 v[48:49], v[84:85], v[48:49], v[88:89]
	v_pk_mul_f32 v[46:47], v[46:47], s[20:21] op_sel_hi:[1,0]
	v_pk_mul_f32 v[48:49], v[48:49], s[20:21] op_sel_hi:[1,0]
	v_pk_fma_f32 v[34:35], v[34:35], v[90:91], v[46:47]
	v_pk_fma_f32 v[36:37], v[36:37], v[92:93], v[48:49]
	global_store_dwordx4 v[110:111], v[34:37], off offset:512
	global_load_dword v47, v[108:109], off
	global_load_dword v46, v[108:109], off offset:4
	s_nop 0
	global_load_dwordx4 v[34:37], v[106:107], off offset:576
	s_waitcnt vmcnt(0)
	v_sub_f32_e32 v45, v45, v47
	v_sub_f32_e32 v44, v44, v47
	v_sub_f32_e32 v43, v43, v47
	v_sub_f32_e32 v42, v42, v47
	v_pk_mul_f32 v[42:43], v[42:43], v[46:47] op_sel_hi:[1,0]
	v_pk_mul_f32 v[44:45], v[44:45], v[46:47] op_sel_hi:[1,0]
	v_pk_fma_f32 v[42:43], v[82:83], v[42:43], v[86:87]
	v_pk_fma_f32 v[44:45], v[84:85], v[44:45], v[88:89]
	v_pk_mul_f32 v[42:43], v[42:43], s[20:21] op_sel_hi:[1,0]
	v_pk_mul_f32 v[44:45], v[44:45], s[20:21] op_sel_hi:[1,0]
	v_pk_fma_f32 v[26:27], v[26:27], v[90:91], v[42:43]
	v_pk_fma_f32 v[28:29], v[28:29], v[92:93], v[44:45]
	global_store_dwordx4 v[106:107], v[26:29], off offset:512
	global_load_dwordx2 v[26:27], v[210:211], off
	s_waitcnt vmcnt(0)
	v_sub_f32_e32 v43, v99, v26
	v_sub_f32_e32 v29, v101, v26
	v_sub_f32_e32 v28, v100, v26
	v_sub_f32_e32 v42, v98, v26
	v_pk_mul_f32 v[42:43], v[42:43], v[26:27] op_sel:[0,1]
	v_pk_mul_f32 v[26:27], v[28:29], v[26:27] op_sel:[0,1]
	v_pk_fma_f32 v[28:29], v[70:71], v[42:43], v[74:75]
	v_pk_fma_f32 v[26:27], v[72:73], v[26:27], v[76:77]
	v_pk_mul_f32 v[42:43], v[28:29], s[20:21] op_sel_hi:[1,0]
	v_pk_mul_f32 v[26:27], v[26:27], s[20:21] op_sel_hi:[1,0]
	s_nop 0
	v_pk_fma_f32 v[28:29], v[40:41], v[64:65], v[26:27]
	v_pk_fma_f32 v[26:27], v[38:39], v[62:63], v[42:43]
	global_store_dwordx4 v[206:207], v[26:29], off offset:576
	global_load_dword v27, v[212:213], off
	s_nop 0
	global_load_dword v26, v[212:213], off offset:4
	s_waitcnt vmcnt(0)
; #define PG8_WAIT_V(n) asm volatile("s_waitcnt vmcnt(" #n ")" ::: "memory")
; #define PG8_BAR __builtin_amdgcn_s_barrier()
; template <class Epi>
; DI void gemm_phase(LAS unsigned char* lds, const Gemm g, const StaticOrder& S, const Epi& E) {
;     ...
;         if (!has_next) break;
; #pragma unroll
;         for (int a = 0; a < 2; ++a)
; #pragma unroll
;             for (int b = 0; b < 2; ++b)
; #pragma unroll
;                 for (int m = 0; m < 4; ++m)
; #pragma unroll
;                     for (int n = 0; n < 2; ++n) acc[a][b][m][n] = (f32x4){0.f, 0.f, 0.f, 0.f};
;         cur = nxt; cA = nA; cB = nB; ++ui;
;     }
;     PG8_WAIT_V(0);
;     if (wr == 0) PG8_BAR;
;     PG8_BAR;
;     DI void operator()(const f32x4 (&acc)[2][2][4][2], const pg8::Unit& u, int wr, int wc, int fr, int fq) const {
;     ...
;             for (int n = 0; n < 2; ++n) {
;                 const int c = col0 + bj * 128 + n * 16;
; #pragma unroll
;                 for (int q = 0; q < 8; ++q) {
;                     const int rr = rl + (q >> 2) * 128 + (q & 3) * 16;
;                     f32x4 x = xv[n][q];
;                     if (mode) { const float mu = stats[2 * (rowt + rr)], rs = stats[2 * (rowt + rr) + 1]; x = (x - mu) * rs * gg[n] + bb[n]; }
;                     *(f32x4*)(dbase + (size_t)rr * D + c) = ALPHA * x + gv[n] * acc[q >> 2][bj][q & 3][n];
;                 }
;             }
	v_sub_f32_e32 v29, v81, v27
	v_sub_f32_e32 v28, v80, v27
	v_sub_f32_e32 v39, v79, v27
	v_sub_f32_e32 v38, v78, v27
	v_pk_mul_f32 v[38:39], v[38:39], v[26:27] op_sel_hi:[1,0]
	v_pk_mul_f32 v[26:27], v[28:29], v[26:27] op_sel_hi:[1,0]
	v_pk_fma_f32 v[28:29], v[70:71], v[38:39], v[74:75]
	v_pk_fma_f32 v[26:27], v[72:73], v[26:27], v[76:77]
	v_pk_mul_f32 v[38:39], v[28:29], s[20:21] op_sel_hi:[1,0]
	v_pk_mul_f32 v[26:27], v[26:27], s[20:21] op_sel_hi:[1,0]
	s_nop 0
	v_pk_fma_f32 v[28:29], v[32:33], v[64:65], v[26:27]
	v_pk_fma_f32 v[26:27], v[30:31], v[62:63], v[38:39]
	global_store_dwordx4 v[208:209], v[26:29], off offset:576
	global_load_dword v27, v[220:221], off
	s_nop 0
	global_load_dword v26, v[220:221], off offset:4
	s_waitcnt vmcnt(0)
	v_sub_f32_e32 v29, v97, v27
	v_sub_f32_e32 v28, v96, v27
	v_sub_f32_e32 v31, v95, v27
	v_sub_f32_e32 v30, v94, v27
	v_pk_mul_f32 v[30:31], v[30:31], v[26:27] op_sel_hi:[1,0]
	v_pk_mul_f32 v[26:27], v[28:29], v[26:27] op_sel_hi:[1,0]
	v_pk_fma_f32 v[28:29], v[70:71], v[30:31], v[74:75]
	v_pk_fma_f32 v[26:27], v[72:73], v[26:27], v[76:77]
	v_pk_mul_f32 v[28:29], v[28:29], s[20:21] op_sel_hi:[1,0]
	v_pk_mul_f32 v[26:27], v[26:27], s[20:21] op_sel_hi:[1,0]
	v_pk_fma_f32 v[22:23], v[22:23], v[62:63], v[28:29]
	v_pk_fma_f32 v[24:25], v[24:25], v[64:65], v[26:27]
	global_store_dwordx4 v[214:215], v[22:25], off offset:576
	global_load_dword v23, v[224:225], off
	s_nop 0
	global_load_dword v22, v[224:225], off offset:4
	s_waitcnt vmcnt(0)
	v_sub_f32_e32 v25, v69, v23
	v_sub_f32_e32 v24, v68, v23
	v_sub_f32_e32 v27, v67, v23
	v_sub_f32_e32 v26, v66, v23
	v_pk_mul_f32 v[26:27], v[26:27], v[22:23] op_sel_hi:[1,0]
	v_pk_mul_f32 v[22:23], v[24:25], v[22:23] op_sel_hi:[1,0]
	v_pk_fma_f32 v[24:25], v[70:71], v[26:27], v[74:75]
	v_pk_fma_f32 v[22:23], v[72:73], v[22:23], v[76:77]
	v_pk_mul_f32 v[24:25], v[24:25], s[20:21] op_sel_hi:[1,0]
	v_pk_mul_f32 v[22:23], v[22:23], s[20:21] op_sel_hi:[1,0]
	v_pk_fma_f32 v[18:19], v[18:19], v[62:63], v[24:25]
	v_pk_fma_f32 v[20:21], v[20:21], v[64:65], v[22:23]
	global_store_dwordx4 v[218:219], v[18:21], off offset:576
	global_load_dwordx2 v[18:19], v[226:227], off
	s_waitcnt vmcnt(0)
	v_sub_f32_e32 v23, v59, v18
	v_sub_f32_e32 v21, v61, v18
	v_sub_f32_e32 v20, v60, v18
	v_sub_f32_e32 v22, v58, v18
	v_pk_mul_f32 v[22:23], v[22:23], v[18:19] op_sel:[0,1]
	v_pk_mul_f32 v[18:19], v[20:21], v[18:19] op_sel:[0,1]
	v_pk_fma_f32 v[20:21], v[70:71], v[22:23], v[74:75]
	v_pk_fma_f32 v[18:19], v[72:73], v[18:19], v[76:77]
	v_pk_mul_f32 v[20:21], v[20:21], s[20:21] op_sel_hi:[1,0]
	v_pk_mul_f32 v[18:19], v[18:19], s[20:21] op_sel_hi:[1,0]
	v_pk_fma_f32 v[14:15], v[14:15], v[62:63], v[20:21]
	v_pk_fma_f32 v[16:17], v[16:17], v[64:65], v[18:19]
	global_store_dwordx4 v[222:223], v[14:17], off offset:576
	global_load_dword v15, v[116:117], off
	s_nop 0
	global_load_dword v14, v[116:117], off offset:4
	s_waitcnt vmcnt(0)
	v_sub_f32_e32 v17, v57, v15
	v_sub_f32_e32 v16, v56, v15
	v_sub_f32_e32 v19, v55, v15
	v_sub_f32_e32 v18, v54, v15
	v_pk_mul_f32 v[18:19], v[18:19], v[14:15] op_sel_hi:[1,0]
	v_pk_mul_f32 v[14:15], v[16:17], v[14:15] op_sel_hi:[1,0]
	v_pk_fma_f32 v[16:17], v[70:71], v[18:19], v[74:75]
	v_pk_fma_f32 v[14:15], v[72:73], v[14:15], v[76:77]
	v_pk_mul_f32 v[16:17], v[16:17], s[20:21] op_sel_hi:[1,0]
	v_pk_mul_f32 v[14:15], v[14:15], s[20:21] op_sel_hi:[1,0]
	v_pk_fma_f32 v[10:11], v[10:11], v[62:63], v[16:17]
	v_pk_fma_f32 v[12:13], v[12:13], v[64:65], v[14:15]
	global_store_dwordx4 v[114:115], v[10:13], off offset:576
	global_load_dword v11, v[112:113], off
	s_nop 0
	global_load_dword v10, v[112:113], off offset:4
	s_waitcnt vmcnt(0)
	v_sub_f32_e32 v13, v53, v11
	v_sub_f32_e32 v12, v52, v11
	v_sub_f32_e32 v15, v51, v11
	v_sub_f32_e32 v14, v50, v11
	v_pk_mul_f32 v[14:15], v[14:15], v[10:11] op_sel_hi:[1,0]
	v_pk_mul_f32 v[10:11], v[12:13], v[10:11] op_sel_hi:[1,0]
	v_pk_fma_f32 v[12:13], v[70:71], v[14:15], v[74:75]
	v_pk_fma_f32 v[10:11], v[72:73], v[10:11], v[76:77]
	v_pk_mul_f32 v[12:13], v[12:13], s[20:21] op_sel_hi:[1,0]
	v_pk_mul_f32 v[10:11], v[10:11], s[20:21] op_sel_hi:[1,0]
	v_pk_fma_f32 v[6:7], v[6:7], v[62:63], v[12:13]
	v_pk_fma_f32 v[8:9], v[8:9], v[64:65], v[10:11]
	global_store_dwordx4 v[110:111], v[6:9], off offset:576
	global_load_dword v7, v[108:109], off
	s_nop 0
	global_load_dword v6, v[108:109], off offset:4
	s_waitcnt vmcnt(0)
	v_sub_f32_e32 v9, v37, v7
	v_sub_f32_e32 v8, v36, v7
	v_sub_f32_e32 v11, v35, v7
	v_sub_f32_e32 v10, v34, v7
	v_pk_mul_f32 v[10:11], v[10:11], v[6:7] op_sel_hi:[1,0]
	v_pk_mul_f32 v[6:7], v[8:9], v[6:7] op_sel_hi:[1,0]
	v_pk_fma_f32 v[8:9], v[70:71], v[10:11], v[74:75]
	v_pk_fma_f32 v[6:7], v[72:73], v[6:7], v[76:77]
	v_pk_mul_f32 v[8:9], v[8:9], s[20:21] op_sel_hi:[1,0]
	v_pk_mul_f32 v[6:7], v[6:7], s[20:21] op_sel_hi:[1,0]
	v_pk_fma_f32 v[2:3], v[2:3], v[62:63], v[8:9]
	v_pk_fma_f32 v[4:5], v[4:5], v[64:65], v[6:7]
	global_store_dwordx4 v[106:107], v[2:5], off offset:576
	s_cbranch_vccz .LBB0_1287
	s_waitcnt vmcnt(0)
	s_cmpk_gt_u32 s21, 0xff
	s_cbranch_scc1 .LBB0_1296
	s_barrier

; #define PG8_STAGE(bufoff, gbase, voff) do { _Pragma("unroll") for (int _i = 0; _i < 2; ++_i) \
;         __builtin_amdgcn_global_load_lds((const unsigned*)((const char*)(gbase) + (voff)[_i]), (LAS unsigned*)(lds + (bufoff) + ldsw + _i * 8192), 16, 0, 0); } while (0)
; #define PG8_LDA(dst, b, h) do { _Pragma("unroll") for (int m = 0; m < 4; ++m) _Pragma("unroll") for (int k = 0; k < 2; ++k) dst[m][k] = *(const LAS bf16x8*)(lds + PG8_SA(b, h) + aoff + m * 2048 + k * 1024); } while (0)
; #define PG8_LDB(dst, b, h) do { _Pragma("unroll") for (int n = 0; n < 2; ++n) _Pragma("unroll") for (int k = 0; k < 2; ++k) dst[n][k] = *(const LAS bf16x8*)(lds + PG8_SB(b, h) + boff + n * 2048 + k * 1024); } while (0)
; #define PG8_MMA(ai, bj, At, Bt) do { __builtin_amdgcn_s_setprio(1); _Pragma("unroll") for (int m = 0; m < 4; ++m) _Pragma("unroll") for (int n = 0; n < 2; ++n) _Pragma("unroll") for (int k = 0; k < 2; ++k) \
;         acc[ai][bj][m][n] = __builtin_amdgcn_mfma_f32_16x16x32_bf16(Bt[n][k], At[m][k], acc[ai][bj][m][n], 0, 0, 0); __builtin_amdgcn_s_setprio(0); } while (0)
; #define PG8_WAIT_V(n) asm volatile("s_waitcnt vmcnt(" #n ")" ::: "memory")
; #define PG8_WAIT_L(n) asm volatile("s_waitcnt lgkmcnt(" #n ")" ::: "memory")
; #define PG8_BAR __builtin_amdgcn_s_barrier()
; #define PG8_SCHED __builtin_amdgcn_sched_barrier(0)
; template <class Epi>
; DI void gemm_phase(LAS unsigned char* lds, const Gemm g, const StaticOrder& S, const Epi& E) {
;     ...
;             PG8_LDB(B0, 0, 0); PG8_SCHED; PG8_LDA(At, 0, 0); PG8_STAGE(PG8_SA(1, 1), a1 + hstepA, voffA);
;             PG8_WAIT_L(8); PG8_BAR; PG8_WAIT_L(0); PG8_MMA(0, 0, At, B0); PG8_BAR; PG8_SCHED;
;             PG8_LDB(B1, 0, 1); PG8_STAGE(PG8_SB(0, 0), b2, voffB);
;             PG8_BAR; PG8_WAIT_L(0); PG8_MMA(0, 1, At, B1); PG8_BAR;
;             PG8_LDA(At, 0, 1); PG8_STAGE(PG8_SA(0, 0), a2, voffA);
;             PG8_BAR; PG8_WAIT_L(0); PG8_MMA(1, 0, At, B0); PG8_BAR; PG8_SCHED;
;             PG8_STAGE(PG8_SB(0, 1), b2 + hstepB, voffB);
;             PG8_WAIT_V(6); PG8_BAR; PG8_MMA(1, 1, At, B1); PG8_BAR;
.LBB0_1456:
	ds_read_b128 v[152:155], v148
	ds_read_b128 v[156:159], v148 offset:1024
	ds_read_b128 v[160:163], v148 offset:2048
	ds_read_b128 v[164:167], v148 offset:3072
	s_add_u32 s24, s22, 0xfff80080
	s_addc_u32 s25, s23, -1
	s_cmp_eq_u32 s60, 28
	s_cselect_b32 s27, s17, s25
	s_cselect_b32 s26, s56, s24
	s_cselect_b32 s25, s15, s59
	s_cselect_b32 s24, s57, s58
	v_lshl_add_u64 v[200:201], s[22:23], 0, v[138:139]
	s_add_i32 m0, s13, 0xc000
	ds_read_b128 v[168:171], v149
	ds_read_b128 v[172:175], v149 offset:1024
	ds_read_b128 v[176:179], v149 offset:2048
	ds_read_b128 v[180:183], v149 offset:3072
	ds_read_b128 v[184:187], v149 offset:4096
	ds_read_b128 v[188:191], v149 offset:5120
	ds_read_b128 v[192:195], v149 offset:6144
	ds_read_b128 v[196:199], v149 offset:7168
	global_load_lds_dwordx4 v[200:201], off
	v_lshl_add_u64 v[200:201], s[22:23], 0, v[140:141]
	s_add_i32 m0, s13, 0xe000
	s_nop 0
	global_load_lds_dwordx4 v[200:201], off
	ds_read_b128 v[200:203], v150
	ds_read_b128 v[204:207], v150 offset:1024
	ds_read_b128 v[208:211], v150 offset:2048
	ds_read_b128 v[212:215], v150 offset:3072
	s_waitcnt lgkmcnt(0)
	s_waitcnt vmcnt(8)
	s_barrier
	s_setprio 1
	v_mfma_f32_16x16x32_bf16 v[126:129], v[152:155], v[168:171], v[126:129]
	v_mfma_f32_16x16x32_bf16 v[122:125], v[160:163], v[168:171], v[122:125]
	v_mfma_f32_16x16x32_bf16 v[118:121], v[152:155], v[176:179], v[118:121]
	v_mfma_f32_16x16x32_bf16 v[114:117], v[160:163], v[176:179], v[114:117]
	v_mfma_f32_16x16x32_bf16 v[102:105], v[152:155], v[184:187], v[102:105]
	v_mfma_f32_16x16x32_bf16 v[98:101], v[160:163], v[184:187], v[98:101]
	v_mfma_f32_16x16x32_bf16 v[86:89], v[152:155], v[192:195], v[86:89]
	v_mfma_f32_16x16x32_bf16 v[82:85], v[160:163], v[192:195], v[82:85]
	v_mfma_f32_16x16x32_bf16 v[126:129], v[156:159], v[172:175], v[126:129]
	v_mfma_f32_16x16x32_bf16 v[122:125], v[164:167], v[172:175], v[122:125]
	v_mfma_f32_16x16x32_bf16 v[118:121], v[156:159], v[180:183], v[118:121]
	v_mfma_f32_16x16x32_bf16 v[114:117], v[164:167], v[180:183], v[114:117]
	v_mfma_f32_16x16x32_bf16 v[102:105], v[156:159], v[188:191], v[102:105]
	v_mfma_f32_16x16x32_bf16 v[98:101], v[164:167], v[188:191], v[98:101]
	v_mfma_f32_16x16x32_bf16 v[86:89], v[156:159], v[196:199], v[86:89]
	v_mfma_f32_16x16x32_bf16 v[82:85], v[164:167], v[196:199], v[82:85]
	v_mfma_f32_16x16x32_bf16 v[110:113], v[200:203], v[168:171], v[110:113]
	v_mfma_f32_16x16x32_bf16 v[106:109], v[208:211], v[168:171], v[106:109]
	v_mfma_f32_16x16x32_bf16 v[94:97], v[200:203], v[176:179], v[94:97]
	v_mfma_f32_16x16x32_bf16 v[90:93], v[208:211], v[176:179], v[90:93]
	v_mfma_f32_16x16x32_bf16 v[78:81], v[200:203], v[184:187], v[78:81]
	v_mfma_f32_16x16x32_bf16 v[74:77], v[208:211], v[184:187], v[74:77]
	v_mfma_f32_16x16x32_bf16 v[70:73], v[200:203], v[192:195], v[70:73]
	v_mfma_f32_16x16x32_bf16 v[66:69], v[208:211], v[192:195], v[66:69]
	v_mfma_f32_16x16x32_bf16 v[110:113], v[204:207], v[172:175], v[110:113]
	v_mfma_f32_16x16x32_bf16 v[106:109], v[212:215], v[172:175], v[106:109]
	v_mfma_f32_16x16x32_bf16 v[94:97], v[204:207], v[180:183], v[94:97]
	v_mfma_f32_16x16x32_bf16 v[90:93], v[212:215], v[180:183], v[90:93]
	v_mfma_f32_16x16x32_bf16 v[78:81], v[204:207], v[188:191], v[78:81]
	v_mfma_f32_16x16x32_bf16 v[74:77], v[212:215], v[188:191], v[74:77]
	v_mfma_f32_16x16x32_bf16 v[70:73], v[204:207], v[196:199], v[70:73]
	v_mfma_f32_16x16x32_bf16 v[66:69], v[212:215], v[196:199], v[66:69]
	s_setprio 0
	s_barrier
	s_add_i32 s61, s52, s35
	v_lshl_add_u64 v[216:217], s[24:25], 0, v[132:133]
	s_mov_b32 m0, s61
	s_nop 0
	global_load_lds_dwordx4 v[216:217], off
	v_lshl_add_u64 v[218:219], s[24:25], 0, v[136:137]
	s_add_i32 m0, s61, 0x2000
	s_nop 0
	global_load_lds_dwordx4 v[218:219], off
	s_mov_b32 m0, s13
	v_lshl_add_u64 v[220:221], s[26:27], 0, v[130:131]
	ds_read_b128 v[168:171], v149 offset:16384
	ds_read_b128 v[172:175], v149 offset:17408
	ds_read_b128 v[176:179], v149 offset:18432
	ds_read_b128 v[180:183], v149 offset:19456
	ds_read_b128 v[184:187], v149 offset:20480
	ds_read_b128 v[188:191], v149 offset:21504
	ds_read_b128 v[192:195], v149 offset:22528
	ds_read_b128 v[196:199], v149 offset:23552
	global_load_lds_dwordx4 v[220:221], off
	v_lshl_add_u64 v[222:223], s[26:27], 0, v[134:135]
	s_mov_b32 m0, s36
	s_nop 0
	global_load_lds_dwordx4 v[222:223], off
	s_add_u32 s62, s24, 0x80000
	s_addc_u32 s63, s25, 0
	s_add_i32 s61, s53, s35
	v_lshl_add_u64 v[252:253], s[62:63], 0, v[132:133]
	s_mov_b32 m0, s61
	s_nop 0
	global_load_lds_dwordx4 v[252:253], off
	v_lshl_add_u64 v[252:253], s[62:63], 0, v[136:137]
	s_add_i32 m0, s61, 0x2000
	s_nop 0
	global_load_lds_dwordx4 v[252:253], off
	s_waitcnt lgkmcnt(0)
	s_waitcnt vmcnt(8)
	s_barrier
; #define PG8_STAGE(bufoff, gbase, voff) do { _Pragma("unroll") for (int _i = 0; _i < 2; ++_i) \
;         __builtin_amdgcn_global_load_lds((const unsigned*)((const char*)(gbase) + (voff)[_i]), (LAS unsigned*)(lds + (bufoff) + ldsw + _i * 8192), 16, 0, 0); } while (0)
; #define PG8_LDA(dst, b, h) do { _Pragma("unroll") for (int m = 0; m < 4; ++m) _Pragma("unroll") for (int k = 0; k < 2; ++k) dst[m][k] = *(const LAS bf16x8*)(lds + PG8_SA(b, h) + aoff + m * 2048 + k * 1024); } while (0)
; #define PG8_LDB(dst, b, h) do { _Pragma("unroll") for (int n = 0; n < 2; ++n) _Pragma("unroll") for (int k = 0; k < 2; ++k) dst[n][k] = *(const LAS bf16x8*)(lds + PG8_SB(b, h) + boff + n * 2048 + k * 1024); } while (0)
; #define PG8_MMA(ai, bj, At, Bt) do { __builtin_amdgcn_s_setprio(1); _Pragma("unroll") for (int m = 0; m < 4; ++m) _Pragma("unroll") for (int n = 0; n < 2; ++n) _Pragma("unroll") for (int k = 0; k < 2; ++k) \
;         acc[ai][bj][m][n] = __builtin_amdgcn_mfma_f32_16x16x32_bf16(Bt[n][k], At[m][k], acc[ai][bj][m][n], 0, 0, 0); __builtin_amdgcn_s_setprio(0); } while (0)
; #define PG8_WAIT_V(n) asm volatile("s_waitcnt vmcnt(" #n ")" ::: "memory")
; #define PG8_WAIT_L(n) asm volatile("s_waitcnt lgkmcnt(" #n ")" ::: "memory")
; #define PG8_BAR __builtin_amdgcn_s_barrier()
; #define PG8_SCHED __builtin_amdgcn_sched_barrier(0)
; template <class Epi>
; DI void gemm_phase(LAS unsigned char* lds, const Gemm g, const StaticOrder& S, const Epi& E) {
;     ...
;             PG8_BAR; PG8_WAIT_L(0); PG8_MMA(1, 0, At, B0); PG8_BAR; PG8_SCHED;
;             PG8_STAGE(PG8_SB(0, 1), b2 + hstepB, voffB);
;             PG8_WAIT_V(6); PG8_BAR; PG8_MMA(1, 1, At, B1); PG8_BAR;
;             PG8_LDB(B0, 1, 0); PG8_SCHED; PG8_LDA(At, 1, 0); PG8_STAGE(PG8_SA(0, 1), a2 + hstepA, voffA);
;             PG8_WAIT_L(8); PG8_BAR; PG8_WAIT_L(0); PG8_MMA(0, 0, At, B0); PG8_BAR; PG8_SCHED;
;             PG8_LDB(B1, 1, 1); PG8_STAGE(PG8_SB(1, 0), b3, voffB);
;             PG8_BAR; PG8_WAIT_L(0); PG8_MMA(0, 1, At, B1); PG8_BAR;
;             PG8_LDA(At, 1, 1); PG8_STAGE(PG8_SA(1, 0), a3, voffA);
;             PG8_BAR; PG8_WAIT_L(0); PG8_MMA(1, 0, At, B0); PG8_BAR; PG8_SCHED;
	s_setprio 1
	v_mfma_f32_16x16x32_bf16 v[62:65], v[152:155], v[168:171], v[62:65]
	v_mfma_f32_16x16x32_bf16 v[58:61], v[160:163], v[168:171], v[58:61]
	v_mfma_f32_16x16x32_bf16 v[54:57], v[152:155], v[176:179], v[54:57]
	v_mfma_f32_16x16x32_bf16 v[50:53], v[160:163], v[176:179], v[50:53]
	v_mfma_f32_16x16x32_bf16 v[38:41], v[152:155], v[184:187], v[38:41]
	v_mfma_f32_16x16x32_bf16 v[34:37], v[160:163], v[184:187], v[34:37]
	v_mfma_f32_16x16x32_bf16 v[22:25], v[152:155], v[192:195], v[22:25]
	v_mfma_f32_16x16x32_bf16 v[18:21], v[160:163], v[192:195], v[18:21]
	v_mfma_f32_16x16x32_bf16 v[62:65], v[156:159], v[172:175], v[62:65]
	v_mfma_f32_16x16x32_bf16 v[58:61], v[164:167], v[172:175], v[58:61]
	v_mfma_f32_16x16x32_bf16 v[54:57], v[156:159], v[180:183], v[54:57]
	v_mfma_f32_16x16x32_bf16 v[50:53], v[164:167], v[180:183], v[50:53]
	v_mfma_f32_16x16x32_bf16 v[38:41], v[156:159], v[188:191], v[38:41]
	v_mfma_f32_16x16x32_bf16 v[34:37], v[164:167], v[188:191], v[34:37]
	v_mfma_f32_16x16x32_bf16 v[22:25], v[156:159], v[196:199], v[22:25]
	v_mfma_f32_16x16x32_bf16 v[18:21], v[164:167], v[196:199], v[18:21]
	v_mfma_f32_16x16x32_bf16 v[46:49], v[200:203], v[168:171], v[46:49]
	v_mfma_f32_16x16x32_bf16 v[42:45], v[208:211], v[168:171], v[42:45]
	v_mfma_f32_16x16x32_bf16 v[30:33], v[200:203], v[176:179], v[30:33]
	v_mfma_f32_16x16x32_bf16 v[26:29], v[208:211], v[176:179], v[26:29]
	v_mfma_f32_16x16x32_bf16 v[14:17], v[200:203], v[184:187], v[14:17]
	v_mfma_f32_16x16x32_bf16 v[10:13], v[208:211], v[184:187], v[10:13]
	v_mfma_f32_16x16x32_bf16 v[6:9], v[200:203], v[192:195], v[6:9]
	v_mfma_f32_16x16x32_bf16 v[2:5], v[208:211], v[192:195], v[2:5]
	v_mfma_f32_16x16x32_bf16 v[46:49], v[204:207], v[172:175], v[46:49]
	v_mfma_f32_16x16x32_bf16 v[42:45], v[212:215], v[172:175], v[42:45]
	v_mfma_f32_16x16x32_bf16 v[30:33], v[204:207], v[180:183], v[30:33]
	v_mfma_f32_16x16x32_bf16 v[26:29], v[212:215], v[180:183], v[26:29]
	v_mfma_f32_16x16x32_bf16 v[14:17], v[204:207], v[188:191], v[14:17]
	v_mfma_f32_16x16x32_bf16 v[10:13], v[212:215], v[188:191], v[10:13]
	v_mfma_f32_16x16x32_bf16 v[6:9], v[204:207], v[196:199], v[6:9]
	v_mfma_f32_16x16x32_bf16 v[2:5], v[212:215], v[196:199], v[2:5]
	s_setprio 0
	s_add_i32 s61, 0, 0x18000
	v_add_u32_e32 v151, s61, v146
	s_barrier
	ds_read_b128 v[152:155], v151
	ds_read_b128 v[156:159], v151 offset:1024
	ds_read_b128 v[160:163], v151 offset:2048
	ds_read_b128 v[164:167], v151 offset:3072
	s_add_u32 s26, s26, 0x80000
	s_addc_u32 s27, s27, 0
	s_mov_b32 m0, s37
	v_lshl_add_u64 v[200:201], s[26:27], 0, v[130:131]
	ds_read_b128 v[168:171], v149 offset:32768
	ds_read_b128 v[172:175], v149 offset:33792
	ds_read_b128 v[176:179], v149 offset:34816
	ds_read_b128 v[180:183], v149 offset:35840
	ds_read_b128 v[184:187], v149 offset:36864
	ds_read_b128 v[188:191], v149 offset:37888
	ds_read_b128 v[192:195], v149 offset:38912
	ds_read_b128 v[196:199], v149 offset:39936
	global_load_lds_dwordx4 v[200:201], off
	v_lshl_add_u64 v[200:201], s[26:27], 0, v[134:135]
	s_mov_b32 m0, s38
	s_nop 0
	global_load_lds_dwordx4 v[200:201], off
	s_add_i32 s26, 0, 0x1c000
	v_add_u32_e32 v151, s26, v146
	ds_read_b128 v[200:203], v151
	ds_read_b128 v[204:207], v151 offset:1024
	ds_read_b128 v[208:211], v151 offset:2048
	ds_read_b128 v[212:215], v151 offset:3072
	s_waitcnt lgkmcnt(0)
	s_waitcnt vmcnt(8)
	s_barrier
	s_setprio 1
	v_mfma_f32_16x16x32_bf16 v[126:129], v[152:155], v[168:171], v[126:129]
	v_mfma_f32_16x16x32_bf16 v[122:125], v[160:163], v[168:171], v[122:125]
	v_mfma_f32_16x16x32_bf16 v[118:121], v[152:155], v[176:179], v[118:121]
	v_mfma_f32_16x16x32_bf16 v[114:117], v[160:163], v[176:179], v[114:117]
	v_mfma_f32_16x16x32_bf16 v[102:105], v[152:155], v[184:187], v[102:105]
	v_mfma_f32_16x16x32_bf16 v[98:101], v[160:163], v[184:187], v[98:101]
	v_mfma_f32_16x16x32_bf16 v[86:89], v[152:155], v[192:195], v[86:89]
	v_mfma_f32_16x16x32_bf16 v[82:85], v[160:163], v[192:195], v[82:85]
	v_mfma_f32_16x16x32_bf16 v[126:129], v[156:159], v[172:175], v[126:129]
	v_mfma_f32_16x16x32_bf16 v[122:125], v[164:167], v[172:175], v[122:125]
	v_mfma_f32_16x16x32_bf16 v[118:121], v[156:159], v[180:183], v[118:121]
	v_mfma_f32_16x16x32_bf16 v[114:117], v[164:167], v[180:183], v[114:117]
	v_mfma_f32_16x16x32_bf16 v[102:105], v[156:159], v[188:191], v[102:105]
	v_mfma_f32_16x16x32_bf16 v[98:101], v[164:167], v[188:191], v[98:101]
	v_mfma_f32_16x16x32_bf16 v[86:89], v[156:159], v[196:199], v[86:89]
	v_mfma_f32_16x16x32_bf16 v[82:85], v[164:167], v[196:199], v[82:85]
	v_mfma_f32_16x16x32_bf16 v[110:113], v[200:203], v[168:171], v[110:113]
	v_mfma_f32_16x16x32_bf16 v[106:109], v[208:211], v[168:171], v[106:109]
	v_mfma_f32_16x16x32_bf16 v[94:97], v[200:203], v[176:179], v[94:97]
	v_mfma_f32_16x16x32_bf16 v[90:93], v[208:211], v[176:179], v[90:93]
	v_mfma_f32_16x16x32_bf16 v[78:81], v[200:203], v[184:187], v[78:81]
	v_mfma_f32_16x16x32_bf16 v[74:77], v[208:211], v[184:187], v[74:77]
	v_mfma_f32_16x16x32_bf16 v[70:73], v[200:203], v[192:195], v[70:73]
	v_mfma_f32_16x16x32_bf16 v[66:69], v[208:211], v[192:195], v[66:69]
	v_mfma_f32_16x16x32_bf16 v[110:113], v[204:207], v[172:175], v[110:113]
	v_mfma_f32_16x16x32_bf16 v[106:109], v[212:215], v[172:175], v[106:109]
	v_mfma_f32_16x16x32_bf16 v[94:97], v[204:207], v[180:183], v[94:97]
	v_mfma_f32_16x16x32_bf16 v[90:93], v[212:215], v[180:183], v[90:93]
	v_mfma_f32_16x16x32_bf16 v[78:81], v[204:207], v[188:191], v[78:81]
	v_mfma_f32_16x16x32_bf16 v[74:77], v[212:215], v[188:191], v[74:77]
	v_mfma_f32_16x16x32_bf16 v[70:73], v[204:207], v[196:199], v[70:73]
	v_mfma_f32_16x16x32_bf16 v[66:69], v[212:215], v[196:199], v[66:69]
	s_setprio 0
	s_barrier
; #define PG8_STAGE(bufoff, gbase, voff) do { _Pragma("unroll") for (int _i = 0; _i < 2; ++_i) \
;         __builtin_amdgcn_global_load_lds((const unsigned*)((const char*)(gbase) + (voff)[_i]), (LAS unsigned*)(lds + (bufoff) + ldsw + _i * 8192), 16, 0, 0); } while (0)
; #define PG8_LDA(dst, b, h) do { _Pragma("unroll") for (int m = 0; m < 4; ++m) _Pragma("unroll") for (int k = 0; k < 2; ++k) dst[m][k] = *(const LAS bf16x8*)(lds + PG8_SA(b, h) + aoff + m * 2048 + k * 1024); } while (0)
; #define PG8_LDB(dst, b, h) do { _Pragma("unroll") for (int n = 0; n < 2; ++n) _Pragma("unroll") for (int k = 0; k < 2; ++k) dst[n][k] = *(const LAS bf16x8*)(lds + PG8_SB(b, h) + boff + n * 2048 + k * 1024); } while (0)
; #define PG8_MMA(ai, bj, At, Bt) do { __builtin_amdgcn_s_setprio(1); _Pragma("unroll") for (int m = 0; m < 4; ++m) _Pragma("unroll") for (int n = 0; n < 2; ++n) _Pragma("unroll") for (int k = 0; k < 2; ++k) \
;         acc[ai][bj][m][n] = __builtin_amdgcn_mfma_f32_16x16x32_bf16(Bt[n][k], At[m][k], acc[ai][bj][m][n], 0, 0, 0); __builtin_amdgcn_s_setprio(0); } while (0)
; #define PG8_WAIT_V(n) asm volatile("s_waitcnt vmcnt(" #n ")" ::: "memory")
; #define PG8_WAIT_L(n) asm volatile("s_waitcnt lgkmcnt(" #n ")" ::: "memory")
; #define PG8_BAR __builtin_amdgcn_s_barrier()
; #define PG8_SCHED __builtin_amdgcn_sched_barrier(0)
; template <class Epi>
; DI void gemm_phase(LAS unsigned char* lds, const Gemm g, const StaticOrder& S, const Epi& E) {
;     ...
;             PG8_LDB(B1, 1, 1); PG8_STAGE(PG8_SB(1, 0), b3, voffB);
;             PG8_BAR; PG8_WAIT_L(0); PG8_MMA(0, 1, At, B1); PG8_BAR;
;             PG8_LDA(At, 1, 1); PG8_STAGE(PG8_SA(1, 0), a3, voffA);
;             PG8_BAR; PG8_WAIT_L(0); PG8_MMA(1, 0, At, B0); PG8_BAR; PG8_SCHED;
;             PG8_STAGE(PG8_SB(1, 1), b3 + hstepB, voffB);
;             PG8_WAIT_V(6); PG8_BAR; PG8_MMA(1, 1, At, B1); PG8_BAR;
;         }
	s_add_i32 s27, s61, s35
	v_lshl_add_u64 v[216:217], v[216:217], 0, s[10:11]
	s_mov_b32 m0, s27
	s_nop 0
	global_load_lds_dwordx4 v[216:217], off
	v_lshl_add_u64 v[216:217], v[218:219], 0, s[10:11]
	s_add_i32 m0, s27, 0x2000
	s_nop 0
	global_load_lds_dwordx4 v[216:217], off
	s_mov_b32 m0, s49
	v_lshl_add_u64 v[216:217], v[220:221], 0, s[10:11]
	ds_read_b128 v[168:171], v149 offset:49152
	ds_read_b128 v[172:175], v149 offset:50176
	ds_read_b128 v[176:179], v149 offset:51200
	ds_read_b128 v[180:183], v149 offset:52224
	ds_read_b128 v[184:187], v149 offset:53248
	ds_read_b128 v[188:191], v149 offset:54272
	ds_read_b128 v[192:195], v149 offset:55296
	ds_read_b128 v[196:199], v149 offset:56320
	global_load_lds_dwordx4 v[216:217], off
	v_lshl_add_u64 v[216:217], v[222:223], 0, s[10:11]
	s_mov_b32 m0, s50
	s_nop 0
	global_load_lds_dwordx4 v[216:217], off
	s_add_u32 s24, s24, 0x80080
	s_addc_u32 s25, s25, 0
	s_add_i32 s26, s26, s35
	v_lshl_add_u64 v[252:253], s[24:25], 0, v[132:133]
	s_mov_b32 m0, s26
	s_nop 0
	global_load_lds_dwordx4 v[252:253], off
	v_lshl_add_u64 v[252:253], s[24:25], 0, v[136:137]
	s_add_i32 m0, s26, 0x2000
	s_nop 0
	global_load_lds_dwordx4 v[252:253], off
	s_waitcnt lgkmcnt(0)
	s_waitcnt vmcnt(8)
	s_barrier
	s_setprio 1
	v_mfma_f32_16x16x32_bf16 v[62:65], v[152:155], v[168:171], v[62:65]
	v_mfma_f32_16x16x32_bf16 v[58:61], v[160:163], v[168:171], v[58:61]
	v_mfma_f32_16x16x32_bf16 v[54:57], v[152:155], v[176:179], v[54:57]
	v_mfma_f32_16x16x32_bf16 v[50:53], v[160:163], v[176:179], v[50:53]
	v_mfma_f32_16x16x32_bf16 v[38:41], v[152:155], v[184:187], v[38:41]
	v_mfma_f32_16x16x32_bf16 v[34:37], v[160:163], v[184:187], v[34:37]
	v_mfma_f32_16x16x32_bf16 v[22:25], v[152:155], v[192:195], v[22:25]
	v_mfma_f32_16x16x32_bf16 v[18:21], v[160:163], v[192:195], v[18:21]
	v_mfma_f32_16x16x32_bf16 v[62:65], v[156:159], v[172:175], v[62:65]
	v_mfma_f32_16x16x32_bf16 v[58:61], v[164:167], v[172:175], v[58:61]
	v_mfma_f32_16x16x32_bf16 v[54:57], v[156:159], v[180:183], v[54:57]
	v_mfma_f32_16x16x32_bf16 v[50:53], v[164:167], v[180:183], v[50:53]
	v_mfma_f32_16x16x32_bf16 v[38:41], v[156:159], v[188:191], v[38:41]
	v_mfma_f32_16x16x32_bf16 v[34:37], v[164:167], v[188:191], v[34:37]
	v_mfma_f32_16x16x32_bf16 v[22:25], v[156:159], v[196:199], v[22:25]
	v_mfma_f32_16x16x32_bf16 v[18:21], v[164:167], v[196:199], v[18:21]
	v_mfma_f32_16x16x32_bf16 v[46:49], v[200:203], v[168:171], v[46:49]
	v_mfma_f32_16x16x32_bf16 v[42:45], v[208:211], v[168:171], v[42:45]
	v_mfma_f32_16x16x32_bf16 v[30:33], v[200:203], v[176:179], v[30:33]
	v_mfma_f32_16x16x32_bf16 v[26:29], v[208:211], v[176:179], v[26:29]
	v_mfma_f32_16x16x32_bf16 v[14:17], v[200:203], v[184:187], v[14:17]
	v_mfma_f32_16x16x32_bf16 v[10:13], v[208:211], v[184:187], v[10:13]
	v_mfma_f32_16x16x32_bf16 v[6:9], v[200:203], v[192:195], v[6:9]
	v_mfma_f32_16x16x32_bf16 v[2:5], v[208:211], v[192:195], v[2:5]
	v_mfma_f32_16x16x32_bf16 v[46:49], v[204:207], v[172:175], v[46:49]
	v_mfma_f32_16x16x32_bf16 v[42:45], v[212:215], v[172:175], v[42:45]
	v_mfma_f32_16x16x32_bf16 v[30:33], v[204:207], v[180:183], v[30:33]
	v_mfma_f32_16x16x32_bf16 v[26:29], v[212:215], v[180:183], v[26:29]
	v_mfma_f32_16x16x32_bf16 v[14:17], v[204:207], v[188:191], v[14:17]
	v_mfma_f32_16x16x32_bf16 v[10:13], v[212:215], v[188:191], v[10:13]
	v_mfma_f32_16x16x32_bf16 v[6:9], v[204:207], v[196:199], v[6:9]
	v_mfma_f32_16x16x32_bf16 v[2:5], v[212:215], v[196:199], v[2:5]
	s_setprio 0
	s_add_i32 s60, s60, 2
	s_add_u32 s22, s22, 0x100
	s_addc_u32 s23, s23, 0
	s_add_u32 s58, s58, 0x100
	s_addc_u32 s59, s59, 0
	s_cmp_gt_u32 s60, 29
	s_barrier
	s_cbranch_scc0 .LBB0_1456
; DI unsigned pk2(float lo, float hi) { f32x2 v = {lo, hi}; bfv2 b = __builtin_convertvector(v, bfv2); return __builtin_bit_cast(unsigned, b); }
;     DI void operator()(const f32x4 (&acc)[2][2][4][2], const pg8::Unit& u, int wr, int wc, int fr, int fq) const {
;         const int row0 = u.pm * 256 + wr * 64 + fr, col0 = u.pn * 256 + wc * 32 + 8 * fq;
; #pragma unroll
;         for (int ai = 0; ai < 2; ++ai)
; #pragma unroll
;             for (int m = 0; m < 4; ++m) { bf16_t* rowp = O + (size_t)(row0 + ai * 128 + m * 16) * ldc + col0;
; #pragma unroll
;                 for (int bj = 0; bj < 2; ++bj) { const f32x4 v0 = acc[ai][bj][m][0], v1 = acc[ai][bj][m][1];
;                     u32x4 w; w.x = pk2(v0[0], v0[1]); w.y = pk2(v0[2], v0[3]); w.z = pk2(v1[0], v1[1]); w.w = pk2(v1[2], v1[3]);
;                     *(u32x4*)(rowp + bj * 128) = w; } }
	v_lshl_add_u32 v151, s12, 8, v1
	v_lshl_or_b32 v152, s55, 8, v147
	v_ashrrev_i32_e32 v153, 31, v152
	v_mov_b64_e32 v[154:155], s[8:9]
	v_cvt_pk_bf16_f32 v70, v70, v71
	v_cvt_pk_bf16_f32 v71, v72, v73
	v_cvt_pk_bf16_f32 v72, v66, v67
	v_add_u32_e32 v66, 0x80, v151
	v_mad_i64_i32 v[156:157], s[22:23], v151, s54, v[154:155]
	v_lshlrev_b64 v[152:153], 1, v[152:153]
	v_cvt_pk_bf16_f32 v110, v110, v111
	v_cvt_pk_bf16_f32 v111, v112, v113
	v_cvt_pk_bf16_f32 v112, v106, v107
	v_or_b32_e32 v106, 16, v151
	v_mad_i64_i32 v[66:67], s[22:23], v66, s54, v[154:155]
	v_cvt_pk_bf16_f32 v46, v46, v47
	v_cvt_pk_bf16_f32 v47, v48, v49
	v_cvt_pk_bf16_f32 v48, v42, v43
	v_add_u32_e32 v42, 0x90, v151
	v_lshl_add_u64 v[156:157], v[156:157], 0, v[152:153]
	v_cvt_pk_bf16_f32 v113, v108, v109
	v_mad_i64_i32 v[106:107], s[22:23], v106, s54, v[154:155]
	v_cvt_pk_bf16_f32 v94, v94, v95
	v_cvt_pk_bf16_f32 v95, v96, v97
	v_cvt_pk_bf16_f32 v96, v90, v91
	v_or_b32_e32 v90, 32, v151
	v_lshl_add_u64 v[66:67], v[66:67], 0, v[152:153]
	v_cvt_pk_bf16_f32 v49, v44, v45
	v_mad_i64_i32 v[42:43], s[22:23], v42, s54, v[154:155]
	v_cvt_pk_bf16_f32 v30, v30, v31
	v_cvt_pk_bf16_f32 v31, v32, v33
	v_cvt_pk_bf16_f32 v32, v26, v27
	v_add_u32_e32 v26, 0xa0, v151
	global_store_dwordx4 v[156:157], v[110:113], off offset:256
	v_cvt_pk_bf16_f32 v97, v92, v93
	v_mad_i64_i32 v[90:91], s[22:23], v90, s54, v[154:155]
	v_lshl_add_u64 v[110:111], v[106:107], 0, v[152:153]
	v_cvt_pk_bf16_f32 v78, v78, v79
	v_cvt_pk_bf16_f32 v79, v80, v81
	v_cvt_pk_bf16_f32 v80, v74, v75
	v_or_b32_e32 v74, 48, v151
	global_store_dwordx4 v[66:67], v[46:49], off offset:256
	v_cvt_pk_bf16_f32 v33, v28, v29
	v_mad_i64_i32 v[26:27], s[22:23], v26, s54, v[154:155]
	v_lshl_add_u64 v[46:47], v[42:43], 0, v[152:153]
	v_cvt_pk_bf16_f32 v14, v14, v15
	v_cvt_pk_bf16_f32 v15, v16, v17
	v_cvt_pk_bf16_f32 v16, v10, v11
	v_add_u32_e32 v10, 0xb0, v151
	global_store_dwordx4 v[110:111], v[94:97], off offset:256
	v_cvt_pk_bf16_f32 v81, v76, v77
	v_mad_i64_i32 v[74:75], s[22:23], v74, s54, v[154:155]
	v_lshl_add_u64 v[94:95], v[90:91], 0, v[152:153]
	global_store_dwordx4 v[46:47], v[30:33], off offset:256
	v_cvt_pk_bf16_f32 v17, v12, v13
	v_mad_i64_i32 v[10:11], s[22:23], v10, s54, v[154:155]
	v_lshl_add_u64 v[30:31], v[26:27], 0, v[152:153]
	v_cvt_pk_bf16_f32 v126, v126, v127
	v_cvt_pk_bf16_f32 v127, v128, v129
	v_cvt_pk_bf16_f32 v128, v122, v123
	v_cvt_pk_bf16_f32 v129, v124, v125
	v_cvt_pk_bf16_f32 v106, v118, v119
	v_cvt_pk_bf16_f32 v107, v120, v121
	v_cvt_pk_bf16_f32 v108, v114, v115
	v_cvt_pk_bf16_f32 v109, v116, v117
	v_cvt_pk_bf16_f32 v90, v102, v103
	v_cvt_pk_bf16_f32 v91, v104, v105
	v_cvt_pk_bf16_f32 v92, v98, v99
	v_cvt_pk_bf16_f32 v93, v100, v101
	global_store_dwordx4 v[94:95], v[78:81], off offset:256
	v_cvt_pk_bf16_f32 v76, v82, v83
	v_cvt_pk_bf16_f32 v77, v84, v85
	v_lshl_add_u64 v[78:79], v[74:75], 0, v[152:153]
	v_cvt_pk_bf16_f32 v74, v86, v87
	v_cvt_pk_bf16_f32 v75, v88, v89
	v_cvt_pk_bf16_f32 v73, v68, v69
	v_cvt_pk_bf16_f32 v62, v62, v63
	v_cvt_pk_bf16_f32 v63, v64, v65
	v_cvt_pk_bf16_f32 v64, v58, v59
	v_cvt_pk_bf16_f32 v65, v60, v61
	v_cvt_pk_bf16_f32 v42, v54, v55
	v_cvt_pk_bf16_f32 v43, v56, v57
	v_cvt_pk_bf16_f32 v44, v50, v51
	v_cvt_pk_bf16_f32 v45, v52, v53
	v_cvt_pk_bf16_f32 v26, v38, v39
	v_cvt_pk_bf16_f32 v27, v40, v41
	v_cvt_pk_bf16_f32 v28, v34, v35
	v_cvt_pk_bf16_f32 v29, v36, v37
	global_store_dwordx4 v[30:31], v[14:17], off offset:256
	v_cvt_pk_bf16_f32 v12, v18, v19
	v_cvt_pk_bf16_f32 v13, v20, v21
	v_lshl_add_u64 v[14:15], v[10:11], 0, v[152:153]
	v_cvt_pk_bf16_f32 v10, v22, v23
	v_cvt_pk_bf16_f32 v11, v24, v25
	v_cvt_pk_bf16_f32 v6, v6, v7
	v_cvt_pk_bf16_f32 v7, v8, v9
	v_cvt_pk_bf16_f32 v8, v2, v3
	v_cvt_pk_bf16_f32 v9, v4, v5
	s_and_b64 vcc, exec, s[4:5]
	s_mov_b32 s55, s14
	s_mov_b32 s12, s16
	s_mov_b64 s[24:25], s[20:21]
	s_mov_b64 s[22:23], s[18:19]
	global_store_dwordx4 v[156:157], v[126:129], off
	global_store_dwordx4 v[110:111], v[106:109], off
	global_store_dwordx4 v[94:95], v[90:93], off
	global_store_dwordx4 v[78:79], v[74:77], off
	global_store_dwordx4 v[78:79], v[70:73], off offset:256
	global_store_dwordx4 v[66:67], v[62:65], off
	global_store_dwordx4 v[46:47], v[42:45], off
	global_store_dwordx4 v[30:31], v[26:29], off
	global_store_dwordx4 v[14:15], v[10:13], off
	global_store_dwordx4 v[14:15], v[6:9], off offset:256
	s_cbranch_vccz .LBB0_1449
	s_waitcnt vmcnt(0)
	s_cmpk_gt_u32 s28, 0xff
	s_cbranch_scc1 .LBB0_1460
	s_barrier

; #define PG8_STAGE(bufoff, gbase, voff) do { _Pragma("unroll") for (int _i = 0; _i < 2; ++_i) \
;         __builtin_amdgcn_global_load_lds((const unsigned*)((const char*)(gbase) + (voff)[_i]), (LAS unsigned*)(lds + (bufoff) + ldsw + _i * 8192), 16, 0, 0); } while (0)
; #define PG8_WAIT_V(n) asm volatile("s_waitcnt vmcnt(" #n ")" ::: "memory")
; #define PG8_BAR __builtin_amdgcn_s_barrier()
; template <class Epi>
; DI void gemm_phase(LAS unsigned char* lds, const Gemm g, const StaticOrder& S, const Epi& E) {
;     ...
;     const char* cA = PG8_ABASE(cur); const char* cB = PG8_BBASE(cur);
;     PG8_STAGE(PG8_SB(0, 0), cB, voffB); PG8_STAGE(PG8_SA(0, 0), cA, voffA); PG8_STAGE(PG8_SB(0, 1), cB + hstepB, voffB); PG8_STAGE(PG8_SA(0, 1), cA + hstepA, voffA);
;     if (wr == 1) PG8_BAR;
;     PG8_WAIT_V(4); PG8_BAR;
;     PG8_STAGE(PG8_SB(1, 0), cB + kstep, voffB); PG8_STAGE(PG8_SA(1, 0), cA + kstep, voffA); PG8_STAGE(PG8_SB(1, 1), cB + hstepB + kstep, voffB);
;     PG8_WAIT_V(6); PG8_BAR;
.LBB0_1963:
	s_add_u32 s53, s10, 0x200000
	s_addc_u32 s54, s11, 0
	s_add_u32 s55, s10, 0x28000
	s_addc_u32 s56, s11, 0
	s_add_u32 s10, s10, 0x100000
	s_addc_u32 s11, s11, 0
	s_waitcnt lgkmcnt(0)
	s_add_u32 s14, s4, 0x2000
	s_addc_u32 s15, s5, 0
	s_add_u32 s16, s6, 0x2000
	s_addc_u32 s17, s7, 0
	s_lshl_b32 s4, s18, 5
	s_mov_b64 s[18:19], 0x80
	s_and_b32 s7, s4, 0x60
	s_add_i32 m0, s39, 0x18000
	v_lshl_add_u64 v[8:9], v[8:9], 0, s[18:19]
	s_lshl_b32 s6, s22, 13
	s_lshl_b32 s23, s7, 7
	s_waitcnt vmcnt(0)
	s_barrier
	global_load_lds_dwordx4 v[8:9], off
	v_lshl_add_u64 v[6:7], v[6:7], 0, s[18:19]
	s_add_i32 m0, s39, 0x1a000
	s_add_i32 s57, s39, 0x8000
	s_add_i32 s58, s39, 0xa000
	global_load_lds_dwordx4 v[6:7], off
	v_lshl_add_u64 v[4:5], v[4:5], 0, s[18:19]
	s_mov_b32 m0, s57
	s_add_u32 s4, s28, 0x80080
	global_load_lds_dwordx4 v[4:5], off
	v_lshl_add_u64 v[2:3], v[2:3], 0, s[18:19]
	s_mov_b32 m0, s58
	s_addc_u32 s5, s29, 0
	global_load_lds_dwordx4 v[2:3], off
	s_add_i32 m0, s39, 0x1c000
	v_lshl_add_u64 v[2:3], s[4:5], 0, v[160:161]
	global_load_lds_dwordx4 v[2:3], off
	v_lshl_add_u64 v[2:3], s[4:5], 0, v[164:165]
	s_add_i32 m0, s39, 0x1e000
	v_and_b32_e32 v1, 15, v254
	global_load_lds_dwordx4 v[2:3], off
	v_bfe_u32 v2, v254, 4, 2
	v_lshlrev_b32_e32 v3, 4, v2
	v_lshlrev_b32_e32 v4, 2, v254
	v_lshl_or_b32 v166, s22, 6, v1
	v_lshl_or_b32 v1, v1, 6, v3
	v_and_b32_e32 v4, 32, v4
	v_bitop3_b32 v5, v1, s6, v4 bitop3:0xde
	v_lshlrev_b32_e32 v1, 6, v254
	s_movk_i32 s4, 0x3c0
	v_and_or_b32 v1, v1, s4, v3
	s_waitcnt vmcnt(6)
	v_bitop3_b32 v1, s23, v1, v4 bitop3:0xf6
	v_mov_b32_e32 v167, v161
	v_or_b32_e32 v170, 16, v166
	v_mov_b32_e32 v171, v161
	v_or_b32_e32 v174, 32, v166
	v_mov_b32_e32 v175, v161
	v_or_b32_e32 v178, 48, v166
	v_mov_b32_e32 v179, v161
	v_add_u32_e32 v182, 0x80, v166
	v_mov_b32_e32 v183, v161
	v_add_u32_e32 v186, 0x90, v166
	v_mov_b32_e32 v187, v161
	v_add_u32_e32 v190, 0xa0, v166
	v_mov_b32_e32 v191, v161
	v_add_u32_e32 v194, 0xb0, v166
	v_mov_b32_e32 v195, v161
	s_add_i32 s60, 0, 0x10000
	s_add_i32 s61, 0, 0x14000
	s_sext_i32_i8 s65, s20
	v_lshlrev_b64 v[168:169], 13, v[166:167]
	v_lshlrev_b64 v[172:173], 13, v[170:171]
	v_lshlrev_b64 v[176:177], 13, v[174:175]
	v_lshlrev_b64 v[180:181], 13, v[178:179]
	v_lshlrev_b64 v[184:185], 13, v[182:183]
	v_lshlrev_b64 v[188:189], 13, v[186:187]
	v_lshlrev_b64 v[192:193], 13, v[190:191]
	v_lshlrev_b64 v[196:197], 13, v[194:195]
	s_ashr_i32 s59, s51, 31
	v_lshl_or_b32 v167, v2, 2, s7
	v_add3_u32 v198, v12, v10, v11
	v_mov_b32_e32 v199, v161
	v_add3_u32 v200, v13, v10, v11
	v_mov_b32_e32 v201, v161
	v_mov_b64_e32 v[202:203], 0x400
	v_mov_b64_e32 v[204:205], 0x3ff
	v_add_u32_e32 v171, s60, v1
	v_add_u32_e32 v175, 0, v5
	v_add_u32_e32 v179, s61, v1
	s_movk_i32 s62, 0x1800
	s_mov_b32 s20, 0x3fd744fd
	v_mov_b32_e32 v183, 0x8000
	s_barrier

; #define PG8_STAGE(bufoff, gbase, voff) do { _Pragma("unroll") for (int _i = 0; _i < 2; ++_i) \
;         __builtin_amdgcn_global_load_lds((const unsigned*)((const char*)(gbase) + (voff)[_i]), (LAS unsigned*)(lds + (bufoff) + ldsw + _i * 8192), 16, 0, 0); } while (0)
; #define PG8_LDA(dst, b, h) do { _Pragma("unroll") for (int m = 0; m < 4; ++m) _Pragma("unroll") for (int k = 0; k < 2; ++k) dst[m][k] = *(const LAS bf16x8*)(lds + PG8_SA(b, h) + aoff + m * 2048 + k * 1024); } while (0)
; #define PG8_LDB(dst, b, h) do { _Pragma("unroll") for (int n = 0; n < 2; ++n) _Pragma("unroll") for (int k = 0; k < 2; ++k) dst[n][k] = *(const LAS bf16x8*)(lds + PG8_SB(b, h) + boff + n * 2048 + k * 1024); } while (0)
; #define PG8_MMA(ai, bj, At, Bt) do { __builtin_amdgcn_s_setprio(1); _Pragma("unroll") for (int m = 0; m < 4; ++m) _Pragma("unroll") for (int n = 0; n < 2; ++n) _Pragma("unroll") for (int k = 0; k < 2; ++k) \
;         acc[ai][bj][m][n] = __builtin_amdgcn_mfma_f32_16x16x32_bf16(Bt[n][k], At[m][k], acc[ai][bj][m][n], 0, 0, 0); __builtin_amdgcn_s_setprio(0); } while (0)
; #define PG8_WAIT_V(n) asm volatile("s_waitcnt vmcnt(" #n ")" ::: "memory")
; #define PG8_WAIT_L(n) asm volatile("s_waitcnt lgkmcnt(" #n ")" ::: "memory")
; #define PG8_BAR __builtin_amdgcn_s_barrier()
; #define PG8_SCHED __builtin_amdgcn_sched_barrier(0)
; template <class Epi>
; DI void gemm_phase(LAS unsigned char* lds, const Gemm g, const StaticOrder& S, const Epi& E) {
;     ...
;             PG8_LDB(B0, 0, 0); PG8_SCHED; PG8_LDA(At, 0, 0); PG8_STAGE(PG8_SA(1, 1), a1 + hstepA, voffA);
;             PG8_WAIT_L(8); PG8_BAR; PG8_WAIT_L(0); PG8_MMA(0, 0, At, B0); PG8_BAR; PG8_SCHED;
;             PG8_LDB(B1, 0, 1); PG8_STAGE(PG8_SB(0, 0), b2, voffB);
;             PG8_BAR; PG8_WAIT_L(0); PG8_MMA(0, 1, At, B1); PG8_BAR;
;             PG8_LDA(At, 0, 1); PG8_STAGE(PG8_SA(0, 0), a2, voffA);
;             PG8_BAR; PG8_WAIT_L(0); PG8_MMA(1, 0, At, B0); PG8_BAR; PG8_SCHED;
;             PG8_STAGE(PG8_SB(0, 1), b2 + hstepB, voffB);
;             PG8_WAIT_V(6); PG8_BAR; PG8_MMA(1, 1, At, B1); PG8_BAR;
.LBB0_1969:
	ds_read_b128 v[130:133], v171
	ds_read_b128 v[134:137], v171 offset:1024
	ds_read_b128 v[138:141], v171 offset:2048
	ds_read_b128 v[142:145], v171 offset:3072
	s_add_u32 s28, s6, 0xffdf0080
	s_addc_u32 s29, s7, -1
	s_cmp_eq_u32 s69, 28
	s_cselect_b32 s31, s25, s29
	s_cselect_b32 s30, s24, s28
	s_cselect_b32 s29, s23, s68
	s_cselect_b32 s28, s66, s67
	v_lshl_add_u64 v[214:215], s[6:7], 0, v[198:199]
	s_add_i32 m0, s39, 0xc000
	ds_read_b128 v[146:149], v175
	ds_read_b128 v[150:153], v175 offset:1024
	ds_read_b128 v[154:157], v175 offset:2048
	ds_read_b128 v[206:209], v175 offset:3072
	ds_read_b128 v[210:213], v175 offset:4096
	ds_read_b128 v[218:221], v175 offset:5120
	ds_read_b128 v[222:225], v175 offset:6144
	ds_read_b128 v[226:229], v175 offset:7168
	global_load_lds_dwordx4 v[214:215], off
	v_lshl_add_u64 v[214:215], s[6:7], 0, v[200:201]
	s_add_i32 m0, s39, 0xe000
	s_nop 0
	global_load_lds_dwordx4 v[214:215], off
	ds_read_b128 v[230:233], v179
	ds_read_b128 v[234:237], v179 offset:1024
	ds_read_b128 v[238:241], v179 offset:2048
	ds_read_b128 v[242:245], v179 offset:3072
	s_waitcnt lgkmcnt(0)
	s_waitcnt vmcnt(8)
	s_barrier
	s_setprio 1
	v_mfma_f32_16x16x32_bf16 v[126:129], v[130:133], v[146:149], v[126:129]
	v_mfma_f32_16x16x32_bf16 v[102:105], v[138:141], v[146:149], v[102:105]
	v_mfma_f32_16x16x32_bf16 v[122:125], v[130:133], v[154:157], v[122:125]
	v_mfma_f32_16x16x32_bf16 v[94:97], v[138:141], v[154:157], v[94:97]
	v_mfma_f32_16x16x32_bf16 v[118:121], v[130:133], v[210:213], v[118:121]
	v_mfma_f32_16x16x32_bf16 v[86:89], v[138:141], v[210:213], v[86:89]
	v_mfma_f32_16x16x32_bf16 v[114:117], v[130:133], v[222:225], v[114:117]
	v_mfma_f32_16x16x32_bf16 v[82:85], v[138:141], v[222:225], v[82:85]
	v_mfma_f32_16x16x32_bf16 v[126:129], v[134:137], v[150:153], v[126:129]
	v_mfma_f32_16x16x32_bf16 v[102:105], v[142:145], v[150:153], v[102:105]
	v_mfma_f32_16x16x32_bf16 v[122:125], v[134:137], v[206:209], v[122:125]
	v_mfma_f32_16x16x32_bf16 v[94:97], v[142:145], v[206:209], v[94:97]
	v_mfma_f32_16x16x32_bf16 v[118:121], v[134:137], v[218:221], v[118:121]
	v_mfma_f32_16x16x32_bf16 v[86:89], v[142:145], v[218:221], v[86:89]
	v_mfma_f32_16x16x32_bf16 v[114:117], v[134:137], v[226:229], v[114:117]
	v_mfma_f32_16x16x32_bf16 v[82:85], v[142:145], v[226:229], v[82:85]
	v_mfma_f32_16x16x32_bf16 v[62:65], v[230:233], v[146:149], v[62:65]
	v_mfma_f32_16x16x32_bf16 v[38:41], v[238:241], v[146:149], v[38:41]
	v_mfma_f32_16x16x32_bf16 v[58:61], v[230:233], v[154:157], v[58:61]
	v_mfma_f32_16x16x32_bf16 v[30:33], v[238:241], v[154:157], v[30:33]
	v_mfma_f32_16x16x32_bf16 v[54:57], v[230:233], v[210:213], v[54:57]
	v_mfma_f32_16x16x32_bf16 v[22:25], v[238:241], v[210:213], v[22:25]
	v_mfma_f32_16x16x32_bf16 v[50:53], v[230:233], v[222:225], v[50:53]
	v_mfma_f32_16x16x32_bf16 v[18:21], v[238:241], v[222:225], v[18:21]
	v_mfma_f32_16x16x32_bf16 v[62:65], v[234:237], v[150:153], v[62:65]
	v_mfma_f32_16x16x32_bf16 v[38:41], v[242:245], v[150:153], v[38:41]
	v_mfma_f32_16x16x32_bf16 v[58:61], v[234:237], v[206:209], v[58:61]
	v_mfma_f32_16x16x32_bf16 v[30:33], v[242:245], v[206:209], v[30:33]
	v_mfma_f32_16x16x32_bf16 v[54:57], v[234:237], v[218:221], v[54:57]
	v_mfma_f32_16x16x32_bf16 v[22:25], v[242:245], v[218:221], v[22:25]
	v_mfma_f32_16x16x32_bf16 v[50:53], v[234:237], v[226:229], v[50:53]
	v_mfma_f32_16x16x32_bf16 v[18:21], v[242:245], v[226:229], v[18:21]
	s_setprio 0
	s_barrier
	s_add_i32 s70, s60, s38
	v_lshl_add_u64 v[214:215], s[28:29], 0, v[160:161]
	s_mov_b32 m0, s70
	s_nop 0
	global_load_lds_dwordx4 v[214:215], off
	v_lshl_add_u64 v[216:217], s[28:29], 0, v[164:165]
	s_add_i32 m0, s70, 0x2000
	s_nop 0
	global_load_lds_dwordx4 v[216:217], off
	s_mov_b32 m0, s39
	v_lshl_add_u64 v[246:247], s[30:31], 0, v[158:159]
	ds_read_b128 v[146:149], v175 offset:16384
	ds_read_b128 v[150:153], v175 offset:17408
	ds_read_b128 v[154:157], v175 offset:18432
	ds_read_b128 v[206:209], v175 offset:19456
	ds_read_b128 v[210:213], v175 offset:20480
	ds_read_b128 v[218:221], v175 offset:21504
	ds_read_b128 v[222:225], v175 offset:22528
	ds_read_b128 v[226:229], v175 offset:23552
	global_load_lds_dwordx4 v[246:247], off
	v_lshl_add_u64 v[248:249], s[30:31], 0, v[162:163]
	s_mov_b32 m0, s48
	s_nop 0
	global_load_lds_dwordx4 v[248:249], off
	s_add_u32 s70, s28, 0x80000
	s_addc_u32 s71, s29, 0
	s_add_i32 s72, s61, s38
	v_lshl_add_u64 v[252:253], s[70:71], 0, v[160:161]
	s_mov_b32 m0, s72
	s_nop 0
	global_load_lds_dwordx4 v[252:253], off
	v_lshl_add_u64 v[252:253], s[70:71], 0, v[164:165]
	s_add_i32 m0, s72, 0x2000
	s_nop 0
	global_load_lds_dwordx4 v[252:253], off
	s_waitcnt lgkmcnt(0)
	s_waitcnt vmcnt(8)
	s_barrier
; #define PG8_STAGE(bufoff, gbase, voff) do { _Pragma("unroll") for (int _i = 0; _i < 2; ++_i) \
;         __builtin_amdgcn_global_load_lds((const unsigned*)((const char*)(gbase) + (voff)[_i]), (LAS unsigned*)(lds + (bufoff) + ldsw + _i * 8192), 16, 0, 0); } while (0)
; #define PG8_LDA(dst, b, h) do { _Pragma("unroll") for (int m = 0; m < 4; ++m) _Pragma("unroll") for (int k = 0; k < 2; ++k) dst[m][k] = *(const LAS bf16x8*)(lds + PG8_SA(b, h) + aoff + m * 2048 + k * 1024); } while (0)
; #define PG8_LDB(dst, b, h) do { _Pragma("unroll") for (int n = 0; n < 2; ++n) _Pragma("unroll") for (int k = 0; k < 2; ++k) dst[n][k] = *(const LAS bf16x8*)(lds + PG8_SB(b, h) + boff + n * 2048 + k * 1024); } while (0)
; #define PG8_MMA(ai, bj, At, Bt) do { __builtin_amdgcn_s_setprio(1); _Pragma("unroll") for (int m = 0; m < 4; ++m) _Pragma("unroll") for (int n = 0; n < 2; ++n) _Pragma("unroll") for (int k = 0; k < 2; ++k) \
;         acc[ai][bj][m][n] = __builtin_amdgcn_mfma_f32_16x16x32_bf16(Bt[n][k], At[m][k], acc[ai][bj][m][n], 0, 0, 0); __builtin_amdgcn_s_setprio(0); } while (0)
; #define PG8_WAIT_V(n) asm volatile("s_waitcnt vmcnt(" #n ")" ::: "memory")
; #define PG8_WAIT_L(n) asm volatile("s_waitcnt lgkmcnt(" #n ")" ::: "memory")
; #define PG8_BAR __builtin_amdgcn_s_barrier()
; #define PG8_SCHED __builtin_amdgcn_sched_barrier(0)
; template <class Epi>
; DI void gemm_phase(LAS unsigned char* lds, const Gemm g, const StaticOrder& S, const Epi& E) {
;     ...
;             PG8_BAR; PG8_WAIT_L(0); PG8_MMA(1, 0, At, B0); PG8_BAR; PG8_SCHED;
;             PG8_STAGE(PG8_SB(0, 1), b2 + hstepB, voffB);
;             PG8_WAIT_V(6); PG8_BAR; PG8_MMA(1, 1, At, B1); PG8_BAR;
;             PG8_LDB(B0, 1, 0); PG8_SCHED; PG8_LDA(At, 1, 0); PG8_STAGE(PG8_SA(0, 1), a2 + hstepA, voffA);
;             PG8_WAIT_L(8); PG8_BAR; PG8_WAIT_L(0); PG8_MMA(0, 0, At, B0); PG8_BAR; PG8_SCHED;
;             PG8_LDB(B1, 1, 1); PG8_STAGE(PG8_SB(1, 0), b3, voffB);
;             PG8_BAR; PG8_WAIT_L(0); PG8_MMA(0, 1, At, B1); PG8_BAR;
;             PG8_LDA(At, 1, 1); PG8_STAGE(PG8_SA(1, 0), a3, voffA);
;             PG8_BAR; PG8_WAIT_L(0); PG8_MMA(1, 0, At, B0); PG8_BAR; PG8_SCHED;
	s_setprio 1
	v_mfma_f32_16x16x32_bf16 v[110:113], v[130:133], v[146:149], v[110:113]
	v_mfma_f32_16x16x32_bf16 v[78:81], v[138:141], v[146:149], v[78:81]
	v_mfma_f32_16x16x32_bf16 v[106:109], v[130:133], v[154:157], v[106:109]
	v_mfma_f32_16x16x32_bf16 v[74:77], v[138:141], v[154:157], v[74:77]
	v_mfma_f32_16x16x32_bf16 v[98:101], v[130:133], v[210:213], v[98:101]
	v_mfma_f32_16x16x32_bf16 v[70:73], v[138:141], v[210:213], v[70:73]
	v_mfma_f32_16x16x32_bf16 v[90:93], v[130:133], v[222:225], v[90:93]
	v_mfma_f32_16x16x32_bf16 v[66:69], v[138:141], v[222:225], v[66:69]
	v_mfma_f32_16x16x32_bf16 v[110:113], v[134:137], v[150:153], v[110:113]
	v_mfma_f32_16x16x32_bf16 v[78:81], v[142:145], v[150:153], v[78:81]
	v_mfma_f32_16x16x32_bf16 v[106:109], v[134:137], v[206:209], v[106:109]
	v_mfma_f32_16x16x32_bf16 v[74:77], v[142:145], v[206:209], v[74:77]
	v_mfma_f32_16x16x32_bf16 v[98:101], v[134:137], v[218:221], v[98:101]
	v_mfma_f32_16x16x32_bf16 v[70:73], v[142:145], v[218:221], v[70:73]
	v_mfma_f32_16x16x32_bf16 v[90:93], v[134:137], v[226:229], v[90:93]
	v_mfma_f32_16x16x32_bf16 v[66:69], v[142:145], v[226:229], v[66:69]
	v_mfma_f32_16x16x32_bf16 v[46:49], v[230:233], v[146:149], v[46:49]
	v_mfma_f32_16x16x32_bf16 v[14:17], v[238:241], v[146:149], v[14:17]
	v_mfma_f32_16x16x32_bf16 v[42:45], v[230:233], v[154:157], v[42:45]
	v_mfma_f32_16x16x32_bf16 v[10:13], v[238:241], v[154:157], v[10:13]
	v_mfma_f32_16x16x32_bf16 v[34:37], v[230:233], v[210:213], v[34:37]
	v_mfma_f32_16x16x32_bf16 v[6:9], v[238:241], v[210:213], v[6:9]
	v_mfma_f32_16x16x32_bf16 v[26:29], v[230:233], v[222:225], v[26:29]
	v_mfma_f32_16x16x32_bf16 v[2:5], v[238:241], v[222:225], v[2:5]
	v_mfma_f32_16x16x32_bf16 v[46:49], v[234:237], v[150:153], v[46:49]
	v_mfma_f32_16x16x32_bf16 v[14:17], v[242:245], v[150:153], v[14:17]
	v_mfma_f32_16x16x32_bf16 v[42:45], v[234:237], v[206:209], v[42:45]
	v_mfma_f32_16x16x32_bf16 v[10:13], v[242:245], v[206:209], v[10:13]
	v_mfma_f32_16x16x32_bf16 v[34:37], v[234:237], v[218:221], v[34:37]
	v_mfma_f32_16x16x32_bf16 v[6:9], v[242:245], v[218:221], v[6:9]
	v_mfma_f32_16x16x32_bf16 v[26:29], v[234:237], v[226:229], v[26:29]
	v_mfma_f32_16x16x32_bf16 v[2:5], v[242:245], v[226:229], v[2:5]
	s_setprio 0
	s_add_i32 s70, 0, 0x18000
	v_add_u32_e32 v142, s70, v1
	s_barrier
	ds_read_b128 v[130:133], v142
	ds_read_b128 v[134:137], v142 offset:1024
	ds_read_b128 v[138:141], v142 offset:2048
	ds_read_b128 v[142:145], v142 offset:3072
	s_add_u32 s30, s30, 0x210000
	s_addc_u32 s31, s31, 0
	s_mov_b32 m0, s49
	v_lshl_add_u64 v[230:231], s[30:31], 0, v[158:159]
	ds_read_b128 v[146:149], v175 offset:32768
	ds_read_b128 v[150:153], v175 offset:33792
	ds_read_b128 v[154:157], v175 offset:34816
	ds_read_b128 v[206:209], v175 offset:35840
	ds_read_b128 v[210:213], v175 offset:36864
	ds_read_b128 v[218:221], v175 offset:37888
	ds_read_b128 v[222:225], v175 offset:38912
	ds_read_b128 v[226:229], v175 offset:39936
	global_load_lds_dwordx4 v[230:231], off
	v_lshl_add_u64 v[230:231], s[30:31], 0, v[162:163]
	s_mov_b32 m0, s50
	s_nop 0
	global_load_lds_dwordx4 v[230:231], off
	s_add_i32 s30, 0, 0x1c000
	v_add_u32_e32 v187, s30, v1
	ds_read_b128 v[230:233], v187
	ds_read_b128 v[234:237], v187 offset:1024
	ds_read_b128 v[238:241], v187 offset:2048
	ds_read_b128 v[242:245], v187 offset:3072
	s_waitcnt lgkmcnt(0)
	s_waitcnt vmcnt(8)
	s_barrier
	s_setprio 1
	v_mfma_f32_16x16x32_bf16 v[126:129], v[130:133], v[146:149], v[126:129]
	v_mfma_f32_16x16x32_bf16 v[102:105], v[138:141], v[146:149], v[102:105]
	v_mfma_f32_16x16x32_bf16 v[122:125], v[130:133], v[154:157], v[122:125]
	v_mfma_f32_16x16x32_bf16 v[94:97], v[138:141], v[154:157], v[94:97]
	v_mfma_f32_16x16x32_bf16 v[118:121], v[130:133], v[210:213], v[118:121]
	v_mfma_f32_16x16x32_bf16 v[86:89], v[138:141], v[210:213], v[86:89]
	v_mfma_f32_16x16x32_bf16 v[114:117], v[130:133], v[222:225], v[114:117]
	v_mfma_f32_16x16x32_bf16 v[82:85], v[138:141], v[222:225], v[82:85]
	v_mfma_f32_16x16x32_bf16 v[126:129], v[134:137], v[150:153], v[126:129]
	v_mfma_f32_16x16x32_bf16 v[102:105], v[142:145], v[150:153], v[102:105]
	v_mfma_f32_16x16x32_bf16 v[122:125], v[134:137], v[206:209], v[122:125]
	v_mfma_f32_16x16x32_bf16 v[94:97], v[142:145], v[206:209], v[94:97]
	v_mfma_f32_16x16x32_bf16 v[118:121], v[134:137], v[218:221], v[118:121]
	v_mfma_f32_16x16x32_bf16 v[86:89], v[142:145], v[218:221], v[86:89]
	v_mfma_f32_16x16x32_bf16 v[114:117], v[134:137], v[226:229], v[114:117]
	v_mfma_f32_16x16x32_bf16 v[82:85], v[142:145], v[226:229], v[82:85]
	v_mfma_f32_16x16x32_bf16 v[62:65], v[230:233], v[146:149], v[62:65]
	v_mfma_f32_16x16x32_bf16 v[38:41], v[238:241], v[146:149], v[38:41]
	v_mfma_f32_16x16x32_bf16 v[58:61], v[230:233], v[154:157], v[58:61]
	v_mfma_f32_16x16x32_bf16 v[30:33], v[238:241], v[154:157], v[30:33]
	v_mfma_f32_16x16x32_bf16 v[54:57], v[230:233], v[210:213], v[54:57]
	v_mfma_f32_16x16x32_bf16 v[22:25], v[238:241], v[210:213], v[22:25]
	v_mfma_f32_16x16x32_bf16 v[50:53], v[230:233], v[222:225], v[50:53]
	v_mfma_f32_16x16x32_bf16 v[18:21], v[238:241], v[222:225], v[18:21]
	v_mfma_f32_16x16x32_bf16 v[62:65], v[234:237], v[150:153], v[62:65]
	v_mfma_f32_16x16x32_bf16 v[38:41], v[242:245], v[150:153], v[38:41]
	v_mfma_f32_16x16x32_bf16 v[58:61], v[234:237], v[206:209], v[58:61]
	v_mfma_f32_16x16x32_bf16 v[30:33], v[242:245], v[206:209], v[30:33]
	v_mfma_f32_16x16x32_bf16 v[54:57], v[234:237], v[218:221], v[54:57]
	v_mfma_f32_16x16x32_bf16 v[22:25], v[242:245], v[218:221], v[22:25]
	v_mfma_f32_16x16x32_bf16 v[50:53], v[234:237], v[226:229], v[50:53]
	v_mfma_f32_16x16x32_bf16 v[18:21], v[242:245], v[226:229], v[18:21]
	s_setprio 0
	s_barrier
; #define PG8_STAGE(bufoff, gbase, voff) do { _Pragma("unroll") for (int _i = 0; _i < 2; ++_i) \
;         __builtin_amdgcn_global_load_lds((const unsigned*)((const char*)(gbase) + (voff)[_i]), (LAS unsigned*)(lds + (bufoff) + ldsw + _i * 8192), 16, 0, 0); } while (0)
; #define PG8_WAIT_V(n) asm volatile("s_waitcnt vmcnt(" #n ")" ::: "memory")
; #define PG8_WAIT_L(n) asm volatile("s_waitcnt lgkmcnt(" #n ")" ::: "memory")
; template <class Epi>
; DI void gemm_phase(LAS unsigned char* lds, const Gemm g, const StaticOrder& S, const Epi& E) {
;     ...
;             PG8_LDB(B0, 1, 0); PG8_SCHED; PG8_LDA(At, 1, 0); PG8_STAGE(PG8_SA(0, 1), a2 + hstepA, voffA);
;             PG8_WAIT_L(8); PG8_BAR; PG8_WAIT_L(0); PG8_MMA(0, 0, At, B0); PG8_BAR; PG8_SCHED;
;             PG8_LDB(B1, 1, 1); PG8_STAGE(PG8_SB(1, 0), b3, voffB);
;             PG8_BAR; PG8_WAIT_L(0); PG8_MMA(0, 1, At, B1); PG8_BAR;
;             PG8_LDA(At, 1, 1); PG8_STAGE(PG8_SA(1, 0), a3, voffA);
;             PG8_BAR; PG8_WAIT_L(0); PG8_MMA(1, 0, At, B0); PG8_BAR; PG8_SCHED;
;             PG8_STAGE(PG8_SB(1, 1), b3 + hstepB, voffB);
;             PG8_WAIT_V(6); PG8_BAR; PG8_MMA(1, 1, At, B1); PG8_BAR;
;         }
;     DI void operator()(const f32x4 (&acc)[2][2][4][2], const pg8::Unit& u, int wr, int wc, int fr, int fq) const {
;         const int rowt = row_base + u.pm * 256, col0 = u.pn * 256 + wc * 32 + 4 * fq, rl = wr * 64 + fr;
;         const int cd = cond_of_row(rowt);
;         const float* gtp = gt0 + (size_t)cd * 6144;
;         float* dbase = rowt < TL ? out + (size_t)rowt * D : ctxv + (size_t)(rowt - TL) * D;
;         const float* sbase = mode ? (const float*)dbase : (rowt < TL ? xin + (size_t)rowt * D : cin + (size_t)(rowt - TL) * D);
; #pragma unroll
;         for (int bj = 0; bj < 2; ++bj) {
;             f32x4 gv[2], gg[2], bb[2], xv[2][8];
; #pragma unroll
;             for (int n = 0; n < 2; ++n) {
;                 const int c = col0 + bj * 128 + n * 16;
;                 gv[n] = *(const f32x4*)(gtp + c);
;                 gg[n] = (f32x4){1.f, 1.f, 1.f, 1.f}; bb[n] = (f32x4){0.f, 0.f, 0.f, 0.f};
;                 if (mode) { gg[n] = *(const f32x4*)(lg + c); bb[n] = *(const f32x4*)(lb + c); }
; #pragma unroll
;                 for (int q = 0; q < 8; ++q) { const int rr = rl + (q >> 2) * 128 + (q & 3) * 16; xv[n][q] = *(const f32x4*)(sbase + (size_t)rr * D + c); }
	s_add_i32 s31, s70, s38
	v_lshl_add_u64 v[214:215], v[214:215], 0, s[18:19]
	s_mov_b32 m0, s31
	s_nop 0
	global_load_lds_dwordx4 v[214:215], off
	v_lshl_add_u64 v[214:215], v[216:217], 0, s[18:19]
	s_add_i32 m0, s31, 0x2000
	s_nop 0
	global_load_lds_dwordx4 v[214:215], off
	s_mov_b32 m0, s57
	v_lshl_add_u64 v[214:215], v[246:247], 0, s[18:19]
	ds_read_b128 v[146:149], v175 offset:49152
	ds_read_b128 v[150:153], v175 offset:50176
	ds_read_b128 v[154:157], v175 offset:51200
	ds_read_b128 v[206:209], v175 offset:52224
	ds_read_b128 v[210:213], v175 offset:53248
	ds_read_b128 v[218:221], v175 offset:54272
	ds_read_b128 v[222:225], v175 offset:55296
	ds_read_b128 v[226:229], v175 offset:56320
	global_load_lds_dwordx4 v[214:215], off
	v_lshl_add_u64 v[214:215], v[248:249], 0, s[18:19]
	s_mov_b32 m0, s58
	s_nop 0
	global_load_lds_dwordx4 v[214:215], off
	s_add_u32 s28, s28, 0x80080
	s_addc_u32 s29, s29, 0
	s_add_i32 s30, s30, s38
	v_lshl_add_u64 v[252:253], s[28:29], 0, v[160:161]
	s_mov_b32 m0, s30
	s_nop 0
	global_load_lds_dwordx4 v[252:253], off
	v_lshl_add_u64 v[252:253], s[28:29], 0, v[164:165]
	s_add_i32 m0, s30, 0x2000
	s_nop 0
	global_load_lds_dwordx4 v[252:253], off
	s_waitcnt lgkmcnt(0)
	s_waitcnt vmcnt(8)
	s_barrier
	s_setprio 1
	v_mfma_f32_16x16x32_bf16 v[110:113], v[130:133], v[146:149], v[110:113]
	v_mfma_f32_16x16x32_bf16 v[78:81], v[138:141], v[146:149], v[78:81]
	v_mfma_f32_16x16x32_bf16 v[106:109], v[130:133], v[154:157], v[106:109]
	v_mfma_f32_16x16x32_bf16 v[74:77], v[138:141], v[154:157], v[74:77]
	v_mfma_f32_16x16x32_bf16 v[98:101], v[130:133], v[210:213], v[98:101]
	v_mfma_f32_16x16x32_bf16 v[70:73], v[138:141], v[210:213], v[70:73]
	v_mfma_f32_16x16x32_bf16 v[90:93], v[130:133], v[222:225], v[90:93]
	v_mfma_f32_16x16x32_bf16 v[66:69], v[138:141], v[222:225], v[66:69]
	v_mfma_f32_16x16x32_bf16 v[110:113], v[134:137], v[150:153], v[110:113]
	v_mfma_f32_16x16x32_bf16 v[78:81], v[142:145], v[150:153], v[78:81]
	v_mfma_f32_16x16x32_bf16 v[106:109], v[134:137], v[206:209], v[106:109]
	v_mfma_f32_16x16x32_bf16 v[74:77], v[142:145], v[206:209], v[74:77]
	v_mfma_f32_16x16x32_bf16 v[98:101], v[134:137], v[218:221], v[98:101]
	v_mfma_f32_16x16x32_bf16 v[70:73], v[142:145], v[218:221], v[70:73]
	v_mfma_f32_16x16x32_bf16 v[90:93], v[134:137], v[226:229], v[90:93]
	v_mfma_f32_16x16x32_bf16 v[66:69], v[142:145], v[226:229], v[66:69]
	v_mfma_f32_16x16x32_bf16 v[46:49], v[230:233], v[146:149], v[46:49]
	v_mfma_f32_16x16x32_bf16 v[14:17], v[238:241], v[146:149], v[14:17]
	v_mfma_f32_16x16x32_bf16 v[42:45], v[230:233], v[154:157], v[42:45]
	v_mfma_f32_16x16x32_bf16 v[10:13], v[238:241], v[154:157], v[10:13]
	v_mfma_f32_16x16x32_bf16 v[34:37], v[230:233], v[210:213], v[34:37]
	v_mfma_f32_16x16x32_bf16 v[6:9], v[238:241], v[210:213], v[6:9]
	v_mfma_f32_16x16x32_bf16 v[26:29], v[230:233], v[222:225], v[26:29]
	v_mfma_f32_16x16x32_bf16 v[2:5], v[238:241], v[222:225], v[2:5]
	v_mfma_f32_16x16x32_bf16 v[46:49], v[234:237], v[150:153], v[46:49]
	v_mfma_f32_16x16x32_bf16 v[14:17], v[242:245], v[150:153], v[14:17]
	v_mfma_f32_16x16x32_bf16 v[42:45], v[234:237], v[206:209], v[42:45]
	v_mfma_f32_16x16x32_bf16 v[10:13], v[242:245], v[206:209], v[10:13]
	v_mfma_f32_16x16x32_bf16 v[34:37], v[234:237], v[218:221], v[34:37]
	v_mfma_f32_16x16x32_bf16 v[6:9], v[242:245], v[218:221], v[6:9]
	v_mfma_f32_16x16x32_bf16 v[26:29], v[234:237], v[226:229], v[26:29]
	v_mfma_f32_16x16x32_bf16 v[2:5], v[242:245], v[226:229], v[2:5]
	s_setprio 0
	s_add_i32 s69, s69, 2
	s_add_u32 s6, s6, 0x100
	s_addc_u32 s7, s7, 0
	s_add_u32 s67, s67, 0x100
	s_addc_u32 s68, s68, 0
	s_cmp_gt_u32 s69, 29
	s_barrier
	s_cbranch_scc0 .LBB0_1969
	s_lshl_b32 s6, s64, 8
	v_sub_co_u32_e32 v130, vcc, s6, v183
	s_and_b64 s[28:29], vcc, exec
	s_cselect_b32 s7, s62, 0x3000
	s_cmp_gt_i32 s64, 63
	s_cselect_b32 s7, s7, 0
	s_lshl_b32 s7, s7, 2
	s_add_u32 s28, s55, s7
	s_addc_u32 s29, s56, 0
	s_ashr_i32 s7, s6, 31
	s_cmpk_lt_i32 s64, 0x80
	v_mov_b32_e32 v131, s7
	s_cselect_b64 vcc, -1, 0
	v_mov_b32_e32 v132, s6
	v_lshl_or_b32 v228, s65, 8, v167
	v_cndmask_b32_e32 v131, 0, v131, vcc
	v_cndmask_b32_e32 v130, v130, v132, vcc
	s_cselect_b32 s31, s9, s54
	s_cselect_b32 s30, s8, s53
	v_lshlrev_b64 v[130:131], 13, v[130:131]
	v_ashrrev_i32_e32 v229, 31, v228
	v_lshl_add_u64 v[130:131], s[30:31], 0, v[130:131]
	v_lshlrev_b64 v[132:133], 2, v[228:229]
	v_lshl_add_u64 v[232:233], v[130:131], 0, v[132:133]
	v_add_lshl_u32 v130, s6, v166, 1
	v_ashrrev_i32_e32 v131, 31, v130
	v_lshl_add_u64 v[206:207], v[232:233], 0, v[168:169]
	v_lshl_add_u64 v[210:211], v[130:131], 2, s[10:11]
	global_load_dwordx4 v[218:221], v[206:207], off
	global_load_dwordx2 v[214:215], v[210:211], off
	v_lshl_add_u64 v[130:131], s[14:15], 0, v[132:133]
	global_load_dwordx4 v[146:149], v[130:131], off
	v_lshl_add_u64 v[130:131], s[16:17], 0, v[132:133]
	global_load_dwordx4 v[150:153], v[130:131], off
	v_lshl_add_u64 v[230:231], s[28:29], 0, v[132:133]
	global_load_dwordx4 v[142:145], v[230:231], off
	v_or_b32_e32 v130, 16, v228
	v_add_lshl_u32 v132, s6, v170, 1
	v_ashrrev_i32_e32 v131, 31, v130
	v_ashrrev_i32_e32 v133, 31, v132
	v_lshlrev_b64 v[130:131], 2, v[130:131]
	v_lshl_add_u64 v[212:213], v[132:133], 2, s[10:11]
	v_lshl_add_u64 v[132:133], s[14:15], 0, v[130:131]
	v_lshl_add_u64 v[130:131], s[16:17], 0, v[130:131]
	v_lshl_add_u64 v[208:209], v[232:233], 0, v[172:173]
	global_load_dwordx4 v[134:137], v[132:133], off
	global_load_dwordx4 v[138:141], v[130:131], off
	s_nop 0
	global_load_dwordx4 v[130:133], v[230:231], off offset:64
	global_load_dwordx4 v[222:225], v[208:209], off
	global_load_dwordx4 v[154:157], v[206:207], off offset:64
	s_mov_b32 s65, s22
	s_mov_b64 s[28:29], s[26:27]
	s_mov_b64 s[30:31], s[24:25]
	s_mov_b32 s64, s63
	s_and_b64 vcc, exec, s[4:5]
	s_waitcnt vmcnt(0)
;     DI void operator()(const f32x4 (&acc)[2][2][4][2], const pg8::Unit& u, int wr, int wc, int fr, int fq) const {
;     ...
;         for (int bj = 0; bj < 2; ++bj) {
;             f32x4 gv[2], gg[2], bb[2], xv[2][8];
; #pragma unroll
;             for (int n = 0; n < 2; ++n) {
;                 const int c = col0 + bj * 128 + n * 16;
;                 gv[n] = *(const f32x4*)(gtp + c);
;                 gg[n] = (f32x4){1.f, 1.f, 1.f, 1.f}; bb[n] = (f32x4){0.f, 0.f, 0.f, 0.f};
;                 if (mode) { gg[n] = *(const f32x4*)(lg + c); bb[n] = *(const f32x4*)(lb + c); }
; #pragma unroll
;                 for (int q = 0; q < 8; ++q) { const int rr = rl + (q >> 2) * 128 + (q & 3) * 16; xv[n][q] = *(const f32x4*)(sbase + (size_t)rr * D + c); }
;             }
; #pragma unroll
;             for (int n = 0; n < 2; ++n) {
;                 const int c = col0 + bj * 128 + n * 16;
; #pragma unroll
;                 for (int q = 0; q < 8; ++q) {
;                     const int rr = rl + (q >> 2) * 128 + (q & 3) * 16;
;                     f32x4 x = xv[n][q];
;                     if (mode) { const float mu = stats[2 * (rowt + rr)], rs = stats[2 * (rowt + rr) + 1]; x = (x - mu) * rs * gg[n] + bb[n]; }
;                     *(f32x4*)(dbase + (size_t)rr * D + c) = ALPHA * x + gv[n] * acc[q >> 2][bj][q & 3][n];
;                 }
	v_sub_f32_e32 v217, v221, v214
	v_sub_f32_e32 v216, v220, v214
	v_sub_f32_e32 v219, v219, v214
	v_sub_f32_e32 v218, v218, v214
	v_pk_mul_f32 v[218:219], v[218:219], v[214:215] op_sel:[0,1]
	v_pk_mul_f32 v[214:215], v[216:217], v[214:215] op_sel:[0,1]
	v_pk_fma_f32 v[216:217], v[146:147], v[218:219], v[150:151]
	v_pk_fma_f32 v[214:215], v[148:149], v[214:215], v[152:153]
	v_pk_mul_f32 v[216:217], v[216:217], s[20:21] op_sel_hi:[1,0]
	v_pk_mul_f32 v[214:215], v[214:215], s[20:21] op_sel_hi:[1,0]
	v_pk_fma_f32 v[126:127], v[126:127], v[142:143], v[216:217]
	v_pk_fma_f32 v[128:129], v[128:129], v[144:145], v[214:215]
	global_store_dwordx4 v[206:207], v[126:129], off
	global_load_dword v187, v[212:213], off
	global_load_dword v216, v[212:213], off offset:4
	v_add_lshl_u32 v126, s6, v174, 1
	v_ashrrev_i32_e32 v127, 31, v126
	v_lshl_add_u64 v[214:215], v[232:233], 0, v[176:177]
	v_lshl_add_u64 v[220:221], v[126:127], 2, s[10:11]
	global_load_dwordx4 v[234:237], v[214:215], off
	global_load_dwordx4 v[126:129], v[208:209], off offset:64
	s_waitcnt vmcnt(0)
	v_sub_f32_e32 v219, v225, v187
	v_sub_f32_e32 v218, v224, v187
	v_sub_f32_e32 v223, v223, v187
	v_sub_f32_e32 v222, v222, v187
	v_pk_mul_f32 v[222:223], v[222:223], v[216:217] op_sel_hi:[1,0]
	v_pk_mul_f32 v[216:217], v[218:219], v[216:217] op_sel_hi:[1,0]
	v_pk_fma_f32 v[218:219], v[146:147], v[222:223], v[150:151]
	v_pk_fma_f32 v[216:217], v[148:149], v[216:217], v[152:153]
	v_pk_mul_f32 v[218:219], v[218:219], s[20:21] op_sel_hi:[1,0]
	v_pk_mul_f32 v[216:217], v[216:217], s[20:21] op_sel_hi:[1,0]
	v_pk_fma_f32 v[122:123], v[122:123], v[142:143], v[218:219]
	v_pk_fma_f32 v[124:125], v[124:125], v[144:145], v[216:217]
	global_store_dwordx4 v[208:209], v[122:125], off
	global_load_dword v187, v[220:221], off
	global_load_dword v216, v[220:221], off offset:4
	v_add_lshl_u32 v122, s6, v178, 1
	v_ashrrev_i32_e32 v123, 31, v122
	v_lshl_add_u64 v[218:219], v[232:233], 0, v[180:181]
	v_lshl_add_u64 v[224:225], v[122:123], 2, s[10:11]
	global_load_dwordx4 v[238:241], v[218:219], off
	global_load_dwordx4 v[122:125], v[214:215], off offset:64
	s_waitcnt vmcnt(0)
	v_sub_f32_e32 v223, v237, v187
	v_sub_f32_e32 v222, v236, v187
	v_sub_f32_e32 v227, v235, v187
	v_sub_f32_e32 v226, v234, v187
	v_pk_mul_f32 v[226:227], v[226:227], v[216:217] op_sel_hi:[1,0]
	v_pk_mul_f32 v[216:217], v[222:223], v[216:217] op_sel_hi:[1,0]
	v_pk_fma_f32 v[222:223], v[146:147], v[226:227], v[150:151]
	v_pk_fma_f32 v[216:217], v[148:149], v[216:217], v[152:153]
	v_pk_mul_f32 v[222:223], v[222:223], s[20:21] op_sel_hi:[1,0]
	v_pk_mul_f32 v[216:217], v[216:217], s[20:21] op_sel_hi:[1,0]
	v_pk_fma_f32 v[118:119], v[118:119], v[142:143], v[222:223]
	v_pk_fma_f32 v[120:121], v[120:121], v[144:145], v[216:217]
	global_store_dwordx4 v[214:215], v[118:121], off
	global_load_dword v187, v[224:225], off
	global_load_dword v216, v[224:225], off offset:4
	v_add_lshl_u32 v118, s6, v182, 1
	v_ashrrev_i32_e32 v119, 31, v118
	v_lshl_add_u64 v[222:223], v[232:233], 0, v[184:185]
	v_lshl_add_u64 v[226:227], v[118:119], 2, s[10:11]
	global_load_dwordx4 v[234:237], v[222:223], off
	global_load_dwordx4 v[118:121], v[218:219], off offset:64
	s_waitcnt vmcnt(0)
	v_sub_f32_e32 v241, v241, v187
	v_sub_f32_e32 v240, v240, v187
	v_sub_f32_e32 v239, v239, v187
	v_sub_f32_e32 v238, v238, v187
	v_pk_mul_f32 v[238:239], v[238:239], v[216:217] op_sel_hi:[1,0]
	v_pk_mul_f32 v[216:217], v[240:241], v[216:217] op_sel_hi:[1,0]
	v_pk_fma_f32 v[238:239], v[146:147], v[238:239], v[150:151]
	v_pk_fma_f32 v[216:217], v[148:149], v[216:217], v[152:153]
	v_pk_mul_f32 v[238:239], v[238:239], s[20:21] op_sel_hi:[1,0]
	v_pk_mul_f32 v[216:217], v[216:217], s[20:21] op_sel_hi:[1,0]
	v_pk_fma_f32 v[114:115], v[114:115], v[142:143], v[238:239]
	v_pk_fma_f32 v[116:117], v[116:117], v[144:145], v[216:217]
	global_store_dwordx4 v[218:219], v[114:117], off
	global_load_dwordx2 v[216:217], v[226:227], off
	s_waitcnt vmcnt(0)
	v_sub_f32_e32 v237, v237, v216
	v_sub_f32_e32 v236, v236, v216
	v_sub_f32_e32 v235, v235, v216
	v_sub_f32_e32 v234, v234, v216
	v_pk_mul_f32 v[234:235], v[234:235], v[216:217] op_sel:[0,1]
	v_pk_mul_f32 v[216:217], v[236:237], v[216:217] op_sel:[0,1]
	v_add_lshl_u32 v114, s6, v186, 1
	v_pk_fma_f32 v[216:217], v[148:149], v[216:217], v[152:153]
	v_pk_fma_f32 v[234:235], v[146:147], v[234:235], v[150:151]
	v_ashrrev_i32_e32 v115, 31, v114
	v_pk_mul_f32 v[234:235], v[234:235], s[20:21] op_sel_hi:[1,0]
	v_pk_mul_f32 v[216:217], v[216:217], s[20:21] op_sel_hi:[1,0]
	v_lshl_add_u64 v[116:117], v[114:115], 2, s[10:11]
	v_lshl_add_u64 v[114:115], v[232:233], 0, v[188:189]
	v_pk_fma_f32 v[112:113], v[112:113], v[144:145], v[216:217]
	v_pk_fma_f32 v[110:111], v[110:111], v[142:143], v[234:235]
	global_load_dwordx4 v[238:241], v[114:115], off
	global_load_dwordx4 v[242:245], v[222:223], off offset:64
	s_nop 0
	global_store_dwordx4 v[222:223], v[110:113], off
	global_load_dword v187, v[116:117], off
	global_load_dword v216, v[116:117], off offset:4
	v_add_lshl_u32 v110, s6, v190, 1
	v_ashrrev_i32_e32 v111, 31, v110
	v_lshl_add_u64 v[112:113], v[110:111], 2, s[10:11]
	v_lshl_add_u64 v[110:111], v[232:233], 0, v[192:193]
	global_load_dwordx4 v[234:237], v[110:111], off
	global_load_dwordx4 v[246:249], v[114:115], off offset:64
	s_waitcnt vmcnt(0)
;     DI void operator()(const f32x4 (&acc)[2][2][4][2], const pg8::Unit& u, int wr, int wc, int fr, int fq) const {
;     ...
;         for (int bj = 0; bj < 2; ++bj) {
;             f32x4 gv[2], gg[2], bb[2], xv[2][8];
; #pragma unroll
;             for (int n = 0; n < 2; ++n) {
;                 const int c = col0 + bj * 128 + n * 16;
;                 gv[n] = *(const f32x4*)(gtp + c);
;                 gg[n] = (f32x4){1.f, 1.f, 1.f, 1.f}; bb[n] = (f32x4){0.f, 0.f, 0.f, 0.f};
;                 if (mode) { gg[n] = *(const f32x4*)(lg + c); bb[n] = *(const f32x4*)(lb + c); }
; #pragma unroll
;                 for (int q = 0; q < 8; ++q) { const int rr = rl + (q >> 2) * 128 + (q & 3) * 16; xv[n][q] = *(const f32x4*)(sbase + (size_t)rr * D + c); }
;             }
; #pragma unroll
;             for (int n = 0; n < 2; ++n) {
;                 const int c = col0 + bj * 128 + n * 16;
; #pragma unroll
;                 for (int q = 0; q < 8; ++q) {
;                     const int rr = rl + (q >> 2) * 128 + (q & 3) * 16;
;                     f32x4 x = xv[n][q];
;                     if (mode) { const float mu = stats[2 * (rowt + rr)], rs = stats[2 * (rowt + rr) + 1]; x = (x - mu) * rs * gg[n] + bb[n]; }
;                     *(f32x4*)(dbase + (size_t)rr * D + c) = ALPHA * x + gv[n] * acc[q >> 2][bj][q & 3][n];
;                 }
	v_sub_f32_e32 v241, v241, v187
	v_sub_f32_e32 v240, v240, v187
	v_sub_f32_e32 v239, v239, v187
	v_sub_f32_e32 v238, v238, v187
	v_pk_mul_f32 v[238:239], v[238:239], v[216:217] op_sel_hi:[1,0]
	v_pk_mul_f32 v[216:217], v[240:241], v[216:217] op_sel_hi:[1,0]
	v_pk_fma_f32 v[238:239], v[146:147], v[238:239], v[150:151]
	v_pk_fma_f32 v[216:217], v[148:149], v[216:217], v[152:153]
	v_pk_mul_f32 v[238:239], v[238:239], s[20:21] op_sel_hi:[1,0]
	v_pk_mul_f32 v[216:217], v[216:217], s[20:21] op_sel_hi:[1,0]
	v_pk_fma_f32 v[106:107], v[106:107], v[142:143], v[238:239]
	v_pk_fma_f32 v[108:109], v[108:109], v[144:145], v[216:217]
	global_store_dwordx4 v[114:115], v[106:109], off
	global_load_dword v187, v[112:113], off
	global_load_dword v216, v[112:113], off offset:4
	v_add_lshl_u32 v106, s6, v194, 1
	v_ashrrev_i32_e32 v107, 31, v106
	v_lshl_add_u64 v[108:109], v[106:107], 2, s[10:11]
	v_lshl_add_u64 v[106:107], v[232:233], 0, v[196:197]
	global_load_dwordx4 v[238:241], v[106:107], off
	global_load_dwordx4 v[250:253], v[110:111], off offset:64
	s_waitcnt vmcnt(0)
	v_sub_f32_e32 v233, v237, v187
	v_sub_f32_e32 v232, v236, v187
	v_sub_f32_e32 v235, v235, v187
	v_sub_f32_e32 v234, v234, v187
	v_pk_mul_f32 v[234:235], v[234:235], v[216:217] op_sel_hi:[1,0]
	v_pk_mul_f32 v[216:217], v[232:233], v[216:217] op_sel_hi:[1,0]
	v_pk_fma_f32 v[232:233], v[146:147], v[234:235], v[150:151]
	v_pk_fma_f32 v[216:217], v[148:149], v[216:217], v[152:153]
	v_pk_mul_f32 v[232:233], v[232:233], s[20:21] op_sel_hi:[1,0]
	v_pk_mul_f32 v[216:217], v[216:217], s[20:21] op_sel_hi:[1,0]
	v_pk_fma_f32 v[98:99], v[98:99], v[142:143], v[232:233]
	v_pk_fma_f32 v[100:101], v[100:101], v[144:145], v[216:217]
	global_store_dwordx4 v[110:111], v[98:101], off
	global_load_dword v187, v[108:109], off
	global_load_dword v216, v[108:109], off offset:4
	s_nop 0
	global_load_dwordx4 v[98:101], v[106:107], off offset:64
	s_waitcnt vmcnt(0)
	v_sub_f32_e32 v233, v241, v187
	v_sub_f32_e32 v232, v240, v187
	v_sub_f32_e32 v235, v239, v187
	v_sub_f32_e32 v234, v238, v187
	v_pk_mul_f32 v[234:235], v[234:235], v[216:217] op_sel_hi:[1,0]
	v_pk_mul_f32 v[216:217], v[232:233], v[216:217] op_sel_hi:[1,0]
	v_pk_fma_f32 v[146:147], v[146:147], v[234:235], v[150:151]
	v_pk_fma_f32 v[148:149], v[148:149], v[216:217], v[152:153]
	v_pk_mul_f32 v[146:147], v[146:147], s[20:21] op_sel_hi:[1,0]
	v_pk_mul_f32 v[148:149], v[148:149], s[20:21] op_sel_hi:[1,0]
	v_pk_fma_f32 v[90:91], v[90:91], v[142:143], v[146:147]
	v_pk_fma_f32 v[92:93], v[92:93], v[144:145], v[148:149]
	global_store_dwordx4 v[106:107], v[90:93], off
	global_load_dwordx2 v[90:91], v[210:211], off
	s_waitcnt vmcnt(0)
	v_sub_f32_e32 v143, v155, v90
	v_sub_f32_e32 v93, v157, v90
	v_sub_f32_e32 v92, v156, v90
	v_sub_f32_e32 v142, v154, v90
	v_pk_mul_f32 v[142:143], v[142:143], v[90:91] op_sel:[0,1]
	v_pk_mul_f32 v[90:91], v[92:93], v[90:91] op_sel:[0,1]
	v_pk_fma_f32 v[92:93], v[134:135], v[142:143], v[138:139]
	v_pk_fma_f32 v[90:91], v[136:137], v[90:91], v[140:141]
	v_pk_mul_f32 v[142:143], v[92:93], s[20:21] op_sel_hi:[1,0]
	v_pk_mul_f32 v[90:91], v[90:91], s[20:21] op_sel_hi:[1,0]
	s_nop 0
	v_pk_fma_f32 v[92:93], v[104:105], v[132:133], v[90:91]
	v_pk_fma_f32 v[90:91], v[102:103], v[130:131], v[142:143]
	global_store_dwordx4 v[206:207], v[90:93], off offset:64
	global_load_dword v91, v[212:213], off
	s_nop 0
	global_load_dword v90, v[212:213], off offset:4
	s_waitcnt vmcnt(0)
	v_sub_f32_e32 v93, v129, v91
	v_sub_f32_e32 v92, v128, v91
	v_sub_f32_e32 v103, v127, v91
	v_sub_f32_e32 v102, v126, v91
	v_pk_mul_f32 v[102:103], v[102:103], v[90:91] op_sel_hi:[1,0]
	v_pk_mul_f32 v[90:91], v[92:93], v[90:91] op_sel_hi:[1,0]
	v_pk_fma_f32 v[92:93], v[134:135], v[102:103], v[138:139]
	v_pk_fma_f32 v[90:91], v[136:137], v[90:91], v[140:141]
	v_pk_mul_f32 v[102:103], v[92:93], s[20:21] op_sel_hi:[1,0]
	v_pk_mul_f32 v[90:91], v[90:91], s[20:21] op_sel_hi:[1,0]
	s_nop 0
	v_pk_fma_f32 v[92:93], v[96:97], v[132:133], v[90:91]
	v_pk_fma_f32 v[90:91], v[94:95], v[130:131], v[102:103]
	global_store_dwordx4 v[208:209], v[90:93], off offset:64
	global_load_dword v91, v[220:221], off
	s_nop 0
	global_load_dword v90, v[220:221], off offset:4
	s_waitcnt vmcnt(0)
	v_sub_f32_e32 v93, v125, v91
	v_sub_f32_e32 v92, v124, v91
	v_sub_f32_e32 v95, v123, v91
	v_sub_f32_e32 v94, v122, v91
	v_pk_mul_f32 v[94:95], v[94:95], v[90:91] op_sel_hi:[1,0]
	v_pk_mul_f32 v[90:91], v[92:93], v[90:91] op_sel_hi:[1,0]
	v_pk_fma_f32 v[92:93], v[134:135], v[94:95], v[138:139]
	v_pk_fma_f32 v[90:91], v[136:137], v[90:91], v[140:141]
	v_pk_mul_f32 v[92:93], v[92:93], s[20:21] op_sel_hi:[1,0]
	v_pk_mul_f32 v[90:91], v[90:91], s[20:21] op_sel_hi:[1,0]
	v_pk_fma_f32 v[86:87], v[86:87], v[130:131], v[92:93]
	v_pk_fma_f32 v[88:89], v[88:89], v[132:133], v[90:91]
	global_store_dwordx4 v[214:215], v[86:89], off offset:64
	global_load_dword v87, v[224:225], off
	s_nop 0
	global_load_dword v86, v[224:225], off offset:4
	s_waitcnt vmcnt(0)
	v_sub_f32_e32 v89, v121, v87
	v_sub_f32_e32 v88, v120, v87
	v_sub_f32_e32 v91, v119, v87
	v_sub_f32_e32 v90, v118, v87
	v_pk_mul_f32 v[90:91], v[90:91], v[86:87] op_sel_hi:[1,0]
	v_pk_mul_f32 v[86:87], v[88:89], v[86:87] op_sel_hi:[1,0]
	v_pk_fma_f32 v[88:89], v[134:135], v[90:91], v[138:139]
	v_pk_fma_f32 v[86:87], v[136:137], v[86:87], v[140:141]
	v_pk_mul_f32 v[88:89], v[88:89], s[20:21] op_sel_hi:[1,0]
	v_pk_mul_f32 v[86:87], v[86:87], s[20:21] op_sel_hi:[1,0]
	v_pk_fma_f32 v[82:83], v[82:83], v[130:131], v[88:89]
	v_pk_fma_f32 v[84:85], v[84:85], v[132:133], v[86:87]
	global_store_dwordx4 v[218:219], v[82:85], off offset:64
	global_load_dwordx2 v[82:83], v[226:227], off
	s_waitcnt vmcnt(0)
;     DI void operator()(const f32x4 (&acc)[2][2][4][2], const pg8::Unit& u, int wr, int wc, int fr, int fq) const {
;     ...
;         for (int bj = 0; bj < 2; ++bj) {
;             f32x4 gv[2], gg[2], bb[2], xv[2][8];
; #pragma unroll
;             for (int n = 0; n < 2; ++n) {
;                 const int c = col0 + bj * 128 + n * 16;
;                 gv[n] = *(const f32x4*)(gtp + c);
;                 gg[n] = (f32x4){1.f, 1.f, 1.f, 1.f}; bb[n] = (f32x4){0.f, 0.f, 0.f, 0.f};
;                 if (mode) { gg[n] = *(const f32x4*)(lg + c); bb[n] = *(const f32x4*)(lb + c); }
; #pragma unroll
;                 for (int q = 0; q < 8; ++q) { const int rr = rl + (q >> 2) * 128 + (q & 3) * 16; xv[n][q] = *(const f32x4*)(sbase + (size_t)rr * D + c); }
;             }
; #pragma unroll
;             for (int n = 0; n < 2; ++n) {
;                 const int c = col0 + bj * 128 + n * 16;
; #pragma unroll
;                 for (int q = 0; q < 8; ++q) {
;                     const int rr = rl + (q >> 2) * 128 + (q & 3) * 16;
;                     f32x4 x = xv[n][q];
;                     if (mode) { const float mu = stats[2 * (rowt + rr)], rs = stats[2 * (rowt + rr) + 1]; x = (x - mu) * rs * gg[n] + bb[n]; }
;                     *(f32x4*)(dbase + (size_t)rr * D + c) = ALPHA * x + gv[n] * acc[q >> 2][bj][q & 3][n];
;                 }
	v_sub_f32_e32 v87, v243, v82
	v_sub_f32_e32 v85, v245, v82
	v_sub_f32_e32 v84, v244, v82
	v_sub_f32_e32 v86, v242, v82
	v_pk_mul_f32 v[86:87], v[86:87], v[82:83] op_sel:[0,1]
	v_pk_mul_f32 v[82:83], v[84:85], v[82:83] op_sel:[0,1]
	v_pk_fma_f32 v[84:85], v[134:135], v[86:87], v[138:139]
	v_pk_fma_f32 v[82:83], v[136:137], v[82:83], v[140:141]
	v_pk_mul_f32 v[84:85], v[84:85], s[20:21] op_sel_hi:[1,0]
	v_pk_mul_f32 v[82:83], v[82:83], s[20:21] op_sel_hi:[1,0]
	v_pk_fma_f32 v[78:79], v[78:79], v[130:131], v[84:85]
	v_pk_fma_f32 v[80:81], v[80:81], v[132:133], v[82:83]
	global_store_dwordx4 v[222:223], v[78:81], off offset:64
	global_load_dword v79, v[116:117], off
	s_nop 0
	global_load_dword v78, v[116:117], off offset:4
	s_waitcnt vmcnt(0)
	v_sub_f32_e32 v81, v249, v79
	v_sub_f32_e32 v80, v248, v79
	v_sub_f32_e32 v83, v247, v79
	v_sub_f32_e32 v82, v246, v79
	v_pk_mul_f32 v[82:83], v[82:83], v[78:79] op_sel_hi:[1,0]
	v_pk_mul_f32 v[78:79], v[80:81], v[78:79] op_sel_hi:[1,0]
	v_pk_fma_f32 v[80:81], v[134:135], v[82:83], v[138:139]
	v_pk_fma_f32 v[78:79], v[136:137], v[78:79], v[140:141]
	v_pk_mul_f32 v[80:81], v[80:81], s[20:21] op_sel_hi:[1,0]
	v_pk_mul_f32 v[78:79], v[78:79], s[20:21] op_sel_hi:[1,0]
	v_pk_fma_f32 v[74:75], v[74:75], v[130:131], v[80:81]
	v_pk_fma_f32 v[76:77], v[76:77], v[132:133], v[78:79]
	global_store_dwordx4 v[114:115], v[74:77], off offset:64
	global_load_dword v75, v[112:113], off
	s_nop 0
	global_load_dword v74, v[112:113], off offset:4
	s_waitcnt vmcnt(0)
	v_sub_f32_e32 v77, v253, v75
	v_sub_f32_e32 v76, v252, v75
	v_sub_f32_e32 v79, v251, v75
	v_sub_f32_e32 v78, v250, v75
	v_pk_mul_f32 v[78:79], v[78:79], v[74:75] op_sel_hi:[1,0]
	v_pk_mul_f32 v[74:75], v[76:77], v[74:75] op_sel_hi:[1,0]
	v_pk_fma_f32 v[76:77], v[134:135], v[78:79], v[138:139]
	v_pk_fma_f32 v[74:75], v[136:137], v[74:75], v[140:141]
	v_pk_mul_f32 v[76:77], v[76:77], s[20:21] op_sel_hi:[1,0]
	v_pk_mul_f32 v[74:75], v[74:75], s[20:21] op_sel_hi:[1,0]
	v_pk_fma_f32 v[70:71], v[70:71], v[130:131], v[76:77]
	v_pk_fma_f32 v[72:73], v[72:73], v[132:133], v[74:75]
	global_store_dwordx4 v[110:111], v[70:73], off offset:64
	global_load_dword v71, v[108:109], off
	s_nop 0
	global_load_dword v70, v[108:109], off offset:4
	v_or_b32_e32 v72, 0x80, v228
	global_load_dwordx4 v[78:81], v[206:207], off offset:512
	v_ashrrev_i32_e32 v73, 31, v72
	s_waitcnt vmcnt(0)
	v_sub_f32_e32 v75, v101, v71
	v_sub_f32_e32 v74, v100, v71
	v_sub_f32_e32 v77, v99, v71
	v_sub_f32_e32 v76, v98, v71
	v_pk_mul_f32 v[76:77], v[76:77], v[70:71] op_sel_hi:[1,0]
	v_pk_mul_f32 v[70:71], v[74:75], v[70:71] op_sel_hi:[1,0]
	v_pk_fma_f32 v[74:75], v[134:135], v[76:77], v[138:139]
	v_pk_fma_f32 v[70:71], v[136:137], v[70:71], v[140:141]
	v_pk_mul_f32 v[74:75], v[74:75], s[20:21] op_sel_hi:[1,0]
	v_pk_mul_f32 v[70:71], v[70:71], s[20:21] op_sel_hi:[1,0]
	v_pk_fma_f32 v[66:67], v[66:67], v[130:131], v[74:75]
	v_pk_fma_f32 v[68:69], v[68:69], v[132:133], v[70:71]
	global_store_dwordx4 v[106:107], v[66:69], off offset:64
	global_load_dwordx2 v[102:103], v[210:211], off
	s_waitcnt vmcnt(0)
	v_sub_f32_e32 v81, v81, v102
	v_lshlrev_b64 v[66:67], 2, v[72:73]
	v_lshl_add_u64 v[68:69], s[14:15], 0, v[66:67]
	v_lshl_add_u64 v[66:67], s[16:17], 0, v[66:67]
	global_load_dwordx4 v[82:85], v[68:69], off
	global_load_dwordx4 v[86:89], v[66:67], off
	global_load_dwordx4 v[90:93], v[230:231], off offset:512
	v_sub_f32_e32 v80, v80, v102
	v_sub_f32_e32 v79, v79, v102
	v_sub_f32_e32 v78, v78, v102
	v_or_b32_e32 v66, 0x90, v228
	v_pk_mul_f32 v[78:79], v[78:79], v[102:103] op_sel:[0,1]
	v_pk_mul_f32 v[80:81], v[80:81], v[102:103] op_sel:[0,1]
	v_ashrrev_i32_e32 v67, 31, v66
	v_lshlrev_b64 v[66:67], 2, v[66:67]
	v_lshl_add_u64 v[70:71], s[14:15], 0, v[66:67]
	v_lshl_add_u64 v[74:75], s[16:17], 0, v[66:67]
	global_load_dwordx4 v[94:97], v[208:209], off offset:512
	global_load_dwordx4 v[98:101], v[206:207], off offset:576
	global_load_dwordx4 v[66:69], v[230:231], off offset:576
	s_nop 0
	global_load_dwordx4 v[70:73], v[70:71], off
	s_nop 0
	global_load_dwordx4 v[74:77], v[74:75], off
	s_waitcnt vmcnt(0)
	v_pk_fma_f32 v[80:81], v[84:85], v[80:81], v[88:89]
	v_pk_fma_f32 v[78:79], v[82:83], v[78:79], v[86:87]
	v_pk_mul_f32 v[80:81], v[80:81], s[20:21] op_sel_hi:[1,0]
	v_pk_mul_f32 v[78:79], v[78:79], s[20:21] op_sel_hi:[1,0]
	v_pk_fma_f32 v[64:65], v[64:65], v[92:93], v[80:81]
	v_pk_fma_f32 v[62:63], v[62:63], v[90:91], v[78:79]
	global_store_dwordx4 v[206:207], v[62:65], off offset:512
	global_load_dword v103, v[212:213], off
	global_load_dword v102, v[212:213], off offset:4
	s_nop 0
	global_load_dwordx4 v[62:65], v[214:215], off offset:512
	global_load_dwordx4 v[78:81], v[208:209], off offset:576
	s_waitcnt vmcnt(0)
	v_sub_f32_e32 v97, v97, v103
	v_sub_f32_e32 v96, v96, v103
	v_sub_f32_e32 v95, v95, v103
	v_sub_f32_e32 v94, v94, v103
	v_pk_mul_f32 v[94:95], v[94:95], v[102:103] op_sel_hi:[1,0]
	v_pk_mul_f32 v[96:97], v[96:97], v[102:103] op_sel_hi:[1,0]
	v_pk_fma_f32 v[94:95], v[82:83], v[94:95], v[86:87]
	v_pk_fma_f32 v[96:97], v[84:85], v[96:97], v[88:89]
	v_pk_mul_f32 v[94:95], v[94:95], s[20:21] op_sel_hi:[1,0]
	v_pk_mul_f32 v[96:97], v[96:97], s[20:21] op_sel_hi:[1,0]
	v_pk_fma_f32 v[58:59], v[58:59], v[90:91], v[94:95]
	v_pk_fma_f32 v[60:61], v[60:61], v[92:93], v[96:97]
	global_store_dwordx4 v[208:209], v[58:61], off offset:512
	global_load_dword v103, v[220:221], off
	global_load_dword v102, v[220:221], off offset:4
	s_nop 0
	global_load_dwordx4 v[58:61], v[218:219], off offset:512
	global_load_dwordx4 v[94:97], v[214:215], off offset:576
	s_waitcnt vmcnt(0)
;     DI void operator()(const f32x4 (&acc)[2][2][4][2], const pg8::Unit& u, int wr, int wc, int fr, int fq) const {
;     ...
;         for (int bj = 0; bj < 2; ++bj) {
;             f32x4 gv[2], gg[2], bb[2], xv[2][8];
; #pragma unroll
;             for (int n = 0; n < 2; ++n) {
;                 const int c = col0 + bj * 128 + n * 16;
;                 gv[n] = *(const f32x4*)(gtp + c);
;                 gg[n] = (f32x4){1.f, 1.f, 1.f, 1.f}; bb[n] = (f32x4){0.f, 0.f, 0.f, 0.f};
;                 if (mode) { gg[n] = *(const f32x4*)(lg + c); bb[n] = *(const f32x4*)(lb + c); }
; #pragma unroll
;                 for (int q = 0; q < 8; ++q) { const int rr = rl + (q >> 2) * 128 + (q & 3) * 16; xv[n][q] = *(const f32x4*)(sbase + (size_t)rr * D + c); }
;             }
; #pragma unroll
;             for (int n = 0; n < 2; ++n) {
;                 const int c = col0 + bj * 128 + n * 16;
; #pragma unroll
;                 for (int q = 0; q < 8; ++q) {
;                     const int rr = rl + (q >> 2) * 128 + (q & 3) * 16;
;                     f32x4 x = xv[n][q];
;                     if (mode) { const float mu = stats[2 * (rowt + rr)], rs = stats[2 * (rowt + rr) + 1]; x = (x - mu) * rs * gg[n] + bb[n]; }
;                     *(f32x4*)(dbase + (size_t)rr * D + c) = ALPHA * x + gv[n] * acc[q >> 2][bj][q & 3][n];
;                 }
	v_sub_f32_e32 v65, v65, v103
	v_sub_f32_e32 v64, v64, v103
	v_sub_f32_e32 v63, v63, v103
	v_sub_f32_e32 v62, v62, v103
	v_pk_mul_f32 v[62:63], v[62:63], v[102:103] op_sel_hi:[1,0]
	v_pk_mul_f32 v[64:65], v[64:65], v[102:103] op_sel_hi:[1,0]
	v_pk_fma_f32 v[62:63], v[82:83], v[62:63], v[86:87]
	v_pk_fma_f32 v[64:65], v[84:85], v[64:65], v[88:89]
	v_pk_mul_f32 v[62:63], v[62:63], s[20:21] op_sel_hi:[1,0]
	v_pk_mul_f32 v[64:65], v[64:65], s[20:21] op_sel_hi:[1,0]
	v_pk_fma_f32 v[54:55], v[54:55], v[90:91], v[62:63]
	v_pk_fma_f32 v[56:57], v[56:57], v[92:93], v[64:65]
	global_store_dwordx4 v[214:215], v[54:57], off offset:512
	global_load_dword v103, v[224:225], off
	global_load_dword v102, v[224:225], off offset:4
	s_nop 0
	global_load_dwordx4 v[54:57], v[222:223], off offset:512
	global_load_dwordx4 v[62:65], v[218:219], off offset:576
	s_waitcnt vmcnt(0)
	v_sub_f32_e32 v61, v61, v103
	v_sub_f32_e32 v60, v60, v103
	v_sub_f32_e32 v59, v59, v103
	v_sub_f32_e32 v58, v58, v103
	v_pk_mul_f32 v[58:59], v[58:59], v[102:103] op_sel_hi:[1,0]
	v_pk_mul_f32 v[60:61], v[60:61], v[102:103] op_sel_hi:[1,0]
	v_pk_fma_f32 v[58:59], v[82:83], v[58:59], v[86:87]
	v_pk_fma_f32 v[60:61], v[84:85], v[60:61], v[88:89]
	v_pk_mul_f32 v[58:59], v[58:59], s[20:21] op_sel_hi:[1,0]
	v_pk_mul_f32 v[60:61], v[60:61], s[20:21] op_sel_hi:[1,0]
	v_pk_fma_f32 v[50:51], v[50:51], v[90:91], v[58:59]
	v_pk_fma_f32 v[52:53], v[52:53], v[92:93], v[60:61]
	global_store_dwordx4 v[218:219], v[50:53], off offset:512
	global_load_dwordx2 v[102:103], v[226:227], off
	s_nop 0
	global_load_dwordx4 v[50:53], v[114:115], off offset:512
	global_load_dwordx4 v[58:61], v[222:223], off offset:576
	s_waitcnt vmcnt(0)
	v_sub_f32_e32 v57, v57, v102
	v_sub_f32_e32 v56, v56, v102
	v_sub_f32_e32 v55, v55, v102
	v_sub_f32_e32 v54, v54, v102
	v_pk_mul_f32 v[54:55], v[54:55], v[102:103] op_sel:[0,1]
	v_pk_mul_f32 v[56:57], v[56:57], v[102:103] op_sel:[0,1]
	v_pk_fma_f32 v[54:55], v[82:83], v[54:55], v[86:87]
	v_pk_fma_f32 v[56:57], v[84:85], v[56:57], v[88:89]
	v_pk_mul_f32 v[54:55], v[54:55], s[20:21] op_sel_hi:[1,0]
	v_pk_mul_f32 v[56:57], v[56:57], s[20:21] op_sel_hi:[1,0]
	v_pk_fma_f32 v[46:47], v[46:47], v[90:91], v[54:55]
	v_pk_fma_f32 v[48:49], v[48:49], v[92:93], v[56:57]
	global_store_dwordx4 v[222:223], v[46:49], off offset:512
	global_load_dword v103, v[116:117], off
	global_load_dword v102, v[116:117], off offset:4
	s_nop 0
	global_load_dwordx4 v[46:49], v[110:111], off offset:512
	global_load_dwordx4 v[54:57], v[114:115], off offset:576
	s_waitcnt vmcnt(0)
	v_sub_f32_e32 v53, v53, v103
	v_sub_f32_e32 v52, v52, v103
	v_sub_f32_e32 v51, v51, v103
	v_sub_f32_e32 v50, v50, v103
	v_pk_mul_f32 v[50:51], v[50:51], v[102:103] op_sel_hi:[1,0]
	v_pk_mul_f32 v[52:53], v[52:53], v[102:103] op_sel_hi:[1,0]
	v_pk_fma_f32 v[50:51], v[82:83], v[50:51], v[86:87]
	v_pk_fma_f32 v[52:53], v[84:85], v[52:53], v[88:89]
	v_pk_mul_f32 v[50:51], v[50:51], s[20:21] op_sel_hi:[1,0]
	v_pk_mul_f32 v[52:53], v[52:53], s[20:21] op_sel_hi:[1,0]
	v_pk_fma_f32 v[42:43], v[42:43], v[90:91], v[50:51]
	v_pk_fma_f32 v[44:45], v[44:45], v[92:93], v[52:53]
	global_store_dwordx4 v[114:115], v[42:45], off offset:512
	global_load_dword v103, v[112:113], off
	global_load_dword v102, v[112:113], off offset:4
	s_nop 0
	global_load_dwordx4 v[42:45], v[106:107], off offset:512
	global_load_dwordx4 v[50:53], v[110:111], off offset:576
	s_waitcnt vmcnt(0)
	v_sub_f32_e32 v49, v49, v103
	v_sub_f32_e32 v48, v48, v103
	v_sub_f32_e32 v47, v47, v103
	v_sub_f32_e32 v46, v46, v103
	v_pk_mul_f32 v[46:47], v[46:47], v[102:103] op_sel_hi:[1,0]
	v_pk_mul_f32 v[48:49], v[48:49], v[102:103] op_sel_hi:[1,0]
	v_pk_fma_f32 v[46:47], v[82:83], v[46:47], v[86:87]
	v_pk_fma_f32 v[48:49], v[84:85], v[48:49], v[88:89]
	v_pk_mul_f32 v[46:47], v[46:47], s[20:21] op_sel_hi:[1,0]
	v_pk_mul_f32 v[48:49], v[48:49], s[20:21] op_sel_hi:[1,0]
	v_pk_fma_f32 v[34:35], v[34:35], v[90:91], v[46:47]
	v_pk_fma_f32 v[36:37], v[36:37], v[92:93], v[48:49]
	global_store_dwordx4 v[110:111], v[34:37], off offset:512
	global_load_dword v47, v[108:109], off
	global_load_dword v46, v[108:109], off offset:4
	s_nop 0
	global_load_dwordx4 v[34:37], v[106:107], off offset:576
	s_waitcnt vmcnt(0)
	v_sub_f32_e32 v45, v45, v47
	v_sub_f32_e32 v44, v44, v47
	v_sub_f32_e32 v43, v43, v47
	v_sub_f32_e32 v42, v42, v47
	v_pk_mul_f32 v[42:43], v[42:43], v[46:47] op_sel_hi:[1,0]
	v_pk_mul_f32 v[44:45], v[44:45], v[46:47] op_sel_hi:[1,0]
	v_pk_fma_f32 v[42:43], v[82:83], v[42:43], v[86:87]
	v_pk_fma_f32 v[44:45], v[84:85], v[44:45], v[88:89]
	v_pk_mul_f32 v[42:43], v[42:43], s[20:21] op_sel_hi:[1,0]
	v_pk_mul_f32 v[44:45], v[44:45], s[20:21] op_sel_hi:[1,0]
	v_pk_fma_f32 v[26:27], v[26:27], v[90:91], v[42:43]
	v_pk_fma_f32 v[28:29], v[28:29], v[92:93], v[44:45]
	global_store_dwordx4 v[106:107], v[26:29], off offset:512
	global_load_dwordx2 v[26:27], v[210:211], off
	s_waitcnt vmcnt(0)
	v_sub_f32_e32 v43, v99, v26
	v_sub_f32_e32 v29, v101, v26
	v_sub_f32_e32 v28, v100, v26
	v_sub_f32_e32 v42, v98, v26
	v_pk_mul_f32 v[42:43], v[42:43], v[26:27] op_sel:[0,1]
	v_pk_mul_f32 v[26:27], v[28:29], v[26:27] op_sel:[0,1]
	v_pk_fma_f32 v[28:29], v[70:71], v[42:43], v[74:75]
	v_pk_fma_f32 v[26:27], v[72:73], v[26:27], v[76:77]
	v_pk_mul_f32 v[42:43], v[28:29], s[20:21] op_sel_hi:[1,0]
	v_pk_mul_f32 v[26:27], v[26:27], s[20:21] op_sel_hi:[1,0]
	s_nop 0
	v_pk_fma_f32 v[28:29], v[40:41], v[68:69], v[26:27]
	v_pk_fma_f32 v[26:27], v[38:39], v[66:67], v[42:43]
	global_store_dwordx4 v[206:207], v[26:29], off offset:576
	global_load_dword v27, v[212:213], off
	s_nop 0
	global_load_dword v26, v[212:213], off offset:4
	s_waitcnt vmcnt(0)
; #define PG8_WAIT_V(n) asm volatile("s_waitcnt vmcnt(" #n ")" ::: "memory")
; #define PG8_BAR __builtin_amdgcn_s_barrier()
; template <class Epi>
; DI void gemm_phase(LAS unsigned char* lds, const Gemm g, const StaticOrder& S, const Epi& E) {
;     ...
;         E(acc, cur, wr, wc, fr, fq);
;         if (!has_next) break;
; #pragma unroll
;         for (int a = 0; a < 2; ++a)
; #pragma unroll
;             for (int b = 0; b < 2; ++b)
; #pragma unroll
;                 for (int m = 0; m < 4; ++m)
; #pragma unroll
;                     for (int n = 0; n < 2; ++n) acc[a][b][m][n] = (f32x4){0.f, 0.f, 0.f, 0.f};
;         cur = nxt; cA = nA; cB = nB; ++ui;
;     }
;     PG8_WAIT_V(0);
;     if (wr == 0) PG8_BAR;
;     PG8_BAR;
;     DI void operator()(const f32x4 (&acc)[2][2][4][2], const pg8::Unit& u, int wr, int wc, int fr, int fq) const {
;     ...
;         for (int bj = 0; bj < 2; ++bj) {
;             f32x4 gv[2], gg[2], bb[2], xv[2][8];
; #pragma unroll
;             for (int n = 0; n < 2; ++n) {
;                 const int c = col0 + bj * 128 + n * 16;
;                 gv[n] = *(const f32x4*)(gtp + c);
;                 gg[n] = (f32x4){1.f, 1.f, 1.f, 1.f}; bb[n] = (f32x4){0.f, 0.f, 0.f, 0.f};
;                 if (mode) { gg[n] = *(const f32x4*)(lg + c); bb[n] = *(const f32x4*)(lb + c); }
; #pragma unroll
;                 for (int q = 0; q < 8; ++q) { const int rr = rl + (q >> 2) * 128 + (q & 3) * 16; xv[n][q] = *(const f32x4*)(sbase + (size_t)rr * D + c); }
;             }
; #pragma unroll
;             for (int n = 0; n < 2; ++n) {
;                 const int c = col0 + bj * 128 + n * 16;
; #pragma unroll
;                 for (int q = 0; q < 8; ++q) {
;                     const int rr = rl + (q >> 2) * 128 + (q & 3) * 16;
;                     f32x4 x = xv[n][q];
;                     if (mode) { const float mu = stats[2 * (rowt + rr)], rs = stats[2 * (rowt + rr) + 1]; x = (x - mu) * rs * gg[n] + bb[n]; }
;                     *(f32x4*)(dbase + (size_t)rr * D + c) = ALPHA * x + gv[n] * acc[q >> 2][bj][q & 3][n];
;                 }
	v_sub_f32_e32 v29, v81, v27
	v_sub_f32_e32 v28, v80, v27
	v_sub_f32_e32 v39, v79, v27
	v_sub_f32_e32 v38, v78, v27
	v_pk_mul_f32 v[38:39], v[38:39], v[26:27] op_sel_hi:[1,0]
	v_pk_mul_f32 v[26:27], v[28:29], v[26:27] op_sel_hi:[1,0]
	v_pk_fma_f32 v[28:29], v[70:71], v[38:39], v[74:75]
	v_pk_fma_f32 v[26:27], v[72:73], v[26:27], v[76:77]
	v_pk_mul_f32 v[38:39], v[28:29], s[20:21] op_sel_hi:[1,0]
	v_pk_mul_f32 v[26:27], v[26:27], s[20:21] op_sel_hi:[1,0]
	s_nop 0
	v_pk_fma_f32 v[28:29], v[32:33], v[68:69], v[26:27]
	v_pk_fma_f32 v[26:27], v[30:31], v[66:67], v[38:39]
	global_store_dwordx4 v[208:209], v[26:29], off offset:576
	global_load_dword v27, v[220:221], off
	s_nop 0
	global_load_dword v26, v[220:221], off offset:4
	s_waitcnt vmcnt(0)
	v_sub_f32_e32 v29, v97, v27
	v_sub_f32_e32 v28, v96, v27
	v_sub_f32_e32 v31, v95, v27
	v_sub_f32_e32 v30, v94, v27
	v_pk_mul_f32 v[30:31], v[30:31], v[26:27] op_sel_hi:[1,0]
	v_pk_mul_f32 v[26:27], v[28:29], v[26:27] op_sel_hi:[1,0]
	v_pk_fma_f32 v[28:29], v[70:71], v[30:31], v[74:75]
	v_pk_fma_f32 v[26:27], v[72:73], v[26:27], v[76:77]
	v_pk_mul_f32 v[28:29], v[28:29], s[20:21] op_sel_hi:[1,0]
	v_pk_mul_f32 v[26:27], v[26:27], s[20:21] op_sel_hi:[1,0]
	v_pk_fma_f32 v[22:23], v[22:23], v[66:67], v[28:29]
	v_pk_fma_f32 v[24:25], v[24:25], v[68:69], v[26:27]
	global_store_dwordx4 v[214:215], v[22:25], off offset:576
	global_load_dword v23, v[224:225], off
	s_nop 0
	global_load_dword v22, v[224:225], off offset:4
	s_waitcnt vmcnt(0)
	v_sub_f32_e32 v25, v65, v23
	v_sub_f32_e32 v24, v64, v23
	v_sub_f32_e32 v27, v63, v23
	v_sub_f32_e32 v26, v62, v23
	v_pk_mul_f32 v[26:27], v[26:27], v[22:23] op_sel_hi:[1,0]
	v_pk_mul_f32 v[22:23], v[24:25], v[22:23] op_sel_hi:[1,0]
	v_pk_fma_f32 v[24:25], v[70:71], v[26:27], v[74:75]
	v_pk_fma_f32 v[22:23], v[72:73], v[22:23], v[76:77]
	v_pk_mul_f32 v[24:25], v[24:25], s[20:21] op_sel_hi:[1,0]
	v_pk_mul_f32 v[22:23], v[22:23], s[20:21] op_sel_hi:[1,0]
	v_pk_fma_f32 v[18:19], v[18:19], v[66:67], v[24:25]
	v_pk_fma_f32 v[20:21], v[20:21], v[68:69], v[22:23]
	global_store_dwordx4 v[218:219], v[18:21], off offset:576
	global_load_dwordx2 v[18:19], v[226:227], off
	s_waitcnt vmcnt(0)
	v_sub_f32_e32 v23, v59, v18
	v_sub_f32_e32 v21, v61, v18
	v_sub_f32_e32 v20, v60, v18
	v_sub_f32_e32 v22, v58, v18
	v_pk_mul_f32 v[22:23], v[22:23], v[18:19] op_sel:[0,1]
	v_pk_mul_f32 v[18:19], v[20:21], v[18:19] op_sel:[0,1]
	v_pk_fma_f32 v[20:21], v[70:71], v[22:23], v[74:75]
	v_pk_fma_f32 v[18:19], v[72:73], v[18:19], v[76:77]
	v_pk_mul_f32 v[20:21], v[20:21], s[20:21] op_sel_hi:[1,0]
	v_pk_mul_f32 v[18:19], v[18:19], s[20:21] op_sel_hi:[1,0]
	v_pk_fma_f32 v[14:15], v[14:15], v[66:67], v[20:21]
	v_pk_fma_f32 v[16:17], v[16:17], v[68:69], v[18:19]
	global_store_dwordx4 v[222:223], v[14:17], off offset:576
	global_load_dword v15, v[116:117], off
	s_nop 0
	global_load_dword v14, v[116:117], off offset:4
	s_waitcnt vmcnt(0)
	v_sub_f32_e32 v17, v57, v15
	v_sub_f32_e32 v16, v56, v15
	v_sub_f32_e32 v19, v55, v15
	v_sub_f32_e32 v18, v54, v15
	v_pk_mul_f32 v[18:19], v[18:19], v[14:15] op_sel_hi:[1,0]
	v_pk_mul_f32 v[14:15], v[16:17], v[14:15] op_sel_hi:[1,0]
	v_pk_fma_f32 v[16:17], v[70:71], v[18:19], v[74:75]
	v_pk_fma_f32 v[14:15], v[72:73], v[14:15], v[76:77]
	v_pk_mul_f32 v[16:17], v[16:17], s[20:21] op_sel_hi:[1,0]
	v_pk_mul_f32 v[14:15], v[14:15], s[20:21] op_sel_hi:[1,0]
	v_pk_fma_f32 v[10:11], v[10:11], v[66:67], v[16:17]
	v_pk_fma_f32 v[12:13], v[12:13], v[68:69], v[14:15]
	global_store_dwordx4 v[114:115], v[10:13], off offset:576
	global_load_dword v11, v[112:113], off
	s_nop 0
	global_load_dword v10, v[112:113], off offset:4
	s_waitcnt vmcnt(0)
	v_sub_f32_e32 v13, v53, v11
	v_sub_f32_e32 v12, v52, v11
	v_sub_f32_e32 v15, v51, v11
	v_sub_f32_e32 v14, v50, v11
	v_pk_mul_f32 v[14:15], v[14:15], v[10:11] op_sel_hi:[1,0]
	v_pk_mul_f32 v[10:11], v[12:13], v[10:11] op_sel_hi:[1,0]
	v_pk_fma_f32 v[12:13], v[70:71], v[14:15], v[74:75]
	v_pk_fma_f32 v[10:11], v[72:73], v[10:11], v[76:77]
	v_pk_mul_f32 v[12:13], v[12:13], s[20:21] op_sel_hi:[1,0]
	v_pk_mul_f32 v[10:11], v[10:11], s[20:21] op_sel_hi:[1,0]
	v_pk_fma_f32 v[6:7], v[6:7], v[66:67], v[12:13]
	v_pk_fma_f32 v[8:9], v[8:9], v[68:69], v[10:11]
	global_store_dwordx4 v[110:111], v[6:9], off offset:576
	global_load_dword v7, v[108:109], off
	s_nop 0
	global_load_dword v6, v[108:109], off offset:4
	s_waitcnt vmcnt(0)
	v_sub_f32_e32 v9, v37, v7
	v_sub_f32_e32 v8, v36, v7
	v_sub_f32_e32 v11, v35, v7
	v_sub_f32_e32 v10, v34, v7
	v_pk_mul_f32 v[10:11], v[10:11], v[6:7] op_sel_hi:[1,0]
	v_pk_mul_f32 v[6:7], v[8:9], v[6:7] op_sel_hi:[1,0]
	v_pk_fma_f32 v[8:9], v[70:71], v[10:11], v[74:75]
	v_pk_fma_f32 v[6:7], v[72:73], v[6:7], v[76:77]
	v_pk_mul_f32 v[8:9], v[8:9], s[20:21] op_sel_hi:[1,0]
	v_pk_mul_f32 v[6:7], v[6:7], s[20:21] op_sel_hi:[1,0]
	v_pk_fma_f32 v[2:3], v[2:3], v[66:67], v[8:9]
	v_pk_fma_f32 v[4:5], v[4:5], v[68:69], v[6:7]
	global_store_dwordx4 v[106:107], v[2:5], off offset:576
	s_cbranch_vccz .LBB0_1964
	s_waitcnt vmcnt(0)
	s_cmpk_gt_u32 s21, 0xff
	s_cbranch_scc1 .LBB0_1973
	s_barrier

; #define PG8_STAGE(bufoff, gbase, voff) do { _Pragma("unroll") for (int _i = 0; _i < 2; ++_i) \
;         __builtin_amdgcn_global_load_lds((const unsigned*)((const char*)(gbase) + (voff)[_i]), (LAS unsigned*)(lds + (bufoff) + ldsw + _i * 8192), 16, 0, 0); } while (0)
; #define PG8_WAIT_V(n) asm volatile("s_waitcnt vmcnt(" #n ")" ::: "memory")
; #define PG8_BAR __builtin_amdgcn_s_barrier()
; template <class Epi>
; DI void gemm_phase(LAS unsigned char* lds, const Gemm g, const StaticOrder& S, const Epi& E) {
;     const int tid = threadIdx.x, wid = __builtin_amdgcn_readfirstlane(tid >> 6), lane = tid & 63, wr = wid >> 2, wc = wid & 3, fr = lane & 15, fq = lane >> 4;
;     const int K = g.K, nt = K / BK, lda = g.lda, ldb = g.ldb;
;     unsigned voffA[2], voffB[2];
; #pragma unroll
;     for (int i = 0; i < 2; ++i) { int Rr, C; stage_rc(tid * 16 + i * 8192, Rr, C); const int Rb = Epi::PERM ? ((Rr & ~31) + perm32(Rr & 31)) : Rr;
;         voffA[i] = (unsigned)(Rr * lda + C) * 2u; voffB[i] = (unsigned)(Rb * ldb + C) * 2u; }
;     const size_t kstep = (size_t)(BK * 2);
;     const size_t hstepA = (size_t)HALF * lda * 2, hstepB = (size_t)HALF * ldb * 2;
;     const size_t tstepA = 2 * hstepA, tstepB = 2 * hstepB;
;     const unsigned ldsw = (unsigned)wid * 1024u;
;     const int aoff = lds_byte(wr * 64 + fr, fq * 8), boff = lds_byte(wc * 32 + fr, fq * 8);
;     ...
;     Unit cur, nxt; int ui = 0;
;     if (!S.next(0, cur)) return;
;     f32x4 acc[2][2][4][2];
; #pragma unroll
;     for (int a = 0; a < 2; ++a)
; #pragma unroll
;         for (int b = 0; b < 2; ++b)
; #pragma unroll
;             for (int m = 0; m < 4; ++m)
; #pragma unroll
;                 for (int n = 0; n < 2; ++n) acc[a][b][m][n] = (f32x4){0.f, 0.f, 0.f, 0.f};
;     bf16x8 At[4][2], B0[2][2], B1[2][2];
;     const char* cA = PG8_ABASE(cur); const char* cB = PG8_BBASE(cur);
;     PG8_STAGE(PG8_SB(0, 0), cB, voffB); PG8_STAGE(PG8_SA(0, 0), cA, voffA); PG8_STAGE(PG8_SB(0, 1), cB + hstepB, voffB); PG8_STAGE(PG8_SA(0, 1), cA + hstepA, voffA);
;     if (wr == 1) PG8_BAR;
;     PG8_WAIT_V(4); PG8_BAR;
;     PG8_STAGE(PG8_SB(1, 0), cB + kstep, voffB); PG8_STAGE(PG8_SA(1, 0), cA + kstep, voffA); PG8_STAGE(PG8_SB(1, 1), cB + hstepB + kstep, voffB);
;     PG8_WAIT_V(6); PG8_BAR;
.LBB0_2299:
	s_add_u32 s53, s10, 0x200000
	s_addc_u32 s54, s11, 0
	s_add_u32 s55, s10, 0x3a000
	s_addc_u32 s56, s11, 0
	s_add_u32 s10, s10, 0x100000
	s_addc_u32 s11, s11, 0
	s_waitcnt lgkmcnt(0)
	s_add_u32 s14, s4, 0x4000
	s_addc_u32 s15, s5, 0
	s_add_u32 s16, s6, 0x4000
	s_addc_u32 s17, s7, 0
	s_lshl_b32 s4, s18, 5
	s_mov_b64 s[18:19], 0x80
	s_and_b32 s7, s4, 0x60
	s_add_i32 m0, s39, 0x18000
	v_lshl_add_u64 v[8:9], v[8:9], 0, s[18:19]
	s_lshl_b32 s6, s22, 13
	s_lshl_b32 s23, s7, 7
	s_waitcnt vmcnt(0)
	s_barrier
	global_load_lds_dwordx4 v[8:9], off
	v_lshl_add_u64 v[6:7], v[6:7], 0, s[18:19]
	s_add_i32 m0, s39, 0x1a000
	s_add_i32 s57, s39, 0x8000
	s_add_i32 s58, s39, 0xa000
	global_load_lds_dwordx4 v[6:7], off
	v_lshl_add_u64 v[4:5], v[4:5], 0, s[18:19]
	s_mov_b32 m0, s57
	s_add_u32 s4, s28, 0x80080
	global_load_lds_dwordx4 v[4:5], off
	v_lshl_add_u64 v[2:3], v[2:3], 0, s[18:19]
	s_mov_b32 m0, s58
	s_addc_u32 s5, s29, 0
	global_load_lds_dwordx4 v[2:3], off
	s_add_i32 m0, s39, 0x1c000
	v_lshl_add_u64 v[2:3], s[4:5], 0, v[160:161]
	global_load_lds_dwordx4 v[2:3], off
	v_lshl_add_u64 v[2:3], s[4:5], 0, v[164:165]
	s_add_i32 m0, s39, 0x1e000
	v_and_b32_e32 v1, 15, v254
	global_load_lds_dwordx4 v[2:3], off
	v_bfe_u32 v2, v254, 4, 2
	v_lshlrev_b32_e32 v3, 4, v2
	v_lshlrev_b32_e32 v4, 2, v254
	v_lshl_or_b32 v166, s22, 6, v1
	v_lshl_or_b32 v1, v1, 6, v3
	v_and_b32_e32 v4, 32, v4
	v_bitop3_b32 v5, v1, s6, v4 bitop3:0xde
	v_lshlrev_b32_e32 v1, 6, v254
	s_movk_i32 s4, 0x3c0
	v_and_or_b32 v1, v1, s4, v3
	s_waitcnt vmcnt(6)
	v_bitop3_b32 v1, s23, v1, v4 bitop3:0xf6
	v_mov_b32_e32 v167, v161
	v_or_b32_e32 v170, 16, v166
	v_mov_b32_e32 v171, v161
	v_or_b32_e32 v174, 32, v166
	v_mov_b32_e32 v175, v161
	v_or_b32_e32 v178, 48, v166
	v_mov_b32_e32 v179, v161
	v_add_u32_e32 v182, 0x80, v166
	v_mov_b32_e32 v183, v161
	v_add_u32_e32 v186, 0x90, v166
	v_mov_b32_e32 v187, v161
	v_add_u32_e32 v190, 0xa0, v166
	v_mov_b32_e32 v191, v161
	v_add_u32_e32 v194, 0xb0, v166
	v_mov_b32_e32 v195, v161
	s_add_i32 s60, 0, 0x10000
	s_add_i32 s61, 0, 0x14000
	s_sext_i32_i8 s65, s20
	v_lshlrev_b64 v[168:169], 13, v[166:167]
	v_lshlrev_b64 v[172:173], 13, v[170:171]
	v_lshlrev_b64 v[176:177], 13, v[174:175]
	v_lshlrev_b64 v[180:181], 13, v[178:179]
	v_lshlrev_b64 v[184:185], 13, v[182:183]
	v_lshlrev_b64 v[188:189], 13, v[186:187]
	v_lshlrev_b64 v[192:193], 13, v[190:191]
	v_lshlrev_b64 v[196:197], 13, v[194:195]
	s_ashr_i32 s59, s51, 31
	v_lshl_or_b32 v167, v2, 2, s7
	v_add3_u32 v198, v12, v10, v11
	v_mov_b32_e32 v199, v161
	v_add3_u32 v200, v13, v10, v11
	v_mov_b32_e32 v201, v161
	v_mov_b64_e32 v[202:203], 0x400
	v_mov_b64_e32 v[204:205], 0x3ff
	v_add_u32_e32 v171, s60, v1
	v_add_u32_e32 v175, 0, v5
	v_add_u32_e32 v179, s61, v1
	s_movk_i32 s62, 0x1800
	s_mov_b32 s20, 0x3fd744fd
	v_mov_b32_e32 v183, 0x8000
	s_barrier

; #define PG8_STAGE(bufoff, gbase, voff) do { _Pragma("unroll") for (int _i = 0; _i < 2; ++_i) \
;         __builtin_amdgcn_global_load_lds((const unsigned*)((const char*)(gbase) + (voff)[_i]), (LAS unsigned*)(lds + (bufoff) + ldsw + _i * 8192), 16, 0, 0); } while (0)
; #define PG8_LDA(dst, b, h) do { _Pragma("unroll") for (int m = 0; m < 4; ++m) _Pragma("unroll") for (int k = 0; k < 2; ++k) dst[m][k] = *(const LAS bf16x8*)(lds + PG8_SA(b, h) + aoff + m * 2048 + k * 1024); } while (0)
; #define PG8_LDB(dst, b, h) do { _Pragma("unroll") for (int n = 0; n < 2; ++n) _Pragma("unroll") for (int k = 0; k < 2; ++k) dst[n][k] = *(const LAS bf16x8*)(lds + PG8_SB(b, h) + boff + n * 2048 + k * 1024); } while (0)
; #define PG8_MMA(ai, bj, At, Bt) do { __builtin_amdgcn_s_setprio(1); _Pragma("unroll") for (int m = 0; m < 4; ++m) _Pragma("unroll") for (int n = 0; n < 2; ++n) _Pragma("unroll") for (int k = 0; k < 2; ++k) \
;         acc[ai][bj][m][n] = __builtin_amdgcn_mfma_f32_16x16x32_bf16(Bt[n][k], At[m][k], acc[ai][bj][m][n], 0, 0, 0); __builtin_amdgcn_s_setprio(0); } while (0)
; #define PG8_WAIT_V(n) asm volatile("s_waitcnt vmcnt(" #n ")" ::: "memory")
; #define PG8_WAIT_L(n) asm volatile("s_waitcnt lgkmcnt(" #n ")" ::: "memory")
; #define PG8_BAR __builtin_amdgcn_s_barrier()
; #define PG8_SCHED __builtin_amdgcn_sched_barrier(0)
; template <class Epi>
; DI void gemm_phase(LAS unsigned char* lds, const Gemm g, const StaticOrder& S, const Epi& E) {
;     ...
;             PG8_LDB(B0, 0, 0); PG8_SCHED; PG8_LDA(At, 0, 0); PG8_STAGE(PG8_SA(1, 1), a1 + hstepA, voffA);
;             PG8_WAIT_L(8); PG8_BAR; PG8_WAIT_L(0); PG8_MMA(0, 0, At, B0); PG8_BAR; PG8_SCHED;
;             PG8_LDB(B1, 0, 1); PG8_STAGE(PG8_SB(0, 0), b2, voffB);
;             PG8_BAR; PG8_WAIT_L(0); PG8_MMA(0, 1, At, B1); PG8_BAR;
;             PG8_LDA(At, 0, 1); PG8_STAGE(PG8_SA(0, 0), a2, voffA);
;             PG8_BAR; PG8_WAIT_L(0); PG8_MMA(1, 0, At, B0); PG8_BAR; PG8_SCHED;
;             PG8_STAGE(PG8_SB(0, 1), b2 + hstepB, voffB);
;             PG8_WAIT_V(6); PG8_BAR; PG8_MMA(1, 1, At, B1); PG8_BAR;
;             PG8_LDB(B0, 1, 0); PG8_SCHED; PG8_LDA(At, 1, 0); PG8_STAGE(PG8_SA(0, 1), a2 + hstepA, voffA);
.LBB0_2305:
	ds_read_b128 v[130:133], v171
	ds_read_b128 v[134:137], v171 offset:1024
	ds_read_b128 v[138:141], v171 offset:2048
	ds_read_b128 v[142:145], v171 offset:3072
	s_add_u32 s28, s6, 0xffefc080
	s_addc_u32 s29, s7, -1
	s_cmp_eq_u32 s69, 28
	s_cselect_b32 s31, s25, s29
	s_cselect_b32 s30, s24, s28
	s_cselect_b32 s29, s23, s68
	s_cselect_b32 s28, s66, s67
	v_lshl_add_u64 v[214:215], s[6:7], 0, v[198:199]
	s_add_i32 m0, s39, 0xc000
	ds_read_b128 v[146:149], v175
	ds_read_b128 v[150:153], v175 offset:1024
	ds_read_b128 v[154:157], v175 offset:2048
	ds_read_b128 v[206:209], v175 offset:3072
	ds_read_b128 v[210:213], v175 offset:4096
	ds_read_b128 v[218:221], v175 offset:5120
	ds_read_b128 v[222:225], v175 offset:6144
	ds_read_b128 v[226:229], v175 offset:7168
	global_load_lds_dwordx4 v[214:215], off
	v_lshl_add_u64 v[214:215], s[6:7], 0, v[200:201]
	s_add_i32 m0, s39, 0xe000
	s_nop 0
	global_load_lds_dwordx4 v[214:215], off
	ds_read_b128 v[230:233], v179
	ds_read_b128 v[234:237], v179 offset:1024
	ds_read_b128 v[238:241], v179 offset:2048
	ds_read_b128 v[242:245], v179 offset:3072
	s_waitcnt lgkmcnt(0)
	s_waitcnt vmcnt(8)
	s_barrier
	s_setprio 1
	v_mfma_f32_16x16x32_bf16 v[126:129], v[130:133], v[146:149], v[126:129]
	v_mfma_f32_16x16x32_bf16 v[102:105], v[138:141], v[146:149], v[102:105]
	v_mfma_f32_16x16x32_bf16 v[122:125], v[130:133], v[154:157], v[122:125]
	v_mfma_f32_16x16x32_bf16 v[94:97], v[138:141], v[154:157], v[94:97]
	v_mfma_f32_16x16x32_bf16 v[118:121], v[130:133], v[210:213], v[118:121]
	v_mfma_f32_16x16x32_bf16 v[86:89], v[138:141], v[210:213], v[86:89]
	v_mfma_f32_16x16x32_bf16 v[114:117], v[130:133], v[222:225], v[114:117]
	v_mfma_f32_16x16x32_bf16 v[82:85], v[138:141], v[222:225], v[82:85]
	v_mfma_f32_16x16x32_bf16 v[126:129], v[134:137], v[150:153], v[126:129]
	v_mfma_f32_16x16x32_bf16 v[102:105], v[142:145], v[150:153], v[102:105]
	v_mfma_f32_16x16x32_bf16 v[122:125], v[134:137], v[206:209], v[122:125]
	v_mfma_f32_16x16x32_bf16 v[94:97], v[142:145], v[206:209], v[94:97]
	v_mfma_f32_16x16x32_bf16 v[118:121], v[134:137], v[218:221], v[118:121]
	v_mfma_f32_16x16x32_bf16 v[86:89], v[142:145], v[218:221], v[86:89]
	v_mfma_f32_16x16x32_bf16 v[114:117], v[134:137], v[226:229], v[114:117]
	v_mfma_f32_16x16x32_bf16 v[82:85], v[142:145], v[226:229], v[82:85]
	v_mfma_f32_16x16x32_bf16 v[62:65], v[230:233], v[146:149], v[62:65]
	v_mfma_f32_16x16x32_bf16 v[38:41], v[238:241], v[146:149], v[38:41]
	v_mfma_f32_16x16x32_bf16 v[58:61], v[230:233], v[154:157], v[58:61]
	v_mfma_f32_16x16x32_bf16 v[30:33], v[238:241], v[154:157], v[30:33]
	v_mfma_f32_16x16x32_bf16 v[54:57], v[230:233], v[210:213], v[54:57]
	v_mfma_f32_16x16x32_bf16 v[22:25], v[238:241], v[210:213], v[22:25]
	v_mfma_f32_16x16x32_bf16 v[50:53], v[230:233], v[222:225], v[50:53]
	v_mfma_f32_16x16x32_bf16 v[18:21], v[238:241], v[222:225], v[18:21]
	v_mfma_f32_16x16x32_bf16 v[62:65], v[234:237], v[150:153], v[62:65]
	v_mfma_f32_16x16x32_bf16 v[38:41], v[242:245], v[150:153], v[38:41]
	v_mfma_f32_16x16x32_bf16 v[58:61], v[234:237], v[206:209], v[58:61]
	v_mfma_f32_16x16x32_bf16 v[30:33], v[242:245], v[206:209], v[30:33]
	v_mfma_f32_16x16x32_bf16 v[54:57], v[234:237], v[218:221], v[54:57]
	v_mfma_f32_16x16x32_bf16 v[22:25], v[242:245], v[218:221], v[22:25]
	v_mfma_f32_16x16x32_bf16 v[50:53], v[234:237], v[226:229], v[50:53]
	v_mfma_f32_16x16x32_bf16 v[18:21], v[242:245], v[226:229], v[18:21]
	s_setprio 0
	s_barrier
	s_add_i32 s70, s60, s38
	v_lshl_add_u64 v[214:215], s[28:29], 0, v[160:161]
	s_mov_b32 m0, s70
	s_nop 0
	global_load_lds_dwordx4 v[214:215], off
	v_lshl_add_u64 v[216:217], s[28:29], 0, v[164:165]
	s_add_i32 m0, s70, 0x2000
	s_nop 0
	global_load_lds_dwordx4 v[216:217], off
	s_mov_b32 m0, s39
	v_lshl_add_u64 v[246:247], s[30:31], 0, v[158:159]
	ds_read_b128 v[146:149], v175 offset:16384
	ds_read_b128 v[150:153], v175 offset:17408
	ds_read_b128 v[154:157], v175 offset:18432
	ds_read_b128 v[206:209], v175 offset:19456
	ds_read_b128 v[210:213], v175 offset:20480
	ds_read_b128 v[218:221], v175 offset:21504
	ds_read_b128 v[222:225], v175 offset:22528
	ds_read_b128 v[226:229], v175 offset:23552
	global_load_lds_dwordx4 v[246:247], off
	v_lshl_add_u64 v[248:249], s[30:31], 0, v[162:163]
	s_mov_b32 m0, s48
	s_nop 0
	global_load_lds_dwordx4 v[248:249], off
	s_add_u32 s70, s28, 0x80000
	s_addc_u32 s71, s29, 0
	s_add_i32 s72, s61, s38
	v_lshl_add_u64 v[252:253], s[70:71], 0, v[160:161]
	s_mov_b32 m0, s72
	s_nop 0
	global_load_lds_dwordx4 v[252:253], off
	v_lshl_add_u64 v[252:253], s[70:71], 0, v[164:165]
	s_add_i32 m0, s72, 0x2000
	s_nop 0
	global_load_lds_dwordx4 v[252:253], off
	s_waitcnt lgkmcnt(0)
	s_waitcnt vmcnt(8)
	s_barrier
; #define PG8_STAGE(bufoff, gbase, voff) do { _Pragma("unroll") for (int _i = 0; _i < 2; ++_i) \
;         __builtin_amdgcn_global_load_lds((const unsigned*)((const char*)(gbase) + (voff)[_i]), (LAS unsigned*)(lds + (bufoff) + ldsw + _i * 8192), 16, 0, 0); } while (0)
; #define PG8_LDA(dst, b, h) do { _Pragma("unroll") for (int m = 0; m < 4; ++m) _Pragma("unroll") for (int k = 0; k < 2; ++k) dst[m][k] = *(const LAS bf16x8*)(lds + PG8_SA(b, h) + aoff + m * 2048 + k * 1024); } while (0)
; #define PG8_LDB(dst, b, h) do { _Pragma("unroll") for (int n = 0; n < 2; ++n) _Pragma("unroll") for (int k = 0; k < 2; ++k) dst[n][k] = *(const LAS bf16x8*)(lds + PG8_SB(b, h) + boff + n * 2048 + k * 1024); } while (0)
; #define PG8_MMA(ai, bj, At, Bt) do { __builtin_amdgcn_s_setprio(1); _Pragma("unroll") for (int m = 0; m < 4; ++m) _Pragma("unroll") for (int n = 0; n < 2; ++n) _Pragma("unroll") for (int k = 0; k < 2; ++k) \
;         acc[ai][bj][m][n] = __builtin_amdgcn_mfma_f32_16x16x32_bf16(Bt[n][k], At[m][k], acc[ai][bj][m][n], 0, 0, 0); __builtin_amdgcn_s_setprio(0); } while (0)
; #define PG8_WAIT_V(n) asm volatile("s_waitcnt vmcnt(" #n ")" ::: "memory")
; #define PG8_WAIT_L(n) asm volatile("s_waitcnt lgkmcnt(" #n ")" ::: "memory")
; #define PG8_BAR __builtin_amdgcn_s_barrier()
; #define PG8_SCHED __builtin_amdgcn_sched_barrier(0)
; template <class Epi>
; DI void gemm_phase(LAS unsigned char* lds, const Gemm g, const StaticOrder& S, const Epi& E) {
;     ...
;             PG8_BAR; PG8_WAIT_L(0); PG8_MMA(1, 0, At, B0); PG8_BAR; PG8_SCHED;
;             PG8_STAGE(PG8_SB(0, 1), b2 + hstepB, voffB);
;             PG8_WAIT_V(6); PG8_BAR; PG8_MMA(1, 1, At, B1); PG8_BAR;
;             PG8_LDB(B0, 1, 0); PG8_SCHED; PG8_LDA(At, 1, 0); PG8_STAGE(PG8_SA(0, 1), a2 + hstepA, voffA);
;             PG8_WAIT_L(8); PG8_BAR; PG8_WAIT_L(0); PG8_MMA(0, 0, At, B0); PG8_BAR; PG8_SCHED;
;             PG8_LDB(B1, 1, 1); PG8_STAGE(PG8_SB(1, 0), b3, voffB);
;             PG8_BAR; PG8_WAIT_L(0); PG8_MMA(0, 1, At, B1); PG8_BAR;
;             PG8_LDA(At, 1, 1); PG8_STAGE(PG8_SA(1, 0), a3, voffA);
;             PG8_BAR; PG8_WAIT_L(0); PG8_MMA(1, 0, At, B0); PG8_BAR; PG8_SCHED;
	s_setprio 1
	v_mfma_f32_16x16x32_bf16 v[110:113], v[130:133], v[146:149], v[110:113]
	v_mfma_f32_16x16x32_bf16 v[78:81], v[138:141], v[146:149], v[78:81]
	v_mfma_f32_16x16x32_bf16 v[106:109], v[130:133], v[154:157], v[106:109]
	v_mfma_f32_16x16x32_bf16 v[74:77], v[138:141], v[154:157], v[74:77]
	v_mfma_f32_16x16x32_bf16 v[98:101], v[130:133], v[210:213], v[98:101]
	v_mfma_f32_16x16x32_bf16 v[70:73], v[138:141], v[210:213], v[70:73]
	v_mfma_f32_16x16x32_bf16 v[90:93], v[130:133], v[222:225], v[90:93]
	v_mfma_f32_16x16x32_bf16 v[66:69], v[138:141], v[222:225], v[66:69]
	v_mfma_f32_16x16x32_bf16 v[110:113], v[134:137], v[150:153], v[110:113]
	v_mfma_f32_16x16x32_bf16 v[78:81], v[142:145], v[150:153], v[78:81]
	v_mfma_f32_16x16x32_bf16 v[106:109], v[134:137], v[206:209], v[106:109]
	v_mfma_f32_16x16x32_bf16 v[74:77], v[142:145], v[206:209], v[74:77]
	v_mfma_f32_16x16x32_bf16 v[98:101], v[134:137], v[218:221], v[98:101]
	v_mfma_f32_16x16x32_bf16 v[70:73], v[142:145], v[218:221], v[70:73]
	v_mfma_f32_16x16x32_bf16 v[90:93], v[134:137], v[226:229], v[90:93]
	v_mfma_f32_16x16x32_bf16 v[66:69], v[142:145], v[226:229], v[66:69]
	v_mfma_f32_16x16x32_bf16 v[46:49], v[230:233], v[146:149], v[46:49]
	v_mfma_f32_16x16x32_bf16 v[14:17], v[238:241], v[146:149], v[14:17]
	v_mfma_f32_16x16x32_bf16 v[42:45], v[230:233], v[154:157], v[42:45]
	v_mfma_f32_16x16x32_bf16 v[10:13], v[238:241], v[154:157], v[10:13]
	v_mfma_f32_16x16x32_bf16 v[34:37], v[230:233], v[210:213], v[34:37]
	v_mfma_f32_16x16x32_bf16 v[6:9], v[238:241], v[210:213], v[6:9]
	v_mfma_f32_16x16x32_bf16 v[26:29], v[230:233], v[222:225], v[26:29]
	v_mfma_f32_16x16x32_bf16 v[2:5], v[238:241], v[222:225], v[2:5]
	v_mfma_f32_16x16x32_bf16 v[46:49], v[234:237], v[150:153], v[46:49]
	v_mfma_f32_16x16x32_bf16 v[14:17], v[242:245], v[150:153], v[14:17]
	v_mfma_f32_16x16x32_bf16 v[42:45], v[234:237], v[206:209], v[42:45]
	v_mfma_f32_16x16x32_bf16 v[10:13], v[242:245], v[206:209], v[10:13]
	v_mfma_f32_16x16x32_bf16 v[34:37], v[234:237], v[218:221], v[34:37]
	v_mfma_f32_16x16x32_bf16 v[6:9], v[242:245], v[218:221], v[6:9]
	v_mfma_f32_16x16x32_bf16 v[26:29], v[234:237], v[226:229], v[26:29]
	v_mfma_f32_16x16x32_bf16 v[2:5], v[242:245], v[226:229], v[2:5]
	s_setprio 0
	s_add_i32 s70, 0, 0x18000
	v_add_u32_e32 v142, s70, v1
	s_barrier
	ds_read_b128 v[130:133], v142
	ds_read_b128 v[134:137], v142 offset:1024
	ds_read_b128 v[138:141], v142 offset:2048
	ds_read_b128 v[142:145], v142 offset:3072
	s_add_u32 s30, s30, 0x104000
	s_addc_u32 s31, s31, 0
	s_mov_b32 m0, s49
	v_lshl_add_u64 v[230:231], s[30:31], 0, v[158:159]
	ds_read_b128 v[146:149], v175 offset:32768
	ds_read_b128 v[150:153], v175 offset:33792
	ds_read_b128 v[154:157], v175 offset:34816
	ds_read_b128 v[206:209], v175 offset:35840
	ds_read_b128 v[210:213], v175 offset:36864
	ds_read_b128 v[218:221], v175 offset:37888
	ds_read_b128 v[222:225], v175 offset:38912
	ds_read_b128 v[226:229], v175 offset:39936
	global_load_lds_dwordx4 v[230:231], off
	v_lshl_add_u64 v[230:231], s[30:31], 0, v[162:163]
	s_mov_b32 m0, s50
	s_nop 0
	global_load_lds_dwordx4 v[230:231], off
	s_add_i32 s30, 0, 0x1c000
	v_add_u32_e32 v187, s30, v1
	ds_read_b128 v[230:233], v187
	ds_read_b128 v[234:237], v187 offset:1024
	ds_read_b128 v[238:241], v187 offset:2048
	ds_read_b128 v[242:245], v187 offset:3072
	s_waitcnt lgkmcnt(0)
	s_waitcnt vmcnt(8)
	s_barrier
	s_setprio 1
	v_mfma_f32_16x16x32_bf16 v[126:129], v[130:133], v[146:149], v[126:129]
	v_mfma_f32_16x16x32_bf16 v[102:105], v[138:141], v[146:149], v[102:105]
	v_mfma_f32_16x16x32_bf16 v[122:125], v[130:133], v[154:157], v[122:125]
	v_mfma_f32_16x16x32_bf16 v[94:97], v[138:141], v[154:157], v[94:97]
	v_mfma_f32_16x16x32_bf16 v[118:121], v[130:133], v[210:213], v[118:121]
	v_mfma_f32_16x16x32_bf16 v[86:89], v[138:141], v[210:213], v[86:89]
	v_mfma_f32_16x16x32_bf16 v[114:117], v[130:133], v[222:225], v[114:117]
	v_mfma_f32_16x16x32_bf16 v[82:85], v[138:141], v[222:225], v[82:85]
	v_mfma_f32_16x16x32_bf16 v[126:129], v[134:137], v[150:153], v[126:129]
	v_mfma_f32_16x16x32_bf16 v[102:105], v[142:145], v[150:153], v[102:105]
	v_mfma_f32_16x16x32_bf16 v[122:125], v[134:137], v[206:209], v[122:125]
	v_mfma_f32_16x16x32_bf16 v[94:97], v[142:145], v[206:209], v[94:97]
	v_mfma_f32_16x16x32_bf16 v[118:121], v[134:137], v[218:221], v[118:121]
	v_mfma_f32_16x16x32_bf16 v[86:89], v[142:145], v[218:221], v[86:89]
	v_mfma_f32_16x16x32_bf16 v[114:117], v[134:137], v[226:229], v[114:117]
	v_mfma_f32_16x16x32_bf16 v[82:85], v[142:145], v[226:229], v[82:85]
	v_mfma_f32_16x16x32_bf16 v[62:65], v[230:233], v[146:149], v[62:65]
	v_mfma_f32_16x16x32_bf16 v[38:41], v[238:241], v[146:149], v[38:41]
	v_mfma_f32_16x16x32_bf16 v[58:61], v[230:233], v[154:157], v[58:61]
	v_mfma_f32_16x16x32_bf16 v[30:33], v[238:241], v[154:157], v[30:33]
	v_mfma_f32_16x16x32_bf16 v[54:57], v[230:233], v[210:213], v[54:57]
	v_mfma_f32_16x16x32_bf16 v[22:25], v[238:241], v[210:213], v[22:25]
	v_mfma_f32_16x16x32_bf16 v[50:53], v[230:233], v[222:225], v[50:53]
	v_mfma_f32_16x16x32_bf16 v[18:21], v[238:241], v[222:225], v[18:21]
	v_mfma_f32_16x16x32_bf16 v[62:65], v[234:237], v[150:153], v[62:65]
	v_mfma_f32_16x16x32_bf16 v[38:41], v[242:245], v[150:153], v[38:41]
	v_mfma_f32_16x16x32_bf16 v[58:61], v[234:237], v[206:209], v[58:61]
	v_mfma_f32_16x16x32_bf16 v[30:33], v[242:245], v[206:209], v[30:33]
	v_mfma_f32_16x16x32_bf16 v[54:57], v[234:237], v[218:221], v[54:57]
	v_mfma_f32_16x16x32_bf16 v[22:25], v[242:245], v[218:221], v[22:25]
	v_mfma_f32_16x16x32_bf16 v[50:53], v[234:237], v[226:229], v[50:53]
	v_mfma_f32_16x16x32_bf16 v[18:21], v[242:245], v[226:229], v[18:21]
	s_setprio 0
	s_barrier
; #define PG8_STAGE(bufoff, gbase, voff) do { _Pragma("unroll") for (int _i = 0; _i < 2; ++_i) \
;         __builtin_amdgcn_global_load_lds((const unsigned*)((const char*)(gbase) + (voff)[_i]), (LAS unsigned*)(lds + (bufoff) + ldsw + _i * 8192), 16, 0, 0); } while (0)
; #define PG8_LDA(dst, b, h) do { _Pragma("unroll") for (int m = 0; m < 4; ++m) _Pragma("unroll") for (int k = 0; k < 2; ++k) dst[m][k] = *(const LAS bf16x8*)(lds + PG8_SA(b, h) + aoff + m * 2048 + k * 1024); } while (0)
; #define PG8_WAIT_V(n) asm volatile("s_waitcnt vmcnt(" #n ")" ::: "memory")
; #define PG8_WAIT_L(n) asm volatile("s_waitcnt lgkmcnt(" #n ")" ::: "memory")
; template <class Epi>
; DI void gemm_phase(LAS unsigned char* lds, const Gemm g, const StaticOrder& S, const Epi& E) {
;     ...
;             PG8_LDB(B1, 1, 1); PG8_STAGE(PG8_SB(1, 0), b3, voffB);
;             PG8_BAR; PG8_WAIT_L(0); PG8_MMA(0, 1, At, B1); PG8_BAR;
;             PG8_LDA(At, 1, 1); PG8_STAGE(PG8_SA(1, 0), a3, voffA);
;             PG8_BAR; PG8_WAIT_L(0); PG8_MMA(1, 0, At, B0); PG8_BAR; PG8_SCHED;
;             PG8_STAGE(PG8_SB(1, 1), b3 + hstepB, voffB);
;             PG8_WAIT_V(6); PG8_BAR; PG8_MMA(1, 1, At, B1); PG8_BAR;
;         }
;     DI void operator()(const f32x4 (&acc)[2][2][4][2], const pg8::Unit& u, int wr, int wc, int fr, int fq) const {
;         const int rowt = row_base + u.pm * 256, col0 = u.pn * 256 + wc * 32 + 4 * fq, rl = wr * 64 + fr;
;         const int cd = cond_of_row(rowt);
;         const float* gtp = gt0 + (size_t)cd * 6144;
;         float* dbase = rowt < TL ? out + (size_t)rowt * D : ctxv + (size_t)(rowt - TL) * D;
;         const float* sbase = mode ? (const float*)dbase : (rowt < TL ? xin + (size_t)rowt * D : cin + (size_t)(rowt - TL) * D);
; #pragma unroll
;         for (int bj = 0; bj < 2; ++bj) {
;             f32x4 gv[2], gg[2], bb[2], xv[2][8];
; #pragma unroll
;             for (int n = 0; n < 2; ++n) {
;                 const int c = col0 + bj * 128 + n * 16;
;                 gv[n] = *(const f32x4*)(gtp + c);
;                 gg[n] = (f32x4){1.f, 1.f, 1.f, 1.f}; bb[n] = (f32x4){0.f, 0.f, 0.f, 0.f};
;                 if (mode) { gg[n] = *(const f32x4*)(lg + c); bb[n] = *(const f32x4*)(lb + c); }
; #pragma unroll
;                 for (int q = 0; q < 8; ++q) { const int rr = rl + (q >> 2) * 128 + (q & 3) * 16; xv[n][q] = *(const f32x4*)(sbase + (size_t)rr * D + c); }
	s_add_i32 s31, s70, s38
	v_lshl_add_u64 v[214:215], v[214:215], 0, s[18:19]
	s_mov_b32 m0, s31
	s_nop 0
	global_load_lds_dwordx4 v[214:215], off
	v_lshl_add_u64 v[214:215], v[216:217], 0, s[18:19]
	s_add_i32 m0, s31, 0x2000
	s_nop 0
	global_load_lds_dwordx4 v[214:215], off
	s_mov_b32 m0, s57
	v_lshl_add_u64 v[214:215], v[246:247], 0, s[18:19]
	ds_read_b128 v[146:149], v175 offset:49152
	ds_read_b128 v[150:153], v175 offset:50176
	ds_read_b128 v[154:157], v175 offset:51200
	ds_read_b128 v[206:209], v175 offset:52224
	ds_read_b128 v[210:213], v175 offset:53248
	ds_read_b128 v[218:221], v175 offset:54272
	ds_read_b128 v[222:225], v175 offset:55296
	ds_read_b128 v[226:229], v175 offset:56320
	global_load_lds_dwordx4 v[214:215], off
	v_lshl_add_u64 v[214:215], v[248:249], 0, s[18:19]
	s_mov_b32 m0, s58
	s_nop 0
	global_load_lds_dwordx4 v[214:215], off
	s_add_u32 s28, s28, 0x80080
	s_addc_u32 s29, s29, 0
	s_add_i32 s30, s30, s38
	v_lshl_add_u64 v[252:253], s[28:29], 0, v[160:161]
	s_mov_b32 m0, s30
	s_nop 0
	global_load_lds_dwordx4 v[252:253], off
	v_lshl_add_u64 v[252:253], s[28:29], 0, v[164:165]
	s_add_i32 m0, s30, 0x2000
	s_nop 0
	global_load_lds_dwordx4 v[252:253], off
	s_waitcnt lgkmcnt(0)
	s_waitcnt vmcnt(8)
	s_barrier
	s_setprio 1
	v_mfma_f32_16x16x32_bf16 v[110:113], v[130:133], v[146:149], v[110:113]
	v_mfma_f32_16x16x32_bf16 v[78:81], v[138:141], v[146:149], v[78:81]
	v_mfma_f32_16x16x32_bf16 v[106:109], v[130:133], v[154:157], v[106:109]
	v_mfma_f32_16x16x32_bf16 v[74:77], v[138:141], v[154:157], v[74:77]
	v_mfma_f32_16x16x32_bf16 v[98:101], v[130:133], v[210:213], v[98:101]
	v_mfma_f32_16x16x32_bf16 v[70:73], v[138:141], v[210:213], v[70:73]
	v_mfma_f32_16x16x32_bf16 v[90:93], v[130:133], v[222:225], v[90:93]
	v_mfma_f32_16x16x32_bf16 v[66:69], v[138:141], v[222:225], v[66:69]
	v_mfma_f32_16x16x32_bf16 v[110:113], v[134:137], v[150:153], v[110:113]
	v_mfma_f32_16x16x32_bf16 v[78:81], v[142:145], v[150:153], v[78:81]
	v_mfma_f32_16x16x32_bf16 v[106:109], v[134:137], v[206:209], v[106:109]
	v_mfma_f32_16x16x32_bf16 v[74:77], v[142:145], v[206:209], v[74:77]
	v_mfma_f32_16x16x32_bf16 v[98:101], v[134:137], v[218:221], v[98:101]
	v_mfma_f32_16x16x32_bf16 v[70:73], v[142:145], v[218:221], v[70:73]
	v_mfma_f32_16x16x32_bf16 v[90:93], v[134:137], v[226:229], v[90:93]
	v_mfma_f32_16x16x32_bf16 v[66:69], v[142:145], v[226:229], v[66:69]
	v_mfma_f32_16x16x32_bf16 v[46:49], v[230:233], v[146:149], v[46:49]
	v_mfma_f32_16x16x32_bf16 v[14:17], v[238:241], v[146:149], v[14:17]
	v_mfma_f32_16x16x32_bf16 v[42:45], v[230:233], v[154:157], v[42:45]
	v_mfma_f32_16x16x32_bf16 v[10:13], v[238:241], v[154:157], v[10:13]
	v_mfma_f32_16x16x32_bf16 v[34:37], v[230:233], v[210:213], v[34:37]
	v_mfma_f32_16x16x32_bf16 v[6:9], v[238:241], v[210:213], v[6:9]
	v_mfma_f32_16x16x32_bf16 v[26:29], v[230:233], v[222:225], v[26:29]
	v_mfma_f32_16x16x32_bf16 v[2:5], v[238:241], v[222:225], v[2:5]
	v_mfma_f32_16x16x32_bf16 v[46:49], v[234:237], v[150:153], v[46:49]
	v_mfma_f32_16x16x32_bf16 v[14:17], v[242:245], v[150:153], v[14:17]
	v_mfma_f32_16x16x32_bf16 v[42:45], v[234:237], v[206:209], v[42:45]
	v_mfma_f32_16x16x32_bf16 v[10:13], v[242:245], v[206:209], v[10:13]
	v_mfma_f32_16x16x32_bf16 v[34:37], v[234:237], v[218:221], v[34:37]
	v_mfma_f32_16x16x32_bf16 v[6:9], v[242:245], v[218:221], v[6:9]
	v_mfma_f32_16x16x32_bf16 v[26:29], v[234:237], v[226:229], v[26:29]
	v_mfma_f32_16x16x32_bf16 v[2:5], v[242:245], v[226:229], v[2:5]
	s_setprio 0
	s_add_i32 s69, s69, 2
	s_add_u32 s6, s6, 0x100
	s_addc_u32 s7, s7, 0
	s_add_u32 s67, s67, 0x100
	s_addc_u32 s68, s68, 0
	s_cmp_gt_u32 s69, 29
	s_barrier
	s_cbranch_scc0 .LBB0_2305
	s_lshl_b32 s6, s64, 8
	v_sub_co_u32_e32 v130, vcc, s6, v183
	s_and_b64 s[28:29], vcc, exec
	s_cselect_b32 s7, s62, 0x3000
	s_cmp_gt_i32 s64, 63
	s_cselect_b32 s7, s7, 0
	s_lshl_b32 s7, s7, 2
	s_add_u32 s28, s55, s7
	s_addc_u32 s29, s56, 0
	s_ashr_i32 s7, s6, 31
	s_cmpk_lt_i32 s64, 0x80
	v_mov_b32_e32 v131, s7
	s_cselect_b64 vcc, -1, 0
	v_mov_b32_e32 v132, s6
	v_lshl_or_b32 v228, s65, 8, v167
	v_cndmask_b32_e32 v131, 0, v131, vcc
	v_cndmask_b32_e32 v130, v130, v132, vcc
	s_cselect_b32 s31, s9, s54
	s_cselect_b32 s30, s8, s53
	v_lshlrev_b64 v[130:131], 13, v[130:131]
	v_ashrrev_i32_e32 v229, 31, v228
	v_lshl_add_u64 v[130:131], s[30:31], 0, v[130:131]
	v_lshlrev_b64 v[132:133], 2, v[228:229]
	v_lshl_add_u64 v[232:233], v[130:131], 0, v[132:133]
	v_add_lshl_u32 v130, s6, v166, 1
	v_ashrrev_i32_e32 v131, 31, v130
	v_lshl_add_u64 v[206:207], v[232:233], 0, v[168:169]
	v_lshl_add_u64 v[210:211], v[130:131], 2, s[10:11]
	global_load_dwordx4 v[218:221], v[206:207], off
	global_load_dwordx2 v[214:215], v[210:211], off
	v_lshl_add_u64 v[130:131], s[14:15], 0, v[132:133]
	global_load_dwordx4 v[146:149], v[130:131], off
	v_lshl_add_u64 v[130:131], s[16:17], 0, v[132:133]
	global_load_dwordx4 v[150:153], v[130:131], off
	v_lshl_add_u64 v[230:231], s[28:29], 0, v[132:133]
	global_load_dwordx4 v[142:145], v[230:231], off
	v_or_b32_e32 v130, 16, v228
	v_add_lshl_u32 v132, s6, v170, 1
	v_ashrrev_i32_e32 v131, 31, v130
	v_ashrrev_i32_e32 v133, 31, v132
	v_lshlrev_b64 v[130:131], 2, v[130:131]
	v_lshl_add_u64 v[212:213], v[132:133], 2, s[10:11]
	v_lshl_add_u64 v[132:133], s[14:15], 0, v[130:131]
	v_lshl_add_u64 v[130:131], s[16:17], 0, v[130:131]
	v_lshl_add_u64 v[208:209], v[232:233], 0, v[172:173]
	global_load_dwordx4 v[134:137], v[132:133], off
	global_load_dwordx4 v[138:141], v[130:131], off
	s_nop 0
	global_load_dwordx4 v[130:133], v[230:231], off offset:64
	global_load_dwordx4 v[222:225], v[208:209], off
	global_load_dwordx4 v[154:157], v[206:207], off offset:64
	s_mov_b32 s65, s22
	s_mov_b64 s[28:29], s[26:27]
	s_mov_b64 s[30:31], s[24:25]
	s_mov_b32 s64, s63
	s_and_b64 vcc, exec, s[4:5]
	s_waitcnt vmcnt(0)
;     DI void operator()(const f32x4 (&acc)[2][2][4][2], const pg8::Unit& u, int wr, int wc, int fr, int fq) const {
;     ...
;         for (int bj = 0; bj < 2; ++bj) {
;             f32x4 gv[2], gg[2], bb[2], xv[2][8];
; #pragma unroll
;             for (int n = 0; n < 2; ++n) {
;                 const int c = col0 + bj * 128 + n * 16;
;                 gv[n] = *(const f32x4*)(gtp + c);
;                 gg[n] = (f32x4){1.f, 1.f, 1.f, 1.f}; bb[n] = (f32x4){0.f, 0.f, 0.f, 0.f};
;                 if (mode) { gg[n] = *(const f32x4*)(lg + c); bb[n] = *(const f32x4*)(lb + c); }
; #pragma unroll
;                 for (int q = 0; q < 8; ++q) { const int rr = rl + (q >> 2) * 128 + (q & 3) * 16; xv[n][q] = *(const f32x4*)(sbase + (size_t)rr * D + c); }
;             }
; #pragma unroll
;             for (int n = 0; n < 2; ++n) {
;                 const int c = col0 + bj * 128 + n * 16;
; #pragma unroll
;                 for (int q = 0; q < 8; ++q) {
;                     const int rr = rl + (q >> 2) * 128 + (q & 3) * 16;
;                     f32x4 x = xv[n][q];
;                     if (mode) { const float mu = stats[2 * (rowt + rr)], rs = stats[2 * (rowt + rr) + 1]; x = (x - mu) * rs * gg[n] + bb[n]; }
;                     *(f32x4*)(dbase + (size_t)rr * D + c) = ALPHA * x + gv[n] * acc[q >> 2][bj][q & 3][n];
;                 }
	v_sub_f32_e32 v217, v221, v214
	v_sub_f32_e32 v216, v220, v214
	v_sub_f32_e32 v219, v219, v214
	v_sub_f32_e32 v218, v218, v214
	v_pk_mul_f32 v[218:219], v[218:219], v[214:215] op_sel:[0,1]
	v_pk_mul_f32 v[214:215], v[216:217], v[214:215] op_sel:[0,1]
	v_pk_fma_f32 v[216:217], v[146:147], v[218:219], v[150:151]
	v_pk_fma_f32 v[214:215], v[148:149], v[214:215], v[152:153]
	v_pk_mul_f32 v[216:217], v[216:217], s[20:21] op_sel_hi:[1,0]
	v_pk_mul_f32 v[214:215], v[214:215], s[20:21] op_sel_hi:[1,0]
	v_pk_fma_f32 v[126:127], v[126:127], v[142:143], v[216:217]
	v_pk_fma_f32 v[128:129], v[128:129], v[144:145], v[214:215]
	global_store_dwordx4 v[206:207], v[126:129], off
	global_load_dword v187, v[212:213], off
	global_load_dword v216, v[212:213], off offset:4
	v_add_lshl_u32 v126, s6, v174, 1
	v_ashrrev_i32_e32 v127, 31, v126
	v_lshl_add_u64 v[214:215], v[232:233], 0, v[176:177]
	v_lshl_add_u64 v[220:221], v[126:127], 2, s[10:11]
	global_load_dwordx4 v[234:237], v[214:215], off
	global_load_dwordx4 v[126:129], v[208:209], off offset:64
	s_waitcnt vmcnt(0)
	v_sub_f32_e32 v219, v225, v187
	v_sub_f32_e32 v218, v224, v187
	v_sub_f32_e32 v223, v223, v187
	v_sub_f32_e32 v222, v222, v187
	v_pk_mul_f32 v[222:223], v[222:223], v[216:217] op_sel_hi:[1,0]
	v_pk_mul_f32 v[216:217], v[218:219], v[216:217] op_sel_hi:[1,0]
	v_pk_fma_f32 v[218:219], v[146:147], v[222:223], v[150:151]
	v_pk_fma_f32 v[216:217], v[148:149], v[216:217], v[152:153]
	v_pk_mul_f32 v[218:219], v[218:219], s[20:21] op_sel_hi:[1,0]
	v_pk_mul_f32 v[216:217], v[216:217], s[20:21] op_sel_hi:[1,0]
	v_pk_fma_f32 v[122:123], v[122:123], v[142:143], v[218:219]
	v_pk_fma_f32 v[124:125], v[124:125], v[144:145], v[216:217]
	global_store_dwordx4 v[208:209], v[122:125], off
	global_load_dword v187, v[220:221], off
	global_load_dword v216, v[220:221], off offset:4
	v_add_lshl_u32 v122, s6, v178, 1
	v_ashrrev_i32_e32 v123, 31, v122
	v_lshl_add_u64 v[218:219], v[232:233], 0, v[180:181]
	v_lshl_add_u64 v[224:225], v[122:123], 2, s[10:11]
	global_load_dwordx4 v[238:241], v[218:219], off
	global_load_dwordx4 v[122:125], v[214:215], off offset:64
	s_waitcnt vmcnt(0)
	v_sub_f32_e32 v223, v237, v187
	v_sub_f32_e32 v222, v236, v187
	v_sub_f32_e32 v227, v235, v187
	v_sub_f32_e32 v226, v234, v187
	v_pk_mul_f32 v[226:227], v[226:227], v[216:217] op_sel_hi:[1,0]
	v_pk_mul_f32 v[216:217], v[222:223], v[216:217] op_sel_hi:[1,0]
	v_pk_fma_f32 v[222:223], v[146:147], v[226:227], v[150:151]
	v_pk_fma_f32 v[216:217], v[148:149], v[216:217], v[152:153]
	v_pk_mul_f32 v[222:223], v[222:223], s[20:21] op_sel_hi:[1,0]
	v_pk_mul_f32 v[216:217], v[216:217], s[20:21] op_sel_hi:[1,0]
	v_pk_fma_f32 v[118:119], v[118:119], v[142:143], v[222:223]
	v_pk_fma_f32 v[120:121], v[120:121], v[144:145], v[216:217]
	global_store_dwordx4 v[214:215], v[118:121], off
	global_load_dword v187, v[224:225], off
	global_load_dword v216, v[224:225], off offset:4
	v_add_lshl_u32 v118, s6, v182, 1
	v_ashrrev_i32_e32 v119, 31, v118
	v_lshl_add_u64 v[222:223], v[232:233], 0, v[184:185]
	v_lshl_add_u64 v[226:227], v[118:119], 2, s[10:11]
	global_load_dwordx4 v[234:237], v[222:223], off
	global_load_dwordx4 v[118:121], v[218:219], off offset:64
	s_waitcnt vmcnt(0)
	v_sub_f32_e32 v241, v241, v187
	v_sub_f32_e32 v240, v240, v187
	v_sub_f32_e32 v239, v239, v187
	v_sub_f32_e32 v238, v238, v187
	v_pk_mul_f32 v[238:239], v[238:239], v[216:217] op_sel_hi:[1,0]
	v_pk_mul_f32 v[216:217], v[240:241], v[216:217] op_sel_hi:[1,0]
	v_pk_fma_f32 v[238:239], v[146:147], v[238:239], v[150:151]
	v_pk_fma_f32 v[216:217], v[148:149], v[216:217], v[152:153]
	v_pk_mul_f32 v[238:239], v[238:239], s[20:21] op_sel_hi:[1,0]
	v_pk_mul_f32 v[216:217], v[216:217], s[20:21] op_sel_hi:[1,0]
	v_pk_fma_f32 v[114:115], v[114:115], v[142:143], v[238:239]
	v_pk_fma_f32 v[116:117], v[116:117], v[144:145], v[216:217]
	global_store_dwordx4 v[218:219], v[114:117], off
	global_load_dwordx2 v[216:217], v[226:227], off
	s_waitcnt vmcnt(0)
	v_sub_f32_e32 v237, v237, v216
	v_sub_f32_e32 v236, v236, v216
	v_sub_f32_e32 v235, v235, v216
	v_sub_f32_e32 v234, v234, v216
	v_pk_mul_f32 v[234:235], v[234:235], v[216:217] op_sel:[0,1]
	v_pk_mul_f32 v[216:217], v[236:237], v[216:217] op_sel:[0,1]
	v_add_lshl_u32 v114, s6, v186, 1
	v_pk_fma_f32 v[216:217], v[148:149], v[216:217], v[152:153]
	v_pk_fma_f32 v[234:235], v[146:147], v[234:235], v[150:151]
	v_ashrrev_i32_e32 v115, 31, v114
	v_pk_mul_f32 v[234:235], v[234:235], s[20:21] op_sel_hi:[1,0]
	v_pk_mul_f32 v[216:217], v[216:217], s[20:21] op_sel_hi:[1,0]
	v_lshl_add_u64 v[116:117], v[114:115], 2, s[10:11]
	v_lshl_add_u64 v[114:115], v[232:233], 0, v[188:189]
	v_pk_fma_f32 v[112:113], v[112:113], v[144:145], v[216:217]
	v_pk_fma_f32 v[110:111], v[110:111], v[142:143], v[234:235]
	global_load_dwordx4 v[238:241], v[114:115], off
	global_load_dwordx4 v[242:245], v[222:223], off offset:64
	s_nop 0
	global_store_dwordx4 v[222:223], v[110:113], off
	global_load_dword v187, v[116:117], off
	global_load_dword v216, v[116:117], off offset:4
	v_add_lshl_u32 v110, s6, v190, 1
	v_ashrrev_i32_e32 v111, 31, v110
	v_lshl_add_u64 v[112:113], v[110:111], 2, s[10:11]
	v_lshl_add_u64 v[110:111], v[232:233], 0, v[192:193]
	global_load_dwordx4 v[234:237], v[110:111], off
	global_load_dwordx4 v[246:249], v[114:115], off offset:64
	s_waitcnt vmcnt(0)
;     DI void operator()(const f32x4 (&acc)[2][2][4][2], const pg8::Unit& u, int wr, int wc, int fr, int fq) const {
;     ...
;         for (int bj = 0; bj < 2; ++bj) {
;             f32x4 gv[2], gg[2], bb[2], xv[2][8];
; #pragma unroll
;             for (int n = 0; n < 2; ++n) {
;                 const int c = col0 + bj * 128 + n * 16;
;                 gv[n] = *(const f32x4*)(gtp + c);
;                 gg[n] = (f32x4){1.f, 1.f, 1.f, 1.f}; bb[n] = (f32x4){0.f, 0.f, 0.f, 0.f};
;                 if (mode) { gg[n] = *(const f32x4*)(lg + c); bb[n] = *(const f32x4*)(lb + c); }
; #pragma unroll
;                 for (int q = 0; q < 8; ++q) { const int rr = rl + (q >> 2) * 128 + (q & 3) * 16; xv[n][q] = *(const f32x4*)(sbase + (size_t)rr * D + c); }
;             }
; #pragma unroll
;             for (int n = 0; n < 2; ++n) {
;                 const int c = col0 + bj * 128 + n * 16;
; #pragma unroll
;                 for (int q = 0; q < 8; ++q) {
;                     const int rr = rl + (q >> 2) * 128 + (q & 3) * 16;
;                     f32x4 x = xv[n][q];
;                     if (mode) { const float mu = stats[2 * (rowt + rr)], rs = stats[2 * (rowt + rr) + 1]; x = (x - mu) * rs * gg[n] + bb[n]; }
;                     *(f32x4*)(dbase + (size_t)rr * D + c) = ALPHA * x + gv[n] * acc[q >> 2][bj][q & 3][n];
;                 }
	v_sub_f32_e32 v241, v241, v187
	v_sub_f32_e32 v240, v240, v187
	v_sub_f32_e32 v239, v239, v187
	v_sub_f32_e32 v238, v238, v187
	v_pk_mul_f32 v[238:239], v[238:239], v[216:217] op_sel_hi:[1,0]
	v_pk_mul_f32 v[216:217], v[240:241], v[216:217] op_sel_hi:[1,0]
	v_pk_fma_f32 v[238:239], v[146:147], v[238:239], v[150:151]
	v_pk_fma_f32 v[216:217], v[148:149], v[216:217], v[152:153]
	v_pk_mul_f32 v[238:239], v[238:239], s[20:21] op_sel_hi:[1,0]
	v_pk_mul_f32 v[216:217], v[216:217], s[20:21] op_sel_hi:[1,0]
	v_pk_fma_f32 v[106:107], v[106:107], v[142:143], v[238:239]
	v_pk_fma_f32 v[108:109], v[108:109], v[144:145], v[216:217]
	global_store_dwordx4 v[114:115], v[106:109], off
	global_load_dword v187, v[112:113], off
	global_load_dword v216, v[112:113], off offset:4
	v_add_lshl_u32 v106, s6, v194, 1
	v_ashrrev_i32_e32 v107, 31, v106
	v_lshl_add_u64 v[108:109], v[106:107], 2, s[10:11]
	v_lshl_add_u64 v[106:107], v[232:233], 0, v[196:197]
	global_load_dwordx4 v[238:241], v[106:107], off
	global_load_dwordx4 v[250:253], v[110:111], off offset:64
	s_waitcnt vmcnt(0)
	v_sub_f32_e32 v233, v237, v187
	v_sub_f32_e32 v232, v236, v187
	v_sub_f32_e32 v235, v235, v187
	v_sub_f32_e32 v234, v234, v187
	v_pk_mul_f32 v[234:235], v[234:235], v[216:217] op_sel_hi:[1,0]
	v_pk_mul_f32 v[216:217], v[232:233], v[216:217] op_sel_hi:[1,0]
	v_pk_fma_f32 v[232:233], v[146:147], v[234:235], v[150:151]
	v_pk_fma_f32 v[216:217], v[148:149], v[216:217], v[152:153]
	v_pk_mul_f32 v[232:233], v[232:233], s[20:21] op_sel_hi:[1,0]
	v_pk_mul_f32 v[216:217], v[216:217], s[20:21] op_sel_hi:[1,0]
	v_pk_fma_f32 v[98:99], v[98:99], v[142:143], v[232:233]
	v_pk_fma_f32 v[100:101], v[100:101], v[144:145], v[216:217]
	global_store_dwordx4 v[110:111], v[98:101], off
	global_load_dword v187, v[108:109], off
	global_load_dword v216, v[108:109], off offset:4
	s_nop 0
	global_load_dwordx4 v[98:101], v[106:107], off offset:64
	s_waitcnt vmcnt(0)
	v_sub_f32_e32 v233, v241, v187
	v_sub_f32_e32 v232, v240, v187
	v_sub_f32_e32 v235, v239, v187
	v_sub_f32_e32 v234, v238, v187
	v_pk_mul_f32 v[234:235], v[234:235], v[216:217] op_sel_hi:[1,0]
	v_pk_mul_f32 v[216:217], v[232:233], v[216:217] op_sel_hi:[1,0]
	v_pk_fma_f32 v[146:147], v[146:147], v[234:235], v[150:151]
	v_pk_fma_f32 v[148:149], v[148:149], v[216:217], v[152:153]
	v_pk_mul_f32 v[146:147], v[146:147], s[20:21] op_sel_hi:[1,0]
	v_pk_mul_f32 v[148:149], v[148:149], s[20:21] op_sel_hi:[1,0]
	v_pk_fma_f32 v[90:91], v[90:91], v[142:143], v[146:147]
	v_pk_fma_f32 v[92:93], v[92:93], v[144:145], v[148:149]
	global_store_dwordx4 v[106:107], v[90:93], off
	global_load_dwordx2 v[90:91], v[210:211], off
	s_waitcnt vmcnt(0)
	v_sub_f32_e32 v143, v155, v90
	v_sub_f32_e32 v93, v157, v90
	v_sub_f32_e32 v92, v156, v90
	v_sub_f32_e32 v142, v154, v90
	v_pk_mul_f32 v[142:143], v[142:143], v[90:91] op_sel:[0,1]
	v_pk_mul_f32 v[90:91], v[92:93], v[90:91] op_sel:[0,1]
	v_pk_fma_f32 v[92:93], v[134:135], v[142:143], v[138:139]
	v_pk_fma_f32 v[90:91], v[136:137], v[90:91], v[140:141]
	v_pk_mul_f32 v[142:143], v[92:93], s[20:21] op_sel_hi:[1,0]
	v_pk_mul_f32 v[90:91], v[90:91], s[20:21] op_sel_hi:[1,0]
	s_nop 0
	v_pk_fma_f32 v[92:93], v[104:105], v[132:133], v[90:91]
	v_pk_fma_f32 v[90:91], v[102:103], v[130:131], v[142:143]
	global_store_dwordx4 v[206:207], v[90:93], off offset:64
	global_load_dword v91, v[212:213], off
	s_nop 0
	global_load_dword v90, v[212:213], off offset:4
	s_waitcnt vmcnt(0)
	v_sub_f32_e32 v93, v129, v91
	v_sub_f32_e32 v92, v128, v91
	v_sub_f32_e32 v103, v127, v91
	v_sub_f32_e32 v102, v126, v91
	v_pk_mul_f32 v[102:103], v[102:103], v[90:91] op_sel_hi:[1,0]
	v_pk_mul_f32 v[90:91], v[92:93], v[90:91] op_sel_hi:[1,0]
	v_pk_fma_f32 v[92:93], v[134:135], v[102:103], v[138:139]
	v_pk_fma_f32 v[90:91], v[136:137], v[90:91], v[140:141]
	v_pk_mul_f32 v[102:103], v[92:93], s[20:21] op_sel_hi:[1,0]
	v_pk_mul_f32 v[90:91], v[90:91], s[20:21] op_sel_hi:[1,0]
	s_nop 0
	v_pk_fma_f32 v[92:93], v[96:97], v[132:133], v[90:91]
	v_pk_fma_f32 v[90:91], v[94:95], v[130:131], v[102:103]
	global_store_dwordx4 v[208:209], v[90:93], off offset:64
	global_load_dword v91, v[220:221], off
	s_nop 0
	global_load_dword v90, v[220:221], off offset:4
	s_waitcnt vmcnt(0)
	v_sub_f32_e32 v93, v125, v91
	v_sub_f32_e32 v92, v124, v91
	v_sub_f32_e32 v95, v123, v91
	v_sub_f32_e32 v94, v122, v91
	v_pk_mul_f32 v[94:95], v[94:95], v[90:91] op_sel_hi:[1,0]
	v_pk_mul_f32 v[90:91], v[92:93], v[90:91] op_sel_hi:[1,0]
	v_pk_fma_f32 v[92:93], v[134:135], v[94:95], v[138:139]
	v_pk_fma_f32 v[90:91], v[136:137], v[90:91], v[140:141]
	v_pk_mul_f32 v[92:93], v[92:93], s[20:21] op_sel_hi:[1,0]
	v_pk_mul_f32 v[90:91], v[90:91], s[20:21] op_sel_hi:[1,0]
	v_pk_fma_f32 v[86:87], v[86:87], v[130:131], v[92:93]
	v_pk_fma_f32 v[88:89], v[88:89], v[132:133], v[90:91]
	global_store_dwordx4 v[214:215], v[86:89], off offset:64
	global_load_dword v87, v[224:225], off
	s_nop 0
	global_load_dword v86, v[224:225], off offset:4
	s_waitcnt vmcnt(0)
	v_sub_f32_e32 v89, v121, v87
	v_sub_f32_e32 v88, v120, v87
	v_sub_f32_e32 v91, v119, v87
	v_sub_f32_e32 v90, v118, v87
	v_pk_mul_f32 v[90:91], v[90:91], v[86:87] op_sel_hi:[1,0]
	v_pk_mul_f32 v[86:87], v[88:89], v[86:87] op_sel_hi:[1,0]
	v_pk_fma_f32 v[88:89], v[134:135], v[90:91], v[138:139]
	v_pk_fma_f32 v[86:87], v[136:137], v[86:87], v[140:141]
	v_pk_mul_f32 v[88:89], v[88:89], s[20:21] op_sel_hi:[1,0]
	v_pk_mul_f32 v[86:87], v[86:87], s[20:21] op_sel_hi:[1,0]
	v_pk_fma_f32 v[82:83], v[82:83], v[130:131], v[88:89]
	v_pk_fma_f32 v[84:85], v[84:85], v[132:133], v[86:87]
	global_store_dwordx4 v[218:219], v[82:85], off offset:64
	global_load_dwordx2 v[82:83], v[226:227], off
	s_waitcnt vmcnt(0)
;     DI void operator()(const f32x4 (&acc)[2][2][4][2], const pg8::Unit& u, int wr, int wc, int fr, int fq) const {
;     ...
;         for (int bj = 0; bj < 2; ++bj) {
;             f32x4 gv[2], gg[2], bb[2], xv[2][8];
; #pragma unroll
;             for (int n = 0; n < 2; ++n) {
;                 const int c = col0 + bj * 128 + n * 16;
;                 gv[n] = *(const f32x4*)(gtp + c);
;                 gg[n] = (f32x4){1.f, 1.f, 1.f, 1.f}; bb[n] = (f32x4){0.f, 0.f, 0.f, 0.f};
;                 if (mode) { gg[n] = *(const f32x4*)(lg + c); bb[n] = *(const f32x4*)(lb + c); }
; #pragma unroll
;                 for (int q = 0; q < 8; ++q) { const int rr = rl + (q >> 2) * 128 + (q & 3) * 16; xv[n][q] = *(const f32x4*)(sbase + (size_t)rr * D + c); }
;             }
; #pragma unroll
;             for (int n = 0; n < 2; ++n) {
;                 const int c = col0 + bj * 128 + n * 16;
; #pragma unroll
;                 for (int q = 0; q < 8; ++q) {
;                     const int rr = rl + (q >> 2) * 128 + (q & 3) * 16;
;                     f32x4 x = xv[n][q];
;                     if (mode) { const float mu = stats[2 * (rowt + rr)], rs = stats[2 * (rowt + rr) + 1]; x = (x - mu) * rs * gg[n] + bb[n]; }
;                     *(f32x4*)(dbase + (size_t)rr * D + c) = ALPHA * x + gv[n] * acc[q >> 2][bj][q & 3][n];
;                 }
	v_sub_f32_e32 v87, v243, v82
	v_sub_f32_e32 v85, v245, v82
	v_sub_f32_e32 v84, v244, v82
	v_sub_f32_e32 v86, v242, v82
	v_pk_mul_f32 v[86:87], v[86:87], v[82:83] op_sel:[0,1]
	v_pk_mul_f32 v[82:83], v[84:85], v[82:83] op_sel:[0,1]
	v_pk_fma_f32 v[84:85], v[134:135], v[86:87], v[138:139]
	v_pk_fma_f32 v[82:83], v[136:137], v[82:83], v[140:141]
	v_pk_mul_f32 v[84:85], v[84:85], s[20:21] op_sel_hi:[1,0]
	v_pk_mul_f32 v[82:83], v[82:83], s[20:21] op_sel_hi:[1,0]
	v_pk_fma_f32 v[78:79], v[78:79], v[130:131], v[84:85]
	v_pk_fma_f32 v[80:81], v[80:81], v[132:133], v[82:83]
	global_store_dwordx4 v[222:223], v[78:81], off offset:64
	global_load_dword v79, v[116:117], off
	s_nop 0
	global_load_dword v78, v[116:117], off offset:4
	s_waitcnt vmcnt(0)
	v_sub_f32_e32 v81, v249, v79
	v_sub_f32_e32 v80, v248, v79
	v_sub_f32_e32 v83, v247, v79
	v_sub_f32_e32 v82, v246, v79
	v_pk_mul_f32 v[82:83], v[82:83], v[78:79] op_sel_hi:[1,0]
	v_pk_mul_f32 v[78:79], v[80:81], v[78:79] op_sel_hi:[1,0]
	v_pk_fma_f32 v[80:81], v[134:135], v[82:83], v[138:139]
	v_pk_fma_f32 v[78:79], v[136:137], v[78:79], v[140:141]
	v_pk_mul_f32 v[80:81], v[80:81], s[20:21] op_sel_hi:[1,0]
	v_pk_mul_f32 v[78:79], v[78:79], s[20:21] op_sel_hi:[1,0]
	v_pk_fma_f32 v[74:75], v[74:75], v[130:131], v[80:81]
	v_pk_fma_f32 v[76:77], v[76:77], v[132:133], v[78:79]
	global_store_dwordx4 v[114:115], v[74:77], off offset:64
	global_load_dword v75, v[112:113], off
	s_nop 0
	global_load_dword v74, v[112:113], off offset:4
	s_waitcnt vmcnt(0)
	v_sub_f32_e32 v77, v253, v75
	v_sub_f32_e32 v76, v252, v75
	v_sub_f32_e32 v79, v251, v75
	v_sub_f32_e32 v78, v250, v75
	v_pk_mul_f32 v[78:79], v[78:79], v[74:75] op_sel_hi:[1,0]
	v_pk_mul_f32 v[74:75], v[76:77], v[74:75] op_sel_hi:[1,0]
	v_pk_fma_f32 v[76:77], v[134:135], v[78:79], v[138:139]
	v_pk_fma_f32 v[74:75], v[136:137], v[74:75], v[140:141]
	v_pk_mul_f32 v[76:77], v[76:77], s[20:21] op_sel_hi:[1,0]
	v_pk_mul_f32 v[74:75], v[74:75], s[20:21] op_sel_hi:[1,0]
	v_pk_fma_f32 v[70:71], v[70:71], v[130:131], v[76:77]
	v_pk_fma_f32 v[72:73], v[72:73], v[132:133], v[74:75]
	global_store_dwordx4 v[110:111], v[70:73], off offset:64
	global_load_dword v71, v[108:109], off
	s_nop 0
	global_load_dword v70, v[108:109], off offset:4
	v_or_b32_e32 v72, 0x80, v228
	global_load_dwordx4 v[78:81], v[206:207], off offset:512
	v_ashrrev_i32_e32 v73, 31, v72
	s_waitcnt vmcnt(0)
	v_sub_f32_e32 v75, v101, v71
	v_sub_f32_e32 v74, v100, v71
	v_sub_f32_e32 v77, v99, v71
	v_sub_f32_e32 v76, v98, v71
	v_pk_mul_f32 v[76:77], v[76:77], v[70:71] op_sel_hi:[1,0]
	v_pk_mul_f32 v[70:71], v[74:75], v[70:71] op_sel_hi:[1,0]
	v_pk_fma_f32 v[74:75], v[134:135], v[76:77], v[138:139]
	v_pk_fma_f32 v[70:71], v[136:137], v[70:71], v[140:141]
	v_pk_mul_f32 v[74:75], v[74:75], s[20:21] op_sel_hi:[1,0]
	v_pk_mul_f32 v[70:71], v[70:71], s[20:21] op_sel_hi:[1,0]
	v_pk_fma_f32 v[66:67], v[66:67], v[130:131], v[74:75]
	v_pk_fma_f32 v[68:69], v[68:69], v[132:133], v[70:71]
	global_store_dwordx4 v[106:107], v[66:69], off offset:64
	global_load_dwordx2 v[102:103], v[210:211], off
	s_waitcnt vmcnt(0)
	v_sub_f32_e32 v81, v81, v102
	v_lshlrev_b64 v[66:67], 2, v[72:73]
	v_lshl_add_u64 v[68:69], s[14:15], 0, v[66:67]
	v_lshl_add_u64 v[66:67], s[16:17], 0, v[66:67]
	global_load_dwordx4 v[82:85], v[68:69], off
	global_load_dwordx4 v[86:89], v[66:67], off
	global_load_dwordx4 v[90:93], v[230:231], off offset:512
	v_sub_f32_e32 v80, v80, v102
	v_sub_f32_e32 v79, v79, v102
	v_sub_f32_e32 v78, v78, v102
	v_or_b32_e32 v66, 0x90, v228
	v_pk_mul_f32 v[78:79], v[78:79], v[102:103] op_sel:[0,1]
	v_pk_mul_f32 v[80:81], v[80:81], v[102:103] op_sel:[0,1]
	v_ashrrev_i32_e32 v67, 31, v66
	v_lshlrev_b64 v[66:67], 2, v[66:67]
	v_lshl_add_u64 v[70:71], s[14:15], 0, v[66:67]
	v_lshl_add_u64 v[74:75], s[16:17], 0, v[66:67]
	global_load_dwordx4 v[94:97], v[208:209], off offset:512
	global_load_dwordx4 v[98:101], v[206:207], off offset:576
	global_load_dwordx4 v[66:69], v[230:231], off offset:576
	s_nop 0
	global_load_dwordx4 v[70:73], v[70:71], off
	s_nop 0
	global_load_dwordx4 v[74:77], v[74:75], off
	s_waitcnt vmcnt(0)
	v_pk_fma_f32 v[80:81], v[84:85], v[80:81], v[88:89]
	v_pk_fma_f32 v[78:79], v[82:83], v[78:79], v[86:87]
	v_pk_mul_f32 v[80:81], v[80:81], s[20:21] op_sel_hi:[1,0]
	v_pk_mul_f32 v[78:79], v[78:79], s[20:21] op_sel_hi:[1,0]
	v_pk_fma_f32 v[64:65], v[64:65], v[92:93], v[80:81]
	v_pk_fma_f32 v[62:63], v[62:63], v[90:91], v[78:79]
	global_store_dwordx4 v[206:207], v[62:65], off offset:512
	global_load_dword v103, v[212:213], off
	global_load_dword v102, v[212:213], off offset:4
	s_nop 0
	global_load_dwordx4 v[62:65], v[214:215], off offset:512
	global_load_dwordx4 v[78:81], v[208:209], off offset:576
	s_waitcnt vmcnt(0)
	v_sub_f32_e32 v97, v97, v103
	v_sub_f32_e32 v96, v96, v103
	v_sub_f32_e32 v95, v95, v103
	v_sub_f32_e32 v94, v94, v103
	v_pk_mul_f32 v[94:95], v[94:95], v[102:103] op_sel_hi:[1,0]
	v_pk_mul_f32 v[96:97], v[96:97], v[102:103] op_sel_hi:[1,0]
	v_pk_fma_f32 v[94:95], v[82:83], v[94:95], v[86:87]
	v_pk_fma_f32 v[96:97], v[84:85], v[96:97], v[88:89]
	v_pk_mul_f32 v[94:95], v[94:95], s[20:21] op_sel_hi:[1,0]
	v_pk_mul_f32 v[96:97], v[96:97], s[20:21] op_sel_hi:[1,0]
	v_pk_fma_f32 v[58:59], v[58:59], v[90:91], v[94:95]
	v_pk_fma_f32 v[60:61], v[60:61], v[92:93], v[96:97]
	global_store_dwordx4 v[208:209], v[58:61], off offset:512
	global_load_dword v103, v[220:221], off
	global_load_dword v102, v[220:221], off offset:4
	s_nop 0
	global_load_dwordx4 v[58:61], v[218:219], off offset:512
	global_load_dwordx4 v[94:97], v[214:215], off offset:576
	s_waitcnt vmcnt(0)
;     DI void operator()(const f32x4 (&acc)[2][2][4][2], const pg8::Unit& u, int wr, int wc, int fr, int fq) const {
;     ...
;         for (int bj = 0; bj < 2; ++bj) {
;             f32x4 gv[2], gg[2], bb[2], xv[2][8];
; #pragma unroll
;             for (int n = 0; n < 2; ++n) {
;                 const int c = col0 + bj * 128 + n * 16;
;                 gv[n] = *(const f32x4*)(gtp + c);
;                 gg[n] = (f32x4){1.f, 1.f, 1.f, 1.f}; bb[n] = (f32x4){0.f, 0.f, 0.f, 0.f};
;                 if (mode) { gg[n] = *(const f32x4*)(lg + c); bb[n] = *(const f32x4*)(lb + c); }
; #pragma unroll
;                 for (int q = 0; q < 8; ++q) { const int rr = rl + (q >> 2) * 128 + (q & 3) * 16; xv[n][q] = *(const f32x4*)(sbase + (size_t)rr * D + c); }
;             }
; #pragma unroll
;             for (int n = 0; n < 2; ++n) {
;                 const int c = col0 + bj * 128 + n * 16;
; #pragma unroll
;                 for (int q = 0; q < 8; ++q) {
;                     const int rr = rl + (q >> 2) * 128 + (q & 3) * 16;
;                     f32x4 x = xv[n][q];
;                     if (mode) { const float mu = stats[2 * (rowt + rr)], rs = stats[2 * (rowt + rr) + 1]; x = (x - mu) * rs * gg[n] + bb[n]; }
;                     *(f32x4*)(dbase + (size_t)rr * D + c) = ALPHA * x + gv[n] * acc[q >> 2][bj][q & 3][n];
;                 }
	v_sub_f32_e32 v65, v65, v103
	v_sub_f32_e32 v64, v64, v103
	v_sub_f32_e32 v63, v63, v103
	v_sub_f32_e32 v62, v62, v103
	v_pk_mul_f32 v[62:63], v[62:63], v[102:103] op_sel_hi:[1,0]
	v_pk_mul_f32 v[64:65], v[64:65], v[102:103] op_sel_hi:[1,0]
	v_pk_fma_f32 v[62:63], v[82:83], v[62:63], v[86:87]
	v_pk_fma_f32 v[64:65], v[84:85], v[64:65], v[88:89]
	v_pk_mul_f32 v[62:63], v[62:63], s[20:21] op_sel_hi:[1,0]
	v_pk_mul_f32 v[64:65], v[64:65], s[20:21] op_sel_hi:[1,0]
	v_pk_fma_f32 v[54:55], v[54:55], v[90:91], v[62:63]
	v_pk_fma_f32 v[56:57], v[56:57], v[92:93], v[64:65]
	global_store_dwordx4 v[214:215], v[54:57], off offset:512
	global_load_dword v103, v[224:225], off
	global_load_dword v102, v[224:225], off offset:4
	s_nop 0
	global_load_dwordx4 v[54:57], v[222:223], off offset:512
	global_load_dwordx4 v[62:65], v[218:219], off offset:576
	s_waitcnt vmcnt(0)
	v_sub_f32_e32 v61, v61, v103
	v_sub_f32_e32 v60, v60, v103
	v_sub_f32_e32 v59, v59, v103
	v_sub_f32_e32 v58, v58, v103
	v_pk_mul_f32 v[58:59], v[58:59], v[102:103] op_sel_hi:[1,0]
	v_pk_mul_f32 v[60:61], v[60:61], v[102:103] op_sel_hi:[1,0]
	v_pk_fma_f32 v[58:59], v[82:83], v[58:59], v[86:87]
	v_pk_fma_f32 v[60:61], v[84:85], v[60:61], v[88:89]
	v_pk_mul_f32 v[58:59], v[58:59], s[20:21] op_sel_hi:[1,0]
	v_pk_mul_f32 v[60:61], v[60:61], s[20:21] op_sel_hi:[1,0]
	v_pk_fma_f32 v[50:51], v[50:51], v[90:91], v[58:59]
	v_pk_fma_f32 v[52:53], v[52:53], v[92:93], v[60:61]
	global_store_dwordx4 v[218:219], v[50:53], off offset:512
	global_load_dwordx2 v[102:103], v[226:227], off
	s_nop 0
	global_load_dwordx4 v[50:53], v[114:115], off offset:512
	global_load_dwordx4 v[58:61], v[222:223], off offset:576
	s_waitcnt vmcnt(0)
	v_sub_f32_e32 v57, v57, v102
	v_sub_f32_e32 v56, v56, v102
	v_sub_f32_e32 v55, v55, v102
	v_sub_f32_e32 v54, v54, v102
	v_pk_mul_f32 v[54:55], v[54:55], v[102:103] op_sel:[0,1]
	v_pk_mul_f32 v[56:57], v[56:57], v[102:103] op_sel:[0,1]
	v_pk_fma_f32 v[54:55], v[82:83], v[54:55], v[86:87]
	v_pk_fma_f32 v[56:57], v[84:85], v[56:57], v[88:89]
	v_pk_mul_f32 v[54:55], v[54:55], s[20:21] op_sel_hi:[1,0]
	v_pk_mul_f32 v[56:57], v[56:57], s[20:21] op_sel_hi:[1,0]
	v_pk_fma_f32 v[46:47], v[46:47], v[90:91], v[54:55]
	v_pk_fma_f32 v[48:49], v[48:49], v[92:93], v[56:57]
	global_store_dwordx4 v[222:223], v[46:49], off offset:512
	global_load_dword v103, v[116:117], off
	global_load_dword v102, v[116:117], off offset:4
	s_nop 0
	global_load_dwordx4 v[46:49], v[110:111], off offset:512
	global_load_dwordx4 v[54:57], v[114:115], off offset:576
	s_waitcnt vmcnt(0)
	v_sub_f32_e32 v53, v53, v103
	v_sub_f32_e32 v52, v52, v103
	v_sub_f32_e32 v51, v51, v103
	v_sub_f32_e32 v50, v50, v103
	v_pk_mul_f32 v[50:51], v[50:51], v[102:103] op_sel_hi:[1,0]
	v_pk_mul_f32 v[52:53], v[52:53], v[102:103] op_sel_hi:[1,0]
	v_pk_fma_f32 v[50:51], v[82:83], v[50:51], v[86:87]
	v_pk_fma_f32 v[52:53], v[84:85], v[52:53], v[88:89]
	v_pk_mul_f32 v[50:51], v[50:51], s[20:21] op_sel_hi:[1,0]
	v_pk_mul_f32 v[52:53], v[52:53], s[20:21] op_sel_hi:[1,0]
	v_pk_fma_f32 v[42:43], v[42:43], v[90:91], v[50:51]
	v_pk_fma_f32 v[44:45], v[44:45], v[92:93], v[52:53]
	global_store_dwordx4 v[114:115], v[42:45], off offset:512
	global_load_dword v103, v[112:113], off
	global_load_dword v102, v[112:113], off offset:4
	s_nop 0
	global_load_dwordx4 v[42:45], v[106:107], off offset:512
	global_load_dwordx4 v[50:53], v[110:111], off offset:576
	s_waitcnt vmcnt(0)
	v_sub_f32_e32 v49, v49, v103
	v_sub_f32_e32 v48, v48, v103
	v_sub_f32_e32 v47, v47, v103
	v_sub_f32_e32 v46, v46, v103
	v_pk_mul_f32 v[46:47], v[46:47], v[102:103] op_sel_hi:[1,0]
	v_pk_mul_f32 v[48:49], v[48:49], v[102:103] op_sel_hi:[1,0]
	v_pk_fma_f32 v[46:47], v[82:83], v[46:47], v[86:87]
	v_pk_fma_f32 v[48:49], v[84:85], v[48:49], v[88:89]
	v_pk_mul_f32 v[46:47], v[46:47], s[20:21] op_sel_hi:[1,0]
	v_pk_mul_f32 v[48:49], v[48:49], s[20:21] op_sel_hi:[1,0]
	v_pk_fma_f32 v[34:35], v[34:35], v[90:91], v[46:47]
	v_pk_fma_f32 v[36:37], v[36:37], v[92:93], v[48:49]
	global_store_dwordx4 v[110:111], v[34:37], off offset:512
	global_load_dword v47, v[108:109], off
	global_load_dword v46, v[108:109], off offset:4
	s_nop 0
	global_load_dwordx4 v[34:37], v[106:107], off offset:576
	s_waitcnt vmcnt(0)
	v_sub_f32_e32 v45, v45, v47
	v_sub_f32_e32 v44, v44, v47
	v_sub_f32_e32 v43, v43, v47
	v_sub_f32_e32 v42, v42, v47
	v_pk_mul_f32 v[42:43], v[42:43], v[46:47] op_sel_hi:[1,0]
	v_pk_mul_f32 v[44:45], v[44:45], v[46:47] op_sel_hi:[1,0]
	v_pk_fma_f32 v[42:43], v[82:83], v[42:43], v[86:87]
	v_pk_fma_f32 v[44:45], v[84:85], v[44:45], v[88:89]
	v_pk_mul_f32 v[42:43], v[42:43], s[20:21] op_sel_hi:[1,0]
	v_pk_mul_f32 v[44:45], v[44:45], s[20:21] op_sel_hi:[1,0]
	v_pk_fma_f32 v[26:27], v[26:27], v[90:91], v[42:43]
	v_pk_fma_f32 v[28:29], v[28:29], v[92:93], v[44:45]
	global_store_dwordx4 v[106:107], v[26:29], off offset:512
	global_load_dwordx2 v[26:27], v[210:211], off
	s_waitcnt vmcnt(0)
	v_sub_f32_e32 v43, v99, v26
	v_sub_f32_e32 v29, v101, v26
	v_sub_f32_e32 v28, v100, v26
	v_sub_f32_e32 v42, v98, v26
	v_pk_mul_f32 v[42:43], v[42:43], v[26:27] op_sel:[0,1]
	v_pk_mul_f32 v[26:27], v[28:29], v[26:27] op_sel:[0,1]
	v_pk_fma_f32 v[28:29], v[70:71], v[42:43], v[74:75]
	v_pk_fma_f32 v[26:27], v[72:73], v[26:27], v[76:77]
	v_pk_mul_f32 v[42:43], v[28:29], s[20:21] op_sel_hi:[1,0]
	v_pk_mul_f32 v[26:27], v[26:27], s[20:21] op_sel_hi:[1,0]
	s_nop 0
	v_pk_fma_f32 v[28:29], v[40:41], v[68:69], v[26:27]
	v_pk_fma_f32 v[26:27], v[38:39], v[66:67], v[42:43]
	global_store_dwordx4 v[206:207], v[26:29], off offset:576
	global_load_dword v27, v[212:213], off
	s_nop 0
	global_load_dword v26, v[212:213], off offset:4
	s_waitcnt vmcnt(0)
; #define PG8_WAIT_V(n) asm volatile("s_waitcnt vmcnt(" #n ")" ::: "memory")
; #define PG8_BAR __builtin_amdgcn_s_barrier()
; template <class Epi>
; DI void gemm_phase(LAS unsigned char* lds, const Gemm g, const StaticOrder& S, const Epi& E) {
;     ...
;         E(acc, cur, wr, wc, fr, fq);
;         if (!has_next) break;
; #pragma unroll
;         for (int a = 0; a < 2; ++a)
; #pragma unroll
;             for (int b = 0; b < 2; ++b)
; #pragma unroll
;                 for (int m = 0; m < 4; ++m)
; #pragma unroll
;                     for (int n = 0; n < 2; ++n) acc[a][b][m][n] = (f32x4){0.f, 0.f, 0.f, 0.f};
;         cur = nxt; cA = nA; cB = nB; ++ui;
;     }
;     PG8_WAIT_V(0);
;     if (wr == 0) PG8_BAR;
;     PG8_BAR;
;     DI void operator()(const f32x4 (&acc)[2][2][4][2], const pg8::Unit& u, int wr, int wc, int fr, int fq) const {
;     ...
;         for (int bj = 0; bj < 2; ++bj) {
;             f32x4 gv[2], gg[2], bb[2], xv[2][8];
; #pragma unroll
;             for (int n = 0; n < 2; ++n) {
;                 const int c = col0 + bj * 128 + n * 16;
;                 gv[n] = *(const f32x4*)(gtp + c);
;                 gg[n] = (f32x4){1.f, 1.f, 1.f, 1.f}; bb[n] = (f32x4){0.f, 0.f, 0.f, 0.f};
;                 if (mode) { gg[n] = *(const f32x4*)(lg + c); bb[n] = *(const f32x4*)(lb + c); }
; #pragma unroll
;                 for (int q = 0; q < 8; ++q) { const int rr = rl + (q >> 2) * 128 + (q & 3) * 16; xv[n][q] = *(const f32x4*)(sbase + (size_t)rr * D + c); }
;             }
; #pragma unroll
;             for (int n = 0; n < 2; ++n) {
;                 const int c = col0 + bj * 128 + n * 16;
; #pragma unroll
;                 for (int q = 0; q < 8; ++q) {
;                     const int rr = rl + (q >> 2) * 128 + (q & 3) * 16;
;                     f32x4 x = xv[n][q];
;                     if (mode) { const float mu = stats[2 * (rowt + rr)], rs = stats[2 * (rowt + rr) + 1]; x = (x - mu) * rs * gg[n] + bb[n]; }
;                     *(f32x4*)(dbase + (size_t)rr * D + c) = ALPHA * x + gv[n] * acc[q >> 2][bj][q & 3][n];
;                 }
	v_sub_f32_e32 v29, v81, v27
	v_sub_f32_e32 v28, v80, v27
	v_sub_f32_e32 v39, v79, v27
	v_sub_f32_e32 v38, v78, v27
	v_pk_mul_f32 v[38:39], v[38:39], v[26:27] op_sel_hi:[1,0]
	v_pk_mul_f32 v[26:27], v[28:29], v[26:27] op_sel_hi:[1,0]
	v_pk_fma_f32 v[28:29], v[70:71], v[38:39], v[74:75]
	v_pk_fma_f32 v[26:27], v[72:73], v[26:27], v[76:77]
	v_pk_mul_f32 v[38:39], v[28:29], s[20:21] op_sel_hi:[1,0]
	v_pk_mul_f32 v[26:27], v[26:27], s[20:21] op_sel_hi:[1,0]
	s_nop 0
	v_pk_fma_f32 v[28:29], v[32:33], v[68:69], v[26:27]
	v_pk_fma_f32 v[26:27], v[30:31], v[66:67], v[38:39]
	global_store_dwordx4 v[208:209], v[26:29], off offset:576
	global_load_dword v27, v[220:221], off
	s_nop 0
	global_load_dword v26, v[220:221], off offset:4
	s_waitcnt vmcnt(0)
	v_sub_f32_e32 v29, v97, v27
	v_sub_f32_e32 v28, v96, v27
	v_sub_f32_e32 v31, v95, v27
	v_sub_f32_e32 v30, v94, v27
	v_pk_mul_f32 v[30:31], v[30:31], v[26:27] op_sel_hi:[1,0]
	v_pk_mul_f32 v[26:27], v[28:29], v[26:27] op_sel_hi:[1,0]
	v_pk_fma_f32 v[28:29], v[70:71], v[30:31], v[74:75]
	v_pk_fma_f32 v[26:27], v[72:73], v[26:27], v[76:77]
	v_pk_mul_f32 v[28:29], v[28:29], s[20:21] op_sel_hi:[1,0]
	v_pk_mul_f32 v[26:27], v[26:27], s[20:21] op_sel_hi:[1,0]
	v_pk_fma_f32 v[22:23], v[22:23], v[66:67], v[28:29]
	v_pk_fma_f32 v[24:25], v[24:25], v[68:69], v[26:27]
	global_store_dwordx4 v[214:215], v[22:25], off offset:576
	global_load_dword v23, v[224:225], off
	s_nop 0
	global_load_dword v22, v[224:225], off offset:4
	s_waitcnt vmcnt(0)
	v_sub_f32_e32 v25, v65, v23
	v_sub_f32_e32 v24, v64, v23
	v_sub_f32_e32 v27, v63, v23
	v_sub_f32_e32 v26, v62, v23
	v_pk_mul_f32 v[26:27], v[26:27], v[22:23] op_sel_hi:[1,0]
	v_pk_mul_f32 v[22:23], v[24:25], v[22:23] op_sel_hi:[1,0]
	v_pk_fma_f32 v[24:25], v[70:71], v[26:27], v[74:75]
	v_pk_fma_f32 v[22:23], v[72:73], v[22:23], v[76:77]
	v_pk_mul_f32 v[24:25], v[24:25], s[20:21] op_sel_hi:[1,0]
	v_pk_mul_f32 v[22:23], v[22:23], s[20:21] op_sel_hi:[1,0]
	v_pk_fma_f32 v[18:19], v[18:19], v[66:67], v[24:25]
	v_pk_fma_f32 v[20:21], v[20:21], v[68:69], v[22:23]
	global_store_dwordx4 v[218:219], v[18:21], off offset:576
	global_load_dwordx2 v[18:19], v[226:227], off
	s_waitcnt vmcnt(0)
	v_sub_f32_e32 v23, v59, v18
	v_sub_f32_e32 v21, v61, v18
	v_sub_f32_e32 v20, v60, v18
	v_sub_f32_e32 v22, v58, v18
	v_pk_mul_f32 v[22:23], v[22:23], v[18:19] op_sel:[0,1]
	v_pk_mul_f32 v[18:19], v[20:21], v[18:19] op_sel:[0,1]
	v_pk_fma_f32 v[20:21], v[70:71], v[22:23], v[74:75]
	v_pk_fma_f32 v[18:19], v[72:73], v[18:19], v[76:77]
	v_pk_mul_f32 v[20:21], v[20:21], s[20:21] op_sel_hi:[1,0]
	v_pk_mul_f32 v[18:19], v[18:19], s[20:21] op_sel_hi:[1,0]
	v_pk_fma_f32 v[14:15], v[14:15], v[66:67], v[20:21]
	v_pk_fma_f32 v[16:17], v[16:17], v[68:69], v[18:19]
	global_store_dwordx4 v[222:223], v[14:17], off offset:576
	global_load_dword v15, v[116:117], off
	s_nop 0
	global_load_dword v14, v[116:117], off offset:4
	s_waitcnt vmcnt(0)
	v_sub_f32_e32 v17, v57, v15
	v_sub_f32_e32 v16, v56, v15
	v_sub_f32_e32 v19, v55, v15
	v_sub_f32_e32 v18, v54, v15
	v_pk_mul_f32 v[18:19], v[18:19], v[14:15] op_sel_hi:[1,0]
	v_pk_mul_f32 v[14:15], v[16:17], v[14:15] op_sel_hi:[1,0]
	v_pk_fma_f32 v[16:17], v[70:71], v[18:19], v[74:75]
	v_pk_fma_f32 v[14:15], v[72:73], v[14:15], v[76:77]
	v_pk_mul_f32 v[16:17], v[16:17], s[20:21] op_sel_hi:[1,0]
	v_pk_mul_f32 v[14:15], v[14:15], s[20:21] op_sel_hi:[1,0]
	v_pk_fma_f32 v[10:11], v[10:11], v[66:67], v[16:17]
	v_pk_fma_f32 v[12:13], v[12:13], v[68:69], v[14:15]
	global_store_dwordx4 v[114:115], v[10:13], off offset:576
	global_load_dword v11, v[112:113], off
	s_nop 0
	global_load_dword v10, v[112:113], off offset:4
	s_waitcnt vmcnt(0)
	v_sub_f32_e32 v13, v53, v11
	v_sub_f32_e32 v12, v52, v11
	v_sub_f32_e32 v15, v51, v11
	v_sub_f32_e32 v14, v50, v11
	v_pk_mul_f32 v[14:15], v[14:15], v[10:11] op_sel_hi:[1,0]
	v_pk_mul_f32 v[10:11], v[12:13], v[10:11] op_sel_hi:[1,0]
	v_pk_fma_f32 v[12:13], v[70:71], v[14:15], v[74:75]
	v_pk_fma_f32 v[10:11], v[72:73], v[10:11], v[76:77]
	v_pk_mul_f32 v[12:13], v[12:13], s[20:21] op_sel_hi:[1,0]
	v_pk_mul_f32 v[10:11], v[10:11], s[20:21] op_sel_hi:[1,0]
	v_pk_fma_f32 v[6:7], v[6:7], v[66:67], v[12:13]
	v_pk_fma_f32 v[8:9], v[8:9], v[68:69], v[10:11]
	global_store_dwordx4 v[110:111], v[6:9], off offset:576
	global_load_dword v7, v[108:109], off
	s_nop 0
	global_load_dword v6, v[108:109], off offset:4
	s_waitcnt vmcnt(0)
	v_sub_f32_e32 v9, v37, v7
	v_sub_f32_e32 v8, v36, v7
	v_sub_f32_e32 v11, v35, v7
	v_sub_f32_e32 v10, v34, v7
	v_pk_mul_f32 v[10:11], v[10:11], v[6:7] op_sel_hi:[1,0]
	v_pk_mul_f32 v[6:7], v[8:9], v[6:7] op_sel_hi:[1,0]
	v_pk_fma_f32 v[8:9], v[70:71], v[10:11], v[74:75]
	v_pk_fma_f32 v[6:7], v[72:73], v[6:7], v[76:77]
	v_pk_mul_f32 v[8:9], v[8:9], s[20:21] op_sel_hi:[1,0]
	v_pk_mul_f32 v[6:7], v[6:7], s[20:21] op_sel_hi:[1,0]
	v_pk_fma_f32 v[2:3], v[2:3], v[66:67], v[8:9]
	v_pk_fma_f32 v[4:5], v[4:5], v[68:69], v[6:7]
	global_store_dwordx4 v[106:107], v[2:5], off offset:576
	s_cbranch_vccz .LBB0_2300
	s_waitcnt vmcnt(0)
	s_cmpk_gt_u32 s21, 0xff
	s_cbranch_scc1 .LBB0_2309
	s_barrier
